# lean P3/P10/P13 loops walk each wave's rows from the highest down (cache residency order)
# baseline (speedup 1.0000x reference)
;     __device__ __forceinline__ const float* in(int i) const { return karg_in(i); }
; __device__ __forceinline__ const float* xrow_ptr(const Ctx& C, int row) { return row < MPROMPT ? C.in(0) + (size_t)row * DM : C.in(1) + (size_t)(row - MPROMPT) * DM; }
; __device__ __forceinline__ v4f ld4_bf16(const bf16* p) { const v2u w = *(const v2u*)p; return (v4f){bf_lo(w.x), bf_hi(w.x), bf_lo(w.y), bf_hi(w.y)}; }
; __device__ __forceinline__ float ssq4(v4f v) { return (v.x * v.x + v.y * v.y) + (v.z * v.z + v.w * v.w); }
; #define FTID const int ftid_ = fresh_tid()
; template <int R, bool BASE_F32, bool OUT_F32>
; __device__ __forceinline__ void rows_res(const Ctx& C, int m0, int stride, int mx, const float* gpost, float scale, int lane) {
;     ...
;     const bf16* D = C.D(); bf16* XN = C.XN();
; #pragma unroll
;     for (int r = 0; r < R; ++r) { mr[r] = (r == 4) ? mx : m0 + r * stride; ok[r] = (r == 4) ? (mx < M) : (mr[r] < MPROMPT); const int mm = ok[r] ? mr[r] : 0;
; #pragma unroll
;         for (int j = 0; j < 4; ++j) d[r][j] = ld4_bf16(D + (size_t)mm * DM + 4 * lane + 256 * j);
;         if (BASE_F32) { const float* x = xrow_ptr(C, mm);
; #pragma unroll
;             for (int j = 0; j < 4; ++j) b[r][j] = ld4_f32(x + 4 * lane + 256 * j);
;         } else { const float inv = C.RS()[mm];
; #pragma unroll
;             for (int j = 0; j < 4; ++j) b[r][j] = ld4_bf16(XN + (size_t)mm * DM + 4 * lane + 256 * j) * inv;
;         } }
; #pragma unroll
;     for (int r = 0; r < R; ++r) { float s = 0.f;
; #pragma unroll
;         for (int j = 0; j < 4; ++j) s += ssq4(d[r][j]);
;         r1[r] = s; }
; __global__ void __launch_bounds__(NTHREADS, 2) fwd_kernel(Args args) {
;     ...
;     { FTID; const float* gp = C.in(8); { const int gw_ = GWV, ngw_ = NGWV, nit = (MPROMPT + 4 * ngw_ - 1) / (4 * ngw_);
;       for (int it = 0; it < nit - 1; ++it) rows_res<4, false, false>(C, gw_ + 4 * it * ngw_, ngw_, M, gp, 0.5f, LANE);
.LBB0_366:
	s_or_b64 exec, exec, s[6:7]
	s_waitcnt lgkmcnt(0)
	v_mov_b32_e32 v0, v182
	s_mov_b64 s[0:1], s[80:81]
	s_barrier
	s_load_dwordx2 s[14:15], s[0:1], 0x40
	v_readfirstlane_b32 s0, v0
	s_ashr_i32 s47, s0, 6
	v_readlane_b32 s0, v232, 0
	s_add_i32 s42, s47, s0
	v_readlane_b32 s0, v232, 1
	v_and_b32_e32 v189, 63, v0
	v_readlane_b32 s1, v232, 2
	v_lshlrev_b32_e32 v0, 2, v189
	v_mov_b32_e32 v1, 0
	v_cndmask_b32_e64 v2, 0, 1, s[0:1]
	v_cmp_ne_u32_e64 s[6:7], 1, v2
	s_andn2_b64 vcc, exec, s[0:1]
	v_lshlrev_b32_e32 v2, 2, v0
	v_cmp_ne_u32_e64 s[8:9], 0, v189
	v_lshlrev_b32_e32 v0, 1, v0
	s_load_dwordx2 s[98:99], s[80:81], 0x110
	s_load_dwordx2 s[100:101], s[80:81], 0x40
	v_and_b32_e32 v176, 63, v182
	v_lshlrev_b32_e32 v170, 3, v176
	s_lshl_b32 vcc_lo, s42, 11
	v_add_u32_e32 v170, vcc_lo, v170
	v_add_u32_e32 v171, 0x3000000, v170
	v_add_u32_e32 v170, 0x7100000, v170
	v_mov_b32_e32 v173, v171
	s_lshl_b32 vcc_lo, s42, 2
	v_mov_b32_e32 v172, 0x2a80000
	v_add_u32_e32 v172, vcc_lo, v172
	v_mov_b32_e32 v174, v172
	v_lshlrev_b32_e32 v176, 4, v176
	v_mov_b32_e32 v138, 0x358637bd
	v_add_u32_e32 v170, 0x2c00000, v170
	v_add_u32_e32 v171, 0x2c00000, v171
	v_add_u32_e32 v173, 0x2c00000, v173
	v_add_u32_e32 v172, 0x16000, v172
	v_add_u32_e32 v174, 0x16000, v174
	s_waitcnt lgkmcnt(0)
	global_load_dwordx4 v[192:195], v176, s[100:101]
	global_load_dwordx4 v[196:199], v176, s[100:101] offset:1024
	global_load_dwordx4 v[200:203], v176, s[100:101] offset:2048
	global_load_dwordx4 v[204:207], v176, s[100:101] offset:3072
	global_load_dword v52, v172, s[98:99]
	global_load_dwordx2 v[20:21], v170, s[98:99]
	global_load_dwordx2 v[22:23], v170, s[98:99] offset:512
	global_load_dwordx2 v[24:25], v170, s[98:99] offset:1024
	global_load_dwordx2 v[26:27], v170, s[98:99] offset:1536
	global_load_dwordx2 v[36:37], v171, s[98:99]
	global_load_dwordx2 v[38:39], v171, s[98:99] offset:512
	global_load_dwordx2 v[40:41], v171, s[98:99] offset:1024
	global_load_dwordx2 v[42:43], v171, s[98:99] offset:1536
	v_add_u32_e32 v170, 0xffc00000, v170
	v_add_u32_e32 v171, 0xffc00000, v171
	v_add_u32_e32 v172, 0xffffe000, v172
	global_load_dword v54, v172, s[98:99]
	global_load_dwordx2 v[28:29], v170, s[98:99]
	global_load_dwordx2 v[30:31], v170, s[98:99] offset:512
	global_load_dwordx2 v[32:33], v170, s[98:99] offset:1024
	global_load_dwordx2 v[34:35], v170, s[98:99] offset:1536
	global_load_dwordx2 v[44:45], v171, s[98:99]
	global_load_dwordx2 v[46:47], v171, s[98:99] offset:512
	global_load_dwordx2 v[48:49], v171, s[98:99] offset:1024
	global_load_dwordx2 v[50:51], v171, s[98:99] offset:1536
	v_add_u32_e32 v170, 0xffc00000, v170
	v_add_u32_e32 v171, 0xffc00000, v171
	v_add_u32_e32 v172, 0xffffe000, v172
	global_load_dword v88, v172, s[98:99]
	global_load_dwordx2 v[56:57], v170, s[98:99]
	global_load_dwordx2 v[58:59], v170, s[98:99] offset:512
	global_load_dwordx2 v[60:61], v170, s[98:99] offset:1024
	global_load_dwordx2 v[62:63], v170, s[98:99] offset:1536
	global_load_dwordx2 v[72:73], v171, s[98:99]
	global_load_dwordx2 v[74:75], v171, s[98:99] offset:512
	global_load_dwordx2 v[76:77], v171, s[98:99] offset:1024
	global_load_dwordx2 v[78:79], v171, s[98:99] offset:1536
	v_add_u32_e32 v170, 0xffc00000, v170
	v_add_u32_e32 v171, 0xffc00000, v171
	v_add_u32_e32 v172, 0xffffe000, v172
	global_load_dword v90, v172, s[98:99]
	global_load_dwordx2 v[64:65], v170, s[98:99]
	global_load_dwordx2 v[66:67], v170, s[98:99] offset:512
	global_load_dwordx2 v[68:69], v170, s[98:99] offset:1024
	global_load_dwordx2 v[70:71], v170, s[98:99] offset:1536
	global_load_dwordx2 v[80:81], v171, s[98:99]
	global_load_dwordx2 v[82:83], v171, s[98:99] offset:512
	global_load_dwordx2 v[84:85], v171, s[98:99] offset:1024
	global_load_dwordx2 v[86:87], v171, s[98:99] offset:1536
	v_add_u32_e32 v170, 0xffc00000, v170
	v_add_u32_e32 v171, 0xffc00000, v171
	v_add_u32_e32 v172, 0xffffe000, v172
	s_waitcnt vmcnt(31)
	v_lshlrev_b32_e32 v96, 16, v20
	v_and_b32_e32 v97, 0xffff0000, v20
	v_lshlrev_b32_e32 v98, 16, v21
	v_and_b32_e32 v99, 0xffff0000, v21
	v_lshlrev_b32_e32 v100, 16, v22
	v_and_b32_e32 v101, 0xffff0000, v22
	v_lshlrev_b32_e32 v102, 16, v23
	v_and_b32_e32 v103, 0xffff0000, v23
	v_lshlrev_b32_e32 v104, 16, v24
	v_and_b32_e32 v105, 0xffff0000, v24
	v_lshlrev_b32_e32 v106, 16, v25
	v_and_b32_e32 v107, 0xffff0000, v25
	v_lshlrev_b32_e32 v108, 16, v26
	v_and_b32_e32 v109, 0xffff0000, v26
	v_lshlrev_b32_e32 v110, 16, v27
	v_and_b32_e32 v111, 0xffff0000, v27
	v_pk_mul_f32 v[128:129], v[96:97], v[96:97]
	v_pk_fma_f32 v[128:129], v[98:99], v[98:99], v[128:129]
	v_pk_fma_f32 v[128:129], v[100:101], v[100:101], v[128:129]
	v_pk_fma_f32 v[128:129], v[102:103], v[102:103], v[128:129]
	v_pk_fma_f32 v[128:129], v[104:105], v[104:105], v[128:129]
	v_pk_fma_f32 v[128:129], v[106:107], v[106:107], v[128:129]
	v_pk_fma_f32 v[128:129], v[108:109], v[108:109], v[128:129]
	v_pk_fma_f32 v[128:129], v[110:111], v[110:111], v[128:129]
	s_nop 0
	v_add_f32_e32 v128, v128, v129
	s_waitcnt vmcnt(22)
;     __device__ __forceinline__ float* out() const { return (float*)karg_in(33); }
; __device__ __forceinline__ float ssq4(v4f v) { return (v.x * v.x + v.y * v.y) + (v.z * v.z + v.w * v.w); }
; template <int R, bool BASE_F32, bool OUT_F32>
; __device__ __forceinline__ void rows_res(const Ctx& C, int m0, int stride, int mx, const float* gpost, float scale, int lane) {
;     ...
;     for (int r = 0; r < R; ++r) { float s = 0.f;
; #pragma unroll
;         for (int j = 0; j < 4; ++j) s += ssq4(d[r][j]);
;         r1[r] = s; }
; #pragma unroll
;     for (int r = 0; r < R; ++r) r1[r] = rsqrtf(wave_sum(r1[r]) * (1.f / DM) + EPS) * scale;
; #pragma unroll
;     for (int j = 0; j < 4; ++j) { const v4f gp = ld4_f32(gpost + 4 * lane + 256 * j);
; #pragma unroll
;         for (int r = 0; r < R; ++r) d[r][j] = b[r][j] + d[r][j] * r1[r] * gp; }
;     if (OUT_F32) { float* Y = C.out();
; #pragma unroll
;         for (int r = 0; r < R; ++r)
; #pragma unroll
;             for (int j = 0; j < 4; ++j) if (ok[r]) *(v4f*)(Y + (size_t)mr[r] * DM + 4 * lane + 256 * j) = d[r][j];
;     } else { float* rs = C.RS(); float t[R];
; #pragma unroll
;         for (int r = 0; r < R; ++r) { float s = 0.f;
; #pragma unroll
;             for (int j = 0; j < 4; ++j) s += ssq4(d[r][j]);
;             t[r] = s; }
	v_lshlrev_b32_e32 v112, 16, v28
	v_and_b32_e32 v113, 0xffff0000, v28
	v_lshlrev_b32_e32 v114, 16, v29
	v_and_b32_e32 v115, 0xffff0000, v29
	v_lshlrev_b32_e32 v116, 16, v30
	v_and_b32_e32 v117, 0xffff0000, v30
	v_lshlrev_b32_e32 v118, 16, v31
	v_and_b32_e32 v119, 0xffff0000, v31
	v_lshlrev_b32_e32 v120, 16, v32
	v_and_b32_e32 v121, 0xffff0000, v32
	v_lshlrev_b32_e32 v122, 16, v33
	v_and_b32_e32 v123, 0xffff0000, v33
	v_lshlrev_b32_e32 v124, 16, v34
	v_and_b32_e32 v125, 0xffff0000, v34
	v_lshlrev_b32_e32 v126, 16, v35
	v_and_b32_e32 v127, 0xffff0000, v35
	v_pk_mul_f32 v[130:131], v[112:113], v[112:113]
	v_pk_fma_f32 v[130:131], v[114:115], v[114:115], v[130:131]
	v_pk_fma_f32 v[130:131], v[116:117], v[116:117], v[130:131]
	v_pk_fma_f32 v[130:131], v[118:119], v[118:119], v[130:131]
	v_pk_fma_f32 v[130:131], v[120:121], v[120:121], v[130:131]
	v_pk_fma_f32 v[130:131], v[122:123], v[122:123], v[130:131]
	v_pk_fma_f32 v[130:131], v[124:125], v[124:125], v[130:131]
	v_pk_fma_f32 v[130:131], v[126:127], v[126:127], v[130:131]
	s_nop 0
	v_add_f32_e32 v130, v130, v131
	s_nop 1
	v_add_f32_dpp v128, v128, v128 quad_perm:[1,0,3,2] row_mask:0xf bank_mask:0xf
	v_add_f32_dpp v130, v130, v130 quad_perm:[1,0,3,2] row_mask:0xf bank_mask:0xf
	s_nop 0
	v_add_f32_dpp v128, v128, v128 quad_perm:[2,3,0,1] row_mask:0xf bank_mask:0xf
	v_add_f32_dpp v130, v130, v130 quad_perm:[2,3,0,1] row_mask:0xf bank_mask:0xf
	s_nop 0
	v_add_f32_dpp v128, v128, v128 row_half_mirror row_mask:0xf bank_mask:0xf
	v_add_f32_dpp v130, v130, v130 row_half_mirror row_mask:0xf bank_mask:0xf
	s_nop 0
	v_add_f32_dpp v128, v128, v128 row_mirror row_mask:0xf bank_mask:0xf
	v_add_f32_dpp v130, v130, v130 row_mirror row_mask:0xf bank_mask:0xf
	s_nop 0
	ds_bpermute_b32 v136, v187, v128
	ds_bpermute_b32 v137, v187, v130
	s_waitcnt lgkmcnt(0)
	v_add_f32_e32 v128, v128, v136
	v_add_f32_e32 v130, v130, v137
	ds_bpermute_b32 v136, v188, v128
	ds_bpermute_b32 v137, v188, v130
	s_waitcnt lgkmcnt(0)
	v_add_f32_e32 v128, v128, v136
	v_add_f32_e32 v130, v130, v137
	v_fmamk_f32 v128, v128, 0x3a800000, v138
	v_fmamk_f32 v130, v130, 0x3a800000, v138
	s_nop 0
	v_rsq_f32_e32 v128, v128
	v_rsq_f32_e32 v130, v130
	s_nop 1
	v_mul_f32_e32 v128, 0.5, v128
	v_mul_f32_e32 v130, 0.5, v130
	s_waitcnt vmcnt(18)
	v_pk_mul_f32 v[96:97], v[128:129], v[96:97] op_sel_hi:[0,1]
	v_pk_mul_f32 v[98:99], v[128:129], v[98:99] op_sel_hi:[0,1]
	v_pk_mul_f32 v[100:101], v[128:129], v[100:101] op_sel_hi:[0,1]
	v_pk_mul_f32 v[102:103], v[128:129], v[102:103] op_sel_hi:[0,1]
	v_pk_mul_f32 v[104:105], v[128:129], v[104:105] op_sel_hi:[0,1]
	v_pk_mul_f32 v[106:107], v[128:129], v[106:107] op_sel_hi:[0,1]
	v_pk_mul_f32 v[108:109], v[128:129], v[108:109] op_sel_hi:[0,1]
	v_pk_mul_f32 v[110:111], v[128:129], v[110:111] op_sel_hi:[0,1]
	v_pk_mul_f32 v[96:97], v[96:97], v[192:193]
	v_pk_mul_f32 v[98:99], v[98:99], v[194:195]
	v_pk_mul_f32 v[100:101], v[100:101], v[196:197]
	v_pk_mul_f32 v[102:103], v[102:103], v[198:199]
	v_pk_mul_f32 v[104:105], v[104:105], v[200:201]
	v_pk_mul_f32 v[106:107], v[106:107], v[202:203]
	v_pk_mul_f32 v[108:109], v[108:109], v[204:205]
	v_pk_mul_f32 v[110:111], v[110:111], v[206:207]
	v_lshlrev_b32_e32 v20, 16, v36
	v_and_b32_e32 v21, 0xffff0000, v36
	v_lshlrev_b32_e32 v22, 16, v37
	v_and_b32_e32 v23, 0xffff0000, v37
	v_lshlrev_b32_e32 v24, 16, v38
	v_and_b32_e32 v25, 0xffff0000, v38
	v_lshlrev_b32_e32 v26, 16, v39
	v_and_b32_e32 v27, 0xffff0000, v39
	v_pk_fma_f32 v[96:97], v[52:53], v[20:21], v[96:97] op_sel_hi:[0,1,1]
	v_pk_fma_f32 v[98:99], v[52:53], v[22:23], v[98:99] op_sel_hi:[0,1,1]
	v_pk_fma_f32 v[100:101], v[52:53], v[24:25], v[100:101] op_sel_hi:[0,1,1]
	v_pk_fma_f32 v[102:103], v[52:53], v[26:27], v[102:103] op_sel_hi:[0,1,1]
	v_lshlrev_b32_e32 v20, 16, v40
	v_and_b32_e32 v21, 0xffff0000, v40
	v_lshlrev_b32_e32 v22, 16, v41
	v_and_b32_e32 v23, 0xffff0000, v41
	v_lshlrev_b32_e32 v24, 16, v42
	v_and_b32_e32 v25, 0xffff0000, v42
	v_lshlrev_b32_e32 v26, 16, v43
	v_and_b32_e32 v27, 0xffff0000, v43
	v_pk_fma_f32 v[104:105], v[52:53], v[20:21], v[104:105] op_sel_hi:[0,1,1]
	v_pk_fma_f32 v[106:107], v[52:53], v[22:23], v[106:107] op_sel_hi:[0,1,1]
	v_pk_fma_f32 v[108:109], v[52:53], v[24:25], v[108:109] op_sel_hi:[0,1,1]
	v_pk_fma_f32 v[110:111], v[52:53], v[26:27], v[110:111] op_sel_hi:[0,1,1]
	v_pk_mul_f32 v[132:133], v[96:97], v[96:97]
	v_pk_fma_f32 v[132:133], v[98:99], v[98:99], v[132:133]
	v_pk_fma_f32 v[132:133], v[100:101], v[100:101], v[132:133]
	v_pk_fma_f32 v[132:133], v[102:103], v[102:103], v[132:133]
	v_pk_fma_f32 v[132:133], v[104:105], v[104:105], v[132:133]
	v_pk_fma_f32 v[132:133], v[106:107], v[106:107], v[132:133]
	v_pk_fma_f32 v[132:133], v[108:109], v[108:109], v[132:133]
	v_pk_fma_f32 v[132:133], v[110:111], v[110:111], v[132:133]
	s_nop 0
	v_add_f32_e32 v132, v132, v133
	v_pk_mul_f32 v[112:113], v[130:131], v[112:113] op_sel_hi:[0,1]
	v_pk_mul_f32 v[114:115], v[130:131], v[114:115] op_sel_hi:[0,1]
	v_pk_mul_f32 v[116:117], v[130:131], v[116:117] op_sel_hi:[0,1]
	v_pk_mul_f32 v[118:119], v[130:131], v[118:119] op_sel_hi:[0,1]
	v_pk_mul_f32 v[120:121], v[130:131], v[120:121] op_sel_hi:[0,1]
	v_pk_mul_f32 v[122:123], v[130:131], v[122:123] op_sel_hi:[0,1]
	v_pk_mul_f32 v[124:125], v[130:131], v[124:125] op_sel_hi:[0,1]
	v_pk_mul_f32 v[126:127], v[130:131], v[126:127] op_sel_hi:[0,1]
	v_pk_mul_f32 v[112:113], v[112:113], v[192:193]
	v_pk_mul_f32 v[114:115], v[114:115], v[194:195]
	v_pk_mul_f32 v[116:117], v[116:117], v[196:197]
	v_pk_mul_f32 v[118:119], v[118:119], v[198:199]
	v_pk_mul_f32 v[120:121], v[120:121], v[200:201]
	v_pk_mul_f32 v[122:123], v[122:123], v[202:203]
;     __device__ __forceinline__ float* out() const { return (float*)karg_in(33); }
; __device__ __forceinline__ const float* xrow_ptr(const Ctx& C, int row) { return row < MPROMPT ? C.in(0) + (size_t)row * DM : C.in(1) + (size_t)(row - MPROMPT) * DM; }
; __device__ __forceinline__ v4f ld4_bf16(const bf16* p) { const v2u w = *(const v2u*)p; return (v4f){bf_lo(w.x), bf_hi(w.x), bf_lo(w.y), bf_hi(w.y)}; }
; __device__ __forceinline__ void st4_bf16(bf16* p, v4f o) { v2u w; w.x = cvt_pk_nv(o.x, o.y); w.y = cvt_pk_nv(o.z, o.w); *(v2u*)p = w; }
; template <int R, bool BASE_F32, bool OUT_F32>
; __device__ __forceinline__ void rows_res(const Ctx& C, int m0, int stride, int mx, const float* gpost, float scale, int lane) {
;     ...
;     for (int r = 0; r < R; ++r) { mr[r] = (r == 4) ? mx : m0 + r * stride; ok[r] = (r == 4) ? (mx < M) : (mr[r] < MPROMPT); const int mm = ok[r] ? mr[r] : 0;
; #pragma unroll
;         for (int j = 0; j < 4; ++j) d[r][j] = ld4_bf16(D + (size_t)mm * DM + 4 * lane + 256 * j);
;         if (BASE_F32) { const float* x = xrow_ptr(C, mm);
; #pragma unroll
;             for (int j = 0; j < 4; ++j) b[r][j] = ld4_f32(x + 4 * lane + 256 * j);
;         } else { const float inv = C.RS()[mm];
; #pragma unroll
;             for (int j = 0; j < 4; ++j) b[r][j] = ld4_bf16(XN + (size_t)mm * DM + 4 * lane + 256 * j) * inv;
;         } }
;     ...
;     for (int j = 0; j < 4; ++j) { const v4f gp = ld4_f32(gpost + 4 * lane + 256 * j);
; #pragma unroll
;         for (int r = 0; r < R; ++r) d[r][j] = b[r][j] + d[r][j] * r1[r] * gp; }
;     if (OUT_F32) { float* Y = C.out();
; #pragma unroll
;         for (int r = 0; r < R; ++r)
; #pragma unroll
;             for (int j = 0; j < 4; ++j) if (ok[r]) *(v4f*)(Y + (size_t)mr[r] * DM + 4 * lane + 256 * j) = d[r][j];
;     } else { float* rs = C.RS(); float t[R];
; #pragma unroll
;         for (int r = 0; r < R; ++r) { float s = 0.f;
; #pragma unroll
;             for (int j = 0; j < 4; ++j) s += ssq4(d[r][j]);
;             t[r] = s; }
; #pragma unroll
;         for (int r = 0; r < R; ++r) t[r] = wave_sum(t[r]) * (1.f / DM) + EPS;
; #pragma unroll
;         for (int r = 0; r < R; ++r) { const float rstd = rsqrtf(t[r]);
; #pragma unroll
;             for (int j = 0; j < 4; ++j) if (ok[r]) st4_bf16(XN + (size_t)mr[r] * DM + 4 * lane + 256 * j, d[r][j] * rstd);
;             if (lane == 0 && ok[r]) rs[mr[r]] = sqrtf(t[r]); }
	v_pk_mul_f32 v[124:125], v[124:125], v[204:205]
	v_pk_mul_f32 v[126:127], v[126:127], v[206:207]
	v_lshlrev_b32_e32 v28, 16, v44
	v_and_b32_e32 v29, 0xffff0000, v44
	v_lshlrev_b32_e32 v30, 16, v45
	v_and_b32_e32 v31, 0xffff0000, v45
	v_lshlrev_b32_e32 v32, 16, v46
	v_and_b32_e32 v33, 0xffff0000, v46
	v_lshlrev_b32_e32 v34, 16, v47
	v_and_b32_e32 v35, 0xffff0000, v47
	v_pk_fma_f32 v[112:113], v[54:55], v[28:29], v[112:113] op_sel_hi:[0,1,1]
	v_pk_fma_f32 v[114:115], v[54:55], v[30:31], v[114:115] op_sel_hi:[0,1,1]
	v_pk_fma_f32 v[116:117], v[54:55], v[32:33], v[116:117] op_sel_hi:[0,1,1]
	v_pk_fma_f32 v[118:119], v[54:55], v[34:35], v[118:119] op_sel_hi:[0,1,1]
	v_lshlrev_b32_e32 v28, 16, v48
	v_and_b32_e32 v29, 0xffff0000, v48
	v_lshlrev_b32_e32 v30, 16, v49
	v_and_b32_e32 v31, 0xffff0000, v49
	v_lshlrev_b32_e32 v32, 16, v50
	v_and_b32_e32 v33, 0xffff0000, v50
	v_lshlrev_b32_e32 v34, 16, v51
	v_and_b32_e32 v35, 0xffff0000, v51
	v_pk_fma_f32 v[120:121], v[54:55], v[28:29], v[120:121] op_sel_hi:[0,1,1]
	v_pk_fma_f32 v[122:123], v[54:55], v[30:31], v[122:123] op_sel_hi:[0,1,1]
	v_pk_fma_f32 v[124:125], v[54:55], v[32:33], v[124:125] op_sel_hi:[0,1,1]
	v_pk_fma_f32 v[126:127], v[54:55], v[34:35], v[126:127] op_sel_hi:[0,1,1]
	v_pk_mul_f32 v[134:135], v[112:113], v[112:113]
	v_pk_fma_f32 v[134:135], v[114:115], v[114:115], v[134:135]
	v_pk_fma_f32 v[134:135], v[116:117], v[116:117], v[134:135]
	v_pk_fma_f32 v[134:135], v[118:119], v[118:119], v[134:135]
	v_pk_fma_f32 v[134:135], v[120:121], v[120:121], v[134:135]
	v_pk_fma_f32 v[134:135], v[122:123], v[122:123], v[134:135]
	v_pk_fma_f32 v[134:135], v[124:125], v[124:125], v[134:135]
	v_pk_fma_f32 v[134:135], v[126:127], v[126:127], v[134:135]
	s_nop 0
	v_add_f32_e32 v134, v134, v135
	s_nop 1
	v_add_f32_dpp v132, v132, v132 quad_perm:[1,0,3,2] row_mask:0xf bank_mask:0xf
	v_add_f32_dpp v134, v134, v134 quad_perm:[1,0,3,2] row_mask:0xf bank_mask:0xf
	s_nop 0
	v_add_f32_dpp v132, v132, v132 quad_perm:[2,3,0,1] row_mask:0xf bank_mask:0xf
	v_add_f32_dpp v134, v134, v134 quad_perm:[2,3,0,1] row_mask:0xf bank_mask:0xf
	s_nop 0
	v_add_f32_dpp v132, v132, v132 row_half_mirror row_mask:0xf bank_mask:0xf
	v_add_f32_dpp v134, v134, v134 row_half_mirror row_mask:0xf bank_mask:0xf
	s_nop 0
	v_add_f32_dpp v132, v132, v132 row_mirror row_mask:0xf bank_mask:0xf
	v_add_f32_dpp v134, v134, v134 row_mirror row_mask:0xf bank_mask:0xf
	s_nop 0
	ds_bpermute_b32 v136, v187, v132
	ds_bpermute_b32 v137, v187, v134
	s_waitcnt lgkmcnt(0)
	v_add_f32_e32 v132, v132, v136
	v_add_f32_e32 v134, v134, v137
	ds_bpermute_b32 v136, v188, v132
	ds_bpermute_b32 v137, v188, v134
	s_waitcnt lgkmcnt(0)
	v_add_f32_e32 v132, v132, v136
	v_add_f32_e32 v134, v134, v137
	v_fmamk_f32 v164, v132, 0x3a800000, v138
	v_fmamk_f32 v167, v134, 0x3a800000, v138
	s_nop 0
	v_rsq_f32_e32 v132, v164
	v_rsq_f32_e32 v134, v167
	v_sqrt_f32_e32 v165, v164
	v_sqrt_f32_e32 v168, v167
	s_nop 1
	v_pk_mul_f32 v[140:141], v[96:97], v[132:133] op_sel_hi:[1,0]
	v_cvt_pk_bf16_f32 v148, v140, v141
	v_pk_mul_f32 v[142:143], v[98:99], v[132:133] op_sel_hi:[1,0]
	v_cvt_pk_bf16_f32 v149, v142, v143
	v_pk_mul_f32 v[144:145], v[100:101], v[132:133] op_sel_hi:[1,0]
	v_cvt_pk_bf16_f32 v150, v144, v145
	v_pk_mul_f32 v[146:147], v[102:103], v[132:133] op_sel_hi:[1,0]
	v_cvt_pk_bf16_f32 v151, v146, v147
	v_pk_mul_f32 v[140:141], v[104:105], v[132:133] op_sel_hi:[1,0]
	v_cvt_pk_bf16_f32 v152, v140, v141
	v_pk_mul_f32 v[142:143], v[106:107], v[132:133] op_sel_hi:[1,0]
	v_cvt_pk_bf16_f32 v153, v142, v143
	v_pk_mul_f32 v[144:145], v[108:109], v[132:133] op_sel_hi:[1,0]
	v_cvt_pk_bf16_f32 v154, v144, v145
	v_pk_mul_f32 v[146:147], v[110:111], v[132:133] op_sel_hi:[1,0]
	v_cvt_pk_bf16_f32 v155, v146, v147
	global_store_dwordx2 v173, v[148:149], s[98:99]
	global_store_dwordx2 v173, v[150:151], s[98:99] offset:512
	global_store_dwordx2 v173, v[152:153], s[98:99] offset:1024
	global_store_dwordx2 v173, v[154:155], s[98:99] offset:1536
	v_add_u32_e32 v173, 0xffc00000, v173
	v_pk_mul_f32 v[140:141], v[112:113], v[134:135] op_sel_hi:[1,0]
	v_cvt_pk_bf16_f32 v156, v140, v141
	v_pk_mul_f32 v[142:143], v[114:115], v[134:135] op_sel_hi:[1,0]
	v_cvt_pk_bf16_f32 v157, v142, v143
	v_pk_mul_f32 v[144:145], v[116:117], v[134:135] op_sel_hi:[1,0]
	v_cvt_pk_bf16_f32 v158, v144, v145
	v_pk_mul_f32 v[146:147], v[118:119], v[134:135] op_sel_hi:[1,0]
	v_cvt_pk_bf16_f32 v159, v146, v147
	v_pk_mul_f32 v[140:141], v[120:121], v[134:135] op_sel_hi:[1,0]
	v_cvt_pk_bf16_f32 v160, v140, v141
	v_pk_mul_f32 v[142:143], v[122:123], v[134:135] op_sel_hi:[1,0]
	v_cvt_pk_bf16_f32 v161, v142, v143
	v_pk_mul_f32 v[144:145], v[124:125], v[134:135] op_sel_hi:[1,0]
	v_cvt_pk_bf16_f32 v162, v144, v145
	v_pk_mul_f32 v[146:147], v[126:127], v[134:135] op_sel_hi:[1,0]
	v_cvt_pk_bf16_f32 v163, v146, v147
	global_store_dwordx2 v173, v[156:157], s[98:99]
	global_store_dwordx2 v173, v[158:159], s[98:99] offset:512
	global_store_dwordx2 v173, v[160:161], s[98:99] offset:1024
	global_store_dwordx2 v173, v[162:163], s[98:99] offset:1536
	v_add_u32_e32 v173, 0xffc00000, v173
	v_add_u32_e32 v166, -1, v165
	v_fma_f32 v140, -v166, v165, v164
	v_cmp_ge_f32_e32 vcc, 0, v140
	v_add_u32_e32 v141, 1, v165
	v_cndmask_b32_e32 v166, v165, v166, vcc
	v_fma_f32 v140, -v141, v165, v164
	v_cmp_lt_f32_e32 vcc, 0, v140
	s_nop 1
	v_cndmask_b32_e32 v165, v166, v141, vcc
	v_add_u32_e32 v169, -1, v168
	v_fma_f32 v142, -v169, v168, v167
	v_cmp_ge_f32_e32 vcc, 0, v142
	v_add_u32_e32 v143, 1, v168
	v_cndmask_b32_e32 v169, v168, v169, vcc
	v_fma_f32 v142, -v143, v168, v167
	v_cmp_lt_f32_e32 vcc, 0, v142
	s_nop 1
	v_cndmask_b32_e32 v168, v169, v143, vcc
	s_mov_b64 exec, 1
	global_store_dword v174, v165, s[98:99]
	v_add_u32_e32 v174, 0xffffe000, v174
	global_store_dword v174, v168, s[98:99]
	v_add_u32_e32 v174, 0xffffe000, v174
	s_mov_b64 exec, -1
	global_load_dword v52, v172, s[98:99]
	global_load_dwordx2 v[20:21], v170, s[98:99]
	global_load_dwordx2 v[22:23], v170, s[98:99] offset:512
	global_load_dwordx2 v[24:25], v170, s[98:99] offset:1024
	global_load_dwordx2 v[26:27], v170, s[98:99] offset:1536
	global_load_dwordx2 v[36:37], v171, s[98:99]
	global_load_dwordx2 v[38:39], v171, s[98:99] offset:512
	global_load_dwordx2 v[40:41], v171, s[98:99] offset:1024
	global_load_dwordx2 v[42:43], v171, s[98:99] offset:1536
	v_add_u32_e32 v170, 0xffc00000, v170
	v_add_u32_e32 v171, 0xffc00000, v171
	v_add_u32_e32 v172, 0xffffe000, v172
	global_load_dword v54, v172, s[98:99]
	global_load_dwordx2 v[28:29], v170, s[98:99]
	global_load_dwordx2 v[30:31], v170, s[98:99] offset:512
	global_load_dwordx2 v[32:33], v170, s[98:99] offset:1024
	global_load_dwordx2 v[34:35], v170, s[98:99] offset:1536
	global_load_dwordx2 v[44:45], v171, s[98:99]
	global_load_dwordx2 v[46:47], v171, s[98:99] offset:512
	global_load_dwordx2 v[48:49], v171, s[98:99] offset:1024
	global_load_dwordx2 v[50:51], v171, s[98:99] offset:1536
	v_add_u32_e32 v170, 0xffc00000, v170
	v_add_u32_e32 v171, 0xffc00000, v171
	v_add_u32_e32 v172, 0xffffe000, v172
	s_waitcnt vmcnt(41)
; __device__ __forceinline__ float ssq4(v4f v) { return (v.x * v.x + v.y * v.y) + (v.z * v.z + v.w * v.w); }
; template <int R, bool BASE_F32, bool OUT_F32>
; __device__ __forceinline__ void rows_res(const Ctx& C, int m0, int stride, int mx, const float* gpost, float scale, int lane) {
;     ...
;     for (int r = 0; r < R; ++r) { float s = 0.f;
; #pragma unroll
;         for (int j = 0; j < 4; ++j) s += ssq4(d[r][j]);
;         r1[r] = s; }
; #pragma unroll
;     for (int r = 0; r < R; ++r) r1[r] = rsqrtf(wave_sum(r1[r]) * (1.f / DM) + EPS) * scale;
; #pragma unroll
;     for (int j = 0; j < 4; ++j) { const v4f gp = ld4_f32(gpost + 4 * lane + 256 * j);
; #pragma unroll
;         for (int r = 0; r < R; ++r) d[r][j] = b[r][j] + d[r][j] * r1[r] * gp; }
	v_lshlrev_b32_e32 v96, 16, v56
	v_and_b32_e32 v97, 0xffff0000, v56
	v_lshlrev_b32_e32 v98, 16, v57
	v_and_b32_e32 v99, 0xffff0000, v57
	v_lshlrev_b32_e32 v100, 16, v58
	v_and_b32_e32 v101, 0xffff0000, v58
	v_lshlrev_b32_e32 v102, 16, v59
	v_and_b32_e32 v103, 0xffff0000, v59
	v_lshlrev_b32_e32 v104, 16, v60
	v_and_b32_e32 v105, 0xffff0000, v60
	v_lshlrev_b32_e32 v106, 16, v61
	v_and_b32_e32 v107, 0xffff0000, v61
	v_lshlrev_b32_e32 v108, 16, v62
	v_and_b32_e32 v109, 0xffff0000, v62
	v_lshlrev_b32_e32 v110, 16, v63
	v_and_b32_e32 v111, 0xffff0000, v63
	v_pk_mul_f32 v[128:129], v[96:97], v[96:97]
	v_pk_fma_f32 v[128:129], v[98:99], v[98:99], v[128:129]
	v_pk_fma_f32 v[128:129], v[100:101], v[100:101], v[128:129]
	v_pk_fma_f32 v[128:129], v[102:103], v[102:103], v[128:129]
	v_pk_fma_f32 v[128:129], v[104:105], v[104:105], v[128:129]
	v_pk_fma_f32 v[128:129], v[106:107], v[106:107], v[128:129]
	v_pk_fma_f32 v[128:129], v[108:109], v[108:109], v[128:129]
	v_pk_fma_f32 v[128:129], v[110:111], v[110:111], v[128:129]
	s_nop 0
	v_add_f32_e32 v128, v128, v129
	s_waitcnt vmcnt(32)
	v_lshlrev_b32_e32 v112, 16, v64
	v_and_b32_e32 v113, 0xffff0000, v64
	v_lshlrev_b32_e32 v114, 16, v65
	v_and_b32_e32 v115, 0xffff0000, v65
	v_lshlrev_b32_e32 v116, 16, v66
	v_and_b32_e32 v117, 0xffff0000, v66
	v_lshlrev_b32_e32 v118, 16, v67
	v_and_b32_e32 v119, 0xffff0000, v67
	v_lshlrev_b32_e32 v120, 16, v68
	v_and_b32_e32 v121, 0xffff0000, v68
	v_lshlrev_b32_e32 v122, 16, v69
	v_and_b32_e32 v123, 0xffff0000, v69
	v_lshlrev_b32_e32 v124, 16, v70
	v_and_b32_e32 v125, 0xffff0000, v70
	v_lshlrev_b32_e32 v126, 16, v71
	v_and_b32_e32 v127, 0xffff0000, v71
	v_pk_mul_f32 v[130:131], v[112:113], v[112:113]
	v_pk_fma_f32 v[130:131], v[114:115], v[114:115], v[130:131]
	v_pk_fma_f32 v[130:131], v[116:117], v[116:117], v[130:131]
	v_pk_fma_f32 v[130:131], v[118:119], v[118:119], v[130:131]
	v_pk_fma_f32 v[130:131], v[120:121], v[120:121], v[130:131]
	v_pk_fma_f32 v[130:131], v[122:123], v[122:123], v[130:131]
	v_pk_fma_f32 v[130:131], v[124:125], v[124:125], v[130:131]
	v_pk_fma_f32 v[130:131], v[126:127], v[126:127], v[130:131]
	s_nop 0
	v_add_f32_e32 v130, v130, v131
	s_nop 1
	v_add_f32_dpp v128, v128, v128 quad_perm:[1,0,3,2] row_mask:0xf bank_mask:0xf
	v_add_f32_dpp v130, v130, v130 quad_perm:[1,0,3,2] row_mask:0xf bank_mask:0xf
	s_nop 0
	v_add_f32_dpp v128, v128, v128 quad_perm:[2,3,0,1] row_mask:0xf bank_mask:0xf
	v_add_f32_dpp v130, v130, v130 quad_perm:[2,3,0,1] row_mask:0xf bank_mask:0xf
	s_nop 0
	v_add_f32_dpp v128, v128, v128 row_half_mirror row_mask:0xf bank_mask:0xf
	v_add_f32_dpp v130, v130, v130 row_half_mirror row_mask:0xf bank_mask:0xf
	s_nop 0
	v_add_f32_dpp v128, v128, v128 row_mirror row_mask:0xf bank_mask:0xf
	v_add_f32_dpp v130, v130, v130 row_mirror row_mask:0xf bank_mask:0xf
	s_nop 0
	ds_bpermute_b32 v136, v187, v128
	ds_bpermute_b32 v137, v187, v130
	s_waitcnt lgkmcnt(0)
	v_add_f32_e32 v128, v128, v136
	v_add_f32_e32 v130, v130, v137
	ds_bpermute_b32 v136, v188, v128
	ds_bpermute_b32 v137, v188, v130
	s_waitcnt lgkmcnt(0)
	v_add_f32_e32 v128, v128, v136
	v_add_f32_e32 v130, v130, v137
	v_fmamk_f32 v128, v128, 0x3a800000, v138
	v_fmamk_f32 v130, v130, 0x3a800000, v138
	s_nop 0
	v_rsq_f32_e32 v128, v128
	v_rsq_f32_e32 v130, v130
	s_nop 1
	v_mul_f32_e32 v128, 0.5, v128
	v_mul_f32_e32 v130, 0.5, v130
	s_waitcnt vmcnt(28)
	v_pk_mul_f32 v[96:97], v[128:129], v[96:97] op_sel_hi:[0,1]
	v_pk_mul_f32 v[98:99], v[128:129], v[98:99] op_sel_hi:[0,1]
	v_pk_mul_f32 v[100:101], v[128:129], v[100:101] op_sel_hi:[0,1]
	v_pk_mul_f32 v[102:103], v[128:129], v[102:103] op_sel_hi:[0,1]
	v_pk_mul_f32 v[104:105], v[128:129], v[104:105] op_sel_hi:[0,1]
	v_pk_mul_f32 v[106:107], v[128:129], v[106:107] op_sel_hi:[0,1]
	v_pk_mul_f32 v[108:109], v[128:129], v[108:109] op_sel_hi:[0,1]
	v_pk_mul_f32 v[110:111], v[128:129], v[110:111] op_sel_hi:[0,1]
	v_pk_mul_f32 v[96:97], v[96:97], v[192:193]
	v_pk_mul_f32 v[98:99], v[98:99], v[194:195]
	v_pk_mul_f32 v[100:101], v[100:101], v[196:197]
	v_pk_mul_f32 v[102:103], v[102:103], v[198:199]
	v_pk_mul_f32 v[104:105], v[104:105], v[200:201]
	v_pk_mul_f32 v[106:107], v[106:107], v[202:203]
	v_pk_mul_f32 v[108:109], v[108:109], v[204:205]
	v_pk_mul_f32 v[110:111], v[110:111], v[206:207]
	v_lshlrev_b32_e32 v56, 16, v72
	v_and_b32_e32 v57, 0xffff0000, v72
	v_lshlrev_b32_e32 v58, 16, v73
	v_and_b32_e32 v59, 0xffff0000, v73
	v_lshlrev_b32_e32 v60, 16, v74
	v_and_b32_e32 v61, 0xffff0000, v74
	v_lshlrev_b32_e32 v62, 16, v75
	v_and_b32_e32 v63, 0xffff0000, v75
	v_pk_fma_f32 v[96:97], v[88:89], v[56:57], v[96:97] op_sel_hi:[0,1,1]
	v_pk_fma_f32 v[98:99], v[88:89], v[58:59], v[98:99] op_sel_hi:[0,1,1]
	v_pk_fma_f32 v[100:101], v[88:89], v[60:61], v[100:101] op_sel_hi:[0,1,1]
	v_pk_fma_f32 v[102:103], v[88:89], v[62:63], v[102:103] op_sel_hi:[0,1,1]
	v_lshlrev_b32_e32 v56, 16, v76
	v_and_b32_e32 v57, 0xffff0000, v76
	v_lshlrev_b32_e32 v58, 16, v77
	v_and_b32_e32 v59, 0xffff0000, v77
	v_lshlrev_b32_e32 v60, 16, v78
	v_and_b32_e32 v61, 0xffff0000, v78
	v_lshlrev_b32_e32 v62, 16, v79
	v_and_b32_e32 v63, 0xffff0000, v79
	v_pk_fma_f32 v[104:105], v[88:89], v[56:57], v[104:105] op_sel_hi:[0,1,1]
	v_pk_fma_f32 v[106:107], v[88:89], v[58:59], v[106:107] op_sel_hi:[0,1,1]
	v_pk_fma_f32 v[108:109], v[88:89], v[60:61], v[108:109] op_sel_hi:[0,1,1]
	v_pk_fma_f32 v[110:111], v[88:89], v[62:63], v[110:111] op_sel_hi:[0,1,1]
	v_pk_mul_f32 v[132:133], v[96:97], v[96:97]
	v_pk_fma_f32 v[132:133], v[98:99], v[98:99], v[132:133]
	v_pk_fma_f32 v[132:133], v[100:101], v[100:101], v[132:133]
	v_pk_fma_f32 v[132:133], v[102:103], v[102:103], v[132:133]
;     __device__ __forceinline__ float* out() const { return (float*)karg_in(33); }
; __device__ __forceinline__ void st4_bf16(bf16* p, v4f o) { v2u w; w.x = cvt_pk_nv(o.x, o.y); w.y = cvt_pk_nv(o.z, o.w); *(v2u*)p = w; }
; __device__ __forceinline__ float ssq4(v4f v) { return (v.x * v.x + v.y * v.y) + (v.z * v.z + v.w * v.w); }
; template <int R, bool BASE_F32, bool OUT_F32>
; __device__ __forceinline__ void rows_res(const Ctx& C, int m0, int stride, int mx, const float* gpost, float scale, int lane) {
;     ...
;     for (int j = 0; j < 4; ++j) { const v4f gp = ld4_f32(gpost + 4 * lane + 256 * j);
; #pragma unroll
;         for (int r = 0; r < R; ++r) d[r][j] = b[r][j] + d[r][j] * r1[r] * gp; }
;     if (OUT_F32) { float* Y = C.out();
; #pragma unroll
;         for (int r = 0; r < R; ++r)
; #pragma unroll
;             for (int j = 0; j < 4; ++j) if (ok[r]) *(v4f*)(Y + (size_t)mr[r] * DM + 4 * lane + 256 * j) = d[r][j];
;     } else { float* rs = C.RS(); float t[R];
; #pragma unroll
;         for (int r = 0; r < R; ++r) { float s = 0.f;
; #pragma unroll
;             for (int j = 0; j < 4; ++j) s += ssq4(d[r][j]);
;             t[r] = s; }
; #pragma unroll
;         for (int r = 0; r < R; ++r) t[r] = wave_sum(t[r]) * (1.f / DM) + EPS;
; #pragma unroll
;         for (int r = 0; r < R; ++r) { const float rstd = rsqrtf(t[r]);
; #pragma unroll
;             for (int j = 0; j < 4; ++j) if (ok[r]) st4_bf16(XN + (size_t)mr[r] * DM + 4 * lane + 256 * j, d[r][j] * rstd);
;             if (lane == 0 && ok[r]) rs[mr[r]] = sqrtf(t[r]); }
	v_pk_fma_f32 v[132:133], v[104:105], v[104:105], v[132:133]
	v_pk_fma_f32 v[132:133], v[106:107], v[106:107], v[132:133]
	v_pk_fma_f32 v[132:133], v[108:109], v[108:109], v[132:133]
	v_pk_fma_f32 v[132:133], v[110:111], v[110:111], v[132:133]
	s_nop 0
	v_add_f32_e32 v132, v132, v133
	v_pk_mul_f32 v[112:113], v[130:131], v[112:113] op_sel_hi:[0,1]
	v_pk_mul_f32 v[114:115], v[130:131], v[114:115] op_sel_hi:[0,1]
	v_pk_mul_f32 v[116:117], v[130:131], v[116:117] op_sel_hi:[0,1]
	v_pk_mul_f32 v[118:119], v[130:131], v[118:119] op_sel_hi:[0,1]
	v_pk_mul_f32 v[120:121], v[130:131], v[120:121] op_sel_hi:[0,1]
	v_pk_mul_f32 v[122:123], v[130:131], v[122:123] op_sel_hi:[0,1]
	v_pk_mul_f32 v[124:125], v[130:131], v[124:125] op_sel_hi:[0,1]
	v_pk_mul_f32 v[126:127], v[130:131], v[126:127] op_sel_hi:[0,1]
	v_pk_mul_f32 v[112:113], v[112:113], v[192:193]
	v_pk_mul_f32 v[114:115], v[114:115], v[194:195]
	v_pk_mul_f32 v[116:117], v[116:117], v[196:197]
	v_pk_mul_f32 v[118:119], v[118:119], v[198:199]
	v_pk_mul_f32 v[120:121], v[120:121], v[200:201]
	v_pk_mul_f32 v[122:123], v[122:123], v[202:203]
	v_pk_mul_f32 v[124:125], v[124:125], v[204:205]
	v_pk_mul_f32 v[126:127], v[126:127], v[206:207]
	v_lshlrev_b32_e32 v64, 16, v80
	v_and_b32_e32 v65, 0xffff0000, v80
	v_lshlrev_b32_e32 v66, 16, v81
	v_and_b32_e32 v67, 0xffff0000, v81
	v_lshlrev_b32_e32 v68, 16, v82
	v_and_b32_e32 v69, 0xffff0000, v82
	v_lshlrev_b32_e32 v70, 16, v83
	v_and_b32_e32 v71, 0xffff0000, v83
	v_pk_fma_f32 v[112:113], v[90:91], v[64:65], v[112:113] op_sel_hi:[0,1,1]
	v_pk_fma_f32 v[114:115], v[90:91], v[66:67], v[114:115] op_sel_hi:[0,1,1]
	v_pk_fma_f32 v[116:117], v[90:91], v[68:69], v[116:117] op_sel_hi:[0,1,1]
	v_pk_fma_f32 v[118:119], v[90:91], v[70:71], v[118:119] op_sel_hi:[0,1,1]
	v_lshlrev_b32_e32 v64, 16, v84
	v_and_b32_e32 v65, 0xffff0000, v84
	v_lshlrev_b32_e32 v66, 16, v85
	v_and_b32_e32 v67, 0xffff0000, v85
	v_lshlrev_b32_e32 v68, 16, v86
	v_and_b32_e32 v69, 0xffff0000, v86
	v_lshlrev_b32_e32 v70, 16, v87
	v_and_b32_e32 v71, 0xffff0000, v87
	v_pk_fma_f32 v[120:121], v[90:91], v[64:65], v[120:121] op_sel_hi:[0,1,1]
	v_pk_fma_f32 v[122:123], v[90:91], v[66:67], v[122:123] op_sel_hi:[0,1,1]
	v_pk_fma_f32 v[124:125], v[90:91], v[68:69], v[124:125] op_sel_hi:[0,1,1]
	v_pk_fma_f32 v[126:127], v[90:91], v[70:71], v[126:127] op_sel_hi:[0,1,1]
	v_pk_mul_f32 v[134:135], v[112:113], v[112:113]
	v_pk_fma_f32 v[134:135], v[114:115], v[114:115], v[134:135]
	v_pk_fma_f32 v[134:135], v[116:117], v[116:117], v[134:135]
	v_pk_fma_f32 v[134:135], v[118:119], v[118:119], v[134:135]
	v_pk_fma_f32 v[134:135], v[120:121], v[120:121], v[134:135]
	v_pk_fma_f32 v[134:135], v[122:123], v[122:123], v[134:135]
	v_pk_fma_f32 v[134:135], v[124:125], v[124:125], v[134:135]
	v_pk_fma_f32 v[134:135], v[126:127], v[126:127], v[134:135]
	s_nop 0
	v_add_f32_e32 v134, v134, v135
	s_nop 1
	v_add_f32_dpp v132, v132, v132 quad_perm:[1,0,3,2] row_mask:0xf bank_mask:0xf
	v_add_f32_dpp v134, v134, v134 quad_perm:[1,0,3,2] row_mask:0xf bank_mask:0xf
	s_nop 0
	v_add_f32_dpp v132, v132, v132 quad_perm:[2,3,0,1] row_mask:0xf bank_mask:0xf
	v_add_f32_dpp v134, v134, v134 quad_perm:[2,3,0,1] row_mask:0xf bank_mask:0xf
	s_nop 0
	v_add_f32_dpp v132, v132, v132 row_half_mirror row_mask:0xf bank_mask:0xf
	v_add_f32_dpp v134, v134, v134 row_half_mirror row_mask:0xf bank_mask:0xf
	s_nop 0
	v_add_f32_dpp v132, v132, v132 row_mirror row_mask:0xf bank_mask:0xf
	v_add_f32_dpp v134, v134, v134 row_mirror row_mask:0xf bank_mask:0xf
	s_nop 0
	ds_bpermute_b32 v136, v187, v132
	ds_bpermute_b32 v137, v187, v134
	s_waitcnt lgkmcnt(0)
	v_add_f32_e32 v132, v132, v136
	v_add_f32_e32 v134, v134, v137
	ds_bpermute_b32 v136, v188, v132
	ds_bpermute_b32 v137, v188, v134
	s_waitcnt lgkmcnt(0)
	v_add_f32_e32 v132, v132, v136
	v_add_f32_e32 v134, v134, v137
	v_fmamk_f32 v164, v132, 0x3a800000, v138
	v_fmamk_f32 v167, v134, 0x3a800000, v138
	s_nop 0
	v_rsq_f32_e32 v132, v164
	v_rsq_f32_e32 v134, v167
	v_sqrt_f32_e32 v165, v164
	v_sqrt_f32_e32 v168, v167
	s_nop 1
	v_pk_mul_f32 v[140:141], v[96:97], v[132:133] op_sel_hi:[1,0]
	v_cvt_pk_bf16_f32 v148, v140, v141
	v_pk_mul_f32 v[142:143], v[98:99], v[132:133] op_sel_hi:[1,0]
	v_cvt_pk_bf16_f32 v149, v142, v143
	v_pk_mul_f32 v[144:145], v[100:101], v[132:133] op_sel_hi:[1,0]
	v_cvt_pk_bf16_f32 v150, v144, v145
	v_pk_mul_f32 v[146:147], v[102:103], v[132:133] op_sel_hi:[1,0]
	v_cvt_pk_bf16_f32 v151, v146, v147
	v_pk_mul_f32 v[140:141], v[104:105], v[132:133] op_sel_hi:[1,0]
	v_cvt_pk_bf16_f32 v152, v140, v141
	v_pk_mul_f32 v[142:143], v[106:107], v[132:133] op_sel_hi:[1,0]
	v_cvt_pk_bf16_f32 v153, v142, v143
	v_pk_mul_f32 v[144:145], v[108:109], v[132:133] op_sel_hi:[1,0]
	v_cvt_pk_bf16_f32 v154, v144, v145
	v_pk_mul_f32 v[146:147], v[110:111], v[132:133] op_sel_hi:[1,0]
	v_cvt_pk_bf16_f32 v155, v146, v147
	global_store_dwordx2 v173, v[148:149], s[98:99]
	global_store_dwordx2 v173, v[150:151], s[98:99] offset:512
	global_store_dwordx2 v173, v[152:153], s[98:99] offset:1024
	global_store_dwordx2 v173, v[154:155], s[98:99] offset:1536
	v_add_u32_e32 v173, 0xffc00000, v173
	v_pk_mul_f32 v[140:141], v[112:113], v[134:135] op_sel_hi:[1,0]
	v_cvt_pk_bf16_f32 v156, v140, v141
	v_pk_mul_f32 v[142:143], v[114:115], v[134:135] op_sel_hi:[1,0]
	v_cvt_pk_bf16_f32 v157, v142, v143
	v_pk_mul_f32 v[144:145], v[116:117], v[134:135] op_sel_hi:[1,0]
	v_cvt_pk_bf16_f32 v158, v144, v145
	v_pk_mul_f32 v[146:147], v[118:119], v[134:135] op_sel_hi:[1,0]
	v_cvt_pk_bf16_f32 v159, v146, v147
	v_pk_mul_f32 v[140:141], v[120:121], v[134:135] op_sel_hi:[1,0]
	v_cvt_pk_bf16_f32 v160, v140, v141
	v_pk_mul_f32 v[142:143], v[122:123], v[134:135] op_sel_hi:[1,0]
; __device__ __forceinline__ const float* xrow_ptr(const Ctx& C, int row) { return row < MPROMPT ? C.in(0) + (size_t)row * DM : C.in(1) + (size_t)(row - MPROMPT) * DM; }
; __device__ __forceinline__ v4f ld4_bf16(const bf16* p) { const v2u w = *(const v2u*)p; return (v4f){bf_lo(w.x), bf_hi(w.x), bf_lo(w.y), bf_hi(w.y)}; }
; __device__ __forceinline__ void st4_bf16(bf16* p, v4f o) { v2u w; w.x = cvt_pk_nv(o.x, o.y); w.y = cvt_pk_nv(o.z, o.w); *(v2u*)p = w; }
; __device__ __forceinline__ float ssq4(v4f v) { return (v.x * v.x + v.y * v.y) + (v.z * v.z + v.w * v.w); }
; template <int R, bool BASE_F32, bool OUT_F32>
; __device__ __forceinline__ void rows_res(const Ctx& C, int m0, int stride, int mx, const float* gpost, float scale, int lane) {
;     ...
;     for (int r = 0; r < R; ++r) { mr[r] = (r == 4) ? mx : m0 + r * stride; ok[r] = (r == 4) ? (mx < M) : (mr[r] < MPROMPT); const int mm = ok[r] ? mr[r] : 0;
; #pragma unroll
;         for (int j = 0; j < 4; ++j) d[r][j] = ld4_bf16(D + (size_t)mm * DM + 4 * lane + 256 * j);
;         if (BASE_F32) { const float* x = xrow_ptr(C, mm);
; #pragma unroll
;             for (int j = 0; j < 4; ++j) b[r][j] = ld4_f32(x + 4 * lane + 256 * j);
;         } else { const float inv = C.RS()[mm];
; #pragma unroll
;             for (int j = 0; j < 4; ++j) b[r][j] = ld4_bf16(XN + (size_t)mm * DM + 4 * lane + 256 * j) * inv;
;         } }
; #pragma unroll
;     for (int r = 0; r < R; ++r) { float s = 0.f;
; #pragma unroll
;         for (int j = 0; j < 4; ++j) s += ssq4(d[r][j]);
;         r1[r] = s; }
;     ...
;         for (int r = 0; r < R; ++r) { const float rstd = rsqrtf(t[r]);
; #pragma unroll
;             for (int j = 0; j < 4; ++j) if (ok[r]) st4_bf16(XN + (size_t)mr[r] * DM + 4 * lane + 256 * j, d[r][j] * rstd);
;             if (lane == 0 && ok[r]) rs[mr[r]] = sqrtf(t[r]); }
	v_cvt_pk_bf16_f32 v161, v142, v143
	v_pk_mul_f32 v[144:145], v[124:125], v[134:135] op_sel_hi:[1,0]
	v_cvt_pk_bf16_f32 v162, v144, v145
	v_pk_mul_f32 v[146:147], v[126:127], v[134:135] op_sel_hi:[1,0]
	v_cvt_pk_bf16_f32 v163, v146, v147
	global_store_dwordx2 v173, v[156:157], s[98:99]
	global_store_dwordx2 v173, v[158:159], s[98:99] offset:512
	global_store_dwordx2 v173, v[160:161], s[98:99] offset:1024
	global_store_dwordx2 v173, v[162:163], s[98:99] offset:1536
	v_add_u32_e32 v173, 0xffc00000, v173
	v_add_u32_e32 v166, -1, v165
	v_fma_f32 v140, -v166, v165, v164
	v_cmp_ge_f32_e32 vcc, 0, v140
	v_add_u32_e32 v141, 1, v165
	v_cndmask_b32_e32 v166, v165, v166, vcc
	v_fma_f32 v140, -v141, v165, v164
	v_cmp_lt_f32_e32 vcc, 0, v140
	s_nop 1
	v_cndmask_b32_e32 v165, v166, v141, vcc
	v_add_u32_e32 v169, -1, v168
	v_fma_f32 v142, -v169, v168, v167
	v_cmp_ge_f32_e32 vcc, 0, v142
	v_add_u32_e32 v143, 1, v168
	v_cndmask_b32_e32 v169, v168, v169, vcc
	v_fma_f32 v142, -v143, v168, v167
	v_cmp_lt_f32_e32 vcc, 0, v142
	s_nop 1
	v_cndmask_b32_e32 v168, v169, v143, vcc
	s_mov_b64 exec, 1
	global_store_dword v174, v165, s[98:99]
	v_add_u32_e32 v174, 0xffffe000, v174
	global_store_dword v174, v168, s[98:99]
	v_add_u32_e32 v174, 0xffffe000, v174
	s_mov_b64 exec, -1
	global_load_dword v88, v172, s[98:99]
	global_load_dwordx2 v[56:57], v170, s[98:99]
	global_load_dwordx2 v[58:59], v170, s[98:99] offset:512
	global_load_dwordx2 v[60:61], v170, s[98:99] offset:1024
	global_load_dwordx2 v[62:63], v170, s[98:99] offset:1536
	global_load_dwordx2 v[72:73], v171, s[98:99]
	global_load_dwordx2 v[74:75], v171, s[98:99] offset:512
	global_load_dwordx2 v[76:77], v171, s[98:99] offset:1024
	global_load_dwordx2 v[78:79], v171, s[98:99] offset:1536
	v_add_u32_e32 v170, 0xffc00000, v170
	v_add_u32_e32 v171, 0xffc00000, v171
	v_add_u32_e32 v172, 0xffffe000, v172
	global_load_dword v90, v172, s[98:99]
	global_load_dwordx2 v[64:65], v170, s[98:99]
	global_load_dwordx2 v[66:67], v170, s[98:99] offset:512
	global_load_dwordx2 v[68:69], v170, s[98:99] offset:1024
	global_load_dwordx2 v[70:71], v170, s[98:99] offset:1536
	global_load_dwordx2 v[80:81], v171, s[98:99]
	global_load_dwordx2 v[82:83], v171, s[98:99] offset:512
	global_load_dwordx2 v[84:85], v171, s[98:99] offset:1024
	global_load_dwordx2 v[86:87], v171, s[98:99] offset:1536
	v_add_u32_e32 v170, 0xffc00000, v170
	v_add_u32_e32 v171, 0xffc00000, v171
	v_add_u32_e32 v172, 0xffffe000, v172
	s_waitcnt vmcnt(41)
	v_lshlrev_b32_e32 v96, 16, v20
	v_and_b32_e32 v97, 0xffff0000, v20
	v_lshlrev_b32_e32 v98, 16, v21
	v_and_b32_e32 v99, 0xffff0000, v21
	v_lshlrev_b32_e32 v100, 16, v22
	v_and_b32_e32 v101, 0xffff0000, v22
	v_lshlrev_b32_e32 v102, 16, v23
	v_and_b32_e32 v103, 0xffff0000, v23
	v_lshlrev_b32_e32 v104, 16, v24
	v_and_b32_e32 v105, 0xffff0000, v24
	v_lshlrev_b32_e32 v106, 16, v25
	v_and_b32_e32 v107, 0xffff0000, v25
	v_lshlrev_b32_e32 v108, 16, v26
	v_and_b32_e32 v109, 0xffff0000, v26
	v_lshlrev_b32_e32 v110, 16, v27
	v_and_b32_e32 v111, 0xffff0000, v27
	v_pk_mul_f32 v[128:129], v[96:97], v[96:97]
	v_pk_fma_f32 v[128:129], v[98:99], v[98:99], v[128:129]
	v_pk_fma_f32 v[128:129], v[100:101], v[100:101], v[128:129]
	v_pk_fma_f32 v[128:129], v[102:103], v[102:103], v[128:129]
	v_pk_fma_f32 v[128:129], v[104:105], v[104:105], v[128:129]
	v_pk_fma_f32 v[128:129], v[106:107], v[106:107], v[128:129]
	v_pk_fma_f32 v[128:129], v[108:109], v[108:109], v[128:129]
	v_pk_fma_f32 v[128:129], v[110:111], v[110:111], v[128:129]
	s_nop 0
	v_add_f32_e32 v128, v128, v129
	s_waitcnt vmcnt(32)
	v_lshlrev_b32_e32 v112, 16, v28
	v_and_b32_e32 v113, 0xffff0000, v28
	v_lshlrev_b32_e32 v114, 16, v29
	v_and_b32_e32 v115, 0xffff0000, v29
	v_lshlrev_b32_e32 v116, 16, v30
	v_and_b32_e32 v117, 0xffff0000, v30
	v_lshlrev_b32_e32 v118, 16, v31
	v_and_b32_e32 v119, 0xffff0000, v31
	v_lshlrev_b32_e32 v120, 16, v32
	v_and_b32_e32 v121, 0xffff0000, v32
	v_lshlrev_b32_e32 v122, 16, v33
	v_and_b32_e32 v123, 0xffff0000, v33
	v_lshlrev_b32_e32 v124, 16, v34
	v_and_b32_e32 v125, 0xffff0000, v34
	v_lshlrev_b32_e32 v126, 16, v35
	v_and_b32_e32 v127, 0xffff0000, v35
	v_pk_mul_f32 v[130:131], v[112:113], v[112:113]
	v_pk_fma_f32 v[130:131], v[114:115], v[114:115], v[130:131]
	v_pk_fma_f32 v[130:131], v[116:117], v[116:117], v[130:131]
	v_pk_fma_f32 v[130:131], v[118:119], v[118:119], v[130:131]
	v_pk_fma_f32 v[130:131], v[120:121], v[120:121], v[130:131]
	v_pk_fma_f32 v[130:131], v[122:123], v[122:123], v[130:131]
	v_pk_fma_f32 v[130:131], v[124:125], v[124:125], v[130:131]
	v_pk_fma_f32 v[130:131], v[126:127], v[126:127], v[130:131]
	s_nop 0
	v_add_f32_e32 v130, v130, v131
	s_nop 1
	v_add_f32_dpp v128, v128, v128 quad_perm:[1,0,3,2] row_mask:0xf bank_mask:0xf
	v_add_f32_dpp v130, v130, v130 quad_perm:[1,0,3,2] row_mask:0xf bank_mask:0xf
	s_nop 0
	v_add_f32_dpp v128, v128, v128 quad_perm:[2,3,0,1] row_mask:0xf bank_mask:0xf
	v_add_f32_dpp v130, v130, v130 quad_perm:[2,3,0,1] row_mask:0xf bank_mask:0xf
	s_nop 0
	v_add_f32_dpp v128, v128, v128 row_half_mirror row_mask:0xf bank_mask:0xf
	v_add_f32_dpp v130, v130, v130 row_half_mirror row_mask:0xf bank_mask:0xf
	s_nop 0
	v_add_f32_dpp v128, v128, v128 row_mirror row_mask:0xf bank_mask:0xf
	v_add_f32_dpp v130, v130, v130 row_mirror row_mask:0xf bank_mask:0xf
	s_nop 0
	ds_bpermute_b32 v136, v187, v128
	ds_bpermute_b32 v137, v187, v130
	s_waitcnt lgkmcnt(0)
	v_add_f32_e32 v128, v128, v136
	v_add_f32_e32 v130, v130, v137
	ds_bpermute_b32 v136, v188, v128
	ds_bpermute_b32 v137, v188, v130
	s_waitcnt lgkmcnt(0)
;     __device__ __forceinline__ float* out() const { return (float*)karg_in(33); }
; __device__ __forceinline__ float ssq4(v4f v) { return (v.x * v.x + v.y * v.y) + (v.z * v.z + v.w * v.w); }
; template <int R, bool BASE_F32, bool OUT_F32>
; __device__ __forceinline__ void rows_res(const Ctx& C, int m0, int stride, int mx, const float* gpost, float scale, int lane) {
;     ...
;     for (int r = 0; r < R; ++r) r1[r] = rsqrtf(wave_sum(r1[r]) * (1.f / DM) + EPS) * scale;
; #pragma unroll
;     for (int j = 0; j < 4; ++j) { const v4f gp = ld4_f32(gpost + 4 * lane + 256 * j);
; #pragma unroll
;         for (int r = 0; r < R; ++r) d[r][j] = b[r][j] + d[r][j] * r1[r] * gp; }
;     if (OUT_F32) { float* Y = C.out();
; #pragma unroll
;         for (int r = 0; r < R; ++r)
; #pragma unroll
;             for (int j = 0; j < 4; ++j) if (ok[r]) *(v4f*)(Y + (size_t)mr[r] * DM + 4 * lane + 256 * j) = d[r][j];
;     } else { float* rs = C.RS(); float t[R];
; #pragma unroll
;         for (int r = 0; r < R; ++r) { float s = 0.f;
; #pragma unroll
;             for (int j = 0; j < 4; ++j) s += ssq4(d[r][j]);
;             t[r] = s; }
; #pragma unroll
;         for (int r = 0; r < R; ++r) t[r] = wave_sum(t[r]) * (1.f / DM) + EPS;
	v_add_f32_e32 v128, v128, v136
	v_add_f32_e32 v130, v130, v137
	v_fmamk_f32 v128, v128, 0x3a800000, v138
	v_fmamk_f32 v130, v130, 0x3a800000, v138
	s_nop 0
	v_rsq_f32_e32 v128, v128
	v_rsq_f32_e32 v130, v130
	s_nop 1
	v_mul_f32_e32 v128, 0.5, v128
	v_mul_f32_e32 v130, 0.5, v130
	s_waitcnt vmcnt(28)
	v_pk_mul_f32 v[96:97], v[128:129], v[96:97] op_sel_hi:[0,1]
	v_pk_mul_f32 v[98:99], v[128:129], v[98:99] op_sel_hi:[0,1]
	v_pk_mul_f32 v[100:101], v[128:129], v[100:101] op_sel_hi:[0,1]
	v_pk_mul_f32 v[102:103], v[128:129], v[102:103] op_sel_hi:[0,1]
	v_pk_mul_f32 v[104:105], v[128:129], v[104:105] op_sel_hi:[0,1]
	v_pk_mul_f32 v[106:107], v[128:129], v[106:107] op_sel_hi:[0,1]
	v_pk_mul_f32 v[108:109], v[128:129], v[108:109] op_sel_hi:[0,1]
	v_pk_mul_f32 v[110:111], v[128:129], v[110:111] op_sel_hi:[0,1]
	v_pk_mul_f32 v[96:97], v[96:97], v[192:193]
	v_pk_mul_f32 v[98:99], v[98:99], v[194:195]
	v_pk_mul_f32 v[100:101], v[100:101], v[196:197]
	v_pk_mul_f32 v[102:103], v[102:103], v[198:199]
	v_pk_mul_f32 v[104:105], v[104:105], v[200:201]
	v_pk_mul_f32 v[106:107], v[106:107], v[202:203]
	v_pk_mul_f32 v[108:109], v[108:109], v[204:205]
	v_pk_mul_f32 v[110:111], v[110:111], v[206:207]
	v_lshlrev_b32_e32 v20, 16, v36
	v_and_b32_e32 v21, 0xffff0000, v36
	v_lshlrev_b32_e32 v22, 16, v37
	v_and_b32_e32 v23, 0xffff0000, v37
	v_lshlrev_b32_e32 v24, 16, v38
	v_and_b32_e32 v25, 0xffff0000, v38
	v_lshlrev_b32_e32 v26, 16, v39
	v_and_b32_e32 v27, 0xffff0000, v39
	v_pk_fma_f32 v[96:97], v[52:53], v[20:21], v[96:97] op_sel_hi:[0,1,1]
	v_pk_fma_f32 v[98:99], v[52:53], v[22:23], v[98:99] op_sel_hi:[0,1,1]
	v_pk_fma_f32 v[100:101], v[52:53], v[24:25], v[100:101] op_sel_hi:[0,1,1]
	v_pk_fma_f32 v[102:103], v[52:53], v[26:27], v[102:103] op_sel_hi:[0,1,1]
	v_lshlrev_b32_e32 v20, 16, v40
	v_and_b32_e32 v21, 0xffff0000, v40
	v_lshlrev_b32_e32 v22, 16, v41
	v_and_b32_e32 v23, 0xffff0000, v41
	v_lshlrev_b32_e32 v24, 16, v42
	v_and_b32_e32 v25, 0xffff0000, v42
	v_lshlrev_b32_e32 v26, 16, v43
	v_and_b32_e32 v27, 0xffff0000, v43
	v_pk_fma_f32 v[104:105], v[52:53], v[20:21], v[104:105] op_sel_hi:[0,1,1]
	v_pk_fma_f32 v[106:107], v[52:53], v[22:23], v[106:107] op_sel_hi:[0,1,1]
	v_pk_fma_f32 v[108:109], v[52:53], v[24:25], v[108:109] op_sel_hi:[0,1,1]
	v_pk_fma_f32 v[110:111], v[52:53], v[26:27], v[110:111] op_sel_hi:[0,1,1]
	v_pk_mul_f32 v[132:133], v[96:97], v[96:97]
	v_pk_fma_f32 v[132:133], v[98:99], v[98:99], v[132:133]
	v_pk_fma_f32 v[132:133], v[100:101], v[100:101], v[132:133]
	v_pk_fma_f32 v[132:133], v[102:103], v[102:103], v[132:133]
	v_pk_fma_f32 v[132:133], v[104:105], v[104:105], v[132:133]
	v_pk_fma_f32 v[132:133], v[106:107], v[106:107], v[132:133]
	v_pk_fma_f32 v[132:133], v[108:109], v[108:109], v[132:133]
	v_pk_fma_f32 v[132:133], v[110:111], v[110:111], v[132:133]
	s_nop 0
	v_add_f32_e32 v132, v132, v133
	v_pk_mul_f32 v[112:113], v[130:131], v[112:113] op_sel_hi:[0,1]
	v_pk_mul_f32 v[114:115], v[130:131], v[114:115] op_sel_hi:[0,1]
	v_pk_mul_f32 v[116:117], v[130:131], v[116:117] op_sel_hi:[0,1]
	v_pk_mul_f32 v[118:119], v[130:131], v[118:119] op_sel_hi:[0,1]
	v_pk_mul_f32 v[120:121], v[130:131], v[120:121] op_sel_hi:[0,1]
	v_pk_mul_f32 v[122:123], v[130:131], v[122:123] op_sel_hi:[0,1]
	v_pk_mul_f32 v[124:125], v[130:131], v[124:125] op_sel_hi:[0,1]
	v_pk_mul_f32 v[126:127], v[130:131], v[126:127] op_sel_hi:[0,1]
	v_pk_mul_f32 v[112:113], v[112:113], v[192:193]
	v_pk_mul_f32 v[114:115], v[114:115], v[194:195]
	v_pk_mul_f32 v[116:117], v[116:117], v[196:197]
	v_pk_mul_f32 v[118:119], v[118:119], v[198:199]
	v_pk_mul_f32 v[120:121], v[120:121], v[200:201]
	v_pk_mul_f32 v[122:123], v[122:123], v[202:203]
	v_pk_mul_f32 v[124:125], v[124:125], v[204:205]
	v_pk_mul_f32 v[126:127], v[126:127], v[206:207]
	v_lshlrev_b32_e32 v28, 16, v44
	v_and_b32_e32 v29, 0xffff0000, v44
	v_lshlrev_b32_e32 v30, 16, v45
	v_and_b32_e32 v31, 0xffff0000, v45
	v_lshlrev_b32_e32 v32, 16, v46
	v_and_b32_e32 v33, 0xffff0000, v46
	v_lshlrev_b32_e32 v34, 16, v47
	v_and_b32_e32 v35, 0xffff0000, v47
	v_pk_fma_f32 v[112:113], v[54:55], v[28:29], v[112:113] op_sel_hi:[0,1,1]
	v_pk_fma_f32 v[114:115], v[54:55], v[30:31], v[114:115] op_sel_hi:[0,1,1]
	v_pk_fma_f32 v[116:117], v[54:55], v[32:33], v[116:117] op_sel_hi:[0,1,1]
	v_pk_fma_f32 v[118:119], v[54:55], v[34:35], v[118:119] op_sel_hi:[0,1,1]
	v_lshlrev_b32_e32 v28, 16, v48
	v_and_b32_e32 v29, 0xffff0000, v48
	v_lshlrev_b32_e32 v30, 16, v49
	v_and_b32_e32 v31, 0xffff0000, v49
	v_lshlrev_b32_e32 v32, 16, v50
	v_and_b32_e32 v33, 0xffff0000, v50
	v_lshlrev_b32_e32 v34, 16, v51
	v_and_b32_e32 v35, 0xffff0000, v51
	v_pk_fma_f32 v[120:121], v[54:55], v[28:29], v[120:121] op_sel_hi:[0,1,1]
	v_pk_fma_f32 v[122:123], v[54:55], v[30:31], v[122:123] op_sel_hi:[0,1,1]
	v_pk_fma_f32 v[124:125], v[54:55], v[32:33], v[124:125] op_sel_hi:[0,1,1]
	v_pk_fma_f32 v[126:127], v[54:55], v[34:35], v[126:127] op_sel_hi:[0,1,1]
	v_pk_mul_f32 v[134:135], v[112:113], v[112:113]
	v_pk_fma_f32 v[134:135], v[114:115], v[114:115], v[134:135]
	v_pk_fma_f32 v[134:135], v[116:117], v[116:117], v[134:135]
	v_pk_fma_f32 v[134:135], v[118:119], v[118:119], v[134:135]
	v_pk_fma_f32 v[134:135], v[120:121], v[120:121], v[134:135]
	v_pk_fma_f32 v[134:135], v[122:123], v[122:123], v[134:135]
	v_pk_fma_f32 v[134:135], v[124:125], v[124:125], v[134:135]
	v_pk_fma_f32 v[134:135], v[126:127], v[126:127], v[134:135]
	s_nop 0
	v_add_f32_e32 v134, v134, v135
	s_nop 1
	v_add_f32_dpp v132, v132, v132 quad_perm:[1,0,3,2] row_mask:0xf bank_mask:0xf
	v_add_f32_dpp v134, v134, v134 quad_perm:[1,0,3,2] row_mask:0xf bank_mask:0xf
	s_nop 0
	v_add_f32_dpp v132, v132, v132 quad_perm:[2,3,0,1] row_mask:0xf bank_mask:0xf
	v_add_f32_dpp v134, v134, v134 quad_perm:[2,3,0,1] row_mask:0xf bank_mask:0xf
	s_nop 0
	v_add_f32_dpp v132, v132, v132 row_half_mirror row_mask:0xf bank_mask:0xf
	v_add_f32_dpp v134, v134, v134 row_half_mirror row_mask:0xf bank_mask:0xf
	s_nop 0
	v_add_f32_dpp v132, v132, v132 row_mirror row_mask:0xf bank_mask:0xf
	v_add_f32_dpp v134, v134, v134 row_mirror row_mask:0xf bank_mask:0xf
	s_nop 0
	ds_bpermute_b32 v136, v187, v132
	ds_bpermute_b32 v137, v187, v134
	s_waitcnt lgkmcnt(0)
; __device__ __forceinline__ const float* xrow_ptr(const Ctx& C, int row) { return row < MPROMPT ? C.in(0) + (size_t)row * DM : C.in(1) + (size_t)(row - MPROMPT) * DM; }
; __device__ __forceinline__ v4f ld4_bf16(const bf16* p) { const v2u w = *(const v2u*)p; return (v4f){bf_lo(w.x), bf_hi(w.x), bf_lo(w.y), bf_hi(w.y)}; }
; __device__ __forceinline__ void st4_bf16(bf16* p, v4f o) { v2u w; w.x = cvt_pk_nv(o.x, o.y); w.y = cvt_pk_nv(o.z, o.w); *(v2u*)p = w; }
; __device__ __forceinline__ float ssq4(v4f v) { return (v.x * v.x + v.y * v.y) + (v.z * v.z + v.w * v.w); }
; template <int R, bool BASE_F32, bool OUT_F32>
; __device__ __forceinline__ void rows_res(const Ctx& C, int m0, int stride, int mx, const float* gpost, float scale, int lane) {
;     ...
;     for (int r = 0; r < R; ++r) { mr[r] = (r == 4) ? mx : m0 + r * stride; ok[r] = (r == 4) ? (mx < M) : (mr[r] < MPROMPT); const int mm = ok[r] ? mr[r] : 0;
; #pragma unroll
;         for (int j = 0; j < 4; ++j) d[r][j] = ld4_bf16(D + (size_t)mm * DM + 4 * lane + 256 * j);
;         if (BASE_F32) { const float* x = xrow_ptr(C, mm);
; #pragma unroll
;             for (int j = 0; j < 4; ++j) b[r][j] = ld4_f32(x + 4 * lane + 256 * j);
;         } else { const float inv = C.RS()[mm];
; #pragma unroll
;             for (int j = 0; j < 4; ++j) b[r][j] = ld4_bf16(XN + (size_t)mm * DM + 4 * lane + 256 * j) * inv;
;         } }
; #pragma unroll
;     for (int r = 0; r < R; ++r) { float s = 0.f;
; #pragma unroll
;         for (int j = 0; j < 4; ++j) s += ssq4(d[r][j]);
;         r1[r] = s; }
;     ...
;         for (int r = 0; r < R; ++r) { float s = 0.f;
; #pragma unroll
;             for (int j = 0; j < 4; ++j) s += ssq4(d[r][j]);
;             t[r] = s; }
; #pragma unroll
;         for (int r = 0; r < R; ++r) t[r] = wave_sum(t[r]) * (1.f / DM) + EPS;
; #pragma unroll
;         for (int r = 0; r < R; ++r) { const float rstd = rsqrtf(t[r]);
; #pragma unroll
;             for (int j = 0; j < 4; ++j) if (ok[r]) st4_bf16(XN + (size_t)mr[r] * DM + 4 * lane + 256 * j, d[r][j] * rstd);
;             if (lane == 0 && ok[r]) rs[mr[r]] = sqrtf(t[r]); }
	v_add_f32_e32 v132, v132, v136
	v_add_f32_e32 v134, v134, v137
	ds_bpermute_b32 v136, v188, v132
	ds_bpermute_b32 v137, v188, v134
	s_waitcnt lgkmcnt(0)
	v_add_f32_e32 v132, v132, v136
	v_add_f32_e32 v134, v134, v137
	v_fmamk_f32 v164, v132, 0x3a800000, v138
	v_fmamk_f32 v167, v134, 0x3a800000, v138
	s_nop 0
	v_rsq_f32_e32 v132, v164
	v_rsq_f32_e32 v134, v167
	v_sqrt_f32_e32 v165, v164
	v_sqrt_f32_e32 v168, v167
	s_nop 1
	v_pk_mul_f32 v[140:141], v[96:97], v[132:133] op_sel_hi:[1,0]
	v_cvt_pk_bf16_f32 v148, v140, v141
	v_pk_mul_f32 v[142:143], v[98:99], v[132:133] op_sel_hi:[1,0]
	v_cvt_pk_bf16_f32 v149, v142, v143
	v_pk_mul_f32 v[144:145], v[100:101], v[132:133] op_sel_hi:[1,0]
	v_cvt_pk_bf16_f32 v150, v144, v145
	v_pk_mul_f32 v[146:147], v[102:103], v[132:133] op_sel_hi:[1,0]
	v_cvt_pk_bf16_f32 v151, v146, v147
	v_pk_mul_f32 v[140:141], v[104:105], v[132:133] op_sel_hi:[1,0]
	v_cvt_pk_bf16_f32 v152, v140, v141
	v_pk_mul_f32 v[142:143], v[106:107], v[132:133] op_sel_hi:[1,0]
	v_cvt_pk_bf16_f32 v153, v142, v143
	v_pk_mul_f32 v[144:145], v[108:109], v[132:133] op_sel_hi:[1,0]
	v_cvt_pk_bf16_f32 v154, v144, v145
	v_pk_mul_f32 v[146:147], v[110:111], v[132:133] op_sel_hi:[1,0]
	v_cvt_pk_bf16_f32 v155, v146, v147
	global_store_dwordx2 v173, v[148:149], s[98:99]
	global_store_dwordx2 v173, v[150:151], s[98:99] offset:512
	global_store_dwordx2 v173, v[152:153], s[98:99] offset:1024
	global_store_dwordx2 v173, v[154:155], s[98:99] offset:1536
	v_add_u32_e32 v173, 0xffc00000, v173
	v_pk_mul_f32 v[140:141], v[112:113], v[134:135] op_sel_hi:[1,0]
	v_cvt_pk_bf16_f32 v156, v140, v141
	v_pk_mul_f32 v[142:143], v[114:115], v[134:135] op_sel_hi:[1,0]
	v_cvt_pk_bf16_f32 v157, v142, v143
	v_pk_mul_f32 v[144:145], v[116:117], v[134:135] op_sel_hi:[1,0]
	v_cvt_pk_bf16_f32 v158, v144, v145
	v_pk_mul_f32 v[146:147], v[118:119], v[134:135] op_sel_hi:[1,0]
	v_cvt_pk_bf16_f32 v159, v146, v147
	v_pk_mul_f32 v[140:141], v[120:121], v[134:135] op_sel_hi:[1,0]
	v_cvt_pk_bf16_f32 v160, v140, v141
	v_pk_mul_f32 v[142:143], v[122:123], v[134:135] op_sel_hi:[1,0]
	v_cvt_pk_bf16_f32 v161, v142, v143
	v_pk_mul_f32 v[144:145], v[124:125], v[134:135] op_sel_hi:[1,0]
	v_cvt_pk_bf16_f32 v162, v144, v145
	v_pk_mul_f32 v[146:147], v[126:127], v[134:135] op_sel_hi:[1,0]
	v_cvt_pk_bf16_f32 v163, v146, v147
	global_store_dwordx2 v173, v[156:157], s[98:99]
	global_store_dwordx2 v173, v[158:159], s[98:99] offset:512
	global_store_dwordx2 v173, v[160:161], s[98:99] offset:1024
	global_store_dwordx2 v173, v[162:163], s[98:99] offset:1536
	v_add_u32_e32 v173, 0xffc00000, v173
	v_add_u32_e32 v166, -1, v165
	v_fma_f32 v140, -v166, v165, v164
	v_cmp_ge_f32_e32 vcc, 0, v140
	v_add_u32_e32 v141, 1, v165
	v_cndmask_b32_e32 v166, v165, v166, vcc
	v_fma_f32 v140, -v141, v165, v164
	v_cmp_lt_f32_e32 vcc, 0, v140
	s_nop 1
	v_cndmask_b32_e32 v165, v166, v141, vcc
	v_add_u32_e32 v169, -1, v168
	v_fma_f32 v142, -v169, v168, v167
	v_cmp_ge_f32_e32 vcc, 0, v142
	v_add_u32_e32 v143, 1, v168
	v_cndmask_b32_e32 v169, v168, v169, vcc
	v_fma_f32 v142, -v143, v168, v167
	v_cmp_lt_f32_e32 vcc, 0, v142
	s_nop 1
	v_cndmask_b32_e32 v168, v169, v143, vcc
	s_mov_b64 exec, 1
	global_store_dword v174, v165, s[98:99]
	v_add_u32_e32 v174, 0xffffe000, v174
	global_store_dword v174, v168, s[98:99]
	v_add_u32_e32 v174, 0xffffe000, v174
	s_mov_b64 exec, -1
	global_load_dword v52, v172, s[98:99]
	global_load_dwordx2 v[20:21], v170, s[98:99]
	global_load_dwordx2 v[22:23], v170, s[98:99] offset:512
	global_load_dwordx2 v[24:25], v170, s[98:99] offset:1024
	global_load_dwordx2 v[26:27], v170, s[98:99] offset:1536
	global_load_dwordx2 v[36:37], v171, s[98:99]
	global_load_dwordx2 v[38:39], v171, s[98:99] offset:512
	global_load_dwordx2 v[40:41], v171, s[98:99] offset:1024
	global_load_dwordx2 v[42:43], v171, s[98:99] offset:1536
	v_add_u32_e32 v170, 0xffc00000, v170
	v_add_u32_e32 v171, 0xffc00000, v171
	v_add_u32_e32 v172, 0xffffe000, v172
	global_load_dword v54, v172, s[98:99]
	global_load_dwordx2 v[28:29], v170, s[98:99]
	global_load_dwordx2 v[30:31], v170, s[98:99] offset:512
	global_load_dwordx2 v[32:33], v170, s[98:99] offset:1024
	global_load_dwordx2 v[34:35], v170, s[98:99] offset:1536
	global_load_dwordx2 v[44:45], v171, s[98:99]
	global_load_dwordx2 v[46:47], v171, s[98:99] offset:512
	global_load_dwordx2 v[48:49], v171, s[98:99] offset:1024
	global_load_dwordx2 v[50:51], v171, s[98:99] offset:1536
	v_add_u32_e32 v170, 0xffc00000, v170
	v_add_u32_e32 v171, 0xffc00000, v171
	v_add_u32_e32 v172, 0xffffe000, v172
	s_waitcnt vmcnt(41)
	v_lshlrev_b32_e32 v96, 16, v56
	v_and_b32_e32 v97, 0xffff0000, v56
	v_lshlrev_b32_e32 v98, 16, v57
	v_and_b32_e32 v99, 0xffff0000, v57
	v_lshlrev_b32_e32 v100, 16, v58
	v_and_b32_e32 v101, 0xffff0000, v58
	v_lshlrev_b32_e32 v102, 16, v59
	v_and_b32_e32 v103, 0xffff0000, v59
	v_lshlrev_b32_e32 v104, 16, v60
	v_and_b32_e32 v105, 0xffff0000, v60
	v_lshlrev_b32_e32 v106, 16, v61
	v_and_b32_e32 v107, 0xffff0000, v61
	v_lshlrev_b32_e32 v108, 16, v62
	v_and_b32_e32 v109, 0xffff0000, v62
	v_lshlrev_b32_e32 v110, 16, v63
	v_and_b32_e32 v111, 0xffff0000, v63
	v_pk_mul_f32 v[128:129], v[96:97], v[96:97]
	v_pk_fma_f32 v[128:129], v[98:99], v[98:99], v[128:129]
	v_pk_fma_f32 v[128:129], v[100:101], v[100:101], v[128:129]
	v_pk_fma_f32 v[128:129], v[102:103], v[102:103], v[128:129]
	v_pk_fma_f32 v[128:129], v[104:105], v[104:105], v[128:129]
	v_pk_fma_f32 v[128:129], v[106:107], v[106:107], v[128:129]
	v_pk_fma_f32 v[128:129], v[108:109], v[108:109], v[128:129]
	v_pk_fma_f32 v[128:129], v[110:111], v[110:111], v[128:129]
	s_nop 0
	v_add_f32_e32 v128, v128, v129
	s_waitcnt vmcnt(32)
;     __device__ __forceinline__ float* out() const { return (float*)karg_in(33); }
; __device__ __forceinline__ float ssq4(v4f v) { return (v.x * v.x + v.y * v.y) + (v.z * v.z + v.w * v.w); }
; template <int R, bool BASE_F32, bool OUT_F32>
; __device__ __forceinline__ void rows_res(const Ctx& C, int m0, int stride, int mx, const float* gpost, float scale, int lane) {
;     ...
;     for (int r = 0; r < R; ++r) { float s = 0.f;
; #pragma unroll
;         for (int j = 0; j < 4; ++j) s += ssq4(d[r][j]);
;         r1[r] = s; }
; #pragma unroll
;     for (int r = 0; r < R; ++r) r1[r] = rsqrtf(wave_sum(r1[r]) * (1.f / DM) + EPS) * scale;
; #pragma unroll
;     for (int j = 0; j < 4; ++j) { const v4f gp = ld4_f32(gpost + 4 * lane + 256 * j);
; #pragma unroll
;         for (int r = 0; r < R; ++r) d[r][j] = b[r][j] + d[r][j] * r1[r] * gp; }
;     if (OUT_F32) { float* Y = C.out();
; #pragma unroll
;         for (int r = 0; r < R; ++r)
; #pragma unroll
;             for (int j = 0; j < 4; ++j) if (ok[r]) *(v4f*)(Y + (size_t)mr[r] * DM + 4 * lane + 256 * j) = d[r][j];
;     } else { float* rs = C.RS(); float t[R];
; #pragma unroll
;         for (int r = 0; r < R; ++r) { float s = 0.f;
; #pragma unroll
;             for (int j = 0; j < 4; ++j) s += ssq4(d[r][j]);
;             t[r] = s; }
	v_lshlrev_b32_e32 v112, 16, v64
	v_and_b32_e32 v113, 0xffff0000, v64
	v_lshlrev_b32_e32 v114, 16, v65
	v_and_b32_e32 v115, 0xffff0000, v65
	v_lshlrev_b32_e32 v116, 16, v66
	v_and_b32_e32 v117, 0xffff0000, v66
	v_lshlrev_b32_e32 v118, 16, v67
	v_and_b32_e32 v119, 0xffff0000, v67
	v_lshlrev_b32_e32 v120, 16, v68
	v_and_b32_e32 v121, 0xffff0000, v68
	v_lshlrev_b32_e32 v122, 16, v69
	v_and_b32_e32 v123, 0xffff0000, v69
	v_lshlrev_b32_e32 v124, 16, v70
	v_and_b32_e32 v125, 0xffff0000, v70
	v_lshlrev_b32_e32 v126, 16, v71
	v_and_b32_e32 v127, 0xffff0000, v71
	v_pk_mul_f32 v[130:131], v[112:113], v[112:113]
	v_pk_fma_f32 v[130:131], v[114:115], v[114:115], v[130:131]
	v_pk_fma_f32 v[130:131], v[116:117], v[116:117], v[130:131]
	v_pk_fma_f32 v[130:131], v[118:119], v[118:119], v[130:131]
	v_pk_fma_f32 v[130:131], v[120:121], v[120:121], v[130:131]
	v_pk_fma_f32 v[130:131], v[122:123], v[122:123], v[130:131]
	v_pk_fma_f32 v[130:131], v[124:125], v[124:125], v[130:131]
	v_pk_fma_f32 v[130:131], v[126:127], v[126:127], v[130:131]
	s_nop 0
	v_add_f32_e32 v130, v130, v131
	s_nop 1
	v_add_f32_dpp v128, v128, v128 quad_perm:[1,0,3,2] row_mask:0xf bank_mask:0xf
	v_add_f32_dpp v130, v130, v130 quad_perm:[1,0,3,2] row_mask:0xf bank_mask:0xf
	s_nop 0
	v_add_f32_dpp v128, v128, v128 quad_perm:[2,3,0,1] row_mask:0xf bank_mask:0xf
	v_add_f32_dpp v130, v130, v130 quad_perm:[2,3,0,1] row_mask:0xf bank_mask:0xf
	s_nop 0
	v_add_f32_dpp v128, v128, v128 row_half_mirror row_mask:0xf bank_mask:0xf
	v_add_f32_dpp v130, v130, v130 row_half_mirror row_mask:0xf bank_mask:0xf
	s_nop 0
	v_add_f32_dpp v128, v128, v128 row_mirror row_mask:0xf bank_mask:0xf
	v_add_f32_dpp v130, v130, v130 row_mirror row_mask:0xf bank_mask:0xf
	s_nop 0
	ds_bpermute_b32 v136, v187, v128
	ds_bpermute_b32 v137, v187, v130
	s_waitcnt lgkmcnt(0)
	v_add_f32_e32 v128, v128, v136
	v_add_f32_e32 v130, v130, v137
	ds_bpermute_b32 v136, v188, v128
	ds_bpermute_b32 v137, v188, v130
	s_waitcnt lgkmcnt(0)
	v_add_f32_e32 v128, v128, v136
	v_add_f32_e32 v130, v130, v137
	v_fmamk_f32 v128, v128, 0x3a800000, v138
	v_fmamk_f32 v130, v130, 0x3a800000, v138
	s_nop 0
	v_rsq_f32_e32 v128, v128
	v_rsq_f32_e32 v130, v130
	s_nop 1
	v_mul_f32_e32 v128, 0.5, v128
	v_mul_f32_e32 v130, 0.5, v130
	s_waitcnt vmcnt(28)
	v_pk_mul_f32 v[96:97], v[128:129], v[96:97] op_sel_hi:[0,1]
	v_pk_mul_f32 v[98:99], v[128:129], v[98:99] op_sel_hi:[0,1]
	v_pk_mul_f32 v[100:101], v[128:129], v[100:101] op_sel_hi:[0,1]
	v_pk_mul_f32 v[102:103], v[128:129], v[102:103] op_sel_hi:[0,1]
	v_pk_mul_f32 v[104:105], v[128:129], v[104:105] op_sel_hi:[0,1]
	v_pk_mul_f32 v[106:107], v[128:129], v[106:107] op_sel_hi:[0,1]
	v_pk_mul_f32 v[108:109], v[128:129], v[108:109] op_sel_hi:[0,1]
	v_pk_mul_f32 v[110:111], v[128:129], v[110:111] op_sel_hi:[0,1]
	v_pk_mul_f32 v[96:97], v[96:97], v[192:193]
	v_pk_mul_f32 v[98:99], v[98:99], v[194:195]
	v_pk_mul_f32 v[100:101], v[100:101], v[196:197]
	v_pk_mul_f32 v[102:103], v[102:103], v[198:199]
	v_pk_mul_f32 v[104:105], v[104:105], v[200:201]
	v_pk_mul_f32 v[106:107], v[106:107], v[202:203]
	v_pk_mul_f32 v[108:109], v[108:109], v[204:205]
	v_pk_mul_f32 v[110:111], v[110:111], v[206:207]
	v_lshlrev_b32_e32 v56, 16, v72
	v_and_b32_e32 v57, 0xffff0000, v72
	v_lshlrev_b32_e32 v58, 16, v73
	v_and_b32_e32 v59, 0xffff0000, v73
	v_lshlrev_b32_e32 v60, 16, v74
	v_and_b32_e32 v61, 0xffff0000, v74
	v_lshlrev_b32_e32 v62, 16, v75
	v_and_b32_e32 v63, 0xffff0000, v75
	v_pk_fma_f32 v[96:97], v[88:89], v[56:57], v[96:97] op_sel_hi:[0,1,1]
	v_pk_fma_f32 v[98:99], v[88:89], v[58:59], v[98:99] op_sel_hi:[0,1,1]
	v_pk_fma_f32 v[100:101], v[88:89], v[60:61], v[100:101] op_sel_hi:[0,1,1]
	v_pk_fma_f32 v[102:103], v[88:89], v[62:63], v[102:103] op_sel_hi:[0,1,1]
	v_lshlrev_b32_e32 v56, 16, v76
	v_and_b32_e32 v57, 0xffff0000, v76
	v_lshlrev_b32_e32 v58, 16, v77
	v_and_b32_e32 v59, 0xffff0000, v77
	v_lshlrev_b32_e32 v60, 16, v78
	v_and_b32_e32 v61, 0xffff0000, v78
	v_lshlrev_b32_e32 v62, 16, v79
	v_and_b32_e32 v63, 0xffff0000, v79
	v_pk_fma_f32 v[104:105], v[88:89], v[56:57], v[104:105] op_sel_hi:[0,1,1]
	v_pk_fma_f32 v[106:107], v[88:89], v[58:59], v[106:107] op_sel_hi:[0,1,1]
	v_pk_fma_f32 v[108:109], v[88:89], v[60:61], v[108:109] op_sel_hi:[0,1,1]
	v_pk_fma_f32 v[110:111], v[88:89], v[62:63], v[110:111] op_sel_hi:[0,1,1]
	v_pk_mul_f32 v[132:133], v[96:97], v[96:97]
	v_pk_fma_f32 v[132:133], v[98:99], v[98:99], v[132:133]
	v_pk_fma_f32 v[132:133], v[100:101], v[100:101], v[132:133]
	v_pk_fma_f32 v[132:133], v[102:103], v[102:103], v[132:133]
	v_pk_fma_f32 v[132:133], v[104:105], v[104:105], v[132:133]
	v_pk_fma_f32 v[132:133], v[106:107], v[106:107], v[132:133]
	v_pk_fma_f32 v[132:133], v[108:109], v[108:109], v[132:133]
	v_pk_fma_f32 v[132:133], v[110:111], v[110:111], v[132:133]
	s_nop 0
	v_add_f32_e32 v132, v132, v133
	v_pk_mul_f32 v[112:113], v[130:131], v[112:113] op_sel_hi:[0,1]
	v_pk_mul_f32 v[114:115], v[130:131], v[114:115] op_sel_hi:[0,1]
	v_pk_mul_f32 v[116:117], v[130:131], v[116:117] op_sel_hi:[0,1]
	v_pk_mul_f32 v[118:119], v[130:131], v[118:119] op_sel_hi:[0,1]
	v_pk_mul_f32 v[120:121], v[130:131], v[120:121] op_sel_hi:[0,1]
	v_pk_mul_f32 v[122:123], v[130:131], v[122:123] op_sel_hi:[0,1]
	v_pk_mul_f32 v[124:125], v[130:131], v[124:125] op_sel_hi:[0,1]
	v_pk_mul_f32 v[126:127], v[130:131], v[126:127] op_sel_hi:[0,1]
	v_pk_mul_f32 v[112:113], v[112:113], v[192:193]
	v_pk_mul_f32 v[114:115], v[114:115], v[194:195]
	v_pk_mul_f32 v[116:117], v[116:117], v[196:197]
	v_pk_mul_f32 v[118:119], v[118:119], v[198:199]
	v_pk_mul_f32 v[120:121], v[120:121], v[200:201]
	v_pk_mul_f32 v[122:123], v[122:123], v[202:203]
;     __device__ __forceinline__ float* out() const { return (float*)karg_in(33); }
; __device__ __forceinline__ const float* xrow_ptr(const Ctx& C, int row) { return row < MPROMPT ? C.in(0) + (size_t)row * DM : C.in(1) + (size_t)(row - MPROMPT) * DM; }
; __device__ __forceinline__ v4f ld4_bf16(const bf16* p) { const v2u w = *(const v2u*)p; return (v4f){bf_lo(w.x), bf_hi(w.x), bf_lo(w.y), bf_hi(w.y)}; }
; __device__ __forceinline__ void st4_bf16(bf16* p, v4f o) { v2u w; w.x = cvt_pk_nv(o.x, o.y); w.y = cvt_pk_nv(o.z, o.w); *(v2u*)p = w; }
; template <int R, bool BASE_F32, bool OUT_F32>
; __device__ __forceinline__ void rows_res(const Ctx& C, int m0, int stride, int mx, const float* gpost, float scale, int lane) {
;     ...
;     for (int r = 0; r < R; ++r) { mr[r] = (r == 4) ? mx : m0 + r * stride; ok[r] = (r == 4) ? (mx < M) : (mr[r] < MPROMPT); const int mm = ok[r] ? mr[r] : 0;
; #pragma unroll
;         for (int j = 0; j < 4; ++j) d[r][j] = ld4_bf16(D + (size_t)mm * DM + 4 * lane + 256 * j);
;         if (BASE_F32) { const float* x = xrow_ptr(C, mm);
; #pragma unroll
;             for (int j = 0; j < 4; ++j) b[r][j] = ld4_f32(x + 4 * lane + 256 * j);
;         } else { const float inv = C.RS()[mm];
; #pragma unroll
;             for (int j = 0; j < 4; ++j) b[r][j] = ld4_bf16(XN + (size_t)mm * DM + 4 * lane + 256 * j) * inv;
;         } }
;     ...
;     for (int j = 0; j < 4; ++j) { const v4f gp = ld4_f32(gpost + 4 * lane + 256 * j);
; #pragma unroll
;         for (int r = 0; r < R; ++r) d[r][j] = b[r][j] + d[r][j] * r1[r] * gp; }
;     if (OUT_F32) { float* Y = C.out();
; #pragma unroll
;         for (int r = 0; r < R; ++r)
; #pragma unroll
;             for (int j = 0; j < 4; ++j) if (ok[r]) *(v4f*)(Y + (size_t)mr[r] * DM + 4 * lane + 256 * j) = d[r][j];
;     } else { float* rs = C.RS(); float t[R];
; #pragma unroll
;         for (int r = 0; r < R; ++r) { float s = 0.f;
; #pragma unroll
;             for (int j = 0; j < 4; ++j) s += ssq4(d[r][j]);
;             t[r] = s; }
; #pragma unroll
;         for (int r = 0; r < R; ++r) t[r] = wave_sum(t[r]) * (1.f / DM) + EPS;
; #pragma unroll
;         for (int r = 0; r < R; ++r) { const float rstd = rsqrtf(t[r]);
; #pragma unroll
;             for (int j = 0; j < 4; ++j) if (ok[r]) st4_bf16(XN + (size_t)mr[r] * DM + 4 * lane + 256 * j, d[r][j] * rstd);
;             if (lane == 0 && ok[r]) rs[mr[r]] = sqrtf(t[r]); }
	v_pk_mul_f32 v[124:125], v[124:125], v[204:205]
	v_pk_mul_f32 v[126:127], v[126:127], v[206:207]
	v_lshlrev_b32_e32 v64, 16, v80
	v_and_b32_e32 v65, 0xffff0000, v80
	v_lshlrev_b32_e32 v66, 16, v81
	v_and_b32_e32 v67, 0xffff0000, v81
	v_lshlrev_b32_e32 v68, 16, v82
	v_and_b32_e32 v69, 0xffff0000, v82
	v_lshlrev_b32_e32 v70, 16, v83
	v_and_b32_e32 v71, 0xffff0000, v83
	v_pk_fma_f32 v[112:113], v[90:91], v[64:65], v[112:113] op_sel_hi:[0,1,1]
	v_pk_fma_f32 v[114:115], v[90:91], v[66:67], v[114:115] op_sel_hi:[0,1,1]
	v_pk_fma_f32 v[116:117], v[90:91], v[68:69], v[116:117] op_sel_hi:[0,1,1]
	v_pk_fma_f32 v[118:119], v[90:91], v[70:71], v[118:119] op_sel_hi:[0,1,1]
	v_lshlrev_b32_e32 v64, 16, v84
	v_and_b32_e32 v65, 0xffff0000, v84
	v_lshlrev_b32_e32 v66, 16, v85
	v_and_b32_e32 v67, 0xffff0000, v85
	v_lshlrev_b32_e32 v68, 16, v86
	v_and_b32_e32 v69, 0xffff0000, v86
	v_lshlrev_b32_e32 v70, 16, v87
	v_and_b32_e32 v71, 0xffff0000, v87
	v_pk_fma_f32 v[120:121], v[90:91], v[64:65], v[120:121] op_sel_hi:[0,1,1]
	v_pk_fma_f32 v[122:123], v[90:91], v[66:67], v[122:123] op_sel_hi:[0,1,1]
	v_pk_fma_f32 v[124:125], v[90:91], v[68:69], v[124:125] op_sel_hi:[0,1,1]
	v_pk_fma_f32 v[126:127], v[90:91], v[70:71], v[126:127] op_sel_hi:[0,1,1]
	v_pk_mul_f32 v[134:135], v[112:113], v[112:113]
	v_pk_fma_f32 v[134:135], v[114:115], v[114:115], v[134:135]
	v_pk_fma_f32 v[134:135], v[116:117], v[116:117], v[134:135]
	v_pk_fma_f32 v[134:135], v[118:119], v[118:119], v[134:135]
	v_pk_fma_f32 v[134:135], v[120:121], v[120:121], v[134:135]
	v_pk_fma_f32 v[134:135], v[122:123], v[122:123], v[134:135]
	v_pk_fma_f32 v[134:135], v[124:125], v[124:125], v[134:135]
	v_pk_fma_f32 v[134:135], v[126:127], v[126:127], v[134:135]
	s_nop 0
	v_add_f32_e32 v134, v134, v135
	s_nop 1
	v_add_f32_dpp v132, v132, v132 quad_perm:[1,0,3,2] row_mask:0xf bank_mask:0xf
	v_add_f32_dpp v134, v134, v134 quad_perm:[1,0,3,2] row_mask:0xf bank_mask:0xf
	s_nop 0
	v_add_f32_dpp v132, v132, v132 quad_perm:[2,3,0,1] row_mask:0xf bank_mask:0xf
	v_add_f32_dpp v134, v134, v134 quad_perm:[2,3,0,1] row_mask:0xf bank_mask:0xf
	s_nop 0
	v_add_f32_dpp v132, v132, v132 row_half_mirror row_mask:0xf bank_mask:0xf
	v_add_f32_dpp v134, v134, v134 row_half_mirror row_mask:0xf bank_mask:0xf
	s_nop 0
	v_add_f32_dpp v132, v132, v132 row_mirror row_mask:0xf bank_mask:0xf
	v_add_f32_dpp v134, v134, v134 row_mirror row_mask:0xf bank_mask:0xf
	s_nop 0
	ds_bpermute_b32 v136, v187, v132
	ds_bpermute_b32 v137, v187, v134
	s_waitcnt lgkmcnt(0)
	v_add_f32_e32 v132, v132, v136
	v_add_f32_e32 v134, v134, v137
	ds_bpermute_b32 v136, v188, v132
	ds_bpermute_b32 v137, v188, v134
	s_waitcnt lgkmcnt(0)
	v_add_f32_e32 v132, v132, v136
	v_add_f32_e32 v134, v134, v137
	v_fmamk_f32 v164, v132, 0x3a800000, v138
	v_fmamk_f32 v167, v134, 0x3a800000, v138
	s_nop 0
	v_rsq_f32_e32 v132, v164
	v_rsq_f32_e32 v134, v167
	v_sqrt_f32_e32 v165, v164
	v_sqrt_f32_e32 v168, v167
	s_nop 1
	v_pk_mul_f32 v[140:141], v[96:97], v[132:133] op_sel_hi:[1,0]
	v_cvt_pk_bf16_f32 v148, v140, v141
	v_pk_mul_f32 v[142:143], v[98:99], v[132:133] op_sel_hi:[1,0]
	v_cvt_pk_bf16_f32 v149, v142, v143
	v_pk_mul_f32 v[144:145], v[100:101], v[132:133] op_sel_hi:[1,0]
	v_cvt_pk_bf16_f32 v150, v144, v145
	v_pk_mul_f32 v[146:147], v[102:103], v[132:133] op_sel_hi:[1,0]
	v_cvt_pk_bf16_f32 v151, v146, v147
	v_pk_mul_f32 v[140:141], v[104:105], v[132:133] op_sel_hi:[1,0]
	v_cvt_pk_bf16_f32 v152, v140, v141
	v_pk_mul_f32 v[142:143], v[106:107], v[132:133] op_sel_hi:[1,0]
	v_cvt_pk_bf16_f32 v153, v142, v143
	v_pk_mul_f32 v[144:145], v[108:109], v[132:133] op_sel_hi:[1,0]
	v_cvt_pk_bf16_f32 v154, v144, v145
	v_pk_mul_f32 v[146:147], v[110:111], v[132:133] op_sel_hi:[1,0]
	v_cvt_pk_bf16_f32 v155, v146, v147
	global_store_dwordx2 v173, v[148:149], s[98:99]
	global_store_dwordx2 v173, v[150:151], s[98:99] offset:512
	global_store_dwordx2 v173, v[152:153], s[98:99] offset:1024
	global_store_dwordx2 v173, v[154:155], s[98:99] offset:1536
	v_add_u32_e32 v173, 0xffc00000, v173
	v_pk_mul_f32 v[140:141], v[112:113], v[134:135] op_sel_hi:[1,0]
	v_cvt_pk_bf16_f32 v156, v140, v141
	v_pk_mul_f32 v[142:143], v[114:115], v[134:135] op_sel_hi:[1,0]
	v_cvt_pk_bf16_f32 v157, v142, v143
	v_pk_mul_f32 v[144:145], v[116:117], v[134:135] op_sel_hi:[1,0]
	v_cvt_pk_bf16_f32 v158, v144, v145
	v_pk_mul_f32 v[146:147], v[118:119], v[134:135] op_sel_hi:[1,0]
	v_cvt_pk_bf16_f32 v159, v146, v147
	v_pk_mul_f32 v[140:141], v[120:121], v[134:135] op_sel_hi:[1,0]
	v_cvt_pk_bf16_f32 v160, v140, v141
	v_pk_mul_f32 v[142:143], v[122:123], v[134:135] op_sel_hi:[1,0]
	v_cvt_pk_bf16_f32 v161, v142, v143
	v_pk_mul_f32 v[144:145], v[124:125], v[134:135] op_sel_hi:[1,0]
	v_cvt_pk_bf16_f32 v162, v144, v145
	v_pk_mul_f32 v[146:147], v[126:127], v[134:135] op_sel_hi:[1,0]
	v_cvt_pk_bf16_f32 v163, v146, v147
	global_store_dwordx2 v173, v[156:157], s[98:99]
	global_store_dwordx2 v173, v[158:159], s[98:99] offset:512
	global_store_dwordx2 v173, v[160:161], s[98:99] offset:1024
	global_store_dwordx2 v173, v[162:163], s[98:99] offset:1536
	v_add_u32_e32 v173, 0xffc00000, v173
	v_add_u32_e32 v166, -1, v165
	v_fma_f32 v140, -v166, v165, v164
	v_cmp_ge_f32_e32 vcc, 0, v140
	v_add_u32_e32 v141, 1, v165
	v_cndmask_b32_e32 v166, v165, v166, vcc
	v_fma_f32 v140, -v141, v165, v164
	v_cmp_lt_f32_e32 vcc, 0, v140
	s_nop 1
	v_cndmask_b32_e32 v165, v166, v141, vcc
	v_add_u32_e32 v169, -1, v168
	v_fma_f32 v142, -v169, v168, v167
	v_cmp_ge_f32_e32 vcc, 0, v142
	v_add_u32_e32 v143, 1, v168
	v_cndmask_b32_e32 v169, v168, v169, vcc
	v_fma_f32 v142, -v143, v168, v167
	v_cmp_lt_f32_e32 vcc, 0, v142
	s_nop 1
	v_cndmask_b32_e32 v168, v169, v143, vcc
	s_mov_b64 exec, 1
	global_store_dword v174, v165, s[98:99]
	v_add_u32_e32 v174, 0xffffe000, v174
	global_store_dword v174, v168, s[98:99]
	v_add_u32_e32 v174, 0xffffe000, v174
	s_mov_b64 exec, -1
	global_load_dword v88, v172, s[98:99]
	global_load_dwordx2 v[56:57], v170, s[98:99]
	global_load_dwordx2 v[58:59], v170, s[98:99] offset:512
	global_load_dwordx2 v[60:61], v170, s[98:99] offset:1024
	global_load_dwordx2 v[62:63], v170, s[98:99] offset:1536
	global_load_dwordx2 v[72:73], v171, s[98:99]
	global_load_dwordx2 v[74:75], v171, s[98:99] offset:512
	global_load_dwordx2 v[76:77], v171, s[98:99] offset:1024
	global_load_dwordx2 v[78:79], v171, s[98:99] offset:1536
	v_add_u32_e32 v170, 0xffc00000, v170
	v_add_u32_e32 v171, 0xffc00000, v171
	v_add_u32_e32 v172, 0xffffe000, v172
	global_load_dword v90, v172, s[98:99]
	global_load_dwordx2 v[64:65], v170, s[98:99]
	global_load_dwordx2 v[66:67], v170, s[98:99] offset:512
	global_load_dwordx2 v[68:69], v170, s[98:99] offset:1024
	global_load_dwordx2 v[70:71], v170, s[98:99] offset:1536
	global_load_dwordx2 v[80:81], v171, s[98:99]
	global_load_dwordx2 v[82:83], v171, s[98:99] offset:512
	global_load_dwordx2 v[84:85], v171, s[98:99] offset:1024
	global_load_dwordx2 v[86:87], v171, s[98:99] offset:1536
	v_add_u32_e32 v170, 0xffc00000, v170
	v_add_u32_e32 v171, 0xffc00000, v171
	v_add_u32_e32 v172, 0xffffe000, v172
	s_waitcnt vmcnt(41)
;     __device__ __forceinline__ float* out() const { return (float*)karg_in(33); }
; __device__ __forceinline__ float ssq4(v4f v) { return (v.x * v.x + v.y * v.y) + (v.z * v.z + v.w * v.w); }
; template <int R, bool BASE_F32, bool OUT_F32>
; __device__ __forceinline__ void rows_res(const Ctx& C, int m0, int stride, int mx, const float* gpost, float scale, int lane) {
;     ...
;     for (int r = 0; r < R; ++r) { float s = 0.f;
; #pragma unroll
;         for (int j = 0; j < 4; ++j) s += ssq4(d[r][j]);
;         r1[r] = s; }
; #pragma unroll
;     for (int r = 0; r < R; ++r) r1[r] = rsqrtf(wave_sum(r1[r]) * (1.f / DM) + EPS) * scale;
; #pragma unroll
;     for (int j = 0; j < 4; ++j) { const v4f gp = ld4_f32(gpost + 4 * lane + 256 * j);
; #pragma unroll
;         for (int r = 0; r < R; ++r) d[r][j] = b[r][j] + d[r][j] * r1[r] * gp; }
;     if (OUT_F32) { float* Y = C.out();
; #pragma unroll
;         for (int r = 0; r < R; ++r)
; #pragma unroll
;             for (int j = 0; j < 4; ++j) if (ok[r]) *(v4f*)(Y + (size_t)mr[r] * DM + 4 * lane + 256 * j) = d[r][j];
;     } else { float* rs = C.RS(); float t[R];
; #pragma unroll
;         for (int r = 0; r < R; ++r) { float s = 0.f;
; #pragma unroll
;             for (int j = 0; j < 4; ++j) s += ssq4(d[r][j]);
;             t[r] = s; }
	v_lshlrev_b32_e32 v96, 16, v20
	v_and_b32_e32 v97, 0xffff0000, v20
	v_lshlrev_b32_e32 v98, 16, v21
	v_and_b32_e32 v99, 0xffff0000, v21
	v_lshlrev_b32_e32 v100, 16, v22
	v_and_b32_e32 v101, 0xffff0000, v22
	v_lshlrev_b32_e32 v102, 16, v23
	v_and_b32_e32 v103, 0xffff0000, v23
	v_lshlrev_b32_e32 v104, 16, v24
	v_and_b32_e32 v105, 0xffff0000, v24
	v_lshlrev_b32_e32 v106, 16, v25
	v_and_b32_e32 v107, 0xffff0000, v25
	v_lshlrev_b32_e32 v108, 16, v26
	v_and_b32_e32 v109, 0xffff0000, v26
	v_lshlrev_b32_e32 v110, 16, v27
	v_and_b32_e32 v111, 0xffff0000, v27
	v_pk_mul_f32 v[128:129], v[96:97], v[96:97]
	v_pk_fma_f32 v[128:129], v[98:99], v[98:99], v[128:129]
	v_pk_fma_f32 v[128:129], v[100:101], v[100:101], v[128:129]
	v_pk_fma_f32 v[128:129], v[102:103], v[102:103], v[128:129]
	v_pk_fma_f32 v[128:129], v[104:105], v[104:105], v[128:129]
	v_pk_fma_f32 v[128:129], v[106:107], v[106:107], v[128:129]
	v_pk_fma_f32 v[128:129], v[108:109], v[108:109], v[128:129]
	v_pk_fma_f32 v[128:129], v[110:111], v[110:111], v[128:129]
	s_nop 0
	v_add_f32_e32 v128, v128, v129
	s_waitcnt vmcnt(32)
	v_lshlrev_b32_e32 v112, 16, v28
	v_and_b32_e32 v113, 0xffff0000, v28
	v_lshlrev_b32_e32 v114, 16, v29
	v_and_b32_e32 v115, 0xffff0000, v29
	v_lshlrev_b32_e32 v116, 16, v30
	v_and_b32_e32 v117, 0xffff0000, v30
	v_lshlrev_b32_e32 v118, 16, v31
	v_and_b32_e32 v119, 0xffff0000, v31
	v_lshlrev_b32_e32 v120, 16, v32
	v_and_b32_e32 v121, 0xffff0000, v32
	v_lshlrev_b32_e32 v122, 16, v33
	v_and_b32_e32 v123, 0xffff0000, v33
	v_lshlrev_b32_e32 v124, 16, v34
	v_and_b32_e32 v125, 0xffff0000, v34
	v_lshlrev_b32_e32 v126, 16, v35
	v_and_b32_e32 v127, 0xffff0000, v35
	v_pk_mul_f32 v[130:131], v[112:113], v[112:113]
	v_pk_fma_f32 v[130:131], v[114:115], v[114:115], v[130:131]
	v_pk_fma_f32 v[130:131], v[116:117], v[116:117], v[130:131]
	v_pk_fma_f32 v[130:131], v[118:119], v[118:119], v[130:131]
	v_pk_fma_f32 v[130:131], v[120:121], v[120:121], v[130:131]
	v_pk_fma_f32 v[130:131], v[122:123], v[122:123], v[130:131]
	v_pk_fma_f32 v[130:131], v[124:125], v[124:125], v[130:131]
	v_pk_fma_f32 v[130:131], v[126:127], v[126:127], v[130:131]
	s_nop 0
	v_add_f32_e32 v130, v130, v131
	s_nop 1
	v_add_f32_dpp v128, v128, v128 quad_perm:[1,0,3,2] row_mask:0xf bank_mask:0xf
	v_add_f32_dpp v130, v130, v130 quad_perm:[1,0,3,2] row_mask:0xf bank_mask:0xf
	s_nop 0
	v_add_f32_dpp v128, v128, v128 quad_perm:[2,3,0,1] row_mask:0xf bank_mask:0xf
	v_add_f32_dpp v130, v130, v130 quad_perm:[2,3,0,1] row_mask:0xf bank_mask:0xf
	s_nop 0
	v_add_f32_dpp v128, v128, v128 row_half_mirror row_mask:0xf bank_mask:0xf
	v_add_f32_dpp v130, v130, v130 row_half_mirror row_mask:0xf bank_mask:0xf
	s_nop 0
	v_add_f32_dpp v128, v128, v128 row_mirror row_mask:0xf bank_mask:0xf
	v_add_f32_dpp v130, v130, v130 row_mirror row_mask:0xf bank_mask:0xf
	s_nop 0
	ds_bpermute_b32 v136, v187, v128
	ds_bpermute_b32 v137, v187, v130
	s_waitcnt lgkmcnt(0)
	v_add_f32_e32 v128, v128, v136
	v_add_f32_e32 v130, v130, v137
	ds_bpermute_b32 v136, v188, v128
	ds_bpermute_b32 v137, v188, v130
	s_waitcnt lgkmcnt(0)
	v_add_f32_e32 v128, v128, v136
	v_add_f32_e32 v130, v130, v137
	v_fmamk_f32 v128, v128, 0x3a800000, v138
	v_fmamk_f32 v130, v130, 0x3a800000, v138
	s_nop 0
	v_rsq_f32_e32 v128, v128
	v_rsq_f32_e32 v130, v130
	s_nop 1
	v_mul_f32_e32 v128, 0.5, v128
	v_mul_f32_e32 v130, 0.5, v130
	s_waitcnt vmcnt(28)
	v_pk_mul_f32 v[96:97], v[128:129], v[96:97] op_sel_hi:[0,1]
	v_pk_mul_f32 v[98:99], v[128:129], v[98:99] op_sel_hi:[0,1]
	v_pk_mul_f32 v[100:101], v[128:129], v[100:101] op_sel_hi:[0,1]
	v_pk_mul_f32 v[102:103], v[128:129], v[102:103] op_sel_hi:[0,1]
	v_pk_mul_f32 v[104:105], v[128:129], v[104:105] op_sel_hi:[0,1]
	v_pk_mul_f32 v[106:107], v[128:129], v[106:107] op_sel_hi:[0,1]
	v_pk_mul_f32 v[108:109], v[128:129], v[108:109] op_sel_hi:[0,1]
	v_pk_mul_f32 v[110:111], v[128:129], v[110:111] op_sel_hi:[0,1]
	v_pk_mul_f32 v[96:97], v[96:97], v[192:193]
	v_pk_mul_f32 v[98:99], v[98:99], v[194:195]
	v_pk_mul_f32 v[100:101], v[100:101], v[196:197]
	v_pk_mul_f32 v[102:103], v[102:103], v[198:199]
	v_pk_mul_f32 v[104:105], v[104:105], v[200:201]
	v_pk_mul_f32 v[106:107], v[106:107], v[202:203]
	v_pk_mul_f32 v[108:109], v[108:109], v[204:205]
	v_pk_mul_f32 v[110:111], v[110:111], v[206:207]
	v_lshlrev_b32_e32 v20, 16, v36
	v_and_b32_e32 v21, 0xffff0000, v36
	v_lshlrev_b32_e32 v22, 16, v37
	v_and_b32_e32 v23, 0xffff0000, v37
	v_lshlrev_b32_e32 v24, 16, v38
	v_and_b32_e32 v25, 0xffff0000, v38
	v_lshlrev_b32_e32 v26, 16, v39
	v_and_b32_e32 v27, 0xffff0000, v39
	v_pk_fma_f32 v[96:97], v[52:53], v[20:21], v[96:97] op_sel_hi:[0,1,1]
	v_pk_fma_f32 v[98:99], v[52:53], v[22:23], v[98:99] op_sel_hi:[0,1,1]
	v_pk_fma_f32 v[100:101], v[52:53], v[24:25], v[100:101] op_sel_hi:[0,1,1]
	v_pk_fma_f32 v[102:103], v[52:53], v[26:27], v[102:103] op_sel_hi:[0,1,1]
	v_lshlrev_b32_e32 v20, 16, v40
	v_and_b32_e32 v21, 0xffff0000, v40
	v_lshlrev_b32_e32 v22, 16, v41
	v_and_b32_e32 v23, 0xffff0000, v41
	v_lshlrev_b32_e32 v24, 16, v42
	v_and_b32_e32 v25, 0xffff0000, v42
	v_lshlrev_b32_e32 v26, 16, v43
	v_and_b32_e32 v27, 0xffff0000, v43
	v_pk_fma_f32 v[104:105], v[52:53], v[20:21], v[104:105] op_sel_hi:[0,1,1]
	v_pk_fma_f32 v[106:107], v[52:53], v[22:23], v[106:107] op_sel_hi:[0,1,1]
	v_pk_fma_f32 v[108:109], v[52:53], v[24:25], v[108:109] op_sel_hi:[0,1,1]
	v_pk_fma_f32 v[110:111], v[52:53], v[26:27], v[110:111] op_sel_hi:[0,1,1]
	v_pk_mul_f32 v[132:133], v[96:97], v[96:97]
	v_pk_fma_f32 v[132:133], v[98:99], v[98:99], v[132:133]
	v_pk_fma_f32 v[132:133], v[100:101], v[100:101], v[132:133]
	v_pk_fma_f32 v[132:133], v[102:103], v[102:103], v[132:133]
;     __device__ __forceinline__ float* out() const { return (float*)karg_in(33); }
; __device__ __forceinline__ void st4_bf16(bf16* p, v4f o) { v2u w; w.x = cvt_pk_nv(o.x, o.y); w.y = cvt_pk_nv(o.z, o.w); *(v2u*)p = w; }
; __device__ __forceinline__ float ssq4(v4f v) { return (v.x * v.x + v.y * v.y) + (v.z * v.z + v.w * v.w); }
; template <int R, bool BASE_F32, bool OUT_F32>
; __device__ __forceinline__ void rows_res(const Ctx& C, int m0, int stride, int mx, const float* gpost, float scale, int lane) {
;     ...
;     for (int j = 0; j < 4; ++j) { const v4f gp = ld4_f32(gpost + 4 * lane + 256 * j);
; #pragma unroll
;         for (int r = 0; r < R; ++r) d[r][j] = b[r][j] + d[r][j] * r1[r] * gp; }
;     if (OUT_F32) { float* Y = C.out();
; #pragma unroll
;         for (int r = 0; r < R; ++r)
; #pragma unroll
;             for (int j = 0; j < 4; ++j) if (ok[r]) *(v4f*)(Y + (size_t)mr[r] * DM + 4 * lane + 256 * j) = d[r][j];
;     } else { float* rs = C.RS(); float t[R];
; #pragma unroll
;         for (int r = 0; r < R; ++r) { float s = 0.f;
; #pragma unroll
;             for (int j = 0; j < 4; ++j) s += ssq4(d[r][j]);
;             t[r] = s; }
; #pragma unroll
;         for (int r = 0; r < R; ++r) t[r] = wave_sum(t[r]) * (1.f / DM) + EPS;
; #pragma unroll
;         for (int r = 0; r < R; ++r) { const float rstd = rsqrtf(t[r]);
; #pragma unroll
;             for (int j = 0; j < 4; ++j) if (ok[r]) st4_bf16(XN + (size_t)mr[r] * DM + 4 * lane + 256 * j, d[r][j] * rstd);
;             if (lane == 0 && ok[r]) rs[mr[r]] = sqrtf(t[r]); }
	v_pk_fma_f32 v[132:133], v[104:105], v[104:105], v[132:133]
	v_pk_fma_f32 v[132:133], v[106:107], v[106:107], v[132:133]
	v_pk_fma_f32 v[132:133], v[108:109], v[108:109], v[132:133]
	v_pk_fma_f32 v[132:133], v[110:111], v[110:111], v[132:133]
	s_nop 0
	v_add_f32_e32 v132, v132, v133
	v_pk_mul_f32 v[112:113], v[130:131], v[112:113] op_sel_hi:[0,1]
	v_pk_mul_f32 v[114:115], v[130:131], v[114:115] op_sel_hi:[0,1]
	v_pk_mul_f32 v[116:117], v[130:131], v[116:117] op_sel_hi:[0,1]
	v_pk_mul_f32 v[118:119], v[130:131], v[118:119] op_sel_hi:[0,1]
	v_pk_mul_f32 v[120:121], v[130:131], v[120:121] op_sel_hi:[0,1]
	v_pk_mul_f32 v[122:123], v[130:131], v[122:123] op_sel_hi:[0,1]
	v_pk_mul_f32 v[124:125], v[130:131], v[124:125] op_sel_hi:[0,1]
	v_pk_mul_f32 v[126:127], v[130:131], v[126:127] op_sel_hi:[0,1]
	v_pk_mul_f32 v[112:113], v[112:113], v[192:193]
	v_pk_mul_f32 v[114:115], v[114:115], v[194:195]
	v_pk_mul_f32 v[116:117], v[116:117], v[196:197]
	v_pk_mul_f32 v[118:119], v[118:119], v[198:199]
	v_pk_mul_f32 v[120:121], v[120:121], v[200:201]
	v_pk_mul_f32 v[122:123], v[122:123], v[202:203]
	v_pk_mul_f32 v[124:125], v[124:125], v[204:205]
	v_pk_mul_f32 v[126:127], v[126:127], v[206:207]
	v_lshlrev_b32_e32 v28, 16, v44
	v_and_b32_e32 v29, 0xffff0000, v44
	v_lshlrev_b32_e32 v30, 16, v45
	v_and_b32_e32 v31, 0xffff0000, v45
	v_lshlrev_b32_e32 v32, 16, v46
	v_and_b32_e32 v33, 0xffff0000, v46
	v_lshlrev_b32_e32 v34, 16, v47
	v_and_b32_e32 v35, 0xffff0000, v47
	v_pk_fma_f32 v[112:113], v[54:55], v[28:29], v[112:113] op_sel_hi:[0,1,1]
	v_pk_fma_f32 v[114:115], v[54:55], v[30:31], v[114:115] op_sel_hi:[0,1,1]
	v_pk_fma_f32 v[116:117], v[54:55], v[32:33], v[116:117] op_sel_hi:[0,1,1]
	v_pk_fma_f32 v[118:119], v[54:55], v[34:35], v[118:119] op_sel_hi:[0,1,1]
	v_lshlrev_b32_e32 v28, 16, v48
	v_and_b32_e32 v29, 0xffff0000, v48
	v_lshlrev_b32_e32 v30, 16, v49
	v_and_b32_e32 v31, 0xffff0000, v49
	v_lshlrev_b32_e32 v32, 16, v50
	v_and_b32_e32 v33, 0xffff0000, v50
	v_lshlrev_b32_e32 v34, 16, v51
	v_and_b32_e32 v35, 0xffff0000, v51
	v_pk_fma_f32 v[120:121], v[54:55], v[28:29], v[120:121] op_sel_hi:[0,1,1]
	v_pk_fma_f32 v[122:123], v[54:55], v[30:31], v[122:123] op_sel_hi:[0,1,1]
	v_pk_fma_f32 v[124:125], v[54:55], v[32:33], v[124:125] op_sel_hi:[0,1,1]
	v_pk_fma_f32 v[126:127], v[54:55], v[34:35], v[126:127] op_sel_hi:[0,1,1]
	v_pk_mul_f32 v[134:135], v[112:113], v[112:113]
	v_pk_fma_f32 v[134:135], v[114:115], v[114:115], v[134:135]
	v_pk_fma_f32 v[134:135], v[116:117], v[116:117], v[134:135]
	v_pk_fma_f32 v[134:135], v[118:119], v[118:119], v[134:135]
	v_pk_fma_f32 v[134:135], v[120:121], v[120:121], v[134:135]
	v_pk_fma_f32 v[134:135], v[122:123], v[122:123], v[134:135]
	v_pk_fma_f32 v[134:135], v[124:125], v[124:125], v[134:135]
	v_pk_fma_f32 v[134:135], v[126:127], v[126:127], v[134:135]
	s_nop 0
	v_add_f32_e32 v134, v134, v135
	s_nop 1
	v_add_f32_dpp v132, v132, v132 quad_perm:[1,0,3,2] row_mask:0xf bank_mask:0xf
	v_add_f32_dpp v134, v134, v134 quad_perm:[1,0,3,2] row_mask:0xf bank_mask:0xf
	s_nop 0
	v_add_f32_dpp v132, v132, v132 quad_perm:[2,3,0,1] row_mask:0xf bank_mask:0xf
	v_add_f32_dpp v134, v134, v134 quad_perm:[2,3,0,1] row_mask:0xf bank_mask:0xf
	s_nop 0
	v_add_f32_dpp v132, v132, v132 row_half_mirror row_mask:0xf bank_mask:0xf
	v_add_f32_dpp v134, v134, v134 row_half_mirror row_mask:0xf bank_mask:0xf
	s_nop 0
	v_add_f32_dpp v132, v132, v132 row_mirror row_mask:0xf bank_mask:0xf
	v_add_f32_dpp v134, v134, v134 row_mirror row_mask:0xf bank_mask:0xf
	s_nop 0
	ds_bpermute_b32 v136, v187, v132
	ds_bpermute_b32 v137, v187, v134
	s_waitcnt lgkmcnt(0)
	v_add_f32_e32 v132, v132, v136
	v_add_f32_e32 v134, v134, v137
	ds_bpermute_b32 v136, v188, v132
	ds_bpermute_b32 v137, v188, v134
	s_waitcnt lgkmcnt(0)
	v_add_f32_e32 v132, v132, v136
	v_add_f32_e32 v134, v134, v137
	v_fmamk_f32 v164, v132, 0x3a800000, v138
	v_fmamk_f32 v167, v134, 0x3a800000, v138
	s_nop 0
	v_rsq_f32_e32 v132, v164
	v_rsq_f32_e32 v134, v167
	v_sqrt_f32_e32 v165, v164
	v_sqrt_f32_e32 v168, v167
	s_nop 1
	v_pk_mul_f32 v[140:141], v[96:97], v[132:133] op_sel_hi:[1,0]
	v_cvt_pk_bf16_f32 v148, v140, v141
	v_pk_mul_f32 v[142:143], v[98:99], v[132:133] op_sel_hi:[1,0]
	v_cvt_pk_bf16_f32 v149, v142, v143
	v_pk_mul_f32 v[144:145], v[100:101], v[132:133] op_sel_hi:[1,0]
	v_cvt_pk_bf16_f32 v150, v144, v145
	v_pk_mul_f32 v[146:147], v[102:103], v[132:133] op_sel_hi:[1,0]
	v_cvt_pk_bf16_f32 v151, v146, v147
	v_pk_mul_f32 v[140:141], v[104:105], v[132:133] op_sel_hi:[1,0]
	v_cvt_pk_bf16_f32 v152, v140, v141
	v_pk_mul_f32 v[142:143], v[106:107], v[132:133] op_sel_hi:[1,0]
	v_cvt_pk_bf16_f32 v153, v142, v143
	v_pk_mul_f32 v[144:145], v[108:109], v[132:133] op_sel_hi:[1,0]
	v_cvt_pk_bf16_f32 v154, v144, v145
	v_pk_mul_f32 v[146:147], v[110:111], v[132:133] op_sel_hi:[1,0]
	v_cvt_pk_bf16_f32 v155, v146, v147
	global_store_dwordx2 v173, v[148:149], s[98:99]
	global_store_dwordx2 v173, v[150:151], s[98:99] offset:512
	global_store_dwordx2 v173, v[152:153], s[98:99] offset:1024
	global_store_dwordx2 v173, v[154:155], s[98:99] offset:1536
	v_add_u32_e32 v173, 0xffc00000, v173
	v_pk_mul_f32 v[140:141], v[112:113], v[134:135] op_sel_hi:[1,0]
	v_cvt_pk_bf16_f32 v156, v140, v141
	v_pk_mul_f32 v[142:143], v[114:115], v[134:135] op_sel_hi:[1,0]
	v_cvt_pk_bf16_f32 v157, v142, v143
	v_pk_mul_f32 v[144:145], v[116:117], v[134:135] op_sel_hi:[1,0]
	v_cvt_pk_bf16_f32 v158, v144, v145
	v_pk_mul_f32 v[146:147], v[118:119], v[134:135] op_sel_hi:[1,0]
	v_cvt_pk_bf16_f32 v159, v146, v147
	v_pk_mul_f32 v[140:141], v[120:121], v[134:135] op_sel_hi:[1,0]
	v_cvt_pk_bf16_f32 v160, v140, v141
	v_pk_mul_f32 v[142:143], v[122:123], v[134:135] op_sel_hi:[1,0]
	v_cvt_pk_bf16_f32 v161, v142, v143
	v_pk_mul_f32 v[144:145], v[124:125], v[134:135] op_sel_hi:[1,0]
	v_cvt_pk_bf16_f32 v162, v144, v145
	v_pk_mul_f32 v[146:147], v[126:127], v[134:135] op_sel_hi:[1,0]
	v_cvt_pk_bf16_f32 v163, v146, v147
	global_store_dwordx2 v173, v[156:157], s[98:99]
	global_store_dwordx2 v173, v[158:159], s[98:99] offset:512
	global_store_dwordx2 v173, v[160:161], s[98:99] offset:1024
	global_store_dwordx2 v173, v[162:163], s[98:99] offset:1536
	v_add_u32_e32 v173, 0xffc00000, v173
	v_add_u32_e32 v166, -1, v165
	v_fma_f32 v140, -v166, v165, v164
	v_cmp_ge_f32_e32 vcc, 0, v140
	v_add_u32_e32 v141, 1, v165
	v_cndmask_b32_e32 v166, v165, v166, vcc
	v_fma_f32 v140, -v141, v165, v164
	v_cmp_lt_f32_e32 vcc, 0, v140
	s_nop 1
	v_cndmask_b32_e32 v165, v166, v141, vcc
	v_add_u32_e32 v169, -1, v168
	v_fma_f32 v142, -v169, v168, v167
	v_cmp_ge_f32_e32 vcc, 0, v142
	v_add_u32_e32 v143, 1, v168
	v_cndmask_b32_e32 v169, v168, v169, vcc
	v_fma_f32 v142, -v143, v168, v167
	v_cmp_lt_f32_e32 vcc, 0, v142
	s_nop 1
	v_cndmask_b32_e32 v168, v169, v143, vcc
	s_mov_b64 exec, 1
	global_store_dword v174, v165, s[98:99]
	v_add_u32_e32 v174, 0xffffe000, v174
	global_store_dword v174, v168, s[98:99]
	v_add_u32_e32 v174, 0xffffe000, v174
	s_mov_b64 exec, -1
	s_waitcnt vmcnt(23)
;     __device__ __forceinline__ float* out() const { return (float*)karg_in(33); }
; __device__ __forceinline__ float ssq4(v4f v) { return (v.x * v.x + v.y * v.y) + (v.z * v.z + v.w * v.w); }
; template <int R, bool BASE_F32, bool OUT_F32>
; __device__ __forceinline__ void rows_res(const Ctx& C, int m0, int stride, int mx, const float* gpost, float scale, int lane) {
;     ...
;     for (int r = 0; r < R; ++r) { float s = 0.f;
; #pragma unroll
;         for (int j = 0; j < 4; ++j) s += ssq4(d[r][j]);
;         r1[r] = s; }
; #pragma unroll
;     for (int r = 0; r < R; ++r) r1[r] = rsqrtf(wave_sum(r1[r]) * (1.f / DM) + EPS) * scale;
; #pragma unroll
;     for (int j = 0; j < 4; ++j) { const v4f gp = ld4_f32(gpost + 4 * lane + 256 * j);
; #pragma unroll
;         for (int r = 0; r < R; ++r) d[r][j] = b[r][j] + d[r][j] * r1[r] * gp; }
;     if (OUT_F32) { float* Y = C.out();
; #pragma unroll
;         for (int r = 0; r < R; ++r)
; #pragma unroll
;             for (int j = 0; j < 4; ++j) if (ok[r]) *(v4f*)(Y + (size_t)mr[r] * DM + 4 * lane + 256 * j) = d[r][j];
;     } else { float* rs = C.RS(); float t[R];
; #pragma unroll
;         for (int r = 0; r < R; ++r) { float s = 0.f;
; #pragma unroll
;             for (int j = 0; j < 4; ++j) s += ssq4(d[r][j]);
;             t[r] = s; }
	v_lshlrev_b32_e32 v96, 16, v56
	v_and_b32_e32 v97, 0xffff0000, v56
	v_lshlrev_b32_e32 v98, 16, v57
	v_and_b32_e32 v99, 0xffff0000, v57
	v_lshlrev_b32_e32 v100, 16, v58
	v_and_b32_e32 v101, 0xffff0000, v58
	v_lshlrev_b32_e32 v102, 16, v59
	v_and_b32_e32 v103, 0xffff0000, v59
	v_lshlrev_b32_e32 v104, 16, v60
	v_and_b32_e32 v105, 0xffff0000, v60
	v_lshlrev_b32_e32 v106, 16, v61
	v_and_b32_e32 v107, 0xffff0000, v61
	v_lshlrev_b32_e32 v108, 16, v62
	v_and_b32_e32 v109, 0xffff0000, v62
	v_lshlrev_b32_e32 v110, 16, v63
	v_and_b32_e32 v111, 0xffff0000, v63
	v_pk_mul_f32 v[128:129], v[96:97], v[96:97]
	v_pk_fma_f32 v[128:129], v[98:99], v[98:99], v[128:129]
	v_pk_fma_f32 v[128:129], v[100:101], v[100:101], v[128:129]
	v_pk_fma_f32 v[128:129], v[102:103], v[102:103], v[128:129]
	v_pk_fma_f32 v[128:129], v[104:105], v[104:105], v[128:129]
	v_pk_fma_f32 v[128:129], v[106:107], v[106:107], v[128:129]
	v_pk_fma_f32 v[128:129], v[108:109], v[108:109], v[128:129]
	v_pk_fma_f32 v[128:129], v[110:111], v[110:111], v[128:129]
	s_nop 0
	v_add_f32_e32 v128, v128, v129
	s_waitcnt vmcnt(14)
	v_lshlrev_b32_e32 v112, 16, v64
	v_and_b32_e32 v113, 0xffff0000, v64
	v_lshlrev_b32_e32 v114, 16, v65
	v_and_b32_e32 v115, 0xffff0000, v65
	v_lshlrev_b32_e32 v116, 16, v66
	v_and_b32_e32 v117, 0xffff0000, v66
	v_lshlrev_b32_e32 v118, 16, v67
	v_and_b32_e32 v119, 0xffff0000, v67
	v_lshlrev_b32_e32 v120, 16, v68
	v_and_b32_e32 v121, 0xffff0000, v68
	v_lshlrev_b32_e32 v122, 16, v69
	v_and_b32_e32 v123, 0xffff0000, v69
	v_lshlrev_b32_e32 v124, 16, v70
	v_and_b32_e32 v125, 0xffff0000, v70
	v_lshlrev_b32_e32 v126, 16, v71
	v_and_b32_e32 v127, 0xffff0000, v71
	v_pk_mul_f32 v[130:131], v[112:113], v[112:113]
	v_pk_fma_f32 v[130:131], v[114:115], v[114:115], v[130:131]
	v_pk_fma_f32 v[130:131], v[116:117], v[116:117], v[130:131]
	v_pk_fma_f32 v[130:131], v[118:119], v[118:119], v[130:131]
	v_pk_fma_f32 v[130:131], v[120:121], v[120:121], v[130:131]
	v_pk_fma_f32 v[130:131], v[122:123], v[122:123], v[130:131]
	v_pk_fma_f32 v[130:131], v[124:125], v[124:125], v[130:131]
	v_pk_fma_f32 v[130:131], v[126:127], v[126:127], v[130:131]
	s_nop 0
	v_add_f32_e32 v130, v130, v131
	s_nop 1
	v_add_f32_dpp v128, v128, v128 quad_perm:[1,0,3,2] row_mask:0xf bank_mask:0xf
	v_add_f32_dpp v130, v130, v130 quad_perm:[1,0,3,2] row_mask:0xf bank_mask:0xf
	s_nop 0
	v_add_f32_dpp v128, v128, v128 quad_perm:[2,3,0,1] row_mask:0xf bank_mask:0xf
	v_add_f32_dpp v130, v130, v130 quad_perm:[2,3,0,1] row_mask:0xf bank_mask:0xf
	s_nop 0
	v_add_f32_dpp v128, v128, v128 row_half_mirror row_mask:0xf bank_mask:0xf
	v_add_f32_dpp v130, v130, v130 row_half_mirror row_mask:0xf bank_mask:0xf
	s_nop 0
	v_add_f32_dpp v128, v128, v128 row_mirror row_mask:0xf bank_mask:0xf
	v_add_f32_dpp v130, v130, v130 row_mirror row_mask:0xf bank_mask:0xf
	s_nop 0
	ds_bpermute_b32 v136, v187, v128
	ds_bpermute_b32 v137, v187, v130
	s_waitcnt lgkmcnt(0)
	v_add_f32_e32 v128, v128, v136
	v_add_f32_e32 v130, v130, v137
	ds_bpermute_b32 v136, v188, v128
	ds_bpermute_b32 v137, v188, v130
	s_waitcnt lgkmcnt(0)
	v_add_f32_e32 v128, v128, v136
	v_add_f32_e32 v130, v130, v137
	v_fmamk_f32 v128, v128, 0x3a800000, v138
	v_fmamk_f32 v130, v130, 0x3a800000, v138
	s_nop 0
	v_rsq_f32_e32 v128, v128
	v_rsq_f32_e32 v130, v130
	s_nop 1
	v_mul_f32_e32 v128, 0.5, v128
	v_mul_f32_e32 v130, 0.5, v130
	s_waitcnt vmcnt(10)
	v_pk_mul_f32 v[96:97], v[128:129], v[96:97] op_sel_hi:[0,1]
	v_pk_mul_f32 v[98:99], v[128:129], v[98:99] op_sel_hi:[0,1]
	v_pk_mul_f32 v[100:101], v[128:129], v[100:101] op_sel_hi:[0,1]
	v_pk_mul_f32 v[102:103], v[128:129], v[102:103] op_sel_hi:[0,1]
	v_pk_mul_f32 v[104:105], v[128:129], v[104:105] op_sel_hi:[0,1]
	v_pk_mul_f32 v[106:107], v[128:129], v[106:107] op_sel_hi:[0,1]
	v_pk_mul_f32 v[108:109], v[128:129], v[108:109] op_sel_hi:[0,1]
	v_pk_mul_f32 v[110:111], v[128:129], v[110:111] op_sel_hi:[0,1]
	v_pk_mul_f32 v[96:97], v[96:97], v[192:193]
	v_pk_mul_f32 v[98:99], v[98:99], v[194:195]
	v_pk_mul_f32 v[100:101], v[100:101], v[196:197]
	v_pk_mul_f32 v[102:103], v[102:103], v[198:199]
	v_pk_mul_f32 v[104:105], v[104:105], v[200:201]
	v_pk_mul_f32 v[106:107], v[106:107], v[202:203]
	v_pk_mul_f32 v[108:109], v[108:109], v[204:205]
	v_pk_mul_f32 v[110:111], v[110:111], v[206:207]
	v_lshlrev_b32_e32 v56, 16, v72
	v_and_b32_e32 v57, 0xffff0000, v72
	v_lshlrev_b32_e32 v58, 16, v73
	v_and_b32_e32 v59, 0xffff0000, v73
	v_lshlrev_b32_e32 v60, 16, v74
	v_and_b32_e32 v61, 0xffff0000, v74
	v_lshlrev_b32_e32 v62, 16, v75
	v_and_b32_e32 v63, 0xffff0000, v75
	v_pk_fma_f32 v[96:97], v[88:89], v[56:57], v[96:97] op_sel_hi:[0,1,1]
	v_pk_fma_f32 v[98:99], v[88:89], v[58:59], v[98:99] op_sel_hi:[0,1,1]
	v_pk_fma_f32 v[100:101], v[88:89], v[60:61], v[100:101] op_sel_hi:[0,1,1]
	v_pk_fma_f32 v[102:103], v[88:89], v[62:63], v[102:103] op_sel_hi:[0,1,1]
	v_lshlrev_b32_e32 v56, 16, v76
	v_and_b32_e32 v57, 0xffff0000, v76
	v_lshlrev_b32_e32 v58, 16, v77
	v_and_b32_e32 v59, 0xffff0000, v77
	v_lshlrev_b32_e32 v60, 16, v78
	v_and_b32_e32 v61, 0xffff0000, v78
	v_lshlrev_b32_e32 v62, 16, v79
	v_and_b32_e32 v63, 0xffff0000, v79
	v_pk_fma_f32 v[104:105], v[88:89], v[56:57], v[104:105] op_sel_hi:[0,1,1]
	v_pk_fma_f32 v[106:107], v[88:89], v[58:59], v[106:107] op_sel_hi:[0,1,1]
	v_pk_fma_f32 v[108:109], v[88:89], v[60:61], v[108:109] op_sel_hi:[0,1,1]
	v_pk_fma_f32 v[110:111], v[88:89], v[62:63], v[110:111] op_sel_hi:[0,1,1]
	v_pk_mul_f32 v[132:133], v[96:97], v[96:97]
	v_pk_fma_f32 v[132:133], v[98:99], v[98:99], v[132:133]
	v_pk_fma_f32 v[132:133], v[100:101], v[100:101], v[132:133]
	v_pk_fma_f32 v[132:133], v[102:103], v[102:103], v[132:133]
;     __device__ __forceinline__ float* out() const { return (float*)karg_in(33); }
; __device__ __forceinline__ void st4_bf16(bf16* p, v4f o) { v2u w; w.x = cvt_pk_nv(o.x, o.y); w.y = cvt_pk_nv(o.z, o.w); *(v2u*)p = w; }
; __device__ __forceinline__ float ssq4(v4f v) { return (v.x * v.x + v.y * v.y) + (v.z * v.z + v.w * v.w); }
; template <int R, bool BASE_F32, bool OUT_F32>
; __device__ __forceinline__ void rows_res(const Ctx& C, int m0, int stride, int mx, const float* gpost, float scale, int lane) {
;     ...
;     for (int j = 0; j < 4; ++j) { const v4f gp = ld4_f32(gpost + 4 * lane + 256 * j);
; #pragma unroll
;         for (int r = 0; r < R; ++r) d[r][j] = b[r][j] + d[r][j] * r1[r] * gp; }
;     if (OUT_F32) { float* Y = C.out();
; #pragma unroll
;         for (int r = 0; r < R; ++r)
; #pragma unroll
;             for (int j = 0; j < 4; ++j) if (ok[r]) *(v4f*)(Y + (size_t)mr[r] * DM + 4 * lane + 256 * j) = d[r][j];
;     } else { float* rs = C.RS(); float t[R];
; #pragma unroll
;         for (int r = 0; r < R; ++r) { float s = 0.f;
; #pragma unroll
;             for (int j = 0; j < 4; ++j) s += ssq4(d[r][j]);
;             t[r] = s; }
; #pragma unroll
;         for (int r = 0; r < R; ++r) t[r] = wave_sum(t[r]) * (1.f / DM) + EPS;
; #pragma unroll
;         for (int r = 0; r < R; ++r) { const float rstd = rsqrtf(t[r]);
; #pragma unroll
;             for (int j = 0; j < 4; ++j) if (ok[r]) st4_bf16(XN + (size_t)mr[r] * DM + 4 * lane + 256 * j, d[r][j] * rstd);
;             if (lane == 0 && ok[r]) rs[mr[r]] = sqrtf(t[r]); }
	v_pk_fma_f32 v[132:133], v[104:105], v[104:105], v[132:133]
	v_pk_fma_f32 v[132:133], v[106:107], v[106:107], v[132:133]
	v_pk_fma_f32 v[132:133], v[108:109], v[108:109], v[132:133]
	v_pk_fma_f32 v[132:133], v[110:111], v[110:111], v[132:133]
	s_nop 0
	v_add_f32_e32 v132, v132, v133
	v_pk_mul_f32 v[112:113], v[130:131], v[112:113] op_sel_hi:[0,1]
	v_pk_mul_f32 v[114:115], v[130:131], v[114:115] op_sel_hi:[0,1]
	v_pk_mul_f32 v[116:117], v[130:131], v[116:117] op_sel_hi:[0,1]
	v_pk_mul_f32 v[118:119], v[130:131], v[118:119] op_sel_hi:[0,1]
	v_pk_mul_f32 v[120:121], v[130:131], v[120:121] op_sel_hi:[0,1]
	v_pk_mul_f32 v[122:123], v[130:131], v[122:123] op_sel_hi:[0,1]
	v_pk_mul_f32 v[124:125], v[130:131], v[124:125] op_sel_hi:[0,1]
	v_pk_mul_f32 v[126:127], v[130:131], v[126:127] op_sel_hi:[0,1]
	v_pk_mul_f32 v[112:113], v[112:113], v[192:193]
	v_pk_mul_f32 v[114:115], v[114:115], v[194:195]
	v_pk_mul_f32 v[116:117], v[116:117], v[196:197]
	v_pk_mul_f32 v[118:119], v[118:119], v[198:199]
	v_pk_mul_f32 v[120:121], v[120:121], v[200:201]
	v_pk_mul_f32 v[122:123], v[122:123], v[202:203]
	v_pk_mul_f32 v[124:125], v[124:125], v[204:205]
	v_pk_mul_f32 v[126:127], v[126:127], v[206:207]
	v_lshlrev_b32_e32 v64, 16, v80
	v_and_b32_e32 v65, 0xffff0000, v80
	v_lshlrev_b32_e32 v66, 16, v81
	v_and_b32_e32 v67, 0xffff0000, v81
	v_lshlrev_b32_e32 v68, 16, v82
	v_and_b32_e32 v69, 0xffff0000, v82
	v_lshlrev_b32_e32 v70, 16, v83
	v_and_b32_e32 v71, 0xffff0000, v83
	v_pk_fma_f32 v[112:113], v[90:91], v[64:65], v[112:113] op_sel_hi:[0,1,1]
	v_pk_fma_f32 v[114:115], v[90:91], v[66:67], v[114:115] op_sel_hi:[0,1,1]
	v_pk_fma_f32 v[116:117], v[90:91], v[68:69], v[116:117] op_sel_hi:[0,1,1]
	v_pk_fma_f32 v[118:119], v[90:91], v[70:71], v[118:119] op_sel_hi:[0,1,1]
	v_lshlrev_b32_e32 v64, 16, v84
	v_and_b32_e32 v65, 0xffff0000, v84
	v_lshlrev_b32_e32 v66, 16, v85
	v_and_b32_e32 v67, 0xffff0000, v85
	v_lshlrev_b32_e32 v68, 16, v86
	v_and_b32_e32 v69, 0xffff0000, v86
	v_lshlrev_b32_e32 v70, 16, v87
	v_and_b32_e32 v71, 0xffff0000, v87
	v_pk_fma_f32 v[120:121], v[90:91], v[64:65], v[120:121] op_sel_hi:[0,1,1]
	v_pk_fma_f32 v[122:123], v[90:91], v[66:67], v[122:123] op_sel_hi:[0,1,1]
	v_pk_fma_f32 v[124:125], v[90:91], v[68:69], v[124:125] op_sel_hi:[0,1,1]
	v_pk_fma_f32 v[126:127], v[90:91], v[70:71], v[126:127] op_sel_hi:[0,1,1]
	v_pk_mul_f32 v[134:135], v[112:113], v[112:113]
	v_pk_fma_f32 v[134:135], v[114:115], v[114:115], v[134:135]
	v_pk_fma_f32 v[134:135], v[116:117], v[116:117], v[134:135]
	v_pk_fma_f32 v[134:135], v[118:119], v[118:119], v[134:135]
	v_pk_fma_f32 v[134:135], v[120:121], v[120:121], v[134:135]
	v_pk_fma_f32 v[134:135], v[122:123], v[122:123], v[134:135]
	v_pk_fma_f32 v[134:135], v[124:125], v[124:125], v[134:135]
	v_pk_fma_f32 v[134:135], v[126:127], v[126:127], v[134:135]
	s_nop 0
	v_add_f32_e32 v134, v134, v135
	s_nop 1
	v_add_f32_dpp v132, v132, v132 quad_perm:[1,0,3,2] row_mask:0xf bank_mask:0xf
	v_add_f32_dpp v134, v134, v134 quad_perm:[1,0,3,2] row_mask:0xf bank_mask:0xf
	s_nop 0
	v_add_f32_dpp v132, v132, v132 quad_perm:[2,3,0,1] row_mask:0xf bank_mask:0xf
	v_add_f32_dpp v134, v134, v134 quad_perm:[2,3,0,1] row_mask:0xf bank_mask:0xf
	s_nop 0
	v_add_f32_dpp v132, v132, v132 row_half_mirror row_mask:0xf bank_mask:0xf
	v_add_f32_dpp v134, v134, v134 row_half_mirror row_mask:0xf bank_mask:0xf
	s_nop 0
	v_add_f32_dpp v132, v132, v132 row_mirror row_mask:0xf bank_mask:0xf
	v_add_f32_dpp v134, v134, v134 row_mirror row_mask:0xf bank_mask:0xf
	s_nop 0
	ds_bpermute_b32 v136, v187, v132
	ds_bpermute_b32 v137, v187, v134
	s_waitcnt lgkmcnt(0)
	v_add_f32_e32 v132, v132, v136
	v_add_f32_e32 v134, v134, v137
	ds_bpermute_b32 v136, v188, v132
	ds_bpermute_b32 v137, v188, v134
	s_waitcnt lgkmcnt(0)
	v_add_f32_e32 v132, v132, v136
	v_add_f32_e32 v134, v134, v137
	v_fmamk_f32 v164, v132, 0x3a800000, v138
	v_fmamk_f32 v167, v134, 0x3a800000, v138
	s_nop 0
	v_rsq_f32_e32 v132, v164
	v_rsq_f32_e32 v134, v167
	v_sqrt_f32_e32 v165, v164
	v_sqrt_f32_e32 v168, v167
	s_nop 1
	v_pk_mul_f32 v[140:141], v[96:97], v[132:133] op_sel_hi:[1,0]
	v_cvt_pk_bf16_f32 v148, v140, v141
	v_pk_mul_f32 v[142:143], v[98:99], v[132:133] op_sel_hi:[1,0]
	v_cvt_pk_bf16_f32 v149, v142, v143
	v_pk_mul_f32 v[144:145], v[100:101], v[132:133] op_sel_hi:[1,0]
	v_cvt_pk_bf16_f32 v150, v144, v145
	v_pk_mul_f32 v[146:147], v[102:103], v[132:133] op_sel_hi:[1,0]
	v_cvt_pk_bf16_f32 v151, v146, v147
	v_pk_mul_f32 v[140:141], v[104:105], v[132:133] op_sel_hi:[1,0]
	v_cvt_pk_bf16_f32 v152, v140, v141
	v_pk_mul_f32 v[142:143], v[106:107], v[132:133] op_sel_hi:[1,0]
	v_cvt_pk_bf16_f32 v153, v142, v143
	v_pk_mul_f32 v[144:145], v[108:109], v[132:133] op_sel_hi:[1,0]
	v_cvt_pk_bf16_f32 v154, v144, v145
	v_pk_mul_f32 v[146:147], v[110:111], v[132:133] op_sel_hi:[1,0]
	v_cvt_pk_bf16_f32 v155, v146, v147
	global_store_dwordx2 v173, v[148:149], s[98:99]
	global_store_dwordx2 v173, v[150:151], s[98:99] offset:512
	global_store_dwordx2 v173, v[152:153], s[98:99] offset:1024
	global_store_dwordx2 v173, v[154:155], s[98:99] offset:1536
	v_add_u32_e32 v173, 0xffc00000, v173
	v_pk_mul_f32 v[140:141], v[112:113], v[134:135] op_sel_hi:[1,0]
	v_cvt_pk_bf16_f32 v156, v140, v141
	v_pk_mul_f32 v[142:143], v[114:115], v[134:135] op_sel_hi:[1,0]
	v_cvt_pk_bf16_f32 v157, v142, v143
	v_pk_mul_f32 v[144:145], v[116:117], v[134:135] op_sel_hi:[1,0]
	v_cvt_pk_bf16_f32 v158, v144, v145
	v_pk_mul_f32 v[146:147], v[118:119], v[134:135] op_sel_hi:[1,0]
	v_cvt_pk_bf16_f32 v159, v146, v147
	v_pk_mul_f32 v[140:141], v[120:121], v[134:135] op_sel_hi:[1,0]
	v_cvt_pk_bf16_f32 v160, v140, v141
	v_pk_mul_f32 v[142:143], v[122:123], v[134:135] op_sel_hi:[1,0]
	v_cvt_pk_bf16_f32 v161, v142, v143
	v_pk_mul_f32 v[144:145], v[124:125], v[134:135] op_sel_hi:[1,0]
	v_cvt_pk_bf16_f32 v162, v144, v145
	v_pk_mul_f32 v[146:147], v[126:127], v[134:135] op_sel_hi:[1,0]
	v_cvt_pk_bf16_f32 v163, v146, v147
	global_store_dwordx2 v173, v[156:157], s[98:99]
	global_store_dwordx2 v173, v[158:159], s[98:99] offset:512
	global_store_dwordx2 v173, v[160:161], s[98:99] offset:1024
	global_store_dwordx2 v173, v[162:163], s[98:99] offset:1536
	v_add_u32_e32 v173, 0xffc00000, v173
	v_add_u32_e32 v166, -1, v165
	v_fma_f32 v140, -v166, v165, v164
	v_cmp_ge_f32_e32 vcc, 0, v140
	v_add_u32_e32 v141, 1, v165
	v_cndmask_b32_e32 v166, v165, v166, vcc
	v_fma_f32 v140, -v141, v165, v164
	v_cmp_lt_f32_e32 vcc, 0, v140
	s_nop 1
	v_cndmask_b32_e32 v165, v166, v141, vcc
	v_add_u32_e32 v169, -1, v168
	v_fma_f32 v142, -v169, v168, v167
	v_cmp_ge_f32_e32 vcc, 0, v142
	v_add_u32_e32 v143, 1, v168
	v_cndmask_b32_e32 v169, v168, v169, vcc
	v_fma_f32 v142, -v143, v168, v167
	v_cmp_lt_f32_e32 vcc, 0, v142
	s_nop 1
	v_cndmask_b32_e32 v168, v169, v143, vcc
	s_mov_b64 exec, 1
	global_store_dword v174, v165, s[98:99]
	v_add_u32_e32 v174, 0xffffe000, v174
	global_store_dword v174, v168, s[98:99]
	v_add_u32_e32 v174, 0xffffe000, v174
	s_mov_b64 exec, -1
	s_branch .LBB0_385
;     __device__ __forceinline__ const float* in(int i) const { return karg_in(i); }
; #define FTID const int ftid_ = fresh_tid()
; __global__ void __launch_bounds__(NTHREADS, 2) fwd_kernel(Args args) {
;     ...
;     { FTID; const float* gp = C.in(8); { const int gw_ = GWV, ngw_ = NGWV, nit = (MPROMPT + 4 * ngw_ - 1) / (4 * ngw_);
;       for (int it = 0; it < nit - 1; ++it) rows_res<4, false, false>(C, gw_ + 4 * it * ngw_, ngw_, M, gp, 0.5f, LANE);
;       rows_res<5, false, false>(C, gw_ + 4 * (nit - 1) * ngw_, ngw_, MPROMPT + gw_, gp, 0.5f, LANE);
	v_mov_b32_e32 v3, v1
	s_mov_b32 s0, 0x358637bd
	s_waitcnt lgkmcnt(0)
	v_lshl_add_u64 v[4:5], s[14:15], 0, v[2:3]
	s_mov_b64 s[12:13], 0x7100000
	s_mov_b64 s[16:17], 0x3000000
	v_mov_b32_e32 v3, 0x2a80000
	s_mov_b32 s18, 0x3a800000
	v_mov_b64_e32 v[6:7], s[0:1]
	s_mov_b32 s19, 0x800000
	v_mov_b32_e32 v37, 0x358637bd
	s_mov_b32 s43, 0xf800000
	v_mov_b32_e32 v148, 0x260
	s_mov_b32 s20, s42
	v_readlane_b32 s54, v232, 5
	s_branch .LBB0_369

;     __device__ __forceinline__ const float* in(int i) const { return karg_in(i); }
; __device__ __forceinline__ const float* xrow_ptr(const Ctx& C, int row) { return row < MPROMPT ? C.in(0) + (size_t)row * DM : C.in(1) + (size_t)(row - MPROMPT) * DM; }
; __device__ __forceinline__ v4f ld4_bf16(const bf16* p) { const v2u w = *(const v2u*)p; return (v4f){bf_lo(w.x), bf_hi(w.x), bf_lo(w.y), bf_hi(w.y)}; }
; __device__ __forceinline__ float ssq4(v4f v) { return (v.x * v.x + v.y * v.y) + (v.z * v.z + v.w * v.w); }
; #define FTID const int ftid_ = fresh_tid()
; template <int R, bool BASE_F32, bool OUT_F32>
; __device__ __forceinline__ void rows_res(const Ctx& C, int m0, int stride, int mx, const float* gpost, float scale, int lane) {
;     ...
;     const bf16* D = C.D(); bf16* XN = C.XN();
; #pragma unroll
;     for (int r = 0; r < R; ++r) { mr[r] = (r == 4) ? mx : m0 + r * stride; ok[r] = (r == 4) ? (mx < M) : (mr[r] < MPROMPT); const int mm = ok[r] ? mr[r] : 0;
; #pragma unroll
;         for (int j = 0; j < 4; ++j) d[r][j] = ld4_bf16(D + (size_t)mm * DM + 4 * lane + 256 * j);
;         if (BASE_F32) { const float* x = xrow_ptr(C, mm);
; #pragma unroll
;             for (int j = 0; j < 4; ++j) b[r][j] = ld4_f32(x + 4 * lane + 256 * j);
;         } else { const float inv = C.RS()[mm];
; #pragma unroll
;             for (int j = 0; j < 4; ++j) b[r][j] = ld4_bf16(XN + (size_t)mm * DM + 4 * lane + 256 * j) * inv;
;         } }
; #pragma unroll
;     for (int r = 0; r < R; ++r) { float s = 0.f;
; #pragma unroll
;         for (int j = 0; j < 4; ++j) s += ssq4(d[r][j]);
;         r1[r] = s; }
; __global__ void __launch_bounds__(NTHREADS, 2) fwd_kernel(Args args) {
;     ...
;     { FTID; const float* gp = C.in(27); { const int gw_ = GWV, ngw_ = NGWV, nit = (MPROMPT + 4 * ngw_ - 1) / (4 * ngw_);
;       for (int it = 0; it < nit - 1; ++it) rows_res<4, false, false>(C, gw_ + 4 * it * ngw_, ngw_, M, gp, 1.0f, LANE);
.LBB0_994:
	s_or_b64 exec, exec, s[10:11]
	s_waitcnt lgkmcnt(0)
	v_mov_b32_e32 v0, v182
	s_mov_b64 s[0:1], s[80:81]
	s_barrier
	s_load_dwordx2 s[16:17], s[0:1], 0xd8
	v_readfirstlane_b32 s0, v0
	v_and_b32_e32 v189, 63, v0
	s_ashr_i32 s47, s0, 6
	v_readlane_b32 s0, v232, 0
	v_lshlrev_b32_e32 v0, 2, v189
	s_add_i32 s23, s47, s0
	v_mov_b32_e32 v1, 0
	s_and_b64 vcc, exec, s[6:7]
	v_lshlrev_b32_e32 v2, 2, v0
	v_cmp_ne_u32_e64 s[10:11], 0, v189
	v_lshlrev_b32_e32 v0, 1, v0
	s_load_dwordx2 s[98:99], s[80:81], 0x110
	s_load_dwordx2 s[100:101], s[80:81], 0xd8
	v_and_b32_e32 v176, 63, v182
	v_lshlrev_b32_e32 v170, 3, v176
	s_lshl_b32 vcc_lo, s23, 11
	v_add_u32_e32 v170, vcc_lo, v170
	v_add_u32_e32 v171, 0x3000000, v170
	v_add_u32_e32 v170, 0x7100000, v170
	v_mov_b32_e32 v173, v171
	s_lshl_b32 vcc_lo, s23, 2
	v_mov_b32_e32 v172, 0x2a80000
	v_add_u32_e32 v172, vcc_lo, v172
	v_mov_b32_e32 v174, v172
	v_lshlrev_b32_e32 v176, 4, v176
	v_mov_b32_e32 v138, 0x358637bd
	v_add_u32_e32 v170, 0x2c00000, v170
	v_add_u32_e32 v171, 0x2c00000, v171
	v_add_u32_e32 v173, 0x2c00000, v173
	v_add_u32_e32 v172, 0x16000, v172
	v_add_u32_e32 v174, 0x16000, v174
	s_waitcnt lgkmcnt(0)
	global_load_dwordx4 v[192:195], v176, s[100:101]
	global_load_dwordx4 v[196:199], v176, s[100:101] offset:1024
	global_load_dwordx4 v[200:203], v176, s[100:101] offset:2048
	global_load_dwordx4 v[204:207], v176, s[100:101] offset:3072
	global_load_dword v52, v172, s[98:99]
	global_load_dwordx2 v[20:21], v170, s[98:99]
	global_load_dwordx2 v[22:23], v170, s[98:99] offset:512
	global_load_dwordx2 v[24:25], v170, s[98:99] offset:1024
	global_load_dwordx2 v[26:27], v170, s[98:99] offset:1536
	global_load_dwordx2 v[36:37], v171, s[98:99]
	global_load_dwordx2 v[38:39], v171, s[98:99] offset:512
	global_load_dwordx2 v[40:41], v171, s[98:99] offset:1024
	global_load_dwordx2 v[42:43], v171, s[98:99] offset:1536
	v_add_u32_e32 v170, 0xffc00000, v170
	v_add_u32_e32 v171, 0xffc00000, v171
	v_add_u32_e32 v172, 0xffffe000, v172
	global_load_dword v54, v172, s[98:99]
	global_load_dwordx2 v[28:29], v170, s[98:99]
	global_load_dwordx2 v[30:31], v170, s[98:99] offset:512
	global_load_dwordx2 v[32:33], v170, s[98:99] offset:1024
	global_load_dwordx2 v[34:35], v170, s[98:99] offset:1536
	global_load_dwordx2 v[44:45], v171, s[98:99]
	global_load_dwordx2 v[46:47], v171, s[98:99] offset:512
	global_load_dwordx2 v[48:49], v171, s[98:99] offset:1024
	global_load_dwordx2 v[50:51], v171, s[98:99] offset:1536
	v_add_u32_e32 v170, 0xffc00000, v170
	v_add_u32_e32 v171, 0xffc00000, v171
	v_add_u32_e32 v172, 0xffffe000, v172
	global_load_dword v88, v172, s[98:99]
	global_load_dwordx2 v[56:57], v170, s[98:99]
	global_load_dwordx2 v[58:59], v170, s[98:99] offset:512
	global_load_dwordx2 v[60:61], v170, s[98:99] offset:1024
	global_load_dwordx2 v[62:63], v170, s[98:99] offset:1536
	global_load_dwordx2 v[72:73], v171, s[98:99]
	global_load_dwordx2 v[74:75], v171, s[98:99] offset:512
	global_load_dwordx2 v[76:77], v171, s[98:99] offset:1024
	global_load_dwordx2 v[78:79], v171, s[98:99] offset:1536
	v_add_u32_e32 v170, 0xffc00000, v170
	v_add_u32_e32 v171, 0xffc00000, v171
	v_add_u32_e32 v172, 0xffffe000, v172
	global_load_dword v90, v172, s[98:99]
	global_load_dwordx2 v[64:65], v170, s[98:99]
	global_load_dwordx2 v[66:67], v170, s[98:99] offset:512
	global_load_dwordx2 v[68:69], v170, s[98:99] offset:1024
	global_load_dwordx2 v[70:71], v170, s[98:99] offset:1536
	global_load_dwordx2 v[80:81], v171, s[98:99]
	global_load_dwordx2 v[82:83], v171, s[98:99] offset:512
	global_load_dwordx2 v[84:85], v171, s[98:99] offset:1024
	global_load_dwordx2 v[86:87], v171, s[98:99] offset:1536
	v_add_u32_e32 v170, 0xffc00000, v170
	v_add_u32_e32 v171, 0xffc00000, v171
	v_add_u32_e32 v172, 0xffffe000, v172
	s_waitcnt vmcnt(31)
	v_lshlrev_b32_e32 v96, 16, v20
	v_and_b32_e32 v97, 0xffff0000, v20
	v_lshlrev_b32_e32 v98, 16, v21
	v_and_b32_e32 v99, 0xffff0000, v21
	v_lshlrev_b32_e32 v100, 16, v22
	v_and_b32_e32 v101, 0xffff0000, v22
	v_lshlrev_b32_e32 v102, 16, v23
	v_and_b32_e32 v103, 0xffff0000, v23
	v_lshlrev_b32_e32 v104, 16, v24
	v_and_b32_e32 v105, 0xffff0000, v24
	v_lshlrev_b32_e32 v106, 16, v25
	v_and_b32_e32 v107, 0xffff0000, v25
	v_lshlrev_b32_e32 v108, 16, v26
	v_and_b32_e32 v109, 0xffff0000, v26
	v_lshlrev_b32_e32 v110, 16, v27
	v_and_b32_e32 v111, 0xffff0000, v27
	v_pk_mul_f32 v[128:129], v[96:97], v[96:97]
	v_pk_fma_f32 v[128:129], v[98:99], v[98:99], v[128:129]
	v_pk_fma_f32 v[128:129], v[100:101], v[100:101], v[128:129]
	v_pk_fma_f32 v[128:129], v[102:103], v[102:103], v[128:129]
	v_pk_fma_f32 v[128:129], v[104:105], v[104:105], v[128:129]
	v_pk_fma_f32 v[128:129], v[106:107], v[106:107], v[128:129]
	v_pk_fma_f32 v[128:129], v[108:109], v[108:109], v[128:129]
	v_pk_fma_f32 v[128:129], v[110:111], v[110:111], v[128:129]
	s_nop 0
	v_add_f32_e32 v128, v128, v129
	s_waitcnt vmcnt(22)
; __device__ __forceinline__ float ssq4(v4f v) { return (v.x * v.x + v.y * v.y) + (v.z * v.z + v.w * v.w); }
; template <int R, bool BASE_F32, bool OUT_F32>
; __device__ __forceinline__ void rows_res(const Ctx& C, int m0, int stride, int mx, const float* gpost, float scale, int lane) {
;     ...
;     for (int r = 0; r < R; ++r) { float s = 0.f;
; #pragma unroll
;         for (int j = 0; j < 4; ++j) s += ssq4(d[r][j]);
;         r1[r] = s; }
; #pragma unroll
;     for (int r = 0; r < R; ++r) r1[r] = rsqrtf(wave_sum(r1[r]) * (1.f / DM) + EPS) * scale;
; #pragma unroll
;     for (int j = 0; j < 4; ++j) { const v4f gp = ld4_f32(gpost + 4 * lane + 256 * j);
; #pragma unroll
;         for (int r = 0; r < R; ++r) d[r][j] = b[r][j] + d[r][j] * r1[r] * gp; }
	v_lshlrev_b32_e32 v112, 16, v28
	v_and_b32_e32 v113, 0xffff0000, v28
	v_lshlrev_b32_e32 v114, 16, v29
	v_and_b32_e32 v115, 0xffff0000, v29
	v_lshlrev_b32_e32 v116, 16, v30
	v_and_b32_e32 v117, 0xffff0000, v30
	v_lshlrev_b32_e32 v118, 16, v31
	v_and_b32_e32 v119, 0xffff0000, v31
	v_lshlrev_b32_e32 v120, 16, v32
	v_and_b32_e32 v121, 0xffff0000, v32
	v_lshlrev_b32_e32 v122, 16, v33
	v_and_b32_e32 v123, 0xffff0000, v33
	v_lshlrev_b32_e32 v124, 16, v34
	v_and_b32_e32 v125, 0xffff0000, v34
	v_lshlrev_b32_e32 v126, 16, v35
	v_and_b32_e32 v127, 0xffff0000, v35
	v_pk_mul_f32 v[130:131], v[112:113], v[112:113]
	v_pk_fma_f32 v[130:131], v[114:115], v[114:115], v[130:131]
	v_pk_fma_f32 v[130:131], v[116:117], v[116:117], v[130:131]
	v_pk_fma_f32 v[130:131], v[118:119], v[118:119], v[130:131]
	v_pk_fma_f32 v[130:131], v[120:121], v[120:121], v[130:131]
	v_pk_fma_f32 v[130:131], v[122:123], v[122:123], v[130:131]
	v_pk_fma_f32 v[130:131], v[124:125], v[124:125], v[130:131]
	v_pk_fma_f32 v[130:131], v[126:127], v[126:127], v[130:131]
	s_nop 0
	v_add_f32_e32 v130, v130, v131
	s_nop 1
	v_add_f32_dpp v128, v128, v128 quad_perm:[1,0,3,2] row_mask:0xf bank_mask:0xf
	v_add_f32_dpp v130, v130, v130 quad_perm:[1,0,3,2] row_mask:0xf bank_mask:0xf
	s_nop 0
	v_add_f32_dpp v128, v128, v128 quad_perm:[2,3,0,1] row_mask:0xf bank_mask:0xf
	v_add_f32_dpp v130, v130, v130 quad_perm:[2,3,0,1] row_mask:0xf bank_mask:0xf
	s_nop 0
	v_add_f32_dpp v128, v128, v128 row_half_mirror row_mask:0xf bank_mask:0xf
	v_add_f32_dpp v130, v130, v130 row_half_mirror row_mask:0xf bank_mask:0xf
	s_nop 0
	v_add_f32_dpp v128, v128, v128 row_mirror row_mask:0xf bank_mask:0xf
	v_add_f32_dpp v130, v130, v130 row_mirror row_mask:0xf bank_mask:0xf
	s_nop 0
	ds_bpermute_b32 v136, v187, v128
	ds_bpermute_b32 v137, v187, v130
	s_waitcnt lgkmcnt(0)
	v_add_f32_e32 v128, v128, v136
	v_add_f32_e32 v130, v130, v137
	ds_bpermute_b32 v136, v188, v128
	ds_bpermute_b32 v137, v188, v130
	s_waitcnt lgkmcnt(0)
	v_add_f32_e32 v128, v128, v136
	v_add_f32_e32 v130, v130, v137
	v_fmamk_f32 v128, v128, 0x3a800000, v138
	v_fmamk_f32 v130, v130, 0x3a800000, v138
	s_nop 0
	v_rsq_f32_e32 v128, v128
	v_rsq_f32_e32 v130, v130
	s_nop 1
	s_waitcnt vmcnt(18)
	v_pk_mul_f32 v[96:97], v[128:129], v[96:97] op_sel_hi:[0,1]
	v_pk_mul_f32 v[98:99], v[128:129], v[98:99] op_sel_hi:[0,1]
	v_pk_mul_f32 v[100:101], v[128:129], v[100:101] op_sel_hi:[0,1]
	v_pk_mul_f32 v[102:103], v[128:129], v[102:103] op_sel_hi:[0,1]
	v_pk_mul_f32 v[104:105], v[128:129], v[104:105] op_sel_hi:[0,1]
	v_pk_mul_f32 v[106:107], v[128:129], v[106:107] op_sel_hi:[0,1]
	v_pk_mul_f32 v[108:109], v[128:129], v[108:109] op_sel_hi:[0,1]
	v_pk_mul_f32 v[110:111], v[128:129], v[110:111] op_sel_hi:[0,1]
	v_pk_mul_f32 v[96:97], v[96:97], v[192:193]
	v_pk_mul_f32 v[98:99], v[98:99], v[194:195]
	v_pk_mul_f32 v[100:101], v[100:101], v[196:197]
	v_pk_mul_f32 v[102:103], v[102:103], v[198:199]
	v_pk_mul_f32 v[104:105], v[104:105], v[200:201]
	v_pk_mul_f32 v[106:107], v[106:107], v[202:203]
	v_pk_mul_f32 v[108:109], v[108:109], v[204:205]
	v_pk_mul_f32 v[110:111], v[110:111], v[206:207]
	v_lshlrev_b32_e32 v20, 16, v36
	v_and_b32_e32 v21, 0xffff0000, v36
	v_lshlrev_b32_e32 v22, 16, v37
	v_and_b32_e32 v23, 0xffff0000, v37
	v_lshlrev_b32_e32 v24, 16, v38
	v_and_b32_e32 v25, 0xffff0000, v38
	v_lshlrev_b32_e32 v26, 16, v39
	v_and_b32_e32 v27, 0xffff0000, v39
	v_pk_fma_f32 v[96:97], v[52:53], v[20:21], v[96:97] op_sel_hi:[0,1,1]
	v_pk_fma_f32 v[98:99], v[52:53], v[22:23], v[98:99] op_sel_hi:[0,1,1]
	v_pk_fma_f32 v[100:101], v[52:53], v[24:25], v[100:101] op_sel_hi:[0,1,1]
	v_pk_fma_f32 v[102:103], v[52:53], v[26:27], v[102:103] op_sel_hi:[0,1,1]
	v_lshlrev_b32_e32 v20, 16, v40
	v_and_b32_e32 v21, 0xffff0000, v40
	v_lshlrev_b32_e32 v22, 16, v41
	v_and_b32_e32 v23, 0xffff0000, v41
	v_lshlrev_b32_e32 v24, 16, v42
	v_and_b32_e32 v25, 0xffff0000, v42
	v_lshlrev_b32_e32 v26, 16, v43
	v_and_b32_e32 v27, 0xffff0000, v43
	v_pk_fma_f32 v[104:105], v[52:53], v[20:21], v[104:105] op_sel_hi:[0,1,1]
	v_pk_fma_f32 v[106:107], v[52:53], v[22:23], v[106:107] op_sel_hi:[0,1,1]
	v_pk_fma_f32 v[108:109], v[52:53], v[24:25], v[108:109] op_sel_hi:[0,1,1]
	v_pk_fma_f32 v[110:111], v[52:53], v[26:27], v[110:111] op_sel_hi:[0,1,1]
	v_pk_mul_f32 v[132:133], v[96:97], v[96:97]
	v_pk_fma_f32 v[132:133], v[98:99], v[98:99], v[132:133]
	v_pk_fma_f32 v[132:133], v[100:101], v[100:101], v[132:133]
	v_pk_fma_f32 v[132:133], v[102:103], v[102:103], v[132:133]
	v_pk_fma_f32 v[132:133], v[104:105], v[104:105], v[132:133]
	v_pk_fma_f32 v[132:133], v[106:107], v[106:107], v[132:133]
	v_pk_fma_f32 v[132:133], v[108:109], v[108:109], v[132:133]
	v_pk_fma_f32 v[132:133], v[110:111], v[110:111], v[132:133]
	s_nop 0
	v_add_f32_e32 v132, v132, v133
	v_pk_mul_f32 v[112:113], v[130:131], v[112:113] op_sel_hi:[0,1]
	v_pk_mul_f32 v[114:115], v[130:131], v[114:115] op_sel_hi:[0,1]
	v_pk_mul_f32 v[116:117], v[130:131], v[116:117] op_sel_hi:[0,1]
	v_pk_mul_f32 v[118:119], v[130:131], v[118:119] op_sel_hi:[0,1]
	v_pk_mul_f32 v[120:121], v[130:131], v[120:121] op_sel_hi:[0,1]
	v_pk_mul_f32 v[122:123], v[130:131], v[122:123] op_sel_hi:[0,1]
	v_pk_mul_f32 v[124:125], v[130:131], v[124:125] op_sel_hi:[0,1]
	v_pk_mul_f32 v[126:127], v[130:131], v[126:127] op_sel_hi:[0,1]
	v_pk_mul_f32 v[112:113], v[112:113], v[192:193]
	v_pk_mul_f32 v[114:115], v[114:115], v[194:195]
	v_pk_mul_f32 v[116:117], v[116:117], v[196:197]
	v_pk_mul_f32 v[118:119], v[118:119], v[198:199]
	v_pk_mul_f32 v[120:121], v[120:121], v[200:201]
	v_pk_mul_f32 v[122:123], v[122:123], v[202:203]
	v_pk_mul_f32 v[124:125], v[124:125], v[204:205]
	v_pk_mul_f32 v[126:127], v[126:127], v[206:207]
;     __device__ __forceinline__ float* out() const { return (float*)karg_in(33); }
; __device__ __forceinline__ void st4_bf16(bf16* p, v4f o) { v2u w; w.x = cvt_pk_nv(o.x, o.y); w.y = cvt_pk_nv(o.z, o.w); *(v2u*)p = w; }
; __device__ __forceinline__ float ssq4(v4f v) { return (v.x * v.x + v.y * v.y) + (v.z * v.z + v.w * v.w); }
; template <int R, bool BASE_F32, bool OUT_F32>
; __device__ __forceinline__ void rows_res(const Ctx& C, int m0, int stride, int mx, const float* gpost, float scale, int lane) {
;     ...
;         for (int r = 0; r < R; ++r) d[r][j] = b[r][j] + d[r][j] * r1[r] * gp; }
;     if (OUT_F32) { float* Y = C.out();
; #pragma unroll
;         for (int r = 0; r < R; ++r)
; #pragma unroll
;             for (int j = 0; j < 4; ++j) if (ok[r]) *(v4f*)(Y + (size_t)mr[r] * DM + 4 * lane + 256 * j) = d[r][j];
;     } else { float* rs = C.RS(); float t[R];
; #pragma unroll
;         for (int r = 0; r < R; ++r) { float s = 0.f;
; #pragma unroll
;             for (int j = 0; j < 4; ++j) s += ssq4(d[r][j]);
;             t[r] = s; }
; #pragma unroll
;         for (int r = 0; r < R; ++r) t[r] = wave_sum(t[r]) * (1.f / DM) + EPS;
; #pragma unroll
;         for (int r = 0; r < R; ++r) { const float rstd = rsqrtf(t[r]);
; #pragma unroll
;             for (int j = 0; j < 4; ++j) if (ok[r]) st4_bf16(XN + (size_t)mr[r] * DM + 4 * lane + 256 * j, d[r][j] * rstd);
;             if (lane == 0 && ok[r]) rs[mr[r]] = sqrtf(t[r]); }
	v_lshlrev_b32_e32 v28, 16, v44
	v_and_b32_e32 v29, 0xffff0000, v44
	v_lshlrev_b32_e32 v30, 16, v45
	v_and_b32_e32 v31, 0xffff0000, v45
	v_lshlrev_b32_e32 v32, 16, v46
	v_and_b32_e32 v33, 0xffff0000, v46
	v_lshlrev_b32_e32 v34, 16, v47
	v_and_b32_e32 v35, 0xffff0000, v47
	v_pk_fma_f32 v[112:113], v[54:55], v[28:29], v[112:113] op_sel_hi:[0,1,1]
	v_pk_fma_f32 v[114:115], v[54:55], v[30:31], v[114:115] op_sel_hi:[0,1,1]
	v_pk_fma_f32 v[116:117], v[54:55], v[32:33], v[116:117] op_sel_hi:[0,1,1]
	v_pk_fma_f32 v[118:119], v[54:55], v[34:35], v[118:119] op_sel_hi:[0,1,1]
	v_lshlrev_b32_e32 v28, 16, v48
	v_and_b32_e32 v29, 0xffff0000, v48
	v_lshlrev_b32_e32 v30, 16, v49
	v_and_b32_e32 v31, 0xffff0000, v49
	v_lshlrev_b32_e32 v32, 16, v50
	v_and_b32_e32 v33, 0xffff0000, v50
	v_lshlrev_b32_e32 v34, 16, v51
	v_and_b32_e32 v35, 0xffff0000, v51
	v_pk_fma_f32 v[120:121], v[54:55], v[28:29], v[120:121] op_sel_hi:[0,1,1]
	v_pk_fma_f32 v[122:123], v[54:55], v[30:31], v[122:123] op_sel_hi:[0,1,1]
	v_pk_fma_f32 v[124:125], v[54:55], v[32:33], v[124:125] op_sel_hi:[0,1,1]
	v_pk_fma_f32 v[126:127], v[54:55], v[34:35], v[126:127] op_sel_hi:[0,1,1]
	v_pk_mul_f32 v[134:135], v[112:113], v[112:113]
	v_pk_fma_f32 v[134:135], v[114:115], v[114:115], v[134:135]
	v_pk_fma_f32 v[134:135], v[116:117], v[116:117], v[134:135]
	v_pk_fma_f32 v[134:135], v[118:119], v[118:119], v[134:135]
	v_pk_fma_f32 v[134:135], v[120:121], v[120:121], v[134:135]
	v_pk_fma_f32 v[134:135], v[122:123], v[122:123], v[134:135]
	v_pk_fma_f32 v[134:135], v[124:125], v[124:125], v[134:135]
	v_pk_fma_f32 v[134:135], v[126:127], v[126:127], v[134:135]
	s_nop 0
	v_add_f32_e32 v134, v134, v135
	s_nop 1
	v_add_f32_dpp v132, v132, v132 quad_perm:[1,0,3,2] row_mask:0xf bank_mask:0xf
	v_add_f32_dpp v134, v134, v134 quad_perm:[1,0,3,2] row_mask:0xf bank_mask:0xf
	s_nop 0
	v_add_f32_dpp v132, v132, v132 quad_perm:[2,3,0,1] row_mask:0xf bank_mask:0xf
	v_add_f32_dpp v134, v134, v134 quad_perm:[2,3,0,1] row_mask:0xf bank_mask:0xf
	s_nop 0
	v_add_f32_dpp v132, v132, v132 row_half_mirror row_mask:0xf bank_mask:0xf
	v_add_f32_dpp v134, v134, v134 row_half_mirror row_mask:0xf bank_mask:0xf
	s_nop 0
	v_add_f32_dpp v132, v132, v132 row_mirror row_mask:0xf bank_mask:0xf
	v_add_f32_dpp v134, v134, v134 row_mirror row_mask:0xf bank_mask:0xf
	s_nop 0
	ds_bpermute_b32 v136, v187, v132
	ds_bpermute_b32 v137, v187, v134
	s_waitcnt lgkmcnt(0)
	v_add_f32_e32 v132, v132, v136
	v_add_f32_e32 v134, v134, v137
	ds_bpermute_b32 v136, v188, v132
	ds_bpermute_b32 v137, v188, v134
	s_waitcnt lgkmcnt(0)
	v_add_f32_e32 v132, v132, v136
	v_add_f32_e32 v134, v134, v137
	v_fmamk_f32 v164, v132, 0x3a800000, v138
	v_fmamk_f32 v167, v134, 0x3a800000, v138
	s_nop 0
	v_rsq_f32_e32 v132, v164
	v_rsq_f32_e32 v134, v167
	v_sqrt_f32_e32 v165, v164
	v_sqrt_f32_e32 v168, v167
	s_nop 1
	v_pk_mul_f32 v[140:141], v[96:97], v[132:133] op_sel_hi:[1,0]
	v_cvt_pk_bf16_f32 v148, v140, v141
	v_pk_mul_f32 v[142:143], v[98:99], v[132:133] op_sel_hi:[1,0]
	v_cvt_pk_bf16_f32 v149, v142, v143
	v_pk_mul_f32 v[144:145], v[100:101], v[132:133] op_sel_hi:[1,0]
	v_cvt_pk_bf16_f32 v150, v144, v145
	v_pk_mul_f32 v[146:147], v[102:103], v[132:133] op_sel_hi:[1,0]
	v_cvt_pk_bf16_f32 v151, v146, v147
	v_pk_mul_f32 v[140:141], v[104:105], v[132:133] op_sel_hi:[1,0]
	v_cvt_pk_bf16_f32 v152, v140, v141
	v_pk_mul_f32 v[142:143], v[106:107], v[132:133] op_sel_hi:[1,0]
	v_cvt_pk_bf16_f32 v153, v142, v143
	v_pk_mul_f32 v[144:145], v[108:109], v[132:133] op_sel_hi:[1,0]
	v_cvt_pk_bf16_f32 v154, v144, v145
	v_pk_mul_f32 v[146:147], v[110:111], v[132:133] op_sel_hi:[1,0]
	v_cvt_pk_bf16_f32 v155, v146, v147
	global_store_dwordx2 v173, v[148:149], s[98:99]
	global_store_dwordx2 v173, v[150:151], s[98:99] offset:512
	global_store_dwordx2 v173, v[152:153], s[98:99] offset:1024
	global_store_dwordx2 v173, v[154:155], s[98:99] offset:1536
	v_add_u32_e32 v173, 0xffc00000, v173
	v_pk_mul_f32 v[140:141], v[112:113], v[134:135] op_sel_hi:[1,0]
	v_cvt_pk_bf16_f32 v156, v140, v141
	v_pk_mul_f32 v[142:143], v[114:115], v[134:135] op_sel_hi:[1,0]
	v_cvt_pk_bf16_f32 v157, v142, v143
	v_pk_mul_f32 v[144:145], v[116:117], v[134:135] op_sel_hi:[1,0]
	v_cvt_pk_bf16_f32 v158, v144, v145
	v_pk_mul_f32 v[146:147], v[118:119], v[134:135] op_sel_hi:[1,0]
	v_cvt_pk_bf16_f32 v159, v146, v147
	v_pk_mul_f32 v[140:141], v[120:121], v[134:135] op_sel_hi:[1,0]
	v_cvt_pk_bf16_f32 v160, v140, v141
	v_pk_mul_f32 v[142:143], v[122:123], v[134:135] op_sel_hi:[1,0]
	v_cvt_pk_bf16_f32 v161, v142, v143
	v_pk_mul_f32 v[144:145], v[124:125], v[134:135] op_sel_hi:[1,0]
	v_cvt_pk_bf16_f32 v162, v144, v145
	v_pk_mul_f32 v[146:147], v[126:127], v[134:135] op_sel_hi:[1,0]
	v_cvt_pk_bf16_f32 v163, v146, v147
	global_store_dwordx2 v173, v[156:157], s[98:99]
	global_store_dwordx2 v173, v[158:159], s[98:99] offset:512
	global_store_dwordx2 v173, v[160:161], s[98:99] offset:1024
	global_store_dwordx2 v173, v[162:163], s[98:99] offset:1536
	v_add_u32_e32 v173, 0xffc00000, v173
	v_add_u32_e32 v166, -1, v165
	v_fma_f32 v140, -v166, v165, v164
	v_cmp_ge_f32_e32 vcc, 0, v140
	v_add_u32_e32 v141, 1, v165
	v_cndmask_b32_e32 v166, v165, v166, vcc
	v_fma_f32 v140, -v141, v165, v164
	v_cmp_lt_f32_e32 vcc, 0, v140
	s_nop 1
	v_cndmask_b32_e32 v165, v166, v141, vcc
	v_add_u32_e32 v169, -1, v168
	v_fma_f32 v142, -v169, v168, v167
	v_cmp_ge_f32_e32 vcc, 0, v142
	v_add_u32_e32 v143, 1, v168
	v_cndmask_b32_e32 v169, v168, v169, vcc
	v_fma_f32 v142, -v143, v168, v167
	v_cmp_lt_f32_e32 vcc, 0, v142
	s_nop 1
	v_cndmask_b32_e32 v168, v169, v143, vcc
	s_mov_b64 exec, 1
	global_store_dword v174, v165, s[98:99]
	v_add_u32_e32 v174, 0xffffe000, v174
	global_store_dword v174, v168, s[98:99]
	v_add_u32_e32 v174, 0xffffe000, v174
	s_mov_b64 exec, -1
	global_load_dword v52, v172, s[98:99]
	global_load_dwordx2 v[20:21], v170, s[98:99]
	global_load_dwordx2 v[22:23], v170, s[98:99] offset:512
	global_load_dwordx2 v[24:25], v170, s[98:99] offset:1024
	global_load_dwordx2 v[26:27], v170, s[98:99] offset:1536
	global_load_dwordx2 v[36:37], v171, s[98:99]
	global_load_dwordx2 v[38:39], v171, s[98:99] offset:512
	global_load_dwordx2 v[40:41], v171, s[98:99] offset:1024
	global_load_dwordx2 v[42:43], v171, s[98:99] offset:1536
	v_add_u32_e32 v170, 0xffc00000, v170
	v_add_u32_e32 v171, 0xffc00000, v171
	v_add_u32_e32 v172, 0xffffe000, v172
	global_load_dword v54, v172, s[98:99]
	global_load_dwordx2 v[28:29], v170, s[98:99]
	global_load_dwordx2 v[30:31], v170, s[98:99] offset:512
	global_load_dwordx2 v[32:33], v170, s[98:99] offset:1024
	global_load_dwordx2 v[34:35], v170, s[98:99] offset:1536
	global_load_dwordx2 v[44:45], v171, s[98:99]
	global_load_dwordx2 v[46:47], v171, s[98:99] offset:512
	global_load_dwordx2 v[48:49], v171, s[98:99] offset:1024
	global_load_dwordx2 v[50:51], v171, s[98:99] offset:1536
	v_add_u32_e32 v170, 0xffc00000, v170
	v_add_u32_e32 v171, 0xffc00000, v171
	v_add_u32_e32 v172, 0xffffe000, v172
	s_waitcnt vmcnt(41)
; __device__ __forceinline__ float ssq4(v4f v) { return (v.x * v.x + v.y * v.y) + (v.z * v.z + v.w * v.w); }
; template <int R, bool BASE_F32, bool OUT_F32>
; __device__ __forceinline__ void rows_res(const Ctx& C, int m0, int stride, int mx, const float* gpost, float scale, int lane) {
;     ...
;     for (int r = 0; r < R; ++r) { float s = 0.f;
; #pragma unroll
;         for (int j = 0; j < 4; ++j) s += ssq4(d[r][j]);
;         r1[r] = s; }
; #pragma unroll
;     for (int r = 0; r < R; ++r) r1[r] = rsqrtf(wave_sum(r1[r]) * (1.f / DM) + EPS) * scale;
; #pragma unroll
;     for (int j = 0; j < 4; ++j) { const v4f gp = ld4_f32(gpost + 4 * lane + 256 * j);
; #pragma unroll
;         for (int r = 0; r < R; ++r) d[r][j] = b[r][j] + d[r][j] * r1[r] * gp; }
	v_lshlrev_b32_e32 v96, 16, v56
	v_and_b32_e32 v97, 0xffff0000, v56
	v_lshlrev_b32_e32 v98, 16, v57
	v_and_b32_e32 v99, 0xffff0000, v57
	v_lshlrev_b32_e32 v100, 16, v58
	v_and_b32_e32 v101, 0xffff0000, v58
	v_lshlrev_b32_e32 v102, 16, v59
	v_and_b32_e32 v103, 0xffff0000, v59
	v_lshlrev_b32_e32 v104, 16, v60
	v_and_b32_e32 v105, 0xffff0000, v60
	v_lshlrev_b32_e32 v106, 16, v61
	v_and_b32_e32 v107, 0xffff0000, v61
	v_lshlrev_b32_e32 v108, 16, v62
	v_and_b32_e32 v109, 0xffff0000, v62
	v_lshlrev_b32_e32 v110, 16, v63
	v_and_b32_e32 v111, 0xffff0000, v63
	v_pk_mul_f32 v[128:129], v[96:97], v[96:97]
	v_pk_fma_f32 v[128:129], v[98:99], v[98:99], v[128:129]
	v_pk_fma_f32 v[128:129], v[100:101], v[100:101], v[128:129]
	v_pk_fma_f32 v[128:129], v[102:103], v[102:103], v[128:129]
	v_pk_fma_f32 v[128:129], v[104:105], v[104:105], v[128:129]
	v_pk_fma_f32 v[128:129], v[106:107], v[106:107], v[128:129]
	v_pk_fma_f32 v[128:129], v[108:109], v[108:109], v[128:129]
	v_pk_fma_f32 v[128:129], v[110:111], v[110:111], v[128:129]
	s_nop 0
	v_add_f32_e32 v128, v128, v129
	s_waitcnt vmcnt(32)
	v_lshlrev_b32_e32 v112, 16, v64
	v_and_b32_e32 v113, 0xffff0000, v64
	v_lshlrev_b32_e32 v114, 16, v65
	v_and_b32_e32 v115, 0xffff0000, v65
	v_lshlrev_b32_e32 v116, 16, v66
	v_and_b32_e32 v117, 0xffff0000, v66
	v_lshlrev_b32_e32 v118, 16, v67
	v_and_b32_e32 v119, 0xffff0000, v67
	v_lshlrev_b32_e32 v120, 16, v68
	v_and_b32_e32 v121, 0xffff0000, v68
	v_lshlrev_b32_e32 v122, 16, v69
	v_and_b32_e32 v123, 0xffff0000, v69
	v_lshlrev_b32_e32 v124, 16, v70
	v_and_b32_e32 v125, 0xffff0000, v70
	v_lshlrev_b32_e32 v126, 16, v71
	v_and_b32_e32 v127, 0xffff0000, v71
	v_pk_mul_f32 v[130:131], v[112:113], v[112:113]
	v_pk_fma_f32 v[130:131], v[114:115], v[114:115], v[130:131]
	v_pk_fma_f32 v[130:131], v[116:117], v[116:117], v[130:131]
	v_pk_fma_f32 v[130:131], v[118:119], v[118:119], v[130:131]
	v_pk_fma_f32 v[130:131], v[120:121], v[120:121], v[130:131]
	v_pk_fma_f32 v[130:131], v[122:123], v[122:123], v[130:131]
	v_pk_fma_f32 v[130:131], v[124:125], v[124:125], v[130:131]
	v_pk_fma_f32 v[130:131], v[126:127], v[126:127], v[130:131]
	s_nop 0
	v_add_f32_e32 v130, v130, v131
	s_nop 1
	v_add_f32_dpp v128, v128, v128 quad_perm:[1,0,3,2] row_mask:0xf bank_mask:0xf
	v_add_f32_dpp v130, v130, v130 quad_perm:[1,0,3,2] row_mask:0xf bank_mask:0xf
	s_nop 0
	v_add_f32_dpp v128, v128, v128 quad_perm:[2,3,0,1] row_mask:0xf bank_mask:0xf
	v_add_f32_dpp v130, v130, v130 quad_perm:[2,3,0,1] row_mask:0xf bank_mask:0xf
	s_nop 0
	v_add_f32_dpp v128, v128, v128 row_half_mirror row_mask:0xf bank_mask:0xf
	v_add_f32_dpp v130, v130, v130 row_half_mirror row_mask:0xf bank_mask:0xf
	s_nop 0
	v_add_f32_dpp v128, v128, v128 row_mirror row_mask:0xf bank_mask:0xf
	v_add_f32_dpp v130, v130, v130 row_mirror row_mask:0xf bank_mask:0xf
	s_nop 0
	ds_bpermute_b32 v136, v187, v128
	ds_bpermute_b32 v137, v187, v130
	s_waitcnt lgkmcnt(0)
	v_add_f32_e32 v128, v128, v136
	v_add_f32_e32 v130, v130, v137
	ds_bpermute_b32 v136, v188, v128
	ds_bpermute_b32 v137, v188, v130
	s_waitcnt lgkmcnt(0)
	v_add_f32_e32 v128, v128, v136
	v_add_f32_e32 v130, v130, v137
	v_fmamk_f32 v128, v128, 0x3a800000, v138
	v_fmamk_f32 v130, v130, 0x3a800000, v138
	s_nop 0
	v_rsq_f32_e32 v128, v128
	v_rsq_f32_e32 v130, v130
	s_nop 1
	s_waitcnt vmcnt(28)
	v_pk_mul_f32 v[96:97], v[128:129], v[96:97] op_sel_hi:[0,1]
	v_pk_mul_f32 v[98:99], v[128:129], v[98:99] op_sel_hi:[0,1]
	v_pk_mul_f32 v[100:101], v[128:129], v[100:101] op_sel_hi:[0,1]
	v_pk_mul_f32 v[102:103], v[128:129], v[102:103] op_sel_hi:[0,1]
	v_pk_mul_f32 v[104:105], v[128:129], v[104:105] op_sel_hi:[0,1]
	v_pk_mul_f32 v[106:107], v[128:129], v[106:107] op_sel_hi:[0,1]
	v_pk_mul_f32 v[108:109], v[128:129], v[108:109] op_sel_hi:[0,1]
	v_pk_mul_f32 v[110:111], v[128:129], v[110:111] op_sel_hi:[0,1]
	v_pk_mul_f32 v[96:97], v[96:97], v[192:193]
	v_pk_mul_f32 v[98:99], v[98:99], v[194:195]
	v_pk_mul_f32 v[100:101], v[100:101], v[196:197]
	v_pk_mul_f32 v[102:103], v[102:103], v[198:199]
	v_pk_mul_f32 v[104:105], v[104:105], v[200:201]
	v_pk_mul_f32 v[106:107], v[106:107], v[202:203]
	v_pk_mul_f32 v[108:109], v[108:109], v[204:205]
	v_pk_mul_f32 v[110:111], v[110:111], v[206:207]
	v_lshlrev_b32_e32 v56, 16, v72
	v_and_b32_e32 v57, 0xffff0000, v72
	v_lshlrev_b32_e32 v58, 16, v73
	v_and_b32_e32 v59, 0xffff0000, v73
	v_lshlrev_b32_e32 v60, 16, v74
	v_and_b32_e32 v61, 0xffff0000, v74
	v_lshlrev_b32_e32 v62, 16, v75
	v_and_b32_e32 v63, 0xffff0000, v75
	v_pk_fma_f32 v[96:97], v[88:89], v[56:57], v[96:97] op_sel_hi:[0,1,1]
	v_pk_fma_f32 v[98:99], v[88:89], v[58:59], v[98:99] op_sel_hi:[0,1,1]
	v_pk_fma_f32 v[100:101], v[88:89], v[60:61], v[100:101] op_sel_hi:[0,1,1]
	v_pk_fma_f32 v[102:103], v[88:89], v[62:63], v[102:103] op_sel_hi:[0,1,1]
	v_lshlrev_b32_e32 v56, 16, v76
	v_and_b32_e32 v57, 0xffff0000, v76
	v_lshlrev_b32_e32 v58, 16, v77
	v_and_b32_e32 v59, 0xffff0000, v77
	v_lshlrev_b32_e32 v60, 16, v78
	v_and_b32_e32 v61, 0xffff0000, v78
	v_lshlrev_b32_e32 v62, 16, v79
	v_and_b32_e32 v63, 0xffff0000, v79
	v_pk_fma_f32 v[104:105], v[88:89], v[56:57], v[104:105] op_sel_hi:[0,1,1]
	v_pk_fma_f32 v[106:107], v[88:89], v[58:59], v[106:107] op_sel_hi:[0,1,1]
	v_pk_fma_f32 v[108:109], v[88:89], v[60:61], v[108:109] op_sel_hi:[0,1,1]
	v_pk_fma_f32 v[110:111], v[88:89], v[62:63], v[110:111] op_sel_hi:[0,1,1]
	v_pk_mul_f32 v[132:133], v[96:97], v[96:97]
	v_pk_fma_f32 v[132:133], v[98:99], v[98:99], v[132:133]
	v_pk_fma_f32 v[132:133], v[100:101], v[100:101], v[132:133]
	v_pk_fma_f32 v[132:133], v[102:103], v[102:103], v[132:133]
	v_pk_fma_f32 v[132:133], v[104:105], v[104:105], v[132:133]
; __device__ __forceinline__ void st4_bf16(bf16* p, v4f o) { v2u w; w.x = cvt_pk_nv(o.x, o.y); w.y = cvt_pk_nv(o.z, o.w); *(v2u*)p = w; }
; __device__ __forceinline__ float ssq4(v4f v) { return (v.x * v.x + v.y * v.y) + (v.z * v.z + v.w * v.w); }
; template <int R, bool BASE_F32, bool OUT_F32>
; __device__ __forceinline__ void rows_res(const Ctx& C, int m0, int stride, int mx, const float* gpost, float scale, int lane) {
;     ...
;     } else { float* rs = C.RS(); float t[R];
; #pragma unroll
;         for (int r = 0; r < R; ++r) { float s = 0.f;
; #pragma unroll
;             for (int j = 0; j < 4; ++j) s += ssq4(d[r][j]);
;             t[r] = s; }
; #pragma unroll
;         for (int r = 0; r < R; ++r) t[r] = wave_sum(t[r]) * (1.f / DM) + EPS;
; #pragma unroll
;         for (int r = 0; r < R; ++r) { const float rstd = rsqrtf(t[r]);
; #pragma unroll
;             for (int j = 0; j < 4; ++j) if (ok[r]) st4_bf16(XN + (size_t)mr[r] * DM + 4 * lane + 256 * j, d[r][j] * rstd);
;             if (lane == 0 && ok[r]) rs[mr[r]] = sqrtf(t[r]); }
	v_pk_fma_f32 v[132:133], v[106:107], v[106:107], v[132:133]
	v_pk_fma_f32 v[132:133], v[108:109], v[108:109], v[132:133]
	v_pk_fma_f32 v[132:133], v[110:111], v[110:111], v[132:133]
	s_nop 0
	v_add_f32_e32 v132, v132, v133
	v_pk_mul_f32 v[112:113], v[130:131], v[112:113] op_sel_hi:[0,1]
	v_pk_mul_f32 v[114:115], v[130:131], v[114:115] op_sel_hi:[0,1]
	v_pk_mul_f32 v[116:117], v[130:131], v[116:117] op_sel_hi:[0,1]
	v_pk_mul_f32 v[118:119], v[130:131], v[118:119] op_sel_hi:[0,1]
	v_pk_mul_f32 v[120:121], v[130:131], v[120:121] op_sel_hi:[0,1]
	v_pk_mul_f32 v[122:123], v[130:131], v[122:123] op_sel_hi:[0,1]
	v_pk_mul_f32 v[124:125], v[130:131], v[124:125] op_sel_hi:[0,1]
	v_pk_mul_f32 v[126:127], v[130:131], v[126:127] op_sel_hi:[0,1]
	v_pk_mul_f32 v[112:113], v[112:113], v[192:193]
	v_pk_mul_f32 v[114:115], v[114:115], v[194:195]
	v_pk_mul_f32 v[116:117], v[116:117], v[196:197]
	v_pk_mul_f32 v[118:119], v[118:119], v[198:199]
	v_pk_mul_f32 v[120:121], v[120:121], v[200:201]
	v_pk_mul_f32 v[122:123], v[122:123], v[202:203]
	v_pk_mul_f32 v[124:125], v[124:125], v[204:205]
	v_pk_mul_f32 v[126:127], v[126:127], v[206:207]
	v_lshlrev_b32_e32 v64, 16, v80
	v_and_b32_e32 v65, 0xffff0000, v80
	v_lshlrev_b32_e32 v66, 16, v81
	v_and_b32_e32 v67, 0xffff0000, v81
	v_lshlrev_b32_e32 v68, 16, v82
	v_and_b32_e32 v69, 0xffff0000, v82
	v_lshlrev_b32_e32 v70, 16, v83
	v_and_b32_e32 v71, 0xffff0000, v83
	v_pk_fma_f32 v[112:113], v[90:91], v[64:65], v[112:113] op_sel_hi:[0,1,1]
	v_pk_fma_f32 v[114:115], v[90:91], v[66:67], v[114:115] op_sel_hi:[0,1,1]
	v_pk_fma_f32 v[116:117], v[90:91], v[68:69], v[116:117] op_sel_hi:[0,1,1]
	v_pk_fma_f32 v[118:119], v[90:91], v[70:71], v[118:119] op_sel_hi:[0,1,1]
	v_lshlrev_b32_e32 v64, 16, v84
	v_and_b32_e32 v65, 0xffff0000, v84
	v_lshlrev_b32_e32 v66, 16, v85
	v_and_b32_e32 v67, 0xffff0000, v85
	v_lshlrev_b32_e32 v68, 16, v86
	v_and_b32_e32 v69, 0xffff0000, v86
	v_lshlrev_b32_e32 v70, 16, v87
	v_and_b32_e32 v71, 0xffff0000, v87
	v_pk_fma_f32 v[120:121], v[90:91], v[64:65], v[120:121] op_sel_hi:[0,1,1]
	v_pk_fma_f32 v[122:123], v[90:91], v[66:67], v[122:123] op_sel_hi:[0,1,1]
	v_pk_fma_f32 v[124:125], v[90:91], v[68:69], v[124:125] op_sel_hi:[0,1,1]
	v_pk_fma_f32 v[126:127], v[90:91], v[70:71], v[126:127] op_sel_hi:[0,1,1]
	v_pk_mul_f32 v[134:135], v[112:113], v[112:113]
	v_pk_fma_f32 v[134:135], v[114:115], v[114:115], v[134:135]
	v_pk_fma_f32 v[134:135], v[116:117], v[116:117], v[134:135]
	v_pk_fma_f32 v[134:135], v[118:119], v[118:119], v[134:135]
	v_pk_fma_f32 v[134:135], v[120:121], v[120:121], v[134:135]
	v_pk_fma_f32 v[134:135], v[122:123], v[122:123], v[134:135]
	v_pk_fma_f32 v[134:135], v[124:125], v[124:125], v[134:135]
	v_pk_fma_f32 v[134:135], v[126:127], v[126:127], v[134:135]
	s_nop 0
	v_add_f32_e32 v134, v134, v135
	s_nop 1
	v_add_f32_dpp v132, v132, v132 quad_perm:[1,0,3,2] row_mask:0xf bank_mask:0xf
	v_add_f32_dpp v134, v134, v134 quad_perm:[1,0,3,2] row_mask:0xf bank_mask:0xf
	s_nop 0
	v_add_f32_dpp v132, v132, v132 quad_perm:[2,3,0,1] row_mask:0xf bank_mask:0xf
	v_add_f32_dpp v134, v134, v134 quad_perm:[2,3,0,1] row_mask:0xf bank_mask:0xf
	s_nop 0
	v_add_f32_dpp v132, v132, v132 row_half_mirror row_mask:0xf bank_mask:0xf
	v_add_f32_dpp v134, v134, v134 row_half_mirror row_mask:0xf bank_mask:0xf
	s_nop 0
	v_add_f32_dpp v132, v132, v132 row_mirror row_mask:0xf bank_mask:0xf
	v_add_f32_dpp v134, v134, v134 row_mirror row_mask:0xf bank_mask:0xf
	s_nop 0
	ds_bpermute_b32 v136, v187, v132
	ds_bpermute_b32 v137, v187, v134
	s_waitcnt lgkmcnt(0)
	v_add_f32_e32 v132, v132, v136
	v_add_f32_e32 v134, v134, v137
	ds_bpermute_b32 v136, v188, v132
	ds_bpermute_b32 v137, v188, v134
	s_waitcnt lgkmcnt(0)
	v_add_f32_e32 v132, v132, v136
	v_add_f32_e32 v134, v134, v137
	v_fmamk_f32 v164, v132, 0x3a800000, v138
	v_fmamk_f32 v167, v134, 0x3a800000, v138
	s_nop 0
	v_rsq_f32_e32 v132, v164
	v_rsq_f32_e32 v134, v167
	v_sqrt_f32_e32 v165, v164
	v_sqrt_f32_e32 v168, v167
	s_nop 1
	v_pk_mul_f32 v[140:141], v[96:97], v[132:133] op_sel_hi:[1,0]
	v_cvt_pk_bf16_f32 v148, v140, v141
	v_pk_mul_f32 v[142:143], v[98:99], v[132:133] op_sel_hi:[1,0]
	v_cvt_pk_bf16_f32 v149, v142, v143
	v_pk_mul_f32 v[144:145], v[100:101], v[132:133] op_sel_hi:[1,0]
	v_cvt_pk_bf16_f32 v150, v144, v145
	v_pk_mul_f32 v[146:147], v[102:103], v[132:133] op_sel_hi:[1,0]
	v_cvt_pk_bf16_f32 v151, v146, v147
	v_pk_mul_f32 v[140:141], v[104:105], v[132:133] op_sel_hi:[1,0]
	v_cvt_pk_bf16_f32 v152, v140, v141
	v_pk_mul_f32 v[142:143], v[106:107], v[132:133] op_sel_hi:[1,0]
	v_cvt_pk_bf16_f32 v153, v142, v143
	v_pk_mul_f32 v[144:145], v[108:109], v[132:133] op_sel_hi:[1,0]
	v_cvt_pk_bf16_f32 v154, v144, v145
	v_pk_mul_f32 v[146:147], v[110:111], v[132:133] op_sel_hi:[1,0]
	v_cvt_pk_bf16_f32 v155, v146, v147
	global_store_dwordx2 v173, v[148:149], s[98:99]
	global_store_dwordx2 v173, v[150:151], s[98:99] offset:512
	global_store_dwordx2 v173, v[152:153], s[98:99] offset:1024
	global_store_dwordx2 v173, v[154:155], s[98:99] offset:1536
	v_add_u32_e32 v173, 0xffc00000, v173
	v_pk_mul_f32 v[140:141], v[112:113], v[134:135] op_sel_hi:[1,0]
	v_cvt_pk_bf16_f32 v156, v140, v141
	v_pk_mul_f32 v[142:143], v[114:115], v[134:135] op_sel_hi:[1,0]
	v_cvt_pk_bf16_f32 v157, v142, v143
	v_pk_mul_f32 v[144:145], v[116:117], v[134:135] op_sel_hi:[1,0]
	v_cvt_pk_bf16_f32 v158, v144, v145
	v_pk_mul_f32 v[146:147], v[118:119], v[134:135] op_sel_hi:[1,0]
	v_cvt_pk_bf16_f32 v159, v146, v147
	v_pk_mul_f32 v[140:141], v[120:121], v[134:135] op_sel_hi:[1,0]
	v_cvt_pk_bf16_f32 v160, v140, v141
	v_pk_mul_f32 v[142:143], v[122:123], v[134:135] op_sel_hi:[1,0]
	v_cvt_pk_bf16_f32 v161, v142, v143
; __device__ __forceinline__ const float* xrow_ptr(const Ctx& C, int row) { return row < MPROMPT ? C.in(0) + (size_t)row * DM : C.in(1) + (size_t)(row - MPROMPT) * DM; }
; __device__ __forceinline__ v4f ld4_bf16(const bf16* p) { const v2u w = *(const v2u*)p; return (v4f){bf_lo(w.x), bf_hi(w.x), bf_lo(w.y), bf_hi(w.y)}; }
; __device__ __forceinline__ void st4_bf16(bf16* p, v4f o) { v2u w; w.x = cvt_pk_nv(o.x, o.y); w.y = cvt_pk_nv(o.z, o.w); *(v2u*)p = w; }
; __device__ __forceinline__ float ssq4(v4f v) { return (v.x * v.x + v.y * v.y) + (v.z * v.z + v.w * v.w); }
; template <int R, bool BASE_F32, bool OUT_F32>
; __device__ __forceinline__ void rows_res(const Ctx& C, int m0, int stride, int mx, const float* gpost, float scale, int lane) {
;     ...
;     for (int r = 0; r < R; ++r) { mr[r] = (r == 4) ? mx : m0 + r * stride; ok[r] = (r == 4) ? (mx < M) : (mr[r] < MPROMPT); const int mm = ok[r] ? mr[r] : 0;
; #pragma unroll
;         for (int j = 0; j < 4; ++j) d[r][j] = ld4_bf16(D + (size_t)mm * DM + 4 * lane + 256 * j);
;         if (BASE_F32) { const float* x = xrow_ptr(C, mm);
; #pragma unroll
;             for (int j = 0; j < 4; ++j) b[r][j] = ld4_f32(x + 4 * lane + 256 * j);
;         } else { const float inv = C.RS()[mm];
; #pragma unroll
;             for (int j = 0; j < 4; ++j) b[r][j] = ld4_bf16(XN + (size_t)mm * DM + 4 * lane + 256 * j) * inv;
;         } }
; #pragma unroll
;     for (int r = 0; r < R; ++r) { float s = 0.f;
; #pragma unroll
;         for (int j = 0; j < 4; ++j) s += ssq4(d[r][j]);
;         r1[r] = s; }
; #pragma unroll
;     for (int r = 0; r < R; ++r) r1[r] = rsqrtf(wave_sum(r1[r]) * (1.f / DM) + EPS) * scale;
;     ...
;     } else { float* rs = C.RS(); float t[R];
; #pragma unroll
;         for (int r = 0; r < R; ++r) { float s = 0.f;
; #pragma unroll
;             for (int j = 0; j < 4; ++j) s += ssq4(d[r][j]);
;             t[r] = s; }
; #pragma unroll
;         for (int r = 0; r < R; ++r) t[r] = wave_sum(t[r]) * (1.f / DM) + EPS;
; #pragma unroll
;         for (int r = 0; r < R; ++r) { const float rstd = rsqrtf(t[r]);
; #pragma unroll
;             for (int j = 0; j < 4; ++j) if (ok[r]) st4_bf16(XN + (size_t)mr[r] * DM + 4 * lane + 256 * j, d[r][j] * rstd);
;             if (lane == 0 && ok[r]) rs[mr[r]] = sqrtf(t[r]); }
	v_pk_mul_f32 v[144:145], v[124:125], v[134:135] op_sel_hi:[1,0]
	v_cvt_pk_bf16_f32 v162, v144, v145
	v_pk_mul_f32 v[146:147], v[126:127], v[134:135] op_sel_hi:[1,0]
	v_cvt_pk_bf16_f32 v163, v146, v147
	global_store_dwordx2 v173, v[156:157], s[98:99]
	global_store_dwordx2 v173, v[158:159], s[98:99] offset:512
	global_store_dwordx2 v173, v[160:161], s[98:99] offset:1024
	global_store_dwordx2 v173, v[162:163], s[98:99] offset:1536
	v_add_u32_e32 v173, 0xffc00000, v173
	v_add_u32_e32 v166, -1, v165
	v_fma_f32 v140, -v166, v165, v164
	v_cmp_ge_f32_e32 vcc, 0, v140
	v_add_u32_e32 v141, 1, v165
	v_cndmask_b32_e32 v166, v165, v166, vcc
	v_fma_f32 v140, -v141, v165, v164
	v_cmp_lt_f32_e32 vcc, 0, v140
	s_nop 1
	v_cndmask_b32_e32 v165, v166, v141, vcc
	v_add_u32_e32 v169, -1, v168
	v_fma_f32 v142, -v169, v168, v167
	v_cmp_ge_f32_e32 vcc, 0, v142
	v_add_u32_e32 v143, 1, v168
	v_cndmask_b32_e32 v169, v168, v169, vcc
	v_fma_f32 v142, -v143, v168, v167
	v_cmp_lt_f32_e32 vcc, 0, v142
	s_nop 1
	v_cndmask_b32_e32 v168, v169, v143, vcc
	s_mov_b64 exec, 1
	global_store_dword v174, v165, s[98:99]
	v_add_u32_e32 v174, 0xffffe000, v174
	global_store_dword v174, v168, s[98:99]
	v_add_u32_e32 v174, 0xffffe000, v174
	s_mov_b64 exec, -1
	global_load_dword v88, v172, s[98:99]
	global_load_dwordx2 v[56:57], v170, s[98:99]
	global_load_dwordx2 v[58:59], v170, s[98:99] offset:512
	global_load_dwordx2 v[60:61], v170, s[98:99] offset:1024
	global_load_dwordx2 v[62:63], v170, s[98:99] offset:1536
	global_load_dwordx2 v[72:73], v171, s[98:99]
	global_load_dwordx2 v[74:75], v171, s[98:99] offset:512
	global_load_dwordx2 v[76:77], v171, s[98:99] offset:1024
	global_load_dwordx2 v[78:79], v171, s[98:99] offset:1536
	v_add_u32_e32 v170, 0xffc00000, v170
	v_add_u32_e32 v171, 0xffc00000, v171
	v_add_u32_e32 v172, 0xffffe000, v172
	global_load_dword v90, v172, s[98:99]
	global_load_dwordx2 v[64:65], v170, s[98:99]
	global_load_dwordx2 v[66:67], v170, s[98:99] offset:512
	global_load_dwordx2 v[68:69], v170, s[98:99] offset:1024
	global_load_dwordx2 v[70:71], v170, s[98:99] offset:1536
	global_load_dwordx2 v[80:81], v171, s[98:99]
	global_load_dwordx2 v[82:83], v171, s[98:99] offset:512
	global_load_dwordx2 v[84:85], v171, s[98:99] offset:1024
	global_load_dwordx2 v[86:87], v171, s[98:99] offset:1536
	v_add_u32_e32 v170, 0xffc00000, v170
	v_add_u32_e32 v171, 0xffc00000, v171
	v_add_u32_e32 v172, 0xffffe000, v172
	s_waitcnt vmcnt(41)
	v_lshlrev_b32_e32 v96, 16, v20
	v_and_b32_e32 v97, 0xffff0000, v20
	v_lshlrev_b32_e32 v98, 16, v21
	v_and_b32_e32 v99, 0xffff0000, v21
	v_lshlrev_b32_e32 v100, 16, v22
	v_and_b32_e32 v101, 0xffff0000, v22
	v_lshlrev_b32_e32 v102, 16, v23
	v_and_b32_e32 v103, 0xffff0000, v23
	v_lshlrev_b32_e32 v104, 16, v24
	v_and_b32_e32 v105, 0xffff0000, v24
	v_lshlrev_b32_e32 v106, 16, v25
	v_and_b32_e32 v107, 0xffff0000, v25
	v_lshlrev_b32_e32 v108, 16, v26
	v_and_b32_e32 v109, 0xffff0000, v26
	v_lshlrev_b32_e32 v110, 16, v27
	v_and_b32_e32 v111, 0xffff0000, v27
	v_pk_mul_f32 v[128:129], v[96:97], v[96:97]
	v_pk_fma_f32 v[128:129], v[98:99], v[98:99], v[128:129]
	v_pk_fma_f32 v[128:129], v[100:101], v[100:101], v[128:129]
	v_pk_fma_f32 v[128:129], v[102:103], v[102:103], v[128:129]
	v_pk_fma_f32 v[128:129], v[104:105], v[104:105], v[128:129]
	v_pk_fma_f32 v[128:129], v[106:107], v[106:107], v[128:129]
	v_pk_fma_f32 v[128:129], v[108:109], v[108:109], v[128:129]
	v_pk_fma_f32 v[128:129], v[110:111], v[110:111], v[128:129]
	s_nop 0
	v_add_f32_e32 v128, v128, v129
	s_waitcnt vmcnt(32)
	v_lshlrev_b32_e32 v112, 16, v28
	v_and_b32_e32 v113, 0xffff0000, v28
	v_lshlrev_b32_e32 v114, 16, v29
	v_and_b32_e32 v115, 0xffff0000, v29
	v_lshlrev_b32_e32 v116, 16, v30
	v_and_b32_e32 v117, 0xffff0000, v30
	v_lshlrev_b32_e32 v118, 16, v31
	v_and_b32_e32 v119, 0xffff0000, v31
	v_lshlrev_b32_e32 v120, 16, v32
	v_and_b32_e32 v121, 0xffff0000, v32
	v_lshlrev_b32_e32 v122, 16, v33
	v_and_b32_e32 v123, 0xffff0000, v33
	v_lshlrev_b32_e32 v124, 16, v34
	v_and_b32_e32 v125, 0xffff0000, v34
	v_lshlrev_b32_e32 v126, 16, v35
	v_and_b32_e32 v127, 0xffff0000, v35
	v_pk_mul_f32 v[130:131], v[112:113], v[112:113]
	v_pk_fma_f32 v[130:131], v[114:115], v[114:115], v[130:131]
	v_pk_fma_f32 v[130:131], v[116:117], v[116:117], v[130:131]
	v_pk_fma_f32 v[130:131], v[118:119], v[118:119], v[130:131]
	v_pk_fma_f32 v[130:131], v[120:121], v[120:121], v[130:131]
	v_pk_fma_f32 v[130:131], v[122:123], v[122:123], v[130:131]
	v_pk_fma_f32 v[130:131], v[124:125], v[124:125], v[130:131]
	v_pk_fma_f32 v[130:131], v[126:127], v[126:127], v[130:131]
	s_nop 0
	v_add_f32_e32 v130, v130, v131
	s_nop 1
	v_add_f32_dpp v128, v128, v128 quad_perm:[1,0,3,2] row_mask:0xf bank_mask:0xf
	v_add_f32_dpp v130, v130, v130 quad_perm:[1,0,3,2] row_mask:0xf bank_mask:0xf
	s_nop 0
	v_add_f32_dpp v128, v128, v128 quad_perm:[2,3,0,1] row_mask:0xf bank_mask:0xf
	v_add_f32_dpp v130, v130, v130 quad_perm:[2,3,0,1] row_mask:0xf bank_mask:0xf
	s_nop 0
	v_add_f32_dpp v128, v128, v128 row_half_mirror row_mask:0xf bank_mask:0xf
	v_add_f32_dpp v130, v130, v130 row_half_mirror row_mask:0xf bank_mask:0xf
	s_nop 0
	v_add_f32_dpp v128, v128, v128 row_mirror row_mask:0xf bank_mask:0xf
	v_add_f32_dpp v130, v130, v130 row_mirror row_mask:0xf bank_mask:0xf
	s_nop 0
	ds_bpermute_b32 v136, v187, v128
	ds_bpermute_b32 v137, v187, v130
	s_waitcnt lgkmcnt(0)
	v_add_f32_e32 v128, v128, v136
	v_add_f32_e32 v130, v130, v137
	ds_bpermute_b32 v136, v188, v128
	ds_bpermute_b32 v137, v188, v130
	s_waitcnt lgkmcnt(0)
	v_add_f32_e32 v128, v128, v136
	v_add_f32_e32 v130, v130, v137
	v_fmamk_f32 v128, v128, 0x3a800000, v138
	v_fmamk_f32 v130, v130, 0x3a800000, v138
	s_nop 0
	v_rsq_f32_e32 v128, v128
	v_rsq_f32_e32 v130, v130
	s_nop 1
	s_waitcnt vmcnt(28)
;     __device__ __forceinline__ float* out() const { return (float*)karg_in(33); }
; __device__ __forceinline__ float ssq4(v4f v) { return (v.x * v.x + v.y * v.y) + (v.z * v.z + v.w * v.w); }
; template <int R, bool BASE_F32, bool OUT_F32>
; __device__ __forceinline__ void rows_res(const Ctx& C, int m0, int stride, int mx, const float* gpost, float scale, int lane) {
;     ...
;     for (int r = 0; r < R; ++r) r1[r] = rsqrtf(wave_sum(r1[r]) * (1.f / DM) + EPS) * scale;
; #pragma unroll
;     for (int j = 0; j < 4; ++j) { const v4f gp = ld4_f32(gpost + 4 * lane + 256 * j);
; #pragma unroll
;         for (int r = 0; r < R; ++r) d[r][j] = b[r][j] + d[r][j] * r1[r] * gp; }
;     if (OUT_F32) { float* Y = C.out();
; #pragma unroll
;         for (int r = 0; r < R; ++r)
; #pragma unroll
;             for (int j = 0; j < 4; ++j) if (ok[r]) *(v4f*)(Y + (size_t)mr[r] * DM + 4 * lane + 256 * j) = d[r][j];
;     } else { float* rs = C.RS(); float t[R];
; #pragma unroll
;         for (int r = 0; r < R; ++r) { float s = 0.f;
; #pragma unroll
;             for (int j = 0; j < 4; ++j) s += ssq4(d[r][j]);
;             t[r] = s; }
; #pragma unroll
;         for (int r = 0; r < R; ++r) t[r] = wave_sum(t[r]) * (1.f / DM) + EPS;
	v_pk_mul_f32 v[96:97], v[128:129], v[96:97] op_sel_hi:[0,1]
	v_pk_mul_f32 v[98:99], v[128:129], v[98:99] op_sel_hi:[0,1]
	v_pk_mul_f32 v[100:101], v[128:129], v[100:101] op_sel_hi:[0,1]
	v_pk_mul_f32 v[102:103], v[128:129], v[102:103] op_sel_hi:[0,1]
	v_pk_mul_f32 v[104:105], v[128:129], v[104:105] op_sel_hi:[0,1]
	v_pk_mul_f32 v[106:107], v[128:129], v[106:107] op_sel_hi:[0,1]
	v_pk_mul_f32 v[108:109], v[128:129], v[108:109] op_sel_hi:[0,1]
	v_pk_mul_f32 v[110:111], v[128:129], v[110:111] op_sel_hi:[0,1]
	v_pk_mul_f32 v[96:97], v[96:97], v[192:193]
	v_pk_mul_f32 v[98:99], v[98:99], v[194:195]
	v_pk_mul_f32 v[100:101], v[100:101], v[196:197]
	v_pk_mul_f32 v[102:103], v[102:103], v[198:199]
	v_pk_mul_f32 v[104:105], v[104:105], v[200:201]
	v_pk_mul_f32 v[106:107], v[106:107], v[202:203]
	v_pk_mul_f32 v[108:109], v[108:109], v[204:205]
	v_pk_mul_f32 v[110:111], v[110:111], v[206:207]
	v_lshlrev_b32_e32 v20, 16, v36
	v_and_b32_e32 v21, 0xffff0000, v36
	v_lshlrev_b32_e32 v22, 16, v37
	v_and_b32_e32 v23, 0xffff0000, v37
	v_lshlrev_b32_e32 v24, 16, v38
	v_and_b32_e32 v25, 0xffff0000, v38
	v_lshlrev_b32_e32 v26, 16, v39
	v_and_b32_e32 v27, 0xffff0000, v39
	v_pk_fma_f32 v[96:97], v[52:53], v[20:21], v[96:97] op_sel_hi:[0,1,1]
	v_pk_fma_f32 v[98:99], v[52:53], v[22:23], v[98:99] op_sel_hi:[0,1,1]
	v_pk_fma_f32 v[100:101], v[52:53], v[24:25], v[100:101] op_sel_hi:[0,1,1]
	v_pk_fma_f32 v[102:103], v[52:53], v[26:27], v[102:103] op_sel_hi:[0,1,1]
	v_lshlrev_b32_e32 v20, 16, v40
	v_and_b32_e32 v21, 0xffff0000, v40
	v_lshlrev_b32_e32 v22, 16, v41
	v_and_b32_e32 v23, 0xffff0000, v41
	v_lshlrev_b32_e32 v24, 16, v42
	v_and_b32_e32 v25, 0xffff0000, v42
	v_lshlrev_b32_e32 v26, 16, v43
	v_and_b32_e32 v27, 0xffff0000, v43
	v_pk_fma_f32 v[104:105], v[52:53], v[20:21], v[104:105] op_sel_hi:[0,1,1]
	v_pk_fma_f32 v[106:107], v[52:53], v[22:23], v[106:107] op_sel_hi:[0,1,1]
	v_pk_fma_f32 v[108:109], v[52:53], v[24:25], v[108:109] op_sel_hi:[0,1,1]
	v_pk_fma_f32 v[110:111], v[52:53], v[26:27], v[110:111] op_sel_hi:[0,1,1]
	v_pk_mul_f32 v[132:133], v[96:97], v[96:97]
	v_pk_fma_f32 v[132:133], v[98:99], v[98:99], v[132:133]
	v_pk_fma_f32 v[132:133], v[100:101], v[100:101], v[132:133]
	v_pk_fma_f32 v[132:133], v[102:103], v[102:103], v[132:133]
	v_pk_fma_f32 v[132:133], v[104:105], v[104:105], v[132:133]
	v_pk_fma_f32 v[132:133], v[106:107], v[106:107], v[132:133]
	v_pk_fma_f32 v[132:133], v[108:109], v[108:109], v[132:133]
	v_pk_fma_f32 v[132:133], v[110:111], v[110:111], v[132:133]
	s_nop 0
	v_add_f32_e32 v132, v132, v133
	v_pk_mul_f32 v[112:113], v[130:131], v[112:113] op_sel_hi:[0,1]
	v_pk_mul_f32 v[114:115], v[130:131], v[114:115] op_sel_hi:[0,1]
	v_pk_mul_f32 v[116:117], v[130:131], v[116:117] op_sel_hi:[0,1]
	v_pk_mul_f32 v[118:119], v[130:131], v[118:119] op_sel_hi:[0,1]
	v_pk_mul_f32 v[120:121], v[130:131], v[120:121] op_sel_hi:[0,1]
	v_pk_mul_f32 v[122:123], v[130:131], v[122:123] op_sel_hi:[0,1]
	v_pk_mul_f32 v[124:125], v[130:131], v[124:125] op_sel_hi:[0,1]
	v_pk_mul_f32 v[126:127], v[130:131], v[126:127] op_sel_hi:[0,1]
	v_pk_mul_f32 v[112:113], v[112:113], v[192:193]
	v_pk_mul_f32 v[114:115], v[114:115], v[194:195]
	v_pk_mul_f32 v[116:117], v[116:117], v[196:197]
	v_pk_mul_f32 v[118:119], v[118:119], v[198:199]
	v_pk_mul_f32 v[120:121], v[120:121], v[200:201]
	v_pk_mul_f32 v[122:123], v[122:123], v[202:203]
	v_pk_mul_f32 v[124:125], v[124:125], v[204:205]
	v_pk_mul_f32 v[126:127], v[126:127], v[206:207]
	v_lshlrev_b32_e32 v28, 16, v44
	v_and_b32_e32 v29, 0xffff0000, v44
	v_lshlrev_b32_e32 v30, 16, v45
	v_and_b32_e32 v31, 0xffff0000, v45
	v_lshlrev_b32_e32 v32, 16, v46
	v_and_b32_e32 v33, 0xffff0000, v46
	v_lshlrev_b32_e32 v34, 16, v47
	v_and_b32_e32 v35, 0xffff0000, v47
	v_pk_fma_f32 v[112:113], v[54:55], v[28:29], v[112:113] op_sel_hi:[0,1,1]
	v_pk_fma_f32 v[114:115], v[54:55], v[30:31], v[114:115] op_sel_hi:[0,1,1]
	v_pk_fma_f32 v[116:117], v[54:55], v[32:33], v[116:117] op_sel_hi:[0,1,1]
	v_pk_fma_f32 v[118:119], v[54:55], v[34:35], v[118:119] op_sel_hi:[0,1,1]
	v_lshlrev_b32_e32 v28, 16, v48
	v_and_b32_e32 v29, 0xffff0000, v48
	v_lshlrev_b32_e32 v30, 16, v49
	v_and_b32_e32 v31, 0xffff0000, v49
	v_lshlrev_b32_e32 v32, 16, v50
	v_and_b32_e32 v33, 0xffff0000, v50
	v_lshlrev_b32_e32 v34, 16, v51
	v_and_b32_e32 v35, 0xffff0000, v51
	v_pk_fma_f32 v[120:121], v[54:55], v[28:29], v[120:121] op_sel_hi:[0,1,1]
	v_pk_fma_f32 v[122:123], v[54:55], v[30:31], v[122:123] op_sel_hi:[0,1,1]
	v_pk_fma_f32 v[124:125], v[54:55], v[32:33], v[124:125] op_sel_hi:[0,1,1]
	v_pk_fma_f32 v[126:127], v[54:55], v[34:35], v[126:127] op_sel_hi:[0,1,1]
	v_pk_mul_f32 v[134:135], v[112:113], v[112:113]
	v_pk_fma_f32 v[134:135], v[114:115], v[114:115], v[134:135]
	v_pk_fma_f32 v[134:135], v[116:117], v[116:117], v[134:135]
	v_pk_fma_f32 v[134:135], v[118:119], v[118:119], v[134:135]
	v_pk_fma_f32 v[134:135], v[120:121], v[120:121], v[134:135]
	v_pk_fma_f32 v[134:135], v[122:123], v[122:123], v[134:135]
	v_pk_fma_f32 v[134:135], v[124:125], v[124:125], v[134:135]
	v_pk_fma_f32 v[134:135], v[126:127], v[126:127], v[134:135]
	s_nop 0
	v_add_f32_e32 v134, v134, v135
	s_nop 1
	v_add_f32_dpp v132, v132, v132 quad_perm:[1,0,3,2] row_mask:0xf bank_mask:0xf
	v_add_f32_dpp v134, v134, v134 quad_perm:[1,0,3,2] row_mask:0xf bank_mask:0xf
	s_nop 0
	v_add_f32_dpp v132, v132, v132 quad_perm:[2,3,0,1] row_mask:0xf bank_mask:0xf
	v_add_f32_dpp v134, v134, v134 quad_perm:[2,3,0,1] row_mask:0xf bank_mask:0xf
	s_nop 0
	v_add_f32_dpp v132, v132, v132 row_half_mirror row_mask:0xf bank_mask:0xf
	v_add_f32_dpp v134, v134, v134 row_half_mirror row_mask:0xf bank_mask:0xf
	s_nop 0
	v_add_f32_dpp v132, v132, v132 row_mirror row_mask:0xf bank_mask:0xf
	v_add_f32_dpp v134, v134, v134 row_mirror row_mask:0xf bank_mask:0xf
	s_nop 0
	ds_bpermute_b32 v136, v187, v132
	ds_bpermute_b32 v137, v187, v134
	s_waitcnt lgkmcnt(0)
; __device__ __forceinline__ const float* xrow_ptr(const Ctx& C, int row) { return row < MPROMPT ? C.in(0) + (size_t)row * DM : C.in(1) + (size_t)(row - MPROMPT) * DM; }
; __device__ __forceinline__ v4f ld4_bf16(const bf16* p) { const v2u w = *(const v2u*)p; return (v4f){bf_lo(w.x), bf_hi(w.x), bf_lo(w.y), bf_hi(w.y)}; }
; __device__ __forceinline__ void st4_bf16(bf16* p, v4f o) { v2u w; w.x = cvt_pk_nv(o.x, o.y); w.y = cvt_pk_nv(o.z, o.w); *(v2u*)p = w; }
; __device__ __forceinline__ float ssq4(v4f v) { return (v.x * v.x + v.y * v.y) + (v.z * v.z + v.w * v.w); }
; template <int R, bool BASE_F32, bool OUT_F32>
; __device__ __forceinline__ void rows_res(const Ctx& C, int m0, int stride, int mx, const float* gpost, float scale, int lane) {
;     ...
;     for (int r = 0; r < R; ++r) { mr[r] = (r == 4) ? mx : m0 + r * stride; ok[r] = (r == 4) ? (mx < M) : (mr[r] < MPROMPT); const int mm = ok[r] ? mr[r] : 0;
; #pragma unroll
;         for (int j = 0; j < 4; ++j) d[r][j] = ld4_bf16(D + (size_t)mm * DM + 4 * lane + 256 * j);
;         if (BASE_F32) { const float* x = xrow_ptr(C, mm);
; #pragma unroll
;             for (int j = 0; j < 4; ++j) b[r][j] = ld4_f32(x + 4 * lane + 256 * j);
;         } else { const float inv = C.RS()[mm];
; #pragma unroll
;             for (int j = 0; j < 4; ++j) b[r][j] = ld4_bf16(XN + (size_t)mm * DM + 4 * lane + 256 * j) * inv;
;         } }
; #pragma unroll
;     for (int r = 0; r < R; ++r) { float s = 0.f;
; #pragma unroll
;         for (int j = 0; j < 4; ++j) s += ssq4(d[r][j]);
;         r1[r] = s; }
;     ...
;         for (int r = 0; r < R; ++r) t[r] = wave_sum(t[r]) * (1.f / DM) + EPS;
; #pragma unroll
;         for (int r = 0; r < R; ++r) { const float rstd = rsqrtf(t[r]);
; #pragma unroll
;             for (int j = 0; j < 4; ++j) if (ok[r]) st4_bf16(XN + (size_t)mr[r] * DM + 4 * lane + 256 * j, d[r][j] * rstd);
;             if (lane == 0 && ok[r]) rs[mr[r]] = sqrtf(t[r]); }
	v_add_f32_e32 v132, v132, v136
	v_add_f32_e32 v134, v134, v137
	ds_bpermute_b32 v136, v188, v132
	ds_bpermute_b32 v137, v188, v134
	s_waitcnt lgkmcnt(0)
	v_add_f32_e32 v132, v132, v136
	v_add_f32_e32 v134, v134, v137
	v_fmamk_f32 v164, v132, 0x3a800000, v138
	v_fmamk_f32 v167, v134, 0x3a800000, v138
	s_nop 0
	v_rsq_f32_e32 v132, v164
	v_rsq_f32_e32 v134, v167
	v_sqrt_f32_e32 v165, v164
	v_sqrt_f32_e32 v168, v167
	s_nop 1
	v_pk_mul_f32 v[140:141], v[96:97], v[132:133] op_sel_hi:[1,0]
	v_cvt_pk_bf16_f32 v148, v140, v141
	v_pk_mul_f32 v[142:143], v[98:99], v[132:133] op_sel_hi:[1,0]
	v_cvt_pk_bf16_f32 v149, v142, v143
	v_pk_mul_f32 v[144:145], v[100:101], v[132:133] op_sel_hi:[1,0]
	v_cvt_pk_bf16_f32 v150, v144, v145
	v_pk_mul_f32 v[146:147], v[102:103], v[132:133] op_sel_hi:[1,0]
	v_cvt_pk_bf16_f32 v151, v146, v147
	v_pk_mul_f32 v[140:141], v[104:105], v[132:133] op_sel_hi:[1,0]
	v_cvt_pk_bf16_f32 v152, v140, v141
	v_pk_mul_f32 v[142:143], v[106:107], v[132:133] op_sel_hi:[1,0]
	v_cvt_pk_bf16_f32 v153, v142, v143
	v_pk_mul_f32 v[144:145], v[108:109], v[132:133] op_sel_hi:[1,0]
	v_cvt_pk_bf16_f32 v154, v144, v145
	v_pk_mul_f32 v[146:147], v[110:111], v[132:133] op_sel_hi:[1,0]
	v_cvt_pk_bf16_f32 v155, v146, v147
	global_store_dwordx2 v173, v[148:149], s[98:99]
	global_store_dwordx2 v173, v[150:151], s[98:99] offset:512
	global_store_dwordx2 v173, v[152:153], s[98:99] offset:1024
	global_store_dwordx2 v173, v[154:155], s[98:99] offset:1536
	v_add_u32_e32 v173, 0xffc00000, v173
	v_pk_mul_f32 v[140:141], v[112:113], v[134:135] op_sel_hi:[1,0]
	v_cvt_pk_bf16_f32 v156, v140, v141
	v_pk_mul_f32 v[142:143], v[114:115], v[134:135] op_sel_hi:[1,0]
	v_cvt_pk_bf16_f32 v157, v142, v143
	v_pk_mul_f32 v[144:145], v[116:117], v[134:135] op_sel_hi:[1,0]
	v_cvt_pk_bf16_f32 v158, v144, v145
	v_pk_mul_f32 v[146:147], v[118:119], v[134:135] op_sel_hi:[1,0]
	v_cvt_pk_bf16_f32 v159, v146, v147
	v_pk_mul_f32 v[140:141], v[120:121], v[134:135] op_sel_hi:[1,0]
	v_cvt_pk_bf16_f32 v160, v140, v141
	v_pk_mul_f32 v[142:143], v[122:123], v[134:135] op_sel_hi:[1,0]
	v_cvt_pk_bf16_f32 v161, v142, v143
	v_pk_mul_f32 v[144:145], v[124:125], v[134:135] op_sel_hi:[1,0]
	v_cvt_pk_bf16_f32 v162, v144, v145
	v_pk_mul_f32 v[146:147], v[126:127], v[134:135] op_sel_hi:[1,0]
	v_cvt_pk_bf16_f32 v163, v146, v147
	global_store_dwordx2 v173, v[156:157], s[98:99]
	global_store_dwordx2 v173, v[158:159], s[98:99] offset:512
	global_store_dwordx2 v173, v[160:161], s[98:99] offset:1024
	global_store_dwordx2 v173, v[162:163], s[98:99] offset:1536
	v_add_u32_e32 v173, 0xffc00000, v173
	v_add_u32_e32 v166, -1, v165
	v_fma_f32 v140, -v166, v165, v164
	v_cmp_ge_f32_e32 vcc, 0, v140
	v_add_u32_e32 v141, 1, v165
	v_cndmask_b32_e32 v166, v165, v166, vcc
	v_fma_f32 v140, -v141, v165, v164
	v_cmp_lt_f32_e32 vcc, 0, v140
	s_nop 1
	v_cndmask_b32_e32 v165, v166, v141, vcc
	v_add_u32_e32 v169, -1, v168
	v_fma_f32 v142, -v169, v168, v167
	v_cmp_ge_f32_e32 vcc, 0, v142
	v_add_u32_e32 v143, 1, v168
	v_cndmask_b32_e32 v169, v168, v169, vcc
	v_fma_f32 v142, -v143, v168, v167
	v_cmp_lt_f32_e32 vcc, 0, v142
	s_nop 1
	v_cndmask_b32_e32 v168, v169, v143, vcc
	s_mov_b64 exec, 1
	global_store_dword v174, v165, s[98:99]
	v_add_u32_e32 v174, 0xffffe000, v174
	global_store_dword v174, v168, s[98:99]
	v_add_u32_e32 v174, 0xffffe000, v174
	s_mov_b64 exec, -1
	global_load_dword v52, v172, s[98:99]
	global_load_dwordx2 v[20:21], v170, s[98:99]
	global_load_dwordx2 v[22:23], v170, s[98:99] offset:512
	global_load_dwordx2 v[24:25], v170, s[98:99] offset:1024
	global_load_dwordx2 v[26:27], v170, s[98:99] offset:1536
	global_load_dwordx2 v[36:37], v171, s[98:99]
	global_load_dwordx2 v[38:39], v171, s[98:99] offset:512
	global_load_dwordx2 v[40:41], v171, s[98:99] offset:1024
	global_load_dwordx2 v[42:43], v171, s[98:99] offset:1536
	v_add_u32_e32 v170, 0xffc00000, v170
	v_add_u32_e32 v171, 0xffc00000, v171
	v_add_u32_e32 v172, 0xffffe000, v172
	global_load_dword v54, v172, s[98:99]
	global_load_dwordx2 v[28:29], v170, s[98:99]
	global_load_dwordx2 v[30:31], v170, s[98:99] offset:512
	global_load_dwordx2 v[32:33], v170, s[98:99] offset:1024
	global_load_dwordx2 v[34:35], v170, s[98:99] offset:1536
	global_load_dwordx2 v[44:45], v171, s[98:99]
	global_load_dwordx2 v[46:47], v171, s[98:99] offset:512
	global_load_dwordx2 v[48:49], v171, s[98:99] offset:1024
	global_load_dwordx2 v[50:51], v171, s[98:99] offset:1536
	v_add_u32_e32 v170, 0xffc00000, v170
	v_add_u32_e32 v171, 0xffc00000, v171
	v_add_u32_e32 v172, 0xffffe000, v172
	s_waitcnt vmcnt(41)
	v_lshlrev_b32_e32 v96, 16, v56
	v_and_b32_e32 v97, 0xffff0000, v56
	v_lshlrev_b32_e32 v98, 16, v57
	v_and_b32_e32 v99, 0xffff0000, v57
	v_lshlrev_b32_e32 v100, 16, v58
	v_and_b32_e32 v101, 0xffff0000, v58
	v_lshlrev_b32_e32 v102, 16, v59
	v_and_b32_e32 v103, 0xffff0000, v59
	v_lshlrev_b32_e32 v104, 16, v60
	v_and_b32_e32 v105, 0xffff0000, v60
	v_lshlrev_b32_e32 v106, 16, v61
	v_and_b32_e32 v107, 0xffff0000, v61
	v_lshlrev_b32_e32 v108, 16, v62
	v_and_b32_e32 v109, 0xffff0000, v62
	v_lshlrev_b32_e32 v110, 16, v63
	v_and_b32_e32 v111, 0xffff0000, v63
	v_pk_mul_f32 v[128:129], v[96:97], v[96:97]
	v_pk_fma_f32 v[128:129], v[98:99], v[98:99], v[128:129]
	v_pk_fma_f32 v[128:129], v[100:101], v[100:101], v[128:129]
	v_pk_fma_f32 v[128:129], v[102:103], v[102:103], v[128:129]
	v_pk_fma_f32 v[128:129], v[104:105], v[104:105], v[128:129]
	v_pk_fma_f32 v[128:129], v[106:107], v[106:107], v[128:129]
	v_pk_fma_f32 v[128:129], v[108:109], v[108:109], v[128:129]
	v_pk_fma_f32 v[128:129], v[110:111], v[110:111], v[128:129]
	s_nop 0
	v_add_f32_e32 v128, v128, v129
	s_waitcnt vmcnt(32)
; __device__ __forceinline__ float ssq4(v4f v) { return (v.x * v.x + v.y * v.y) + (v.z * v.z + v.w * v.w); }
; template <int R, bool BASE_F32, bool OUT_F32>
; __device__ __forceinline__ void rows_res(const Ctx& C, int m0, int stride, int mx, const float* gpost, float scale, int lane) {
;     ...
;     for (int r = 0; r < R; ++r) { float s = 0.f;
; #pragma unroll
;         for (int j = 0; j < 4; ++j) s += ssq4(d[r][j]);
;         r1[r] = s; }
; #pragma unroll
;     for (int r = 0; r < R; ++r) r1[r] = rsqrtf(wave_sum(r1[r]) * (1.f / DM) + EPS) * scale;
; #pragma unroll
;     for (int j = 0; j < 4; ++j) { const v4f gp = ld4_f32(gpost + 4 * lane + 256 * j);
; #pragma unroll
;         for (int r = 0; r < R; ++r) d[r][j] = b[r][j] + d[r][j] * r1[r] * gp; }
	v_lshlrev_b32_e32 v112, 16, v64
	v_and_b32_e32 v113, 0xffff0000, v64
	v_lshlrev_b32_e32 v114, 16, v65
	v_and_b32_e32 v115, 0xffff0000, v65
	v_lshlrev_b32_e32 v116, 16, v66
	v_and_b32_e32 v117, 0xffff0000, v66
	v_lshlrev_b32_e32 v118, 16, v67
	v_and_b32_e32 v119, 0xffff0000, v67
	v_lshlrev_b32_e32 v120, 16, v68
	v_and_b32_e32 v121, 0xffff0000, v68
	v_lshlrev_b32_e32 v122, 16, v69
	v_and_b32_e32 v123, 0xffff0000, v69
	v_lshlrev_b32_e32 v124, 16, v70
	v_and_b32_e32 v125, 0xffff0000, v70
	v_lshlrev_b32_e32 v126, 16, v71
	v_and_b32_e32 v127, 0xffff0000, v71
	v_pk_mul_f32 v[130:131], v[112:113], v[112:113]
	v_pk_fma_f32 v[130:131], v[114:115], v[114:115], v[130:131]
	v_pk_fma_f32 v[130:131], v[116:117], v[116:117], v[130:131]
	v_pk_fma_f32 v[130:131], v[118:119], v[118:119], v[130:131]
	v_pk_fma_f32 v[130:131], v[120:121], v[120:121], v[130:131]
	v_pk_fma_f32 v[130:131], v[122:123], v[122:123], v[130:131]
	v_pk_fma_f32 v[130:131], v[124:125], v[124:125], v[130:131]
	v_pk_fma_f32 v[130:131], v[126:127], v[126:127], v[130:131]
	s_nop 0
	v_add_f32_e32 v130, v130, v131
	s_nop 1
	v_add_f32_dpp v128, v128, v128 quad_perm:[1,0,3,2] row_mask:0xf bank_mask:0xf
	v_add_f32_dpp v130, v130, v130 quad_perm:[1,0,3,2] row_mask:0xf bank_mask:0xf
	s_nop 0
	v_add_f32_dpp v128, v128, v128 quad_perm:[2,3,0,1] row_mask:0xf bank_mask:0xf
	v_add_f32_dpp v130, v130, v130 quad_perm:[2,3,0,1] row_mask:0xf bank_mask:0xf
	s_nop 0
	v_add_f32_dpp v128, v128, v128 row_half_mirror row_mask:0xf bank_mask:0xf
	v_add_f32_dpp v130, v130, v130 row_half_mirror row_mask:0xf bank_mask:0xf
	s_nop 0
	v_add_f32_dpp v128, v128, v128 row_mirror row_mask:0xf bank_mask:0xf
	v_add_f32_dpp v130, v130, v130 row_mirror row_mask:0xf bank_mask:0xf
	s_nop 0
	ds_bpermute_b32 v136, v187, v128
	ds_bpermute_b32 v137, v187, v130
	s_waitcnt lgkmcnt(0)
	v_add_f32_e32 v128, v128, v136
	v_add_f32_e32 v130, v130, v137
	ds_bpermute_b32 v136, v188, v128
	ds_bpermute_b32 v137, v188, v130
	s_waitcnt lgkmcnt(0)
	v_add_f32_e32 v128, v128, v136
	v_add_f32_e32 v130, v130, v137
	v_fmamk_f32 v128, v128, 0x3a800000, v138
	v_fmamk_f32 v130, v130, 0x3a800000, v138
	s_nop 0
	v_rsq_f32_e32 v128, v128
	v_rsq_f32_e32 v130, v130
	s_nop 1
	s_waitcnt vmcnt(28)
	v_pk_mul_f32 v[96:97], v[128:129], v[96:97] op_sel_hi:[0,1]
	v_pk_mul_f32 v[98:99], v[128:129], v[98:99] op_sel_hi:[0,1]
	v_pk_mul_f32 v[100:101], v[128:129], v[100:101] op_sel_hi:[0,1]
	v_pk_mul_f32 v[102:103], v[128:129], v[102:103] op_sel_hi:[0,1]
	v_pk_mul_f32 v[104:105], v[128:129], v[104:105] op_sel_hi:[0,1]
	v_pk_mul_f32 v[106:107], v[128:129], v[106:107] op_sel_hi:[0,1]
	v_pk_mul_f32 v[108:109], v[128:129], v[108:109] op_sel_hi:[0,1]
	v_pk_mul_f32 v[110:111], v[128:129], v[110:111] op_sel_hi:[0,1]
	v_pk_mul_f32 v[96:97], v[96:97], v[192:193]
	v_pk_mul_f32 v[98:99], v[98:99], v[194:195]
	v_pk_mul_f32 v[100:101], v[100:101], v[196:197]
	v_pk_mul_f32 v[102:103], v[102:103], v[198:199]
	v_pk_mul_f32 v[104:105], v[104:105], v[200:201]
	v_pk_mul_f32 v[106:107], v[106:107], v[202:203]
	v_pk_mul_f32 v[108:109], v[108:109], v[204:205]
	v_pk_mul_f32 v[110:111], v[110:111], v[206:207]
	v_lshlrev_b32_e32 v56, 16, v72
	v_and_b32_e32 v57, 0xffff0000, v72
	v_lshlrev_b32_e32 v58, 16, v73
	v_and_b32_e32 v59, 0xffff0000, v73
	v_lshlrev_b32_e32 v60, 16, v74
	v_and_b32_e32 v61, 0xffff0000, v74
	v_lshlrev_b32_e32 v62, 16, v75
	v_and_b32_e32 v63, 0xffff0000, v75
	v_pk_fma_f32 v[96:97], v[88:89], v[56:57], v[96:97] op_sel_hi:[0,1,1]
	v_pk_fma_f32 v[98:99], v[88:89], v[58:59], v[98:99] op_sel_hi:[0,1,1]
	v_pk_fma_f32 v[100:101], v[88:89], v[60:61], v[100:101] op_sel_hi:[0,1,1]
	v_pk_fma_f32 v[102:103], v[88:89], v[62:63], v[102:103] op_sel_hi:[0,1,1]
	v_lshlrev_b32_e32 v56, 16, v76
	v_and_b32_e32 v57, 0xffff0000, v76
	v_lshlrev_b32_e32 v58, 16, v77
	v_and_b32_e32 v59, 0xffff0000, v77
	v_lshlrev_b32_e32 v60, 16, v78
	v_and_b32_e32 v61, 0xffff0000, v78
	v_lshlrev_b32_e32 v62, 16, v79
	v_and_b32_e32 v63, 0xffff0000, v79
	v_pk_fma_f32 v[104:105], v[88:89], v[56:57], v[104:105] op_sel_hi:[0,1,1]
	v_pk_fma_f32 v[106:107], v[88:89], v[58:59], v[106:107] op_sel_hi:[0,1,1]
	v_pk_fma_f32 v[108:109], v[88:89], v[60:61], v[108:109] op_sel_hi:[0,1,1]
	v_pk_fma_f32 v[110:111], v[88:89], v[62:63], v[110:111] op_sel_hi:[0,1,1]
	v_pk_mul_f32 v[132:133], v[96:97], v[96:97]
	v_pk_fma_f32 v[132:133], v[98:99], v[98:99], v[132:133]
	v_pk_fma_f32 v[132:133], v[100:101], v[100:101], v[132:133]
	v_pk_fma_f32 v[132:133], v[102:103], v[102:103], v[132:133]
	v_pk_fma_f32 v[132:133], v[104:105], v[104:105], v[132:133]
	v_pk_fma_f32 v[132:133], v[106:107], v[106:107], v[132:133]
	v_pk_fma_f32 v[132:133], v[108:109], v[108:109], v[132:133]
	v_pk_fma_f32 v[132:133], v[110:111], v[110:111], v[132:133]
	s_nop 0
	v_add_f32_e32 v132, v132, v133
	v_pk_mul_f32 v[112:113], v[130:131], v[112:113] op_sel_hi:[0,1]
	v_pk_mul_f32 v[114:115], v[130:131], v[114:115] op_sel_hi:[0,1]
	v_pk_mul_f32 v[116:117], v[130:131], v[116:117] op_sel_hi:[0,1]
	v_pk_mul_f32 v[118:119], v[130:131], v[118:119] op_sel_hi:[0,1]
	v_pk_mul_f32 v[120:121], v[130:131], v[120:121] op_sel_hi:[0,1]
	v_pk_mul_f32 v[122:123], v[130:131], v[122:123] op_sel_hi:[0,1]
	v_pk_mul_f32 v[124:125], v[130:131], v[124:125] op_sel_hi:[0,1]
	v_pk_mul_f32 v[126:127], v[130:131], v[126:127] op_sel_hi:[0,1]
	v_pk_mul_f32 v[112:113], v[112:113], v[192:193]
	v_pk_mul_f32 v[114:115], v[114:115], v[194:195]
	v_pk_mul_f32 v[116:117], v[116:117], v[196:197]
	v_pk_mul_f32 v[118:119], v[118:119], v[198:199]
	v_pk_mul_f32 v[120:121], v[120:121], v[200:201]
	v_pk_mul_f32 v[122:123], v[122:123], v[202:203]
	v_pk_mul_f32 v[124:125], v[124:125], v[204:205]
	v_pk_mul_f32 v[126:127], v[126:127], v[206:207]
;     __device__ __forceinline__ float* out() const { return (float*)karg_in(33); }
; __device__ __forceinline__ const float* xrow_ptr(const Ctx& C, int row) { return row < MPROMPT ? C.in(0) + (size_t)row * DM : C.in(1) + (size_t)(row - MPROMPT) * DM; }
; __device__ __forceinline__ v4f ld4_bf16(const bf16* p) { const v2u w = *(const v2u*)p; return (v4f){bf_lo(w.x), bf_hi(w.x), bf_lo(w.y), bf_hi(w.y)}; }
; __device__ __forceinline__ void st4_bf16(bf16* p, v4f o) { v2u w; w.x = cvt_pk_nv(o.x, o.y); w.y = cvt_pk_nv(o.z, o.w); *(v2u*)p = w; }
; __device__ __forceinline__ float ssq4(v4f v) { return (v.x * v.x + v.y * v.y) + (v.z * v.z + v.w * v.w); }
; template <int R, bool BASE_F32, bool OUT_F32>
; __device__ __forceinline__ void rows_res(const Ctx& C, int m0, int stride, int mx, const float* gpost, float scale, int lane) {
;     ...
;     for (int r = 0; r < R; ++r) { mr[r] = (r == 4) ? mx : m0 + r * stride; ok[r] = (r == 4) ? (mx < M) : (mr[r] < MPROMPT); const int mm = ok[r] ? mr[r] : 0;
; #pragma unroll
;         for (int j = 0; j < 4; ++j) d[r][j] = ld4_bf16(D + (size_t)mm * DM + 4 * lane + 256 * j);
;         if (BASE_F32) { const float* x = xrow_ptr(C, mm);
; #pragma unroll
;             for (int j = 0; j < 4; ++j) b[r][j] = ld4_f32(x + 4 * lane + 256 * j);
;         } else { const float inv = C.RS()[mm];
; #pragma unroll
;             for (int j = 0; j < 4; ++j) b[r][j] = ld4_bf16(XN + (size_t)mm * DM + 4 * lane + 256 * j) * inv;
;         } }
;     ...
;         for (int r = 0; r < R; ++r) d[r][j] = b[r][j] + d[r][j] * r1[r] * gp; }
;     if (OUT_F32) { float* Y = C.out();
; #pragma unroll
;         for (int r = 0; r < R; ++r)
; #pragma unroll
;             for (int j = 0; j < 4; ++j) if (ok[r]) *(v4f*)(Y + (size_t)mr[r] * DM + 4 * lane + 256 * j) = d[r][j];
;     } else { float* rs = C.RS(); float t[R];
; #pragma unroll
;         for (int r = 0; r < R; ++r) { float s = 0.f;
; #pragma unroll
;             for (int j = 0; j < 4; ++j) s += ssq4(d[r][j]);
;             t[r] = s; }
; #pragma unroll
;         for (int r = 0; r < R; ++r) t[r] = wave_sum(t[r]) * (1.f / DM) + EPS;
; #pragma unroll
;         for (int r = 0; r < R; ++r) { const float rstd = rsqrtf(t[r]);
; #pragma unroll
;             for (int j = 0; j < 4; ++j) if (ok[r]) st4_bf16(XN + (size_t)mr[r] * DM + 4 * lane + 256 * j, d[r][j] * rstd);
;             if (lane == 0 && ok[r]) rs[mr[r]] = sqrtf(t[r]); }
	v_lshlrev_b32_e32 v64, 16, v80
	v_and_b32_e32 v65, 0xffff0000, v80
	v_lshlrev_b32_e32 v66, 16, v81
	v_and_b32_e32 v67, 0xffff0000, v81
	v_lshlrev_b32_e32 v68, 16, v82
	v_and_b32_e32 v69, 0xffff0000, v82
	v_lshlrev_b32_e32 v70, 16, v83
	v_and_b32_e32 v71, 0xffff0000, v83
	v_pk_fma_f32 v[112:113], v[90:91], v[64:65], v[112:113] op_sel_hi:[0,1,1]
	v_pk_fma_f32 v[114:115], v[90:91], v[66:67], v[114:115] op_sel_hi:[0,1,1]
	v_pk_fma_f32 v[116:117], v[90:91], v[68:69], v[116:117] op_sel_hi:[0,1,1]
	v_pk_fma_f32 v[118:119], v[90:91], v[70:71], v[118:119] op_sel_hi:[0,1,1]
	v_lshlrev_b32_e32 v64, 16, v84
	v_and_b32_e32 v65, 0xffff0000, v84
	v_lshlrev_b32_e32 v66, 16, v85
	v_and_b32_e32 v67, 0xffff0000, v85
	v_lshlrev_b32_e32 v68, 16, v86
	v_and_b32_e32 v69, 0xffff0000, v86
	v_lshlrev_b32_e32 v70, 16, v87
	v_and_b32_e32 v71, 0xffff0000, v87
	v_pk_fma_f32 v[120:121], v[90:91], v[64:65], v[120:121] op_sel_hi:[0,1,1]
	v_pk_fma_f32 v[122:123], v[90:91], v[66:67], v[122:123] op_sel_hi:[0,1,1]
	v_pk_fma_f32 v[124:125], v[90:91], v[68:69], v[124:125] op_sel_hi:[0,1,1]
	v_pk_fma_f32 v[126:127], v[90:91], v[70:71], v[126:127] op_sel_hi:[0,1,1]
	v_pk_mul_f32 v[134:135], v[112:113], v[112:113]
	v_pk_fma_f32 v[134:135], v[114:115], v[114:115], v[134:135]
	v_pk_fma_f32 v[134:135], v[116:117], v[116:117], v[134:135]
	v_pk_fma_f32 v[134:135], v[118:119], v[118:119], v[134:135]
	v_pk_fma_f32 v[134:135], v[120:121], v[120:121], v[134:135]
	v_pk_fma_f32 v[134:135], v[122:123], v[122:123], v[134:135]
	v_pk_fma_f32 v[134:135], v[124:125], v[124:125], v[134:135]
	v_pk_fma_f32 v[134:135], v[126:127], v[126:127], v[134:135]
	s_nop 0
	v_add_f32_e32 v134, v134, v135
	s_nop 1
	v_add_f32_dpp v132, v132, v132 quad_perm:[1,0,3,2] row_mask:0xf bank_mask:0xf
	v_add_f32_dpp v134, v134, v134 quad_perm:[1,0,3,2] row_mask:0xf bank_mask:0xf
	s_nop 0
	v_add_f32_dpp v132, v132, v132 quad_perm:[2,3,0,1] row_mask:0xf bank_mask:0xf
	v_add_f32_dpp v134, v134, v134 quad_perm:[2,3,0,1] row_mask:0xf bank_mask:0xf
	s_nop 0
	v_add_f32_dpp v132, v132, v132 row_half_mirror row_mask:0xf bank_mask:0xf
	v_add_f32_dpp v134, v134, v134 row_half_mirror row_mask:0xf bank_mask:0xf
	s_nop 0
	v_add_f32_dpp v132, v132, v132 row_mirror row_mask:0xf bank_mask:0xf
	v_add_f32_dpp v134, v134, v134 row_mirror row_mask:0xf bank_mask:0xf
	s_nop 0
	ds_bpermute_b32 v136, v187, v132
	ds_bpermute_b32 v137, v187, v134
	s_waitcnt lgkmcnt(0)
	v_add_f32_e32 v132, v132, v136
	v_add_f32_e32 v134, v134, v137
	ds_bpermute_b32 v136, v188, v132
	ds_bpermute_b32 v137, v188, v134
	s_waitcnt lgkmcnt(0)
	v_add_f32_e32 v132, v132, v136
	v_add_f32_e32 v134, v134, v137
	v_fmamk_f32 v164, v132, 0x3a800000, v138
	v_fmamk_f32 v167, v134, 0x3a800000, v138
	s_nop 0
	v_rsq_f32_e32 v132, v164
	v_rsq_f32_e32 v134, v167
	v_sqrt_f32_e32 v165, v164
	v_sqrt_f32_e32 v168, v167
	s_nop 1
	v_pk_mul_f32 v[140:141], v[96:97], v[132:133] op_sel_hi:[1,0]
	v_cvt_pk_bf16_f32 v148, v140, v141
	v_pk_mul_f32 v[142:143], v[98:99], v[132:133] op_sel_hi:[1,0]
	v_cvt_pk_bf16_f32 v149, v142, v143
	v_pk_mul_f32 v[144:145], v[100:101], v[132:133] op_sel_hi:[1,0]
	v_cvt_pk_bf16_f32 v150, v144, v145
	v_pk_mul_f32 v[146:147], v[102:103], v[132:133] op_sel_hi:[1,0]
	v_cvt_pk_bf16_f32 v151, v146, v147
	v_pk_mul_f32 v[140:141], v[104:105], v[132:133] op_sel_hi:[1,0]
	v_cvt_pk_bf16_f32 v152, v140, v141
	v_pk_mul_f32 v[142:143], v[106:107], v[132:133] op_sel_hi:[1,0]
	v_cvt_pk_bf16_f32 v153, v142, v143
	v_pk_mul_f32 v[144:145], v[108:109], v[132:133] op_sel_hi:[1,0]
	v_cvt_pk_bf16_f32 v154, v144, v145
	v_pk_mul_f32 v[146:147], v[110:111], v[132:133] op_sel_hi:[1,0]
	v_cvt_pk_bf16_f32 v155, v146, v147
	global_store_dwordx2 v173, v[148:149], s[98:99]
	global_store_dwordx2 v173, v[150:151], s[98:99] offset:512
	global_store_dwordx2 v173, v[152:153], s[98:99] offset:1024
	global_store_dwordx2 v173, v[154:155], s[98:99] offset:1536
	v_add_u32_e32 v173, 0xffc00000, v173
	v_pk_mul_f32 v[140:141], v[112:113], v[134:135] op_sel_hi:[1,0]
	v_cvt_pk_bf16_f32 v156, v140, v141
	v_pk_mul_f32 v[142:143], v[114:115], v[134:135] op_sel_hi:[1,0]
	v_cvt_pk_bf16_f32 v157, v142, v143
	v_pk_mul_f32 v[144:145], v[116:117], v[134:135] op_sel_hi:[1,0]
	v_cvt_pk_bf16_f32 v158, v144, v145
	v_pk_mul_f32 v[146:147], v[118:119], v[134:135] op_sel_hi:[1,0]
	v_cvt_pk_bf16_f32 v159, v146, v147
	v_pk_mul_f32 v[140:141], v[120:121], v[134:135] op_sel_hi:[1,0]
	v_cvt_pk_bf16_f32 v160, v140, v141
	v_pk_mul_f32 v[142:143], v[122:123], v[134:135] op_sel_hi:[1,0]
	v_cvt_pk_bf16_f32 v161, v142, v143
	v_pk_mul_f32 v[144:145], v[124:125], v[134:135] op_sel_hi:[1,0]
	v_cvt_pk_bf16_f32 v162, v144, v145
	v_pk_mul_f32 v[146:147], v[126:127], v[134:135] op_sel_hi:[1,0]
	v_cvt_pk_bf16_f32 v163, v146, v147
	global_store_dwordx2 v173, v[156:157], s[98:99]
	global_store_dwordx2 v173, v[158:159], s[98:99] offset:512
	global_store_dwordx2 v173, v[160:161], s[98:99] offset:1024
	global_store_dwordx2 v173, v[162:163], s[98:99] offset:1536
	v_add_u32_e32 v173, 0xffc00000, v173
	v_add_u32_e32 v166, -1, v165
	v_fma_f32 v140, -v166, v165, v164
	v_cmp_ge_f32_e32 vcc, 0, v140
	v_add_u32_e32 v141, 1, v165
	v_cndmask_b32_e32 v166, v165, v166, vcc
	v_fma_f32 v140, -v141, v165, v164
	v_cmp_lt_f32_e32 vcc, 0, v140
	s_nop 1
	v_cndmask_b32_e32 v165, v166, v141, vcc
	v_add_u32_e32 v169, -1, v168
	v_fma_f32 v142, -v169, v168, v167
	v_cmp_ge_f32_e32 vcc, 0, v142
	v_add_u32_e32 v143, 1, v168
	v_cndmask_b32_e32 v169, v168, v169, vcc
	v_fma_f32 v142, -v143, v168, v167
	v_cmp_lt_f32_e32 vcc, 0, v142
	s_nop 1
	v_cndmask_b32_e32 v168, v169, v143, vcc
	s_mov_b64 exec, 1
	global_store_dword v174, v165, s[98:99]
	v_add_u32_e32 v174, 0xffffe000, v174
	global_store_dword v174, v168, s[98:99]
	v_add_u32_e32 v174, 0xffffe000, v174
	s_mov_b64 exec, -1
	global_load_dword v88, v172, s[98:99]
	global_load_dwordx2 v[56:57], v170, s[98:99]
	global_load_dwordx2 v[58:59], v170, s[98:99] offset:512
	global_load_dwordx2 v[60:61], v170, s[98:99] offset:1024
	global_load_dwordx2 v[62:63], v170, s[98:99] offset:1536
	global_load_dwordx2 v[72:73], v171, s[98:99]
	global_load_dwordx2 v[74:75], v171, s[98:99] offset:512
	global_load_dwordx2 v[76:77], v171, s[98:99] offset:1024
	global_load_dwordx2 v[78:79], v171, s[98:99] offset:1536
	v_add_u32_e32 v170, 0xffc00000, v170
	v_add_u32_e32 v171, 0xffc00000, v171
	v_add_u32_e32 v172, 0xffffe000, v172
	global_load_dword v90, v172, s[98:99]
	global_load_dwordx2 v[64:65], v170, s[98:99]
	global_load_dwordx2 v[66:67], v170, s[98:99] offset:512
	global_load_dwordx2 v[68:69], v170, s[98:99] offset:1024
	global_load_dwordx2 v[70:71], v170, s[98:99] offset:1536
	global_load_dwordx2 v[80:81], v171, s[98:99]
	global_load_dwordx2 v[82:83], v171, s[98:99] offset:512
	global_load_dwordx2 v[84:85], v171, s[98:99] offset:1024
	global_load_dwordx2 v[86:87], v171, s[98:99] offset:1536
	v_add_u32_e32 v170, 0xffc00000, v170
	v_add_u32_e32 v171, 0xffc00000, v171
	v_add_u32_e32 v172, 0xffffe000, v172
	s_waitcnt vmcnt(41)
; __device__ __forceinline__ float ssq4(v4f v) { return (v.x * v.x + v.y * v.y) + (v.z * v.z + v.w * v.w); }
; template <int R, bool BASE_F32, bool OUT_F32>
; __device__ __forceinline__ void rows_res(const Ctx& C, int m0, int stride, int mx, const float* gpost, float scale, int lane) {
;     ...
;     for (int r = 0; r < R; ++r) { float s = 0.f;
; #pragma unroll
;         for (int j = 0; j < 4; ++j) s += ssq4(d[r][j]);
;         r1[r] = s; }
; #pragma unroll
;     for (int r = 0; r < R; ++r) r1[r] = rsqrtf(wave_sum(r1[r]) * (1.f / DM) + EPS) * scale;
; #pragma unroll
;     for (int j = 0; j < 4; ++j) { const v4f gp = ld4_f32(gpost + 4 * lane + 256 * j);
; #pragma unroll
;         for (int r = 0; r < R; ++r) d[r][j] = b[r][j] + d[r][j] * r1[r] * gp; }
	v_lshlrev_b32_e32 v96, 16, v20
	v_and_b32_e32 v97, 0xffff0000, v20
	v_lshlrev_b32_e32 v98, 16, v21
	v_and_b32_e32 v99, 0xffff0000, v21
	v_lshlrev_b32_e32 v100, 16, v22
	v_and_b32_e32 v101, 0xffff0000, v22
	v_lshlrev_b32_e32 v102, 16, v23
	v_and_b32_e32 v103, 0xffff0000, v23
	v_lshlrev_b32_e32 v104, 16, v24
	v_and_b32_e32 v105, 0xffff0000, v24
	v_lshlrev_b32_e32 v106, 16, v25
	v_and_b32_e32 v107, 0xffff0000, v25
	v_lshlrev_b32_e32 v108, 16, v26
	v_and_b32_e32 v109, 0xffff0000, v26
	v_lshlrev_b32_e32 v110, 16, v27
	v_and_b32_e32 v111, 0xffff0000, v27
	v_pk_mul_f32 v[128:129], v[96:97], v[96:97]
	v_pk_fma_f32 v[128:129], v[98:99], v[98:99], v[128:129]
	v_pk_fma_f32 v[128:129], v[100:101], v[100:101], v[128:129]
	v_pk_fma_f32 v[128:129], v[102:103], v[102:103], v[128:129]
	v_pk_fma_f32 v[128:129], v[104:105], v[104:105], v[128:129]
	v_pk_fma_f32 v[128:129], v[106:107], v[106:107], v[128:129]
	v_pk_fma_f32 v[128:129], v[108:109], v[108:109], v[128:129]
	v_pk_fma_f32 v[128:129], v[110:111], v[110:111], v[128:129]
	s_nop 0
	v_add_f32_e32 v128, v128, v129
	s_waitcnt vmcnt(32)
	v_lshlrev_b32_e32 v112, 16, v28
	v_and_b32_e32 v113, 0xffff0000, v28
	v_lshlrev_b32_e32 v114, 16, v29
	v_and_b32_e32 v115, 0xffff0000, v29
	v_lshlrev_b32_e32 v116, 16, v30
	v_and_b32_e32 v117, 0xffff0000, v30
	v_lshlrev_b32_e32 v118, 16, v31
	v_and_b32_e32 v119, 0xffff0000, v31
	v_lshlrev_b32_e32 v120, 16, v32
	v_and_b32_e32 v121, 0xffff0000, v32
	v_lshlrev_b32_e32 v122, 16, v33
	v_and_b32_e32 v123, 0xffff0000, v33
	v_lshlrev_b32_e32 v124, 16, v34
	v_and_b32_e32 v125, 0xffff0000, v34
	v_lshlrev_b32_e32 v126, 16, v35
	v_and_b32_e32 v127, 0xffff0000, v35
	v_pk_mul_f32 v[130:131], v[112:113], v[112:113]
	v_pk_fma_f32 v[130:131], v[114:115], v[114:115], v[130:131]
	v_pk_fma_f32 v[130:131], v[116:117], v[116:117], v[130:131]
	v_pk_fma_f32 v[130:131], v[118:119], v[118:119], v[130:131]
	v_pk_fma_f32 v[130:131], v[120:121], v[120:121], v[130:131]
	v_pk_fma_f32 v[130:131], v[122:123], v[122:123], v[130:131]
	v_pk_fma_f32 v[130:131], v[124:125], v[124:125], v[130:131]
	v_pk_fma_f32 v[130:131], v[126:127], v[126:127], v[130:131]
	s_nop 0
	v_add_f32_e32 v130, v130, v131
	s_nop 1
	v_add_f32_dpp v128, v128, v128 quad_perm:[1,0,3,2] row_mask:0xf bank_mask:0xf
	v_add_f32_dpp v130, v130, v130 quad_perm:[1,0,3,2] row_mask:0xf bank_mask:0xf
	s_nop 0
	v_add_f32_dpp v128, v128, v128 quad_perm:[2,3,0,1] row_mask:0xf bank_mask:0xf
	v_add_f32_dpp v130, v130, v130 quad_perm:[2,3,0,1] row_mask:0xf bank_mask:0xf
	s_nop 0
	v_add_f32_dpp v128, v128, v128 row_half_mirror row_mask:0xf bank_mask:0xf
	v_add_f32_dpp v130, v130, v130 row_half_mirror row_mask:0xf bank_mask:0xf
	s_nop 0
	v_add_f32_dpp v128, v128, v128 row_mirror row_mask:0xf bank_mask:0xf
	v_add_f32_dpp v130, v130, v130 row_mirror row_mask:0xf bank_mask:0xf
	s_nop 0
	ds_bpermute_b32 v136, v187, v128
	ds_bpermute_b32 v137, v187, v130
	s_waitcnt lgkmcnt(0)
	v_add_f32_e32 v128, v128, v136
	v_add_f32_e32 v130, v130, v137
	ds_bpermute_b32 v136, v188, v128
	ds_bpermute_b32 v137, v188, v130
	s_waitcnt lgkmcnt(0)
	v_add_f32_e32 v128, v128, v136
	v_add_f32_e32 v130, v130, v137
	v_fmamk_f32 v128, v128, 0x3a800000, v138
	v_fmamk_f32 v130, v130, 0x3a800000, v138
	s_nop 0
	v_rsq_f32_e32 v128, v128
	v_rsq_f32_e32 v130, v130
	s_nop 1
	s_waitcnt vmcnt(28)
	v_pk_mul_f32 v[96:97], v[128:129], v[96:97] op_sel_hi:[0,1]
	v_pk_mul_f32 v[98:99], v[128:129], v[98:99] op_sel_hi:[0,1]
	v_pk_mul_f32 v[100:101], v[128:129], v[100:101] op_sel_hi:[0,1]
	v_pk_mul_f32 v[102:103], v[128:129], v[102:103] op_sel_hi:[0,1]
	v_pk_mul_f32 v[104:105], v[128:129], v[104:105] op_sel_hi:[0,1]
	v_pk_mul_f32 v[106:107], v[128:129], v[106:107] op_sel_hi:[0,1]
	v_pk_mul_f32 v[108:109], v[128:129], v[108:109] op_sel_hi:[0,1]
	v_pk_mul_f32 v[110:111], v[128:129], v[110:111] op_sel_hi:[0,1]
	v_pk_mul_f32 v[96:97], v[96:97], v[192:193]
	v_pk_mul_f32 v[98:99], v[98:99], v[194:195]
	v_pk_mul_f32 v[100:101], v[100:101], v[196:197]
	v_pk_mul_f32 v[102:103], v[102:103], v[198:199]
	v_pk_mul_f32 v[104:105], v[104:105], v[200:201]
	v_pk_mul_f32 v[106:107], v[106:107], v[202:203]
	v_pk_mul_f32 v[108:109], v[108:109], v[204:205]
	v_pk_mul_f32 v[110:111], v[110:111], v[206:207]
	v_lshlrev_b32_e32 v20, 16, v36
	v_and_b32_e32 v21, 0xffff0000, v36
	v_lshlrev_b32_e32 v22, 16, v37
	v_and_b32_e32 v23, 0xffff0000, v37
	v_lshlrev_b32_e32 v24, 16, v38
	v_and_b32_e32 v25, 0xffff0000, v38
	v_lshlrev_b32_e32 v26, 16, v39
	v_and_b32_e32 v27, 0xffff0000, v39
	v_pk_fma_f32 v[96:97], v[52:53], v[20:21], v[96:97] op_sel_hi:[0,1,1]
	v_pk_fma_f32 v[98:99], v[52:53], v[22:23], v[98:99] op_sel_hi:[0,1,1]
	v_pk_fma_f32 v[100:101], v[52:53], v[24:25], v[100:101] op_sel_hi:[0,1,1]
	v_pk_fma_f32 v[102:103], v[52:53], v[26:27], v[102:103] op_sel_hi:[0,1,1]
	v_lshlrev_b32_e32 v20, 16, v40
	v_and_b32_e32 v21, 0xffff0000, v40
	v_lshlrev_b32_e32 v22, 16, v41
	v_and_b32_e32 v23, 0xffff0000, v41
	v_lshlrev_b32_e32 v24, 16, v42
	v_and_b32_e32 v25, 0xffff0000, v42
	v_lshlrev_b32_e32 v26, 16, v43
	v_and_b32_e32 v27, 0xffff0000, v43
	v_pk_fma_f32 v[104:105], v[52:53], v[20:21], v[104:105] op_sel_hi:[0,1,1]
	v_pk_fma_f32 v[106:107], v[52:53], v[22:23], v[106:107] op_sel_hi:[0,1,1]
	v_pk_fma_f32 v[108:109], v[52:53], v[24:25], v[108:109] op_sel_hi:[0,1,1]
	v_pk_fma_f32 v[110:111], v[52:53], v[26:27], v[110:111] op_sel_hi:[0,1,1]
	v_pk_mul_f32 v[132:133], v[96:97], v[96:97]
	v_pk_fma_f32 v[132:133], v[98:99], v[98:99], v[132:133]
	v_pk_fma_f32 v[132:133], v[100:101], v[100:101], v[132:133]
	v_pk_fma_f32 v[132:133], v[102:103], v[102:103], v[132:133]
	v_pk_fma_f32 v[132:133], v[104:105], v[104:105], v[132:133]
;     __device__ __forceinline__ float* out() const { return (float*)karg_in(33); }
; __device__ __forceinline__ void st4_bf16(bf16* p, v4f o) { v2u w; w.x = cvt_pk_nv(o.x, o.y); w.y = cvt_pk_nv(o.z, o.w); *(v2u*)p = w; }
; __device__ __forceinline__ float ssq4(v4f v) { return (v.x * v.x + v.y * v.y) + (v.z * v.z + v.w * v.w); }
; template <int R, bool BASE_F32, bool OUT_F32>
; __device__ __forceinline__ void rows_res(const Ctx& C, int m0, int stride, int mx, const float* gpost, float scale, int lane) {
;     ...
;         for (int r = 0; r < R; ++r) d[r][j] = b[r][j] + d[r][j] * r1[r] * gp; }
;     if (OUT_F32) { float* Y = C.out();
; #pragma unroll
;         for (int r = 0; r < R; ++r)
; #pragma unroll
;             for (int j = 0; j < 4; ++j) if (ok[r]) *(v4f*)(Y + (size_t)mr[r] * DM + 4 * lane + 256 * j) = d[r][j];
;     } else { float* rs = C.RS(); float t[R];
; #pragma unroll
;         for (int r = 0; r < R; ++r) { float s = 0.f;
; #pragma unroll
;             for (int j = 0; j < 4; ++j) s += ssq4(d[r][j]);
;             t[r] = s; }
; #pragma unroll
;         for (int r = 0; r < R; ++r) t[r] = wave_sum(t[r]) * (1.f / DM) + EPS;
; #pragma unroll
;         for (int r = 0; r < R; ++r) { const float rstd = rsqrtf(t[r]);
; #pragma unroll
;             for (int j = 0; j < 4; ++j) if (ok[r]) st4_bf16(XN + (size_t)mr[r] * DM + 4 * lane + 256 * j, d[r][j] * rstd);
;             if (lane == 0 && ok[r]) rs[mr[r]] = sqrtf(t[r]); }
	v_pk_fma_f32 v[132:133], v[106:107], v[106:107], v[132:133]
	v_pk_fma_f32 v[132:133], v[108:109], v[108:109], v[132:133]
	v_pk_fma_f32 v[132:133], v[110:111], v[110:111], v[132:133]
	s_nop 0
	v_add_f32_e32 v132, v132, v133
	v_pk_mul_f32 v[112:113], v[130:131], v[112:113] op_sel_hi:[0,1]
	v_pk_mul_f32 v[114:115], v[130:131], v[114:115] op_sel_hi:[0,1]
	v_pk_mul_f32 v[116:117], v[130:131], v[116:117] op_sel_hi:[0,1]
	v_pk_mul_f32 v[118:119], v[130:131], v[118:119] op_sel_hi:[0,1]
	v_pk_mul_f32 v[120:121], v[130:131], v[120:121] op_sel_hi:[0,1]
	v_pk_mul_f32 v[122:123], v[130:131], v[122:123] op_sel_hi:[0,1]
	v_pk_mul_f32 v[124:125], v[130:131], v[124:125] op_sel_hi:[0,1]
	v_pk_mul_f32 v[126:127], v[130:131], v[126:127] op_sel_hi:[0,1]
	v_pk_mul_f32 v[112:113], v[112:113], v[192:193]
	v_pk_mul_f32 v[114:115], v[114:115], v[194:195]
	v_pk_mul_f32 v[116:117], v[116:117], v[196:197]
	v_pk_mul_f32 v[118:119], v[118:119], v[198:199]
	v_pk_mul_f32 v[120:121], v[120:121], v[200:201]
	v_pk_mul_f32 v[122:123], v[122:123], v[202:203]
	v_pk_mul_f32 v[124:125], v[124:125], v[204:205]
	v_pk_mul_f32 v[126:127], v[126:127], v[206:207]
	v_lshlrev_b32_e32 v28, 16, v44
	v_and_b32_e32 v29, 0xffff0000, v44
	v_lshlrev_b32_e32 v30, 16, v45
	v_and_b32_e32 v31, 0xffff0000, v45
	v_lshlrev_b32_e32 v32, 16, v46
	v_and_b32_e32 v33, 0xffff0000, v46
	v_lshlrev_b32_e32 v34, 16, v47
	v_and_b32_e32 v35, 0xffff0000, v47
	v_pk_fma_f32 v[112:113], v[54:55], v[28:29], v[112:113] op_sel_hi:[0,1,1]
	v_pk_fma_f32 v[114:115], v[54:55], v[30:31], v[114:115] op_sel_hi:[0,1,1]
	v_pk_fma_f32 v[116:117], v[54:55], v[32:33], v[116:117] op_sel_hi:[0,1,1]
	v_pk_fma_f32 v[118:119], v[54:55], v[34:35], v[118:119] op_sel_hi:[0,1,1]
	v_lshlrev_b32_e32 v28, 16, v48
	v_and_b32_e32 v29, 0xffff0000, v48
	v_lshlrev_b32_e32 v30, 16, v49
	v_and_b32_e32 v31, 0xffff0000, v49
	v_lshlrev_b32_e32 v32, 16, v50
	v_and_b32_e32 v33, 0xffff0000, v50
	v_lshlrev_b32_e32 v34, 16, v51
	v_and_b32_e32 v35, 0xffff0000, v51
	v_pk_fma_f32 v[120:121], v[54:55], v[28:29], v[120:121] op_sel_hi:[0,1,1]
	v_pk_fma_f32 v[122:123], v[54:55], v[30:31], v[122:123] op_sel_hi:[0,1,1]
	v_pk_fma_f32 v[124:125], v[54:55], v[32:33], v[124:125] op_sel_hi:[0,1,1]
	v_pk_fma_f32 v[126:127], v[54:55], v[34:35], v[126:127] op_sel_hi:[0,1,1]
	v_pk_mul_f32 v[134:135], v[112:113], v[112:113]
	v_pk_fma_f32 v[134:135], v[114:115], v[114:115], v[134:135]
	v_pk_fma_f32 v[134:135], v[116:117], v[116:117], v[134:135]
	v_pk_fma_f32 v[134:135], v[118:119], v[118:119], v[134:135]
	v_pk_fma_f32 v[134:135], v[120:121], v[120:121], v[134:135]
	v_pk_fma_f32 v[134:135], v[122:123], v[122:123], v[134:135]
	v_pk_fma_f32 v[134:135], v[124:125], v[124:125], v[134:135]
	v_pk_fma_f32 v[134:135], v[126:127], v[126:127], v[134:135]
	s_nop 0
	v_add_f32_e32 v134, v134, v135
	s_nop 1
	v_add_f32_dpp v132, v132, v132 quad_perm:[1,0,3,2] row_mask:0xf bank_mask:0xf
	v_add_f32_dpp v134, v134, v134 quad_perm:[1,0,3,2] row_mask:0xf bank_mask:0xf
	s_nop 0
	v_add_f32_dpp v132, v132, v132 quad_perm:[2,3,0,1] row_mask:0xf bank_mask:0xf
	v_add_f32_dpp v134, v134, v134 quad_perm:[2,3,0,1] row_mask:0xf bank_mask:0xf
	s_nop 0
	v_add_f32_dpp v132, v132, v132 row_half_mirror row_mask:0xf bank_mask:0xf
	v_add_f32_dpp v134, v134, v134 row_half_mirror row_mask:0xf bank_mask:0xf
	s_nop 0
	v_add_f32_dpp v132, v132, v132 row_mirror row_mask:0xf bank_mask:0xf
	v_add_f32_dpp v134, v134, v134 row_mirror row_mask:0xf bank_mask:0xf
	s_nop 0
	ds_bpermute_b32 v136, v187, v132
	ds_bpermute_b32 v137, v187, v134
	s_waitcnt lgkmcnt(0)
	v_add_f32_e32 v132, v132, v136
	v_add_f32_e32 v134, v134, v137
	ds_bpermute_b32 v136, v188, v132
	ds_bpermute_b32 v137, v188, v134
	s_waitcnt lgkmcnt(0)
	v_add_f32_e32 v132, v132, v136
	v_add_f32_e32 v134, v134, v137
	v_fmamk_f32 v164, v132, 0x3a800000, v138
	v_fmamk_f32 v167, v134, 0x3a800000, v138
	s_nop 0
	v_rsq_f32_e32 v132, v164
	v_rsq_f32_e32 v134, v167
	v_sqrt_f32_e32 v165, v164
	v_sqrt_f32_e32 v168, v167
	s_nop 1
	v_pk_mul_f32 v[140:141], v[96:97], v[132:133] op_sel_hi:[1,0]
	v_cvt_pk_bf16_f32 v148, v140, v141
	v_pk_mul_f32 v[142:143], v[98:99], v[132:133] op_sel_hi:[1,0]
	v_cvt_pk_bf16_f32 v149, v142, v143
	v_pk_mul_f32 v[144:145], v[100:101], v[132:133] op_sel_hi:[1,0]
	v_cvt_pk_bf16_f32 v150, v144, v145
	v_pk_mul_f32 v[146:147], v[102:103], v[132:133] op_sel_hi:[1,0]
	v_cvt_pk_bf16_f32 v151, v146, v147
	v_pk_mul_f32 v[140:141], v[104:105], v[132:133] op_sel_hi:[1,0]
	v_cvt_pk_bf16_f32 v152, v140, v141
	v_pk_mul_f32 v[142:143], v[106:107], v[132:133] op_sel_hi:[1,0]
	v_cvt_pk_bf16_f32 v153, v142, v143
	v_pk_mul_f32 v[144:145], v[108:109], v[132:133] op_sel_hi:[1,0]
	v_cvt_pk_bf16_f32 v154, v144, v145
	v_pk_mul_f32 v[146:147], v[110:111], v[132:133] op_sel_hi:[1,0]
	v_cvt_pk_bf16_f32 v155, v146, v147
	global_store_dwordx2 v173, v[148:149], s[98:99]
	global_store_dwordx2 v173, v[150:151], s[98:99] offset:512
	global_store_dwordx2 v173, v[152:153], s[98:99] offset:1024
	global_store_dwordx2 v173, v[154:155], s[98:99] offset:1536
	v_add_u32_e32 v173, 0xffc00000, v173
	v_pk_mul_f32 v[140:141], v[112:113], v[134:135] op_sel_hi:[1,0]
	v_cvt_pk_bf16_f32 v156, v140, v141
	v_pk_mul_f32 v[142:143], v[114:115], v[134:135] op_sel_hi:[1,0]
	v_cvt_pk_bf16_f32 v157, v142, v143
	v_pk_mul_f32 v[144:145], v[116:117], v[134:135] op_sel_hi:[1,0]
	v_cvt_pk_bf16_f32 v158, v144, v145
	v_pk_mul_f32 v[146:147], v[118:119], v[134:135] op_sel_hi:[1,0]
	v_cvt_pk_bf16_f32 v159, v146, v147
	v_pk_mul_f32 v[140:141], v[120:121], v[134:135] op_sel_hi:[1,0]
	v_cvt_pk_bf16_f32 v160, v140, v141
	v_pk_mul_f32 v[142:143], v[122:123], v[134:135] op_sel_hi:[1,0]
	v_cvt_pk_bf16_f32 v161, v142, v143
	v_pk_mul_f32 v[144:145], v[124:125], v[134:135] op_sel_hi:[1,0]
	v_cvt_pk_bf16_f32 v162, v144, v145
	v_pk_mul_f32 v[146:147], v[126:127], v[134:135] op_sel_hi:[1,0]
	v_cvt_pk_bf16_f32 v163, v146, v147
	global_store_dwordx2 v173, v[156:157], s[98:99]
	global_store_dwordx2 v173, v[158:159], s[98:99] offset:512
	global_store_dwordx2 v173, v[160:161], s[98:99] offset:1024
	global_store_dwordx2 v173, v[162:163], s[98:99] offset:1536
	v_add_u32_e32 v173, 0xffc00000, v173
	v_add_u32_e32 v166, -1, v165
	v_fma_f32 v140, -v166, v165, v164
	v_cmp_ge_f32_e32 vcc, 0, v140
	v_add_u32_e32 v141, 1, v165
	v_cndmask_b32_e32 v166, v165, v166, vcc
	v_fma_f32 v140, -v141, v165, v164
	v_cmp_lt_f32_e32 vcc, 0, v140
	s_nop 1
	v_cndmask_b32_e32 v165, v166, v141, vcc
	v_add_u32_e32 v169, -1, v168
	v_fma_f32 v142, -v169, v168, v167
	v_cmp_ge_f32_e32 vcc, 0, v142
	v_add_u32_e32 v143, 1, v168
	v_cndmask_b32_e32 v169, v168, v169, vcc
	v_fma_f32 v142, -v143, v168, v167
	v_cmp_lt_f32_e32 vcc, 0, v142
	s_nop 1
	v_cndmask_b32_e32 v168, v169, v143, vcc
	s_mov_b64 exec, 1
	global_store_dword v174, v165, s[98:99]
	v_add_u32_e32 v174, 0xffffe000, v174
	global_store_dword v174, v168, s[98:99]
	v_add_u32_e32 v174, 0xffffe000, v174
	s_mov_b64 exec, -1
	s_waitcnt vmcnt(23)
; __device__ __forceinline__ float ssq4(v4f v) { return (v.x * v.x + v.y * v.y) + (v.z * v.z + v.w * v.w); }
; template <int R, bool BASE_F32, bool OUT_F32>
; __device__ __forceinline__ void rows_res(const Ctx& C, int m0, int stride, int mx, const float* gpost, float scale, int lane) {
;     ...
;     for (int r = 0; r < R; ++r) { float s = 0.f;
; #pragma unroll
;         for (int j = 0; j < 4; ++j) s += ssq4(d[r][j]);
;         r1[r] = s; }
; #pragma unroll
;     for (int r = 0; r < R; ++r) r1[r] = rsqrtf(wave_sum(r1[r]) * (1.f / DM) + EPS) * scale;
; #pragma unroll
;     for (int j = 0; j < 4; ++j) { const v4f gp = ld4_f32(gpost + 4 * lane + 256 * j);
; #pragma unroll
;         for (int r = 0; r < R; ++r) d[r][j] = b[r][j] + d[r][j] * r1[r] * gp; }
	v_lshlrev_b32_e32 v96, 16, v56
	v_and_b32_e32 v97, 0xffff0000, v56
	v_lshlrev_b32_e32 v98, 16, v57
	v_and_b32_e32 v99, 0xffff0000, v57
	v_lshlrev_b32_e32 v100, 16, v58
	v_and_b32_e32 v101, 0xffff0000, v58
	v_lshlrev_b32_e32 v102, 16, v59
	v_and_b32_e32 v103, 0xffff0000, v59
	v_lshlrev_b32_e32 v104, 16, v60
	v_and_b32_e32 v105, 0xffff0000, v60
	v_lshlrev_b32_e32 v106, 16, v61
	v_and_b32_e32 v107, 0xffff0000, v61
	v_lshlrev_b32_e32 v108, 16, v62
	v_and_b32_e32 v109, 0xffff0000, v62
	v_lshlrev_b32_e32 v110, 16, v63
	v_and_b32_e32 v111, 0xffff0000, v63
	v_pk_mul_f32 v[128:129], v[96:97], v[96:97]
	v_pk_fma_f32 v[128:129], v[98:99], v[98:99], v[128:129]
	v_pk_fma_f32 v[128:129], v[100:101], v[100:101], v[128:129]
	v_pk_fma_f32 v[128:129], v[102:103], v[102:103], v[128:129]
	v_pk_fma_f32 v[128:129], v[104:105], v[104:105], v[128:129]
	v_pk_fma_f32 v[128:129], v[106:107], v[106:107], v[128:129]
	v_pk_fma_f32 v[128:129], v[108:109], v[108:109], v[128:129]
	v_pk_fma_f32 v[128:129], v[110:111], v[110:111], v[128:129]
	s_nop 0
	v_add_f32_e32 v128, v128, v129
	s_waitcnt vmcnt(14)
	v_lshlrev_b32_e32 v112, 16, v64
	v_and_b32_e32 v113, 0xffff0000, v64
	v_lshlrev_b32_e32 v114, 16, v65
	v_and_b32_e32 v115, 0xffff0000, v65
	v_lshlrev_b32_e32 v116, 16, v66
	v_and_b32_e32 v117, 0xffff0000, v66
	v_lshlrev_b32_e32 v118, 16, v67
	v_and_b32_e32 v119, 0xffff0000, v67
	v_lshlrev_b32_e32 v120, 16, v68
	v_and_b32_e32 v121, 0xffff0000, v68
	v_lshlrev_b32_e32 v122, 16, v69
	v_and_b32_e32 v123, 0xffff0000, v69
	v_lshlrev_b32_e32 v124, 16, v70
	v_and_b32_e32 v125, 0xffff0000, v70
	v_lshlrev_b32_e32 v126, 16, v71
	v_and_b32_e32 v127, 0xffff0000, v71
	v_pk_mul_f32 v[130:131], v[112:113], v[112:113]
	v_pk_fma_f32 v[130:131], v[114:115], v[114:115], v[130:131]
	v_pk_fma_f32 v[130:131], v[116:117], v[116:117], v[130:131]
	v_pk_fma_f32 v[130:131], v[118:119], v[118:119], v[130:131]
	v_pk_fma_f32 v[130:131], v[120:121], v[120:121], v[130:131]
	v_pk_fma_f32 v[130:131], v[122:123], v[122:123], v[130:131]
	v_pk_fma_f32 v[130:131], v[124:125], v[124:125], v[130:131]
	v_pk_fma_f32 v[130:131], v[126:127], v[126:127], v[130:131]
	s_nop 0
	v_add_f32_e32 v130, v130, v131
	s_nop 1
	v_add_f32_dpp v128, v128, v128 quad_perm:[1,0,3,2] row_mask:0xf bank_mask:0xf
	v_add_f32_dpp v130, v130, v130 quad_perm:[1,0,3,2] row_mask:0xf bank_mask:0xf
	s_nop 0
	v_add_f32_dpp v128, v128, v128 quad_perm:[2,3,0,1] row_mask:0xf bank_mask:0xf
	v_add_f32_dpp v130, v130, v130 quad_perm:[2,3,0,1] row_mask:0xf bank_mask:0xf
	s_nop 0
	v_add_f32_dpp v128, v128, v128 row_half_mirror row_mask:0xf bank_mask:0xf
	v_add_f32_dpp v130, v130, v130 row_half_mirror row_mask:0xf bank_mask:0xf
	s_nop 0
	v_add_f32_dpp v128, v128, v128 row_mirror row_mask:0xf bank_mask:0xf
	v_add_f32_dpp v130, v130, v130 row_mirror row_mask:0xf bank_mask:0xf
	s_nop 0
	ds_bpermute_b32 v136, v187, v128
	ds_bpermute_b32 v137, v187, v130
	s_waitcnt lgkmcnt(0)
	v_add_f32_e32 v128, v128, v136
	v_add_f32_e32 v130, v130, v137
	ds_bpermute_b32 v136, v188, v128
	ds_bpermute_b32 v137, v188, v130
	s_waitcnt lgkmcnt(0)
	v_add_f32_e32 v128, v128, v136
	v_add_f32_e32 v130, v130, v137
	v_fmamk_f32 v128, v128, 0x3a800000, v138
	v_fmamk_f32 v130, v130, 0x3a800000, v138
	s_nop 0
	v_rsq_f32_e32 v128, v128
	v_rsq_f32_e32 v130, v130
	s_nop 1
	s_waitcnt vmcnt(10)
	v_pk_mul_f32 v[96:97], v[128:129], v[96:97] op_sel_hi:[0,1]
	v_pk_mul_f32 v[98:99], v[128:129], v[98:99] op_sel_hi:[0,1]
	v_pk_mul_f32 v[100:101], v[128:129], v[100:101] op_sel_hi:[0,1]
	v_pk_mul_f32 v[102:103], v[128:129], v[102:103] op_sel_hi:[0,1]
	v_pk_mul_f32 v[104:105], v[128:129], v[104:105] op_sel_hi:[0,1]
	v_pk_mul_f32 v[106:107], v[128:129], v[106:107] op_sel_hi:[0,1]
	v_pk_mul_f32 v[108:109], v[128:129], v[108:109] op_sel_hi:[0,1]
	v_pk_mul_f32 v[110:111], v[128:129], v[110:111] op_sel_hi:[0,1]
	v_pk_mul_f32 v[96:97], v[96:97], v[192:193]
	v_pk_mul_f32 v[98:99], v[98:99], v[194:195]
	v_pk_mul_f32 v[100:101], v[100:101], v[196:197]
	v_pk_mul_f32 v[102:103], v[102:103], v[198:199]
	v_pk_mul_f32 v[104:105], v[104:105], v[200:201]
	v_pk_mul_f32 v[106:107], v[106:107], v[202:203]
	v_pk_mul_f32 v[108:109], v[108:109], v[204:205]
	v_pk_mul_f32 v[110:111], v[110:111], v[206:207]
	v_lshlrev_b32_e32 v56, 16, v72
	v_and_b32_e32 v57, 0xffff0000, v72
	v_lshlrev_b32_e32 v58, 16, v73
	v_and_b32_e32 v59, 0xffff0000, v73
	v_lshlrev_b32_e32 v60, 16, v74
	v_and_b32_e32 v61, 0xffff0000, v74
	v_lshlrev_b32_e32 v62, 16, v75
	v_and_b32_e32 v63, 0xffff0000, v75
	v_pk_fma_f32 v[96:97], v[88:89], v[56:57], v[96:97] op_sel_hi:[0,1,1]
	v_pk_fma_f32 v[98:99], v[88:89], v[58:59], v[98:99] op_sel_hi:[0,1,1]
	v_pk_fma_f32 v[100:101], v[88:89], v[60:61], v[100:101] op_sel_hi:[0,1,1]
	v_pk_fma_f32 v[102:103], v[88:89], v[62:63], v[102:103] op_sel_hi:[0,1,1]
	v_lshlrev_b32_e32 v56, 16, v76
	v_and_b32_e32 v57, 0xffff0000, v76
	v_lshlrev_b32_e32 v58, 16, v77
	v_and_b32_e32 v59, 0xffff0000, v77
	v_lshlrev_b32_e32 v60, 16, v78
	v_and_b32_e32 v61, 0xffff0000, v78
	v_lshlrev_b32_e32 v62, 16, v79
	v_and_b32_e32 v63, 0xffff0000, v79
	v_pk_fma_f32 v[104:105], v[88:89], v[56:57], v[104:105] op_sel_hi:[0,1,1]
	v_pk_fma_f32 v[106:107], v[88:89], v[58:59], v[106:107] op_sel_hi:[0,1,1]
	v_pk_fma_f32 v[108:109], v[88:89], v[60:61], v[108:109] op_sel_hi:[0,1,1]
	v_pk_fma_f32 v[110:111], v[88:89], v[62:63], v[110:111] op_sel_hi:[0,1,1]
	v_pk_mul_f32 v[132:133], v[96:97], v[96:97]
	v_pk_fma_f32 v[132:133], v[98:99], v[98:99], v[132:133]
	v_pk_fma_f32 v[132:133], v[100:101], v[100:101], v[132:133]
	v_pk_fma_f32 v[132:133], v[102:103], v[102:103], v[132:133]
	v_pk_fma_f32 v[132:133], v[104:105], v[104:105], v[132:133]
;     __device__ __forceinline__ float* out() const { return (float*)karg_in(33); }
; __device__ __forceinline__ void st4_bf16(bf16* p, v4f o) { v2u w; w.x = cvt_pk_nv(o.x, o.y); w.y = cvt_pk_nv(o.z, o.w); *(v2u*)p = w; }
; __device__ __forceinline__ float ssq4(v4f v) { return (v.x * v.x + v.y * v.y) + (v.z * v.z + v.w * v.w); }
; template <int R, bool BASE_F32, bool OUT_F32>
; __device__ __forceinline__ void rows_res(const Ctx& C, int m0, int stride, int mx, const float* gpost, float scale, int lane) {
;     ...
;         for (int r = 0; r < R; ++r) d[r][j] = b[r][j] + d[r][j] * r1[r] * gp; }
;     if (OUT_F32) { float* Y = C.out();
; #pragma unroll
;         for (int r = 0; r < R; ++r)
; #pragma unroll
;             for (int j = 0; j < 4; ++j) if (ok[r]) *(v4f*)(Y + (size_t)mr[r] * DM + 4 * lane + 256 * j) = d[r][j];
;     } else { float* rs = C.RS(); float t[R];
; #pragma unroll
;         for (int r = 0; r < R; ++r) { float s = 0.f;
; #pragma unroll
;             for (int j = 0; j < 4; ++j) s += ssq4(d[r][j]);
;             t[r] = s; }
; #pragma unroll
;         for (int r = 0; r < R; ++r) t[r] = wave_sum(t[r]) * (1.f / DM) + EPS;
; #pragma unroll
;         for (int r = 0; r < R; ++r) { const float rstd = rsqrtf(t[r]);
; #pragma unroll
;             for (int j = 0; j < 4; ++j) if (ok[r]) st4_bf16(XN + (size_t)mr[r] * DM + 4 * lane + 256 * j, d[r][j] * rstd);
;             if (lane == 0 && ok[r]) rs[mr[r]] = sqrtf(t[r]); }
	v_pk_fma_f32 v[132:133], v[106:107], v[106:107], v[132:133]
	v_pk_fma_f32 v[132:133], v[108:109], v[108:109], v[132:133]
	v_pk_fma_f32 v[132:133], v[110:111], v[110:111], v[132:133]
	s_nop 0
	v_add_f32_e32 v132, v132, v133
	v_pk_mul_f32 v[112:113], v[130:131], v[112:113] op_sel_hi:[0,1]
	v_pk_mul_f32 v[114:115], v[130:131], v[114:115] op_sel_hi:[0,1]
	v_pk_mul_f32 v[116:117], v[130:131], v[116:117] op_sel_hi:[0,1]
	v_pk_mul_f32 v[118:119], v[130:131], v[118:119] op_sel_hi:[0,1]
	v_pk_mul_f32 v[120:121], v[130:131], v[120:121] op_sel_hi:[0,1]
	v_pk_mul_f32 v[122:123], v[130:131], v[122:123] op_sel_hi:[0,1]
	v_pk_mul_f32 v[124:125], v[130:131], v[124:125] op_sel_hi:[0,1]
	v_pk_mul_f32 v[126:127], v[130:131], v[126:127] op_sel_hi:[0,1]
	v_pk_mul_f32 v[112:113], v[112:113], v[192:193]
	v_pk_mul_f32 v[114:115], v[114:115], v[194:195]
	v_pk_mul_f32 v[116:117], v[116:117], v[196:197]
	v_pk_mul_f32 v[118:119], v[118:119], v[198:199]
	v_pk_mul_f32 v[120:121], v[120:121], v[200:201]
	v_pk_mul_f32 v[122:123], v[122:123], v[202:203]
	v_pk_mul_f32 v[124:125], v[124:125], v[204:205]
	v_pk_mul_f32 v[126:127], v[126:127], v[206:207]
	v_lshlrev_b32_e32 v64, 16, v80
	v_and_b32_e32 v65, 0xffff0000, v80
	v_lshlrev_b32_e32 v66, 16, v81
	v_and_b32_e32 v67, 0xffff0000, v81
	v_lshlrev_b32_e32 v68, 16, v82
	v_and_b32_e32 v69, 0xffff0000, v82
	v_lshlrev_b32_e32 v70, 16, v83
	v_and_b32_e32 v71, 0xffff0000, v83
	v_pk_fma_f32 v[112:113], v[90:91], v[64:65], v[112:113] op_sel_hi:[0,1,1]
	v_pk_fma_f32 v[114:115], v[90:91], v[66:67], v[114:115] op_sel_hi:[0,1,1]
	v_pk_fma_f32 v[116:117], v[90:91], v[68:69], v[116:117] op_sel_hi:[0,1,1]
	v_pk_fma_f32 v[118:119], v[90:91], v[70:71], v[118:119] op_sel_hi:[0,1,1]
	v_lshlrev_b32_e32 v64, 16, v84
	v_and_b32_e32 v65, 0xffff0000, v84
	v_lshlrev_b32_e32 v66, 16, v85
	v_and_b32_e32 v67, 0xffff0000, v85
	v_lshlrev_b32_e32 v68, 16, v86
	v_and_b32_e32 v69, 0xffff0000, v86
	v_lshlrev_b32_e32 v70, 16, v87
	v_and_b32_e32 v71, 0xffff0000, v87
	v_pk_fma_f32 v[120:121], v[90:91], v[64:65], v[120:121] op_sel_hi:[0,1,1]
	v_pk_fma_f32 v[122:123], v[90:91], v[66:67], v[122:123] op_sel_hi:[0,1,1]
	v_pk_fma_f32 v[124:125], v[90:91], v[68:69], v[124:125] op_sel_hi:[0,1,1]
	v_pk_fma_f32 v[126:127], v[90:91], v[70:71], v[126:127] op_sel_hi:[0,1,1]
	v_pk_mul_f32 v[134:135], v[112:113], v[112:113]
	v_pk_fma_f32 v[134:135], v[114:115], v[114:115], v[134:135]
	v_pk_fma_f32 v[134:135], v[116:117], v[116:117], v[134:135]
	v_pk_fma_f32 v[134:135], v[118:119], v[118:119], v[134:135]
	v_pk_fma_f32 v[134:135], v[120:121], v[120:121], v[134:135]
	v_pk_fma_f32 v[134:135], v[122:123], v[122:123], v[134:135]
	v_pk_fma_f32 v[134:135], v[124:125], v[124:125], v[134:135]
	v_pk_fma_f32 v[134:135], v[126:127], v[126:127], v[134:135]
	s_nop 0
	v_add_f32_e32 v134, v134, v135
	s_nop 1
	v_add_f32_dpp v132, v132, v132 quad_perm:[1,0,3,2] row_mask:0xf bank_mask:0xf
	v_add_f32_dpp v134, v134, v134 quad_perm:[1,0,3,2] row_mask:0xf bank_mask:0xf
	s_nop 0
	v_add_f32_dpp v132, v132, v132 quad_perm:[2,3,0,1] row_mask:0xf bank_mask:0xf
	v_add_f32_dpp v134, v134, v134 quad_perm:[2,3,0,1] row_mask:0xf bank_mask:0xf
	s_nop 0
	v_add_f32_dpp v132, v132, v132 row_half_mirror row_mask:0xf bank_mask:0xf
	v_add_f32_dpp v134, v134, v134 row_half_mirror row_mask:0xf bank_mask:0xf
	s_nop 0
	v_add_f32_dpp v132, v132, v132 row_mirror row_mask:0xf bank_mask:0xf
	v_add_f32_dpp v134, v134, v134 row_mirror row_mask:0xf bank_mask:0xf
	s_nop 0
	ds_bpermute_b32 v136, v187, v132
	ds_bpermute_b32 v137, v187, v134
	s_waitcnt lgkmcnt(0)
	v_add_f32_e32 v132, v132, v136
	v_add_f32_e32 v134, v134, v137
	ds_bpermute_b32 v136, v188, v132
	ds_bpermute_b32 v137, v188, v134
	s_waitcnt lgkmcnt(0)
	v_add_f32_e32 v132, v132, v136
	v_add_f32_e32 v134, v134, v137
	v_fmamk_f32 v164, v132, 0x3a800000, v138
	v_fmamk_f32 v167, v134, 0x3a800000, v138
	s_nop 0
	v_rsq_f32_e32 v132, v164
	v_rsq_f32_e32 v134, v167
	v_sqrt_f32_e32 v165, v164
	v_sqrt_f32_e32 v168, v167
	s_nop 1
	v_pk_mul_f32 v[140:141], v[96:97], v[132:133] op_sel_hi:[1,0]
	v_cvt_pk_bf16_f32 v148, v140, v141
	v_pk_mul_f32 v[142:143], v[98:99], v[132:133] op_sel_hi:[1,0]
	v_cvt_pk_bf16_f32 v149, v142, v143
	v_pk_mul_f32 v[144:145], v[100:101], v[132:133] op_sel_hi:[1,0]
	v_cvt_pk_bf16_f32 v150, v144, v145
	v_pk_mul_f32 v[146:147], v[102:103], v[132:133] op_sel_hi:[1,0]
	v_cvt_pk_bf16_f32 v151, v146, v147
	v_pk_mul_f32 v[140:141], v[104:105], v[132:133] op_sel_hi:[1,0]
	v_cvt_pk_bf16_f32 v152, v140, v141
	v_pk_mul_f32 v[142:143], v[106:107], v[132:133] op_sel_hi:[1,0]
	v_cvt_pk_bf16_f32 v153, v142, v143
	v_pk_mul_f32 v[144:145], v[108:109], v[132:133] op_sel_hi:[1,0]
	v_cvt_pk_bf16_f32 v154, v144, v145
	v_pk_mul_f32 v[146:147], v[110:111], v[132:133] op_sel_hi:[1,0]
	v_cvt_pk_bf16_f32 v155, v146, v147
	global_store_dwordx2 v173, v[148:149], s[98:99]
	global_store_dwordx2 v173, v[150:151], s[98:99] offset:512
	global_store_dwordx2 v173, v[152:153], s[98:99] offset:1024
	global_store_dwordx2 v173, v[154:155], s[98:99] offset:1536
	v_add_u32_e32 v173, 0xffc00000, v173
	v_pk_mul_f32 v[140:141], v[112:113], v[134:135] op_sel_hi:[1,0]
	v_cvt_pk_bf16_f32 v156, v140, v141
	v_pk_mul_f32 v[142:143], v[114:115], v[134:135] op_sel_hi:[1,0]
	v_cvt_pk_bf16_f32 v157, v142, v143
	v_pk_mul_f32 v[144:145], v[116:117], v[134:135] op_sel_hi:[1,0]
	v_cvt_pk_bf16_f32 v158, v144, v145
	v_pk_mul_f32 v[146:147], v[118:119], v[134:135] op_sel_hi:[1,0]
	v_cvt_pk_bf16_f32 v159, v146, v147
	v_pk_mul_f32 v[140:141], v[120:121], v[134:135] op_sel_hi:[1,0]
	v_cvt_pk_bf16_f32 v160, v140, v141
	v_pk_mul_f32 v[142:143], v[122:123], v[134:135] op_sel_hi:[1,0]
	v_cvt_pk_bf16_f32 v161, v142, v143
	v_pk_mul_f32 v[144:145], v[124:125], v[134:135] op_sel_hi:[1,0]
	v_cvt_pk_bf16_f32 v162, v144, v145
	v_pk_mul_f32 v[146:147], v[126:127], v[134:135] op_sel_hi:[1,0]
	v_cvt_pk_bf16_f32 v163, v146, v147
	global_store_dwordx2 v173, v[156:157], s[98:99]
	global_store_dwordx2 v173, v[158:159], s[98:99] offset:512
	global_store_dwordx2 v173, v[160:161], s[98:99] offset:1024
	global_store_dwordx2 v173, v[162:163], s[98:99] offset:1536
	v_add_u32_e32 v173, 0xffc00000, v173
	v_add_u32_e32 v166, -1, v165
	v_fma_f32 v140, -v166, v165, v164
	v_cmp_ge_f32_e32 vcc, 0, v140
	v_add_u32_e32 v141, 1, v165
	v_cndmask_b32_e32 v166, v165, v166, vcc
	v_fma_f32 v140, -v141, v165, v164
	v_cmp_lt_f32_e32 vcc, 0, v140
	s_nop 1
	v_cndmask_b32_e32 v165, v166, v141, vcc
	v_add_u32_e32 v169, -1, v168
	v_fma_f32 v142, -v169, v168, v167
	v_cmp_ge_f32_e32 vcc, 0, v142
	v_add_u32_e32 v143, 1, v168
	v_cndmask_b32_e32 v169, v168, v169, vcc
	v_fma_f32 v142, -v143, v168, v167
	v_cmp_lt_f32_e32 vcc, 0, v142
	s_nop 1
	v_cndmask_b32_e32 v168, v169, v143, vcc
	s_mov_b64 exec, 1
	global_store_dword v174, v165, s[98:99]
	v_add_u32_e32 v174, 0xffffe000, v174
	global_store_dword v174, v168, s[98:99]
	v_add_u32_e32 v174, 0xffffe000, v174
	s_mov_b64 exec, -1
	s_branch .LBB0_1013
; __device__ __forceinline__ const float* xrow_ptr(const Ctx& C, int row) { return row < MPROMPT ? C.in(0) + (size_t)row * DM : C.in(1) + (size_t)(row - MPROMPT) * DM; }
; __device__ __forceinline__ v4f ld4_bf16(const bf16* p) { const v2u w = *(const v2u*)p; return (v4f){bf_lo(w.x), bf_hi(w.x), bf_lo(w.y), bf_hi(w.y)}; }
; template <int R, bool BASE_F32, bool OUT_F32>
; __device__ __forceinline__ void rows_res(const Ctx& C, int m0, int stride, int mx, const float* gpost, float scale, int lane) {
;     v4f d[R][4], b[R][4]; int mr[R]; bool ok[R]; float r1[R];
;     const bf16* D = C.D(); bf16* XN = C.XN();
; #pragma unroll
;     for (int r = 0; r < R; ++r) { mr[r] = (r == 4) ? mx : m0 + r * stride; ok[r] = (r == 4) ? (mx < M) : (mr[r] < MPROMPT); const int mm = ok[r] ? mr[r] : 0;
; #pragma unroll
;         for (int j = 0; j < 4; ++j) d[r][j] = ld4_bf16(D + (size_t)mm * DM + 4 * lane + 256 * j);
;         if (BASE_F32) { const float* x = xrow_ptr(C, mm);
; #pragma unroll
;             for (int j = 0; j < 4; ++j) b[r][j] = ld4_f32(x + 4 * lane + 256 * j);
;         } else { const float inv = C.RS()[mm];
; #pragma unroll
;             for (int j = 0; j < 4; ++j) b[r][j] = ld4_bf16(XN + (size_t)mm * DM + 4 * lane + 256 * j) * inv;
;         } }
	v_mov_b32_e32 v3, v1
	s_mov_b32 s0, 0x358637bd
	s_waitcnt lgkmcnt(0)
	v_lshl_add_u64 v[4:5], s[16:17], 0, v[2:3]
	s_mov_b64 s[18:19], 0x7100000
	s_mov_b64 s[20:21], 0x3000000
	v_mov_b32_e32 v3, 0x2a80000
	s_mov_b32 s22, 0x3a800000
	v_mov_b64_e32 v[6:7], s[0:1]
	s_mov_b32 s42, 0x800000
	v_mov_b32_e32 v41, 0x358637bd
	s_mov_b32 s43, 0xf800000
	v_mov_b32_e32 v148, 0x260
	s_mov_b32 s24, s23
	v_readlane_b32 s56, v232, 5
	s_branch .LBB0_997

;     __device__ __forceinline__ const float* in(int i) const { return karg_in(i); }
; __device__ __forceinline__ const float* xrow_ptr(const Ctx& C, int row) { return row < MPROMPT ? C.in(0) + (size_t)row * DM : C.in(1) + (size_t)(row - MPROMPT) * DM; }
; __device__ __forceinline__ v4f ld4_bf16(const bf16* p) { const v2u w = *(const v2u*)p; return (v4f){bf_lo(w.x), bf_hi(w.x), bf_lo(w.y), bf_hi(w.y)}; }
; __device__ __forceinline__ float ssq4(v4f v) { return (v.x * v.x + v.y * v.y) + (v.z * v.z + v.w * v.w); }
; #define FTID const int ftid_ = fresh_tid()
; template <int R, bool BASE_F32, bool OUT_F32>
; __device__ __forceinline__ void rows_res(const Ctx& C, int m0, int stride, int mx, const float* gpost, float scale, int lane) {
;     v4f d[R][4], b[R][4]; int mr[R]; bool ok[R]; float r1[R];
;     const bf16* D = C.D(); bf16* XN = C.XN();
; #pragma unroll
;     for (int r = 0; r < R; ++r) { mr[r] = (r == 4) ? mx : m0 + r * stride; ok[r] = (r == 4) ? (mx < M) : (mr[r] < MPROMPT); const int mm = ok[r] ? mr[r] : 0;
; #pragma unroll
;         for (int j = 0; j < 4; ++j) d[r][j] = ld4_bf16(D + (size_t)mm * DM + 4 * lane + 256 * j);
;         if (BASE_F32) { const float* x = xrow_ptr(C, mm);
; #pragma unroll
;             for (int j = 0; j < 4; ++j) b[r][j] = ld4_f32(x + 4 * lane + 256 * j);
;         } else { const float inv = C.RS()[mm];
; #pragma unroll
;             for (int j = 0; j < 4; ++j) b[r][j] = ld4_bf16(XN + (size_t)mm * DM + 4 * lane + 256 * j) * inv;
;         } }
; #pragma unroll
;     for (int r = 0; r < R; ++r) { float s = 0.f;
; #pragma unroll
;         for (int j = 0; j < 4; ++j) s += ssq4(d[r][j]);
;         r1[r] = s; }
; #pragma unroll
;     for (int r = 0; r < R; ++r) r1[r] = rsqrtf(wave_sum(r1[r]) * (1.f / DM) + EPS) * scale;
; __global__ void __launch_bounds__(NTHREADS, 2) fwd_kernel(Args args) {
;     ...
;     { FTID; const float* gp = C.in(32); { const int gw_ = GWV, ngw_ = NGWV, nit = (MPROMPT + 4 * ngw_ - 1) / (4 * ngw_);
;       for (int it = 0; it < nit - 1; ++it) rows_res<4, false, true>(C, gw_ + 4 * it * ngw_, ngw_, M, gp, 0.5f, LANE);
;       rows_res<5, false, true>(C, gw_ + 4 * (nit - 1) * ngw_, ngw_, MPROMPT + gw_, gp, 0.5f, LANE);
.LBB0_1272:
	s_or_b64 exec, exec, s[4:5]
	s_mov_b64 s[0:1], s[80:81]
	s_waitcnt lgkmcnt(0)
	s_barrier
	s_load_dwordx2 s[8:9], s[0:1], 0x100
	v_readfirstlane_b32 s0, v182
	v_lshlrev_b32_e32 v0, 2, v182
	s_ashr_i32 s26, s0, 6
	v_readlane_b32 s0, v232, 0
	v_and_b32_e32 v0, 0xfc, v0
	s_add_i32 s15, s26, s0
	v_mov_b32_e32 v17, 0
	s_and_b64 vcc, exec, s[6:7]
	v_lshlrev_b32_e32 v16, 2, v0
	v_lshlrev_b32_e32 v18, 1, v0
	s_load_dwordx2 s[98:99], s[80:81], 0x110
	s_load_dwordx2 s[100:101], s[80:81], 0x100
	v_and_b32_e32 v176, 63, v182
	v_lshlrev_b32_e32 v170, 3, v176
	s_lshl_b32 vcc_lo, s15, 11
	v_add_u32_e32 v170, vcc_lo, v170
	v_add_u32_e32 v171, 0x3000000, v170
	v_add_u32_e32 v170, 0x7100000, v170
	v_mov_b32_e32 v173, v171
	s_lshl_b32 vcc_lo, s15, 2
	v_mov_b32_e32 v172, 0x2a80000
	v_add_u32_e32 v172, vcc_lo, v172
	v_mov_b32_e32 v174, v172
	s_lshl_b32 vcc_lo, s15, 12
	v_lshlrev_b32_e32 v175, 4, v176
	v_add_u32_e32 v175, vcc_lo, v175
	v_lshlrev_b32_e32 v176, 4, v176
	v_mov_b32_e32 v138, 0x358637bd
	v_add_u32_e32 v170, 0x2c00000, v170
	v_add_u32_e32 v171, 0x2c00000, v171
	v_add_u32_e32 v173, 0x2c00000, v173
	v_add_u32_e32 v172, 0x16000, v172
	v_add_u32_e32 v174, 0x16000, v174
	v_add_u32_e32 v175, 0x5800000, v175
	s_waitcnt lgkmcnt(0)
	global_load_dwordx4 v[192:195], v176, s[100:101]
	global_load_dwordx4 v[196:199], v176, s[100:101] offset:1024
	global_load_dwordx4 v[200:203], v176, s[100:101] offset:2048
	global_load_dwordx4 v[204:207], v176, s[100:101] offset:3072
	s_load_dwordx2 s[100:101], s[80:81], 0x108
	global_load_dword v52, v172, s[98:99]
	global_load_dwordx2 v[20:21], v170, s[98:99]
	global_load_dwordx2 v[22:23], v170, s[98:99] offset:512
	global_load_dwordx2 v[24:25], v170, s[98:99] offset:1024
	global_load_dwordx2 v[26:27], v170, s[98:99] offset:1536
	global_load_dwordx2 v[36:37], v171, s[98:99]
	global_load_dwordx2 v[38:39], v171, s[98:99] offset:512
	global_load_dwordx2 v[40:41], v171, s[98:99] offset:1024
	global_load_dwordx2 v[42:43], v171, s[98:99] offset:1536
	v_add_u32_e32 v170, 0xffc00000, v170
	v_add_u32_e32 v171, 0xffc00000, v171
	v_add_u32_e32 v172, 0xffffe000, v172
	global_load_dword v54, v172, s[98:99]
	global_load_dwordx2 v[28:29], v170, s[98:99]
	global_load_dwordx2 v[30:31], v170, s[98:99] offset:512
	global_load_dwordx2 v[32:33], v170, s[98:99] offset:1024
	global_load_dwordx2 v[34:35], v170, s[98:99] offset:1536
	global_load_dwordx2 v[44:45], v171, s[98:99]
	global_load_dwordx2 v[46:47], v171, s[98:99] offset:512
	global_load_dwordx2 v[48:49], v171, s[98:99] offset:1024
	global_load_dwordx2 v[50:51], v171, s[98:99] offset:1536
	v_add_u32_e32 v170, 0xffc00000, v170
	v_add_u32_e32 v171, 0xffc00000, v171
	v_add_u32_e32 v172, 0xffffe000, v172
	global_load_dword v88, v172, s[98:99]
	global_load_dwordx2 v[56:57], v170, s[98:99]
	global_load_dwordx2 v[58:59], v170, s[98:99] offset:512
	global_load_dwordx2 v[60:61], v170, s[98:99] offset:1024
	global_load_dwordx2 v[62:63], v170, s[98:99] offset:1536
	global_load_dwordx2 v[72:73], v171, s[98:99]
	global_load_dwordx2 v[74:75], v171, s[98:99] offset:512
	global_load_dwordx2 v[76:77], v171, s[98:99] offset:1024
	global_load_dwordx2 v[78:79], v171, s[98:99] offset:1536
	v_add_u32_e32 v170, 0xffc00000, v170
	v_add_u32_e32 v171, 0xffc00000, v171
	v_add_u32_e32 v172, 0xffffe000, v172
	global_load_dword v90, v172, s[98:99]
	global_load_dwordx2 v[64:65], v170, s[98:99]
	global_load_dwordx2 v[66:67], v170, s[98:99] offset:512
	global_load_dwordx2 v[68:69], v170, s[98:99] offset:1024
	global_load_dwordx2 v[70:71], v170, s[98:99] offset:1536
	global_load_dwordx2 v[80:81], v171, s[98:99]
	global_load_dwordx2 v[82:83], v171, s[98:99] offset:512
	global_load_dwordx2 v[84:85], v171, s[98:99] offset:1024
	global_load_dwordx2 v[86:87], v171, s[98:99] offset:1536
	v_add_u32_e32 v170, 0xffc00000, v170
	v_add_u32_e32 v171, 0xffc00000, v171
	v_add_u32_e32 v172, 0xffffe000, v172
	s_waitcnt vmcnt(31)
	v_lshlrev_b32_e32 v96, 16, v20
	v_and_b32_e32 v97, 0xffff0000, v20
	v_lshlrev_b32_e32 v98, 16, v21
	v_and_b32_e32 v99, 0xffff0000, v21
	v_lshlrev_b32_e32 v100, 16, v22
	v_and_b32_e32 v101, 0xffff0000, v22
	v_lshlrev_b32_e32 v102, 16, v23
	v_and_b32_e32 v103, 0xffff0000, v23
	v_lshlrev_b32_e32 v104, 16, v24
	v_and_b32_e32 v105, 0xffff0000, v24
	v_lshlrev_b32_e32 v106, 16, v25
	v_and_b32_e32 v107, 0xffff0000, v25
	v_lshlrev_b32_e32 v108, 16, v26
	v_and_b32_e32 v109, 0xffff0000, v26
	v_lshlrev_b32_e32 v110, 16, v27
	v_and_b32_e32 v111, 0xffff0000, v27
	v_pk_mul_f32 v[128:129], v[96:97], v[96:97]
	v_pk_fma_f32 v[128:129], v[98:99], v[98:99], v[128:129]
	v_pk_fma_f32 v[128:129], v[100:101], v[100:101], v[128:129]
	v_pk_fma_f32 v[128:129], v[102:103], v[102:103], v[128:129]
	v_pk_fma_f32 v[128:129], v[104:105], v[104:105], v[128:129]
	v_pk_fma_f32 v[128:129], v[106:107], v[106:107], v[128:129]
	v_pk_fma_f32 v[128:129], v[108:109], v[108:109], v[128:129]
	v_pk_fma_f32 v[128:129], v[110:111], v[110:111], v[128:129]
	s_nop 0
	v_add_f32_e32 v128, v128, v129
	s_waitcnt vmcnt(22)
;     __device__ __forceinline__ float* out() const { return (float*)karg_in(33); }
; template <int R, bool BASE_F32, bool OUT_F32>
; __device__ __forceinline__ void rows_res(const Ctx& C, int m0, int stride, int mx, const float* gpost, float scale, int lane) {
;     ...
;     for (int r = 0; r < R; ++r) r1[r] = rsqrtf(wave_sum(r1[r]) * (1.f / DM) + EPS) * scale;
; #pragma unroll
;     for (int j = 0; j < 4; ++j) { const v4f gp = ld4_f32(gpost + 4 * lane + 256 * j);
; #pragma unroll
;         for (int r = 0; r < R; ++r) d[r][j] = b[r][j] + d[r][j] * r1[r] * gp; }
;     if (OUT_F32) { float* Y = C.out();
; #pragma unroll
;         for (int r = 0; r < R; ++r)
; #pragma unroll
;             for (int j = 0; j < 4; ++j) if (ok[r]) *(v4f*)(Y + (size_t)mr[r] * DM + 4 * lane + 256 * j) = d[r][j];
	v_lshlrev_b32_e32 v112, 16, v28
	v_and_b32_e32 v113, 0xffff0000, v28
	v_lshlrev_b32_e32 v114, 16, v29
	v_and_b32_e32 v115, 0xffff0000, v29
	v_lshlrev_b32_e32 v116, 16, v30
	v_and_b32_e32 v117, 0xffff0000, v30
	v_lshlrev_b32_e32 v118, 16, v31
	v_and_b32_e32 v119, 0xffff0000, v31
	v_lshlrev_b32_e32 v120, 16, v32
	v_and_b32_e32 v121, 0xffff0000, v32
	v_lshlrev_b32_e32 v122, 16, v33
	v_and_b32_e32 v123, 0xffff0000, v33
	v_lshlrev_b32_e32 v124, 16, v34
	v_and_b32_e32 v125, 0xffff0000, v34
	v_lshlrev_b32_e32 v126, 16, v35
	v_and_b32_e32 v127, 0xffff0000, v35
	v_pk_mul_f32 v[130:131], v[112:113], v[112:113]
	v_pk_fma_f32 v[130:131], v[114:115], v[114:115], v[130:131]
	v_pk_fma_f32 v[130:131], v[116:117], v[116:117], v[130:131]
	v_pk_fma_f32 v[130:131], v[118:119], v[118:119], v[130:131]
	v_pk_fma_f32 v[130:131], v[120:121], v[120:121], v[130:131]
	v_pk_fma_f32 v[130:131], v[122:123], v[122:123], v[130:131]
	v_pk_fma_f32 v[130:131], v[124:125], v[124:125], v[130:131]
	v_pk_fma_f32 v[130:131], v[126:127], v[126:127], v[130:131]
	s_nop 0
	v_add_f32_e32 v130, v130, v131
	s_nop 1
	v_add_f32_dpp v128, v128, v128 quad_perm:[1,0,3,2] row_mask:0xf bank_mask:0xf
	v_add_f32_dpp v130, v130, v130 quad_perm:[1,0,3,2] row_mask:0xf bank_mask:0xf
	s_nop 0
	v_add_f32_dpp v128, v128, v128 quad_perm:[2,3,0,1] row_mask:0xf bank_mask:0xf
	v_add_f32_dpp v130, v130, v130 quad_perm:[2,3,0,1] row_mask:0xf bank_mask:0xf
	s_nop 0
	v_add_f32_dpp v128, v128, v128 row_half_mirror row_mask:0xf bank_mask:0xf
	v_add_f32_dpp v130, v130, v130 row_half_mirror row_mask:0xf bank_mask:0xf
	s_nop 0
	v_add_f32_dpp v128, v128, v128 row_mirror row_mask:0xf bank_mask:0xf
	v_add_f32_dpp v130, v130, v130 row_mirror row_mask:0xf bank_mask:0xf
	s_nop 0
	ds_bpermute_b32 v136, v187, v128
	ds_bpermute_b32 v137, v187, v130
	s_waitcnt lgkmcnt(0)
	v_add_f32_e32 v128, v128, v136
	v_add_f32_e32 v130, v130, v137
	ds_bpermute_b32 v136, v188, v128
	ds_bpermute_b32 v137, v188, v130
	s_waitcnt lgkmcnt(0)
	v_add_f32_e32 v128, v128, v136
	v_add_f32_e32 v130, v130, v137
	v_fmamk_f32 v128, v128, 0x3a800000, v138
	v_fmamk_f32 v130, v130, 0x3a800000, v138
	s_nop 0
	v_rsq_f32_e32 v128, v128
	v_rsq_f32_e32 v130, v130
	s_nop 1
	v_mul_f32_e32 v128, 0.5, v128
	v_mul_f32_e32 v130, 0.5, v130
	s_waitcnt vmcnt(18)
	v_pk_mul_f32 v[96:97], v[128:129], v[96:97] op_sel_hi:[0,1]
	v_pk_mul_f32 v[98:99], v[128:129], v[98:99] op_sel_hi:[0,1]
	v_pk_mul_f32 v[100:101], v[128:129], v[100:101] op_sel_hi:[0,1]
	v_pk_mul_f32 v[102:103], v[128:129], v[102:103] op_sel_hi:[0,1]
	v_pk_mul_f32 v[104:105], v[128:129], v[104:105] op_sel_hi:[0,1]
	v_pk_mul_f32 v[106:107], v[128:129], v[106:107] op_sel_hi:[0,1]
	v_pk_mul_f32 v[108:109], v[128:129], v[108:109] op_sel_hi:[0,1]
	v_pk_mul_f32 v[110:111], v[128:129], v[110:111] op_sel_hi:[0,1]
	v_pk_mul_f32 v[96:97], v[96:97], v[192:193]
	v_pk_mul_f32 v[98:99], v[98:99], v[194:195]
	v_pk_mul_f32 v[100:101], v[100:101], v[196:197]
	v_pk_mul_f32 v[102:103], v[102:103], v[198:199]
	v_pk_mul_f32 v[104:105], v[104:105], v[200:201]
	v_pk_mul_f32 v[106:107], v[106:107], v[202:203]
	v_pk_mul_f32 v[108:109], v[108:109], v[204:205]
	v_pk_mul_f32 v[110:111], v[110:111], v[206:207]
	v_lshlrev_b32_e32 v20, 16, v36
	v_and_b32_e32 v21, 0xffff0000, v36
	v_lshlrev_b32_e32 v22, 16, v37
	v_and_b32_e32 v23, 0xffff0000, v37
	v_lshlrev_b32_e32 v24, 16, v38
	v_and_b32_e32 v25, 0xffff0000, v38
	v_lshlrev_b32_e32 v26, 16, v39
	v_and_b32_e32 v27, 0xffff0000, v39
	v_pk_fma_f32 v[96:97], v[52:53], v[20:21], v[96:97] op_sel_hi:[0,1,1]
	v_pk_fma_f32 v[98:99], v[52:53], v[22:23], v[98:99] op_sel_hi:[0,1,1]
	v_pk_fma_f32 v[100:101], v[52:53], v[24:25], v[100:101] op_sel_hi:[0,1,1]
	v_pk_fma_f32 v[102:103], v[52:53], v[26:27], v[102:103] op_sel_hi:[0,1,1]
	v_lshlrev_b32_e32 v20, 16, v40
	v_and_b32_e32 v21, 0xffff0000, v40
	v_lshlrev_b32_e32 v22, 16, v41
	v_and_b32_e32 v23, 0xffff0000, v41
	v_lshlrev_b32_e32 v24, 16, v42
	v_and_b32_e32 v25, 0xffff0000, v42
	v_lshlrev_b32_e32 v26, 16, v43
	v_and_b32_e32 v27, 0xffff0000, v43
	v_pk_fma_f32 v[104:105], v[52:53], v[20:21], v[104:105] op_sel_hi:[0,1,1]
	v_pk_fma_f32 v[106:107], v[52:53], v[22:23], v[106:107] op_sel_hi:[0,1,1]
	v_pk_fma_f32 v[108:109], v[52:53], v[24:25], v[108:109] op_sel_hi:[0,1,1]
	v_pk_fma_f32 v[110:111], v[52:53], v[26:27], v[110:111] op_sel_hi:[0,1,1]
	global_store_dwordx4 v175, v[96:99], s[100:101]
	global_store_dwordx4 v175, v[100:103], s[100:101] offset:1024
	global_store_dwordx4 v175, v[104:107], s[100:101] offset:2048
	global_store_dwordx4 v175, v[108:111], s[100:101] offset:3072
	v_add_u32_e32 v175, 0xff800000, v175
	v_pk_mul_f32 v[112:113], v[130:131], v[112:113] op_sel_hi:[0,1]
	v_pk_mul_f32 v[114:115], v[130:131], v[114:115] op_sel_hi:[0,1]
	v_pk_mul_f32 v[116:117], v[130:131], v[116:117] op_sel_hi:[0,1]
	v_pk_mul_f32 v[118:119], v[130:131], v[118:119] op_sel_hi:[0,1]
	v_pk_mul_f32 v[120:121], v[130:131], v[120:121] op_sel_hi:[0,1]
	v_pk_mul_f32 v[122:123], v[130:131], v[122:123] op_sel_hi:[0,1]
	v_pk_mul_f32 v[124:125], v[130:131], v[124:125] op_sel_hi:[0,1]
	v_pk_mul_f32 v[126:127], v[130:131], v[126:127] op_sel_hi:[0,1]
	v_pk_mul_f32 v[112:113], v[112:113], v[192:193]
	v_pk_mul_f32 v[114:115], v[114:115], v[194:195]
	v_pk_mul_f32 v[116:117], v[116:117], v[196:197]
	v_pk_mul_f32 v[118:119], v[118:119], v[198:199]
	v_pk_mul_f32 v[120:121], v[120:121], v[200:201]
	v_pk_mul_f32 v[122:123], v[122:123], v[202:203]
	v_pk_mul_f32 v[124:125], v[124:125], v[204:205]
	v_pk_mul_f32 v[126:127], v[126:127], v[206:207]
	v_lshlrev_b32_e32 v28, 16, v44
	v_and_b32_e32 v29, 0xffff0000, v44
	v_lshlrev_b32_e32 v30, 16, v45
	v_and_b32_e32 v31, 0xffff0000, v45
;     __device__ __forceinline__ float* out() const { return (float*)karg_in(33); }
; __device__ __forceinline__ const float* xrow_ptr(const Ctx& C, int row) { return row < MPROMPT ? C.in(0) + (size_t)row * DM : C.in(1) + (size_t)(row - MPROMPT) * DM; }
; __device__ __forceinline__ v4f ld4_bf16(const bf16* p) { const v2u w = *(const v2u*)p; return (v4f){bf_lo(w.x), bf_hi(w.x), bf_lo(w.y), bf_hi(w.y)}; }
; __device__ __forceinline__ float ssq4(v4f v) { return (v.x * v.x + v.y * v.y) + (v.z * v.z + v.w * v.w); }
; template <int R, bool BASE_F32, bool OUT_F32>
; __device__ __forceinline__ void rows_res(const Ctx& C, int m0, int stride, int mx, const float* gpost, float scale, int lane) {
;     ...
;     for (int r = 0; r < R; ++r) { mr[r] = (r == 4) ? mx : m0 + r * stride; ok[r] = (r == 4) ? (mx < M) : (mr[r] < MPROMPT); const int mm = ok[r] ? mr[r] : 0;
; #pragma unroll
;         for (int j = 0; j < 4; ++j) d[r][j] = ld4_bf16(D + (size_t)mm * DM + 4 * lane + 256 * j);
;         if (BASE_F32) { const float* x = xrow_ptr(C, mm);
; #pragma unroll
;             for (int j = 0; j < 4; ++j) b[r][j] = ld4_f32(x + 4 * lane + 256 * j);
;         } else { const float inv = C.RS()[mm];
; #pragma unroll
;             for (int j = 0; j < 4; ++j) b[r][j] = ld4_bf16(XN + (size_t)mm * DM + 4 * lane + 256 * j) * inv;
;         } }
; #pragma unroll
;     for (int r = 0; r < R; ++r) { float s = 0.f;
; #pragma unroll
;         for (int j = 0; j < 4; ++j) s += ssq4(d[r][j]);
;         r1[r] = s; }
;     ...
;     for (int j = 0; j < 4; ++j) { const v4f gp = ld4_f32(gpost + 4 * lane + 256 * j);
; #pragma unroll
;         for (int r = 0; r < R; ++r) d[r][j] = b[r][j] + d[r][j] * r1[r] * gp; }
;     if (OUT_F32) { float* Y = C.out();
; #pragma unroll
;         for (int r = 0; r < R; ++r)
; #pragma unroll
;             for (int j = 0; j < 4; ++j) if (ok[r]) *(v4f*)(Y + (size_t)mr[r] * DM + 4 * lane + 256 * j) = d[r][j];
	v_lshlrev_b32_e32 v32, 16, v46
	v_and_b32_e32 v33, 0xffff0000, v46
	v_lshlrev_b32_e32 v34, 16, v47
	v_and_b32_e32 v35, 0xffff0000, v47
	v_pk_fma_f32 v[112:113], v[54:55], v[28:29], v[112:113] op_sel_hi:[0,1,1]
	v_pk_fma_f32 v[114:115], v[54:55], v[30:31], v[114:115] op_sel_hi:[0,1,1]
	v_pk_fma_f32 v[116:117], v[54:55], v[32:33], v[116:117] op_sel_hi:[0,1,1]
	v_pk_fma_f32 v[118:119], v[54:55], v[34:35], v[118:119] op_sel_hi:[0,1,1]
	v_lshlrev_b32_e32 v28, 16, v48
	v_and_b32_e32 v29, 0xffff0000, v48
	v_lshlrev_b32_e32 v30, 16, v49
	v_and_b32_e32 v31, 0xffff0000, v49
	v_lshlrev_b32_e32 v32, 16, v50
	v_and_b32_e32 v33, 0xffff0000, v50
	v_lshlrev_b32_e32 v34, 16, v51
	v_and_b32_e32 v35, 0xffff0000, v51
	v_pk_fma_f32 v[120:121], v[54:55], v[28:29], v[120:121] op_sel_hi:[0,1,1]
	v_pk_fma_f32 v[122:123], v[54:55], v[30:31], v[122:123] op_sel_hi:[0,1,1]
	v_pk_fma_f32 v[124:125], v[54:55], v[32:33], v[124:125] op_sel_hi:[0,1,1]
	v_pk_fma_f32 v[126:127], v[54:55], v[34:35], v[126:127] op_sel_hi:[0,1,1]
	global_store_dwordx4 v175, v[112:115], s[100:101]
	global_store_dwordx4 v175, v[116:119], s[100:101] offset:1024
	global_store_dwordx4 v175, v[120:123], s[100:101] offset:2048
	global_store_dwordx4 v175, v[124:127], s[100:101] offset:3072
	v_add_u32_e32 v175, 0xff800000, v175
	global_load_dword v52, v172, s[98:99]
	global_load_dwordx2 v[20:21], v170, s[98:99]
	global_load_dwordx2 v[22:23], v170, s[98:99] offset:512
	global_load_dwordx2 v[24:25], v170, s[98:99] offset:1024
	global_load_dwordx2 v[26:27], v170, s[98:99] offset:1536
	global_load_dwordx2 v[36:37], v171, s[98:99]
	global_load_dwordx2 v[38:39], v171, s[98:99] offset:512
	global_load_dwordx2 v[40:41], v171, s[98:99] offset:1024
	global_load_dwordx2 v[42:43], v171, s[98:99] offset:1536
	v_add_u32_e32 v170, 0xffc00000, v170
	v_add_u32_e32 v171, 0xffc00000, v171
	v_add_u32_e32 v172, 0xffffe000, v172
	global_load_dword v54, v172, s[98:99]
	global_load_dwordx2 v[28:29], v170, s[98:99]
	global_load_dwordx2 v[30:31], v170, s[98:99] offset:512
	global_load_dwordx2 v[32:33], v170, s[98:99] offset:1024
	global_load_dwordx2 v[34:35], v170, s[98:99] offset:1536
	global_load_dwordx2 v[44:45], v171, s[98:99]
	global_load_dwordx2 v[46:47], v171, s[98:99] offset:512
	global_load_dwordx2 v[48:49], v171, s[98:99] offset:1024
	global_load_dwordx2 v[50:51], v171, s[98:99] offset:1536
	v_add_u32_e32 v170, 0xffc00000, v170
	v_add_u32_e32 v171, 0xffc00000, v171
	v_add_u32_e32 v172, 0xffffe000, v172
	s_waitcnt vmcnt(39)
	v_lshlrev_b32_e32 v96, 16, v56
	v_and_b32_e32 v97, 0xffff0000, v56
	v_lshlrev_b32_e32 v98, 16, v57
	v_and_b32_e32 v99, 0xffff0000, v57
	v_lshlrev_b32_e32 v100, 16, v58
	v_and_b32_e32 v101, 0xffff0000, v58
	v_lshlrev_b32_e32 v102, 16, v59
	v_and_b32_e32 v103, 0xffff0000, v59
	v_lshlrev_b32_e32 v104, 16, v60
	v_and_b32_e32 v105, 0xffff0000, v60
	v_lshlrev_b32_e32 v106, 16, v61
	v_and_b32_e32 v107, 0xffff0000, v61
	v_lshlrev_b32_e32 v108, 16, v62
	v_and_b32_e32 v109, 0xffff0000, v62
	v_lshlrev_b32_e32 v110, 16, v63
	v_and_b32_e32 v111, 0xffff0000, v63
	v_pk_mul_f32 v[128:129], v[96:97], v[96:97]
	v_pk_fma_f32 v[128:129], v[98:99], v[98:99], v[128:129]
	v_pk_fma_f32 v[128:129], v[100:101], v[100:101], v[128:129]
	v_pk_fma_f32 v[128:129], v[102:103], v[102:103], v[128:129]
	v_pk_fma_f32 v[128:129], v[104:105], v[104:105], v[128:129]
	v_pk_fma_f32 v[128:129], v[106:107], v[106:107], v[128:129]
	v_pk_fma_f32 v[128:129], v[108:109], v[108:109], v[128:129]
	v_pk_fma_f32 v[128:129], v[110:111], v[110:111], v[128:129]
	s_nop 0
	v_add_f32_e32 v128, v128, v129
	s_waitcnt vmcnt(30)
	v_lshlrev_b32_e32 v112, 16, v64
	v_and_b32_e32 v113, 0xffff0000, v64
	v_lshlrev_b32_e32 v114, 16, v65
	v_and_b32_e32 v115, 0xffff0000, v65
	v_lshlrev_b32_e32 v116, 16, v66
	v_and_b32_e32 v117, 0xffff0000, v66
	v_lshlrev_b32_e32 v118, 16, v67
	v_and_b32_e32 v119, 0xffff0000, v67
	v_lshlrev_b32_e32 v120, 16, v68
	v_and_b32_e32 v121, 0xffff0000, v68
	v_lshlrev_b32_e32 v122, 16, v69
	v_and_b32_e32 v123, 0xffff0000, v69
	v_lshlrev_b32_e32 v124, 16, v70
	v_and_b32_e32 v125, 0xffff0000, v70
	v_lshlrev_b32_e32 v126, 16, v71
	v_and_b32_e32 v127, 0xffff0000, v71
	v_pk_mul_f32 v[130:131], v[112:113], v[112:113]
	v_pk_fma_f32 v[130:131], v[114:115], v[114:115], v[130:131]
	v_pk_fma_f32 v[130:131], v[116:117], v[116:117], v[130:131]
	v_pk_fma_f32 v[130:131], v[118:119], v[118:119], v[130:131]
	v_pk_fma_f32 v[130:131], v[120:121], v[120:121], v[130:131]
	v_pk_fma_f32 v[130:131], v[122:123], v[122:123], v[130:131]
	v_pk_fma_f32 v[130:131], v[124:125], v[124:125], v[130:131]
	v_pk_fma_f32 v[130:131], v[126:127], v[126:127], v[130:131]
	s_nop 0
	v_add_f32_e32 v130, v130, v131
	s_nop 1
	v_add_f32_dpp v128, v128, v128 quad_perm:[1,0,3,2] row_mask:0xf bank_mask:0xf
	v_add_f32_dpp v130, v130, v130 quad_perm:[1,0,3,2] row_mask:0xf bank_mask:0xf
	s_nop 0
	v_add_f32_dpp v128, v128, v128 quad_perm:[2,3,0,1] row_mask:0xf bank_mask:0xf
	v_add_f32_dpp v130, v130, v130 quad_perm:[2,3,0,1] row_mask:0xf bank_mask:0xf
	s_nop 0
	v_add_f32_dpp v128, v128, v128 row_half_mirror row_mask:0xf bank_mask:0xf
	v_add_f32_dpp v130, v130, v130 row_half_mirror row_mask:0xf bank_mask:0xf
	s_nop 0
	v_add_f32_dpp v128, v128, v128 row_mirror row_mask:0xf bank_mask:0xf
	v_add_f32_dpp v130, v130, v130 row_mirror row_mask:0xf bank_mask:0xf
	s_nop 0
	ds_bpermute_b32 v136, v187, v128
	ds_bpermute_b32 v137, v187, v130
	s_waitcnt lgkmcnt(0)
	v_add_f32_e32 v128, v128, v136
	v_add_f32_e32 v130, v130, v137
	ds_bpermute_b32 v136, v188, v128
	ds_bpermute_b32 v137, v188, v130
	s_waitcnt lgkmcnt(0)
;     __device__ __forceinline__ float* out() const { return (float*)karg_in(33); }
; template <int R, bool BASE_F32, bool OUT_F32>
; __device__ __forceinline__ void rows_res(const Ctx& C, int m0, int stride, int mx, const float* gpost, float scale, int lane) {
;     ...
;     for (int r = 0; r < R; ++r) r1[r] = rsqrtf(wave_sum(r1[r]) * (1.f / DM) + EPS) * scale;
; #pragma unroll
;     for (int j = 0; j < 4; ++j) { const v4f gp = ld4_f32(gpost + 4 * lane + 256 * j);
; #pragma unroll
;         for (int r = 0; r < R; ++r) d[r][j] = b[r][j] + d[r][j] * r1[r] * gp; }
;     if (OUT_F32) { float* Y = C.out();
; #pragma unroll
;         for (int r = 0; r < R; ++r)
; #pragma unroll
;             for (int j = 0; j < 4; ++j) if (ok[r]) *(v4f*)(Y + (size_t)mr[r] * DM + 4 * lane + 256 * j) = d[r][j];
	v_add_f32_e32 v128, v128, v136
	v_add_f32_e32 v130, v130, v137
	v_fmamk_f32 v128, v128, 0x3a800000, v138
	v_fmamk_f32 v130, v130, 0x3a800000, v138
	s_nop 0
	v_rsq_f32_e32 v128, v128
	v_rsq_f32_e32 v130, v130
	s_nop 1
	v_mul_f32_e32 v128, 0.5, v128
	v_mul_f32_e32 v130, 0.5, v130
	s_waitcnt vmcnt(26)
	v_pk_mul_f32 v[96:97], v[128:129], v[96:97] op_sel_hi:[0,1]
	v_pk_mul_f32 v[98:99], v[128:129], v[98:99] op_sel_hi:[0,1]
	v_pk_mul_f32 v[100:101], v[128:129], v[100:101] op_sel_hi:[0,1]
	v_pk_mul_f32 v[102:103], v[128:129], v[102:103] op_sel_hi:[0,1]
	v_pk_mul_f32 v[104:105], v[128:129], v[104:105] op_sel_hi:[0,1]
	v_pk_mul_f32 v[106:107], v[128:129], v[106:107] op_sel_hi:[0,1]
	v_pk_mul_f32 v[108:109], v[128:129], v[108:109] op_sel_hi:[0,1]
	v_pk_mul_f32 v[110:111], v[128:129], v[110:111] op_sel_hi:[0,1]
	v_pk_mul_f32 v[96:97], v[96:97], v[192:193]
	v_pk_mul_f32 v[98:99], v[98:99], v[194:195]
	v_pk_mul_f32 v[100:101], v[100:101], v[196:197]
	v_pk_mul_f32 v[102:103], v[102:103], v[198:199]
	v_pk_mul_f32 v[104:105], v[104:105], v[200:201]
	v_pk_mul_f32 v[106:107], v[106:107], v[202:203]
	v_pk_mul_f32 v[108:109], v[108:109], v[204:205]
	v_pk_mul_f32 v[110:111], v[110:111], v[206:207]
	v_lshlrev_b32_e32 v56, 16, v72
	v_and_b32_e32 v57, 0xffff0000, v72
	v_lshlrev_b32_e32 v58, 16, v73
	v_and_b32_e32 v59, 0xffff0000, v73
	v_lshlrev_b32_e32 v60, 16, v74
	v_and_b32_e32 v61, 0xffff0000, v74
	v_lshlrev_b32_e32 v62, 16, v75
	v_and_b32_e32 v63, 0xffff0000, v75
	v_pk_fma_f32 v[96:97], v[88:89], v[56:57], v[96:97] op_sel_hi:[0,1,1]
	v_pk_fma_f32 v[98:99], v[88:89], v[58:59], v[98:99] op_sel_hi:[0,1,1]
	v_pk_fma_f32 v[100:101], v[88:89], v[60:61], v[100:101] op_sel_hi:[0,1,1]
	v_pk_fma_f32 v[102:103], v[88:89], v[62:63], v[102:103] op_sel_hi:[0,1,1]
	v_lshlrev_b32_e32 v56, 16, v76
	v_and_b32_e32 v57, 0xffff0000, v76
	v_lshlrev_b32_e32 v58, 16, v77
	v_and_b32_e32 v59, 0xffff0000, v77
	v_lshlrev_b32_e32 v60, 16, v78
	v_and_b32_e32 v61, 0xffff0000, v78
	v_lshlrev_b32_e32 v62, 16, v79
	v_and_b32_e32 v63, 0xffff0000, v79
	v_pk_fma_f32 v[104:105], v[88:89], v[56:57], v[104:105] op_sel_hi:[0,1,1]
	v_pk_fma_f32 v[106:107], v[88:89], v[58:59], v[106:107] op_sel_hi:[0,1,1]
	v_pk_fma_f32 v[108:109], v[88:89], v[60:61], v[108:109] op_sel_hi:[0,1,1]
	v_pk_fma_f32 v[110:111], v[88:89], v[62:63], v[110:111] op_sel_hi:[0,1,1]
	global_store_dwordx4 v175, v[96:99], s[100:101]
	global_store_dwordx4 v175, v[100:103], s[100:101] offset:1024
	global_store_dwordx4 v175, v[104:107], s[100:101] offset:2048
	global_store_dwordx4 v175, v[108:111], s[100:101] offset:3072
	v_add_u32_e32 v175, 0xff800000, v175
	v_pk_mul_f32 v[112:113], v[130:131], v[112:113] op_sel_hi:[0,1]
	v_pk_mul_f32 v[114:115], v[130:131], v[114:115] op_sel_hi:[0,1]
	v_pk_mul_f32 v[116:117], v[130:131], v[116:117] op_sel_hi:[0,1]
	v_pk_mul_f32 v[118:119], v[130:131], v[118:119] op_sel_hi:[0,1]
	v_pk_mul_f32 v[120:121], v[130:131], v[120:121] op_sel_hi:[0,1]
	v_pk_mul_f32 v[122:123], v[130:131], v[122:123] op_sel_hi:[0,1]
	v_pk_mul_f32 v[124:125], v[130:131], v[124:125] op_sel_hi:[0,1]
	v_pk_mul_f32 v[126:127], v[130:131], v[126:127] op_sel_hi:[0,1]
	v_pk_mul_f32 v[112:113], v[112:113], v[192:193]
	v_pk_mul_f32 v[114:115], v[114:115], v[194:195]
	v_pk_mul_f32 v[116:117], v[116:117], v[196:197]
	v_pk_mul_f32 v[118:119], v[118:119], v[198:199]
	v_pk_mul_f32 v[120:121], v[120:121], v[200:201]
	v_pk_mul_f32 v[122:123], v[122:123], v[202:203]
	v_pk_mul_f32 v[124:125], v[124:125], v[204:205]
	v_pk_mul_f32 v[126:127], v[126:127], v[206:207]
	v_lshlrev_b32_e32 v64, 16, v80
	v_and_b32_e32 v65, 0xffff0000, v80
	v_lshlrev_b32_e32 v66, 16, v81
	v_and_b32_e32 v67, 0xffff0000, v81
	v_lshlrev_b32_e32 v68, 16, v82
	v_and_b32_e32 v69, 0xffff0000, v82
	v_lshlrev_b32_e32 v70, 16, v83
	v_and_b32_e32 v71, 0xffff0000, v83
	v_pk_fma_f32 v[112:113], v[90:91], v[64:65], v[112:113] op_sel_hi:[0,1,1]
	v_pk_fma_f32 v[114:115], v[90:91], v[66:67], v[114:115] op_sel_hi:[0,1,1]
	v_pk_fma_f32 v[116:117], v[90:91], v[68:69], v[116:117] op_sel_hi:[0,1,1]
	v_pk_fma_f32 v[118:119], v[90:91], v[70:71], v[118:119] op_sel_hi:[0,1,1]
	v_lshlrev_b32_e32 v64, 16, v84
	v_and_b32_e32 v65, 0xffff0000, v84
	v_lshlrev_b32_e32 v66, 16, v85
	v_and_b32_e32 v67, 0xffff0000, v85
	v_lshlrev_b32_e32 v68, 16, v86
	v_and_b32_e32 v69, 0xffff0000, v86
	v_lshlrev_b32_e32 v70, 16, v87
	v_and_b32_e32 v71, 0xffff0000, v87
	v_pk_fma_f32 v[120:121], v[90:91], v[64:65], v[120:121] op_sel_hi:[0,1,1]
	v_pk_fma_f32 v[122:123], v[90:91], v[66:67], v[122:123] op_sel_hi:[0,1,1]
	v_pk_fma_f32 v[124:125], v[90:91], v[68:69], v[124:125] op_sel_hi:[0,1,1]
	v_pk_fma_f32 v[126:127], v[90:91], v[70:71], v[126:127] op_sel_hi:[0,1,1]
	global_store_dwordx4 v175, v[112:115], s[100:101]
	global_store_dwordx4 v175, v[116:119], s[100:101] offset:1024
	global_store_dwordx4 v175, v[120:123], s[100:101] offset:2048
	global_store_dwordx4 v175, v[124:127], s[100:101] offset:3072
	v_add_u32_e32 v175, 0xff800000, v175
	global_load_dword v88, v172, s[98:99]
	global_load_dwordx2 v[56:57], v170, s[98:99]
	global_load_dwordx2 v[58:59], v170, s[98:99] offset:512
	global_load_dwordx2 v[60:61], v170, s[98:99] offset:1024
	global_load_dwordx2 v[62:63], v170, s[98:99] offset:1536
	global_load_dwordx2 v[72:73], v171, s[98:99]
	global_load_dwordx2 v[74:75], v171, s[98:99] offset:512
	global_load_dwordx2 v[76:77], v171, s[98:99] offset:1024
	global_load_dwordx2 v[78:79], v171, s[98:99] offset:1536
	v_add_u32_e32 v170, 0xffc00000, v170
	v_add_u32_e32 v171, 0xffc00000, v171
	v_add_u32_e32 v172, 0xffffe000, v172
	global_load_dword v90, v172, s[98:99]
	global_load_dwordx2 v[64:65], v170, s[98:99]
	global_load_dwordx2 v[66:67], v170, s[98:99] offset:512
	global_load_dwordx2 v[68:69], v170, s[98:99] offset:1024
	global_load_dwordx2 v[70:71], v170, s[98:99] offset:1536
	global_load_dwordx2 v[80:81], v171, s[98:99]
	global_load_dwordx2 v[82:83], v171, s[98:99] offset:512
	global_load_dwordx2 v[84:85], v171, s[98:99] offset:1024
	global_load_dwordx2 v[86:87], v171, s[98:99] offset:1536
	v_add_u32_e32 v170, 0xffc00000, v170
	v_add_u32_e32 v171, 0xffc00000, v171
	v_add_u32_e32 v172, 0xffffe000, v172
	s_waitcnt vmcnt(39)
;     __device__ __forceinline__ float* out() const { return (float*)karg_in(33); }
; __device__ __forceinline__ float ssq4(v4f v) { return (v.x * v.x + v.y * v.y) + (v.z * v.z + v.w * v.w); }
; template <int R, bool BASE_F32, bool OUT_F32>
; __device__ __forceinline__ void rows_res(const Ctx& C, int m0, int stride, int mx, const float* gpost, float scale, int lane) {
;     ...
;     for (int r = 0; r < R; ++r) { float s = 0.f;
; #pragma unroll
;         for (int j = 0; j < 4; ++j) s += ssq4(d[r][j]);
;         r1[r] = s; }
; #pragma unroll
;     for (int r = 0; r < R; ++r) r1[r] = rsqrtf(wave_sum(r1[r]) * (1.f / DM) + EPS) * scale;
; #pragma unroll
;     for (int j = 0; j < 4; ++j) { const v4f gp = ld4_f32(gpost + 4 * lane + 256 * j);
; #pragma unroll
;         for (int r = 0; r < R; ++r) d[r][j] = b[r][j] + d[r][j] * r1[r] * gp; }
;     if (OUT_F32) { float* Y = C.out();
; #pragma unroll
;         for (int r = 0; r < R; ++r)
; #pragma unroll
;             for (int j = 0; j < 4; ++j) if (ok[r]) *(v4f*)(Y + (size_t)mr[r] * DM + 4 * lane + 256 * j) = d[r][j];
	v_lshlrev_b32_e32 v96, 16, v20
	v_and_b32_e32 v97, 0xffff0000, v20
	v_lshlrev_b32_e32 v98, 16, v21
	v_and_b32_e32 v99, 0xffff0000, v21
	v_lshlrev_b32_e32 v100, 16, v22
	v_and_b32_e32 v101, 0xffff0000, v22
	v_lshlrev_b32_e32 v102, 16, v23
	v_and_b32_e32 v103, 0xffff0000, v23
	v_lshlrev_b32_e32 v104, 16, v24
	v_and_b32_e32 v105, 0xffff0000, v24
	v_lshlrev_b32_e32 v106, 16, v25
	v_and_b32_e32 v107, 0xffff0000, v25
	v_lshlrev_b32_e32 v108, 16, v26
	v_and_b32_e32 v109, 0xffff0000, v26
	v_lshlrev_b32_e32 v110, 16, v27
	v_and_b32_e32 v111, 0xffff0000, v27
	v_pk_mul_f32 v[128:129], v[96:97], v[96:97]
	v_pk_fma_f32 v[128:129], v[98:99], v[98:99], v[128:129]
	v_pk_fma_f32 v[128:129], v[100:101], v[100:101], v[128:129]
	v_pk_fma_f32 v[128:129], v[102:103], v[102:103], v[128:129]
	v_pk_fma_f32 v[128:129], v[104:105], v[104:105], v[128:129]
	v_pk_fma_f32 v[128:129], v[106:107], v[106:107], v[128:129]
	v_pk_fma_f32 v[128:129], v[108:109], v[108:109], v[128:129]
	v_pk_fma_f32 v[128:129], v[110:111], v[110:111], v[128:129]
	s_nop 0
	v_add_f32_e32 v128, v128, v129
	s_waitcnt vmcnt(30)
	v_lshlrev_b32_e32 v112, 16, v28
	v_and_b32_e32 v113, 0xffff0000, v28
	v_lshlrev_b32_e32 v114, 16, v29
	v_and_b32_e32 v115, 0xffff0000, v29
	v_lshlrev_b32_e32 v116, 16, v30
	v_and_b32_e32 v117, 0xffff0000, v30
	v_lshlrev_b32_e32 v118, 16, v31
	v_and_b32_e32 v119, 0xffff0000, v31
	v_lshlrev_b32_e32 v120, 16, v32
	v_and_b32_e32 v121, 0xffff0000, v32
	v_lshlrev_b32_e32 v122, 16, v33
	v_and_b32_e32 v123, 0xffff0000, v33
	v_lshlrev_b32_e32 v124, 16, v34
	v_and_b32_e32 v125, 0xffff0000, v34
	v_lshlrev_b32_e32 v126, 16, v35
	v_and_b32_e32 v127, 0xffff0000, v35
	v_pk_mul_f32 v[130:131], v[112:113], v[112:113]
	v_pk_fma_f32 v[130:131], v[114:115], v[114:115], v[130:131]
	v_pk_fma_f32 v[130:131], v[116:117], v[116:117], v[130:131]
	v_pk_fma_f32 v[130:131], v[118:119], v[118:119], v[130:131]
	v_pk_fma_f32 v[130:131], v[120:121], v[120:121], v[130:131]
	v_pk_fma_f32 v[130:131], v[122:123], v[122:123], v[130:131]
	v_pk_fma_f32 v[130:131], v[124:125], v[124:125], v[130:131]
	v_pk_fma_f32 v[130:131], v[126:127], v[126:127], v[130:131]
	s_nop 0
	v_add_f32_e32 v130, v130, v131
	s_nop 1
	v_add_f32_dpp v128, v128, v128 quad_perm:[1,0,3,2] row_mask:0xf bank_mask:0xf
	v_add_f32_dpp v130, v130, v130 quad_perm:[1,0,3,2] row_mask:0xf bank_mask:0xf
	s_nop 0
	v_add_f32_dpp v128, v128, v128 quad_perm:[2,3,0,1] row_mask:0xf bank_mask:0xf
	v_add_f32_dpp v130, v130, v130 quad_perm:[2,3,0,1] row_mask:0xf bank_mask:0xf
	s_nop 0
	v_add_f32_dpp v128, v128, v128 row_half_mirror row_mask:0xf bank_mask:0xf
	v_add_f32_dpp v130, v130, v130 row_half_mirror row_mask:0xf bank_mask:0xf
	s_nop 0
	v_add_f32_dpp v128, v128, v128 row_mirror row_mask:0xf bank_mask:0xf
	v_add_f32_dpp v130, v130, v130 row_mirror row_mask:0xf bank_mask:0xf
	s_nop 0
	ds_bpermute_b32 v136, v187, v128
	ds_bpermute_b32 v137, v187, v130
	s_waitcnt lgkmcnt(0)
	v_add_f32_e32 v128, v128, v136
	v_add_f32_e32 v130, v130, v137
	ds_bpermute_b32 v136, v188, v128
	ds_bpermute_b32 v137, v188, v130
	s_waitcnt lgkmcnt(0)
	v_add_f32_e32 v128, v128, v136
	v_add_f32_e32 v130, v130, v137
	v_fmamk_f32 v128, v128, 0x3a800000, v138
	v_fmamk_f32 v130, v130, 0x3a800000, v138
	s_nop 0
	v_rsq_f32_e32 v128, v128
	v_rsq_f32_e32 v130, v130
	s_nop 1
	v_mul_f32_e32 v128, 0.5, v128
	v_mul_f32_e32 v130, 0.5, v130
	s_waitcnt vmcnt(26)
	v_pk_mul_f32 v[96:97], v[128:129], v[96:97] op_sel_hi:[0,1]
	v_pk_mul_f32 v[98:99], v[128:129], v[98:99] op_sel_hi:[0,1]
	v_pk_mul_f32 v[100:101], v[128:129], v[100:101] op_sel_hi:[0,1]
	v_pk_mul_f32 v[102:103], v[128:129], v[102:103] op_sel_hi:[0,1]
	v_pk_mul_f32 v[104:105], v[128:129], v[104:105] op_sel_hi:[0,1]
	v_pk_mul_f32 v[106:107], v[128:129], v[106:107] op_sel_hi:[0,1]
	v_pk_mul_f32 v[108:109], v[128:129], v[108:109] op_sel_hi:[0,1]
	v_pk_mul_f32 v[110:111], v[128:129], v[110:111] op_sel_hi:[0,1]
	v_pk_mul_f32 v[96:97], v[96:97], v[192:193]
	v_pk_mul_f32 v[98:99], v[98:99], v[194:195]
	v_pk_mul_f32 v[100:101], v[100:101], v[196:197]
	v_pk_mul_f32 v[102:103], v[102:103], v[198:199]
	v_pk_mul_f32 v[104:105], v[104:105], v[200:201]
	v_pk_mul_f32 v[106:107], v[106:107], v[202:203]
	v_pk_mul_f32 v[108:109], v[108:109], v[204:205]
	v_pk_mul_f32 v[110:111], v[110:111], v[206:207]
	v_lshlrev_b32_e32 v20, 16, v36
	v_and_b32_e32 v21, 0xffff0000, v36
	v_lshlrev_b32_e32 v22, 16, v37
	v_and_b32_e32 v23, 0xffff0000, v37
	v_lshlrev_b32_e32 v24, 16, v38
	v_and_b32_e32 v25, 0xffff0000, v38
	v_lshlrev_b32_e32 v26, 16, v39
	v_and_b32_e32 v27, 0xffff0000, v39
	v_pk_fma_f32 v[96:97], v[52:53], v[20:21], v[96:97] op_sel_hi:[0,1,1]
	v_pk_fma_f32 v[98:99], v[52:53], v[22:23], v[98:99] op_sel_hi:[0,1,1]
	v_pk_fma_f32 v[100:101], v[52:53], v[24:25], v[100:101] op_sel_hi:[0,1,1]
	v_pk_fma_f32 v[102:103], v[52:53], v[26:27], v[102:103] op_sel_hi:[0,1,1]
	v_lshlrev_b32_e32 v20, 16, v40
	v_and_b32_e32 v21, 0xffff0000, v40
	v_lshlrev_b32_e32 v22, 16, v41
	v_and_b32_e32 v23, 0xffff0000, v41
	v_lshlrev_b32_e32 v24, 16, v42
	v_and_b32_e32 v25, 0xffff0000, v42
	v_lshlrev_b32_e32 v26, 16, v43
	v_and_b32_e32 v27, 0xffff0000, v43
	v_pk_fma_f32 v[104:105], v[52:53], v[20:21], v[104:105] op_sel_hi:[0,1,1]
	v_pk_fma_f32 v[106:107], v[52:53], v[22:23], v[106:107] op_sel_hi:[0,1,1]
	v_pk_fma_f32 v[108:109], v[52:53], v[24:25], v[108:109] op_sel_hi:[0,1,1]
	v_pk_fma_f32 v[110:111], v[52:53], v[26:27], v[110:111] op_sel_hi:[0,1,1]
	global_store_dwordx4 v175, v[96:99], s[100:101]
	global_store_dwordx4 v175, v[100:103], s[100:101] offset:1024
	global_store_dwordx4 v175, v[104:107], s[100:101] offset:2048
	global_store_dwordx4 v175, v[108:111], s[100:101] offset:3072
;     __device__ __forceinline__ float* out() const { return (float*)karg_in(33); }
; __device__ __forceinline__ const float* xrow_ptr(const Ctx& C, int row) { return row < MPROMPT ? C.in(0) + (size_t)row * DM : C.in(1) + (size_t)(row - MPROMPT) * DM; }
; __device__ __forceinline__ v4f ld4_bf16(const bf16* p) { const v2u w = *(const v2u*)p; return (v4f){bf_lo(w.x), bf_hi(w.x), bf_lo(w.y), bf_hi(w.y)}; }
; __device__ __forceinline__ float ssq4(v4f v) { return (v.x * v.x + v.y * v.y) + (v.z * v.z + v.w * v.w); }
; template <int R, bool BASE_F32, bool OUT_F32>
; __device__ __forceinline__ void rows_res(const Ctx& C, int m0, int stride, int mx, const float* gpost, float scale, int lane) {
;     ...
;     for (int r = 0; r < R; ++r) { mr[r] = (r == 4) ? mx : m0 + r * stride; ok[r] = (r == 4) ? (mx < M) : (mr[r] < MPROMPT); const int mm = ok[r] ? mr[r] : 0;
; #pragma unroll
;         for (int j = 0; j < 4; ++j) d[r][j] = ld4_bf16(D + (size_t)mm * DM + 4 * lane + 256 * j);
;         if (BASE_F32) { const float* x = xrow_ptr(C, mm);
; #pragma unroll
;             for (int j = 0; j < 4; ++j) b[r][j] = ld4_f32(x + 4 * lane + 256 * j);
;         } else { const float inv = C.RS()[mm];
; #pragma unroll
;             for (int j = 0; j < 4; ++j) b[r][j] = ld4_bf16(XN + (size_t)mm * DM + 4 * lane + 256 * j) * inv;
;         } }
; #pragma unroll
;     for (int r = 0; r < R; ++r) { float s = 0.f;
; #pragma unroll
;         for (int j = 0; j < 4; ++j) s += ssq4(d[r][j]);
;         r1[r] = s; }
;     ...
;     for (int j = 0; j < 4; ++j) { const v4f gp = ld4_f32(gpost + 4 * lane + 256 * j);
; #pragma unroll
;         for (int r = 0; r < R; ++r) d[r][j] = b[r][j] + d[r][j] * r1[r] * gp; }
;     if (OUT_F32) { float* Y = C.out();
; #pragma unroll
;         for (int r = 0; r < R; ++r)
; #pragma unroll
;             for (int j = 0; j < 4; ++j) if (ok[r]) *(v4f*)(Y + (size_t)mr[r] * DM + 4 * lane + 256 * j) = d[r][j];
	v_add_u32_e32 v175, 0xff800000, v175
	v_pk_mul_f32 v[112:113], v[130:131], v[112:113] op_sel_hi:[0,1]
	v_pk_mul_f32 v[114:115], v[130:131], v[114:115] op_sel_hi:[0,1]
	v_pk_mul_f32 v[116:117], v[130:131], v[116:117] op_sel_hi:[0,1]
	v_pk_mul_f32 v[118:119], v[130:131], v[118:119] op_sel_hi:[0,1]
	v_pk_mul_f32 v[120:121], v[130:131], v[120:121] op_sel_hi:[0,1]
	v_pk_mul_f32 v[122:123], v[130:131], v[122:123] op_sel_hi:[0,1]
	v_pk_mul_f32 v[124:125], v[130:131], v[124:125] op_sel_hi:[0,1]
	v_pk_mul_f32 v[126:127], v[130:131], v[126:127] op_sel_hi:[0,1]
	v_pk_mul_f32 v[112:113], v[112:113], v[192:193]
	v_pk_mul_f32 v[114:115], v[114:115], v[194:195]
	v_pk_mul_f32 v[116:117], v[116:117], v[196:197]
	v_pk_mul_f32 v[118:119], v[118:119], v[198:199]
	v_pk_mul_f32 v[120:121], v[120:121], v[200:201]
	v_pk_mul_f32 v[122:123], v[122:123], v[202:203]
	v_pk_mul_f32 v[124:125], v[124:125], v[204:205]
	v_pk_mul_f32 v[126:127], v[126:127], v[206:207]
	v_lshlrev_b32_e32 v28, 16, v44
	v_and_b32_e32 v29, 0xffff0000, v44
	v_lshlrev_b32_e32 v30, 16, v45
	v_and_b32_e32 v31, 0xffff0000, v45
	v_lshlrev_b32_e32 v32, 16, v46
	v_and_b32_e32 v33, 0xffff0000, v46
	v_lshlrev_b32_e32 v34, 16, v47
	v_and_b32_e32 v35, 0xffff0000, v47
	v_pk_fma_f32 v[112:113], v[54:55], v[28:29], v[112:113] op_sel_hi:[0,1,1]
	v_pk_fma_f32 v[114:115], v[54:55], v[30:31], v[114:115] op_sel_hi:[0,1,1]
	v_pk_fma_f32 v[116:117], v[54:55], v[32:33], v[116:117] op_sel_hi:[0,1,1]
	v_pk_fma_f32 v[118:119], v[54:55], v[34:35], v[118:119] op_sel_hi:[0,1,1]
	v_lshlrev_b32_e32 v28, 16, v48
	v_and_b32_e32 v29, 0xffff0000, v48
	v_lshlrev_b32_e32 v30, 16, v49
	v_and_b32_e32 v31, 0xffff0000, v49
	v_lshlrev_b32_e32 v32, 16, v50
	v_and_b32_e32 v33, 0xffff0000, v50
	v_lshlrev_b32_e32 v34, 16, v51
	v_and_b32_e32 v35, 0xffff0000, v51
	v_pk_fma_f32 v[120:121], v[54:55], v[28:29], v[120:121] op_sel_hi:[0,1,1]
	v_pk_fma_f32 v[122:123], v[54:55], v[30:31], v[122:123] op_sel_hi:[0,1,1]
	v_pk_fma_f32 v[124:125], v[54:55], v[32:33], v[124:125] op_sel_hi:[0,1,1]
	v_pk_fma_f32 v[126:127], v[54:55], v[34:35], v[126:127] op_sel_hi:[0,1,1]
	global_store_dwordx4 v175, v[112:115], s[100:101]
	global_store_dwordx4 v175, v[116:119], s[100:101] offset:1024
	global_store_dwordx4 v175, v[120:123], s[100:101] offset:2048
	global_store_dwordx4 v175, v[124:127], s[100:101] offset:3072
	v_add_u32_e32 v175, 0xff800000, v175
	global_load_dword v52, v172, s[98:99]
	global_load_dwordx2 v[20:21], v170, s[98:99]
	global_load_dwordx2 v[22:23], v170, s[98:99] offset:512
	global_load_dwordx2 v[24:25], v170, s[98:99] offset:1024
	global_load_dwordx2 v[26:27], v170, s[98:99] offset:1536
	global_load_dwordx2 v[36:37], v171, s[98:99]
	global_load_dwordx2 v[38:39], v171, s[98:99] offset:512
	global_load_dwordx2 v[40:41], v171, s[98:99] offset:1024
	global_load_dwordx2 v[42:43], v171, s[98:99] offset:1536
	v_add_u32_e32 v170, 0xffc00000, v170
	v_add_u32_e32 v171, 0xffc00000, v171
	v_add_u32_e32 v172, 0xffffe000, v172
	global_load_dword v54, v172, s[98:99]
	global_load_dwordx2 v[28:29], v170, s[98:99]
	global_load_dwordx2 v[30:31], v170, s[98:99] offset:512
	global_load_dwordx2 v[32:33], v170, s[98:99] offset:1024
	global_load_dwordx2 v[34:35], v170, s[98:99] offset:1536
	global_load_dwordx2 v[44:45], v171, s[98:99]
	global_load_dwordx2 v[46:47], v171, s[98:99] offset:512
	global_load_dwordx2 v[48:49], v171, s[98:99] offset:1024
	global_load_dwordx2 v[50:51], v171, s[98:99] offset:1536
	v_add_u32_e32 v170, 0xffc00000, v170
	v_add_u32_e32 v171, 0xffc00000, v171
	v_add_u32_e32 v172, 0xffffe000, v172
	s_waitcnt vmcnt(39)
	v_lshlrev_b32_e32 v96, 16, v56
	v_and_b32_e32 v97, 0xffff0000, v56
	v_lshlrev_b32_e32 v98, 16, v57
	v_and_b32_e32 v99, 0xffff0000, v57
	v_lshlrev_b32_e32 v100, 16, v58
	v_and_b32_e32 v101, 0xffff0000, v58
	v_lshlrev_b32_e32 v102, 16, v59
	v_and_b32_e32 v103, 0xffff0000, v59
	v_lshlrev_b32_e32 v104, 16, v60
	v_and_b32_e32 v105, 0xffff0000, v60
	v_lshlrev_b32_e32 v106, 16, v61
	v_and_b32_e32 v107, 0xffff0000, v61
	v_lshlrev_b32_e32 v108, 16, v62
	v_and_b32_e32 v109, 0xffff0000, v62
	v_lshlrev_b32_e32 v110, 16, v63
	v_and_b32_e32 v111, 0xffff0000, v63
	v_pk_mul_f32 v[128:129], v[96:97], v[96:97]
	v_pk_fma_f32 v[128:129], v[98:99], v[98:99], v[128:129]
	v_pk_fma_f32 v[128:129], v[100:101], v[100:101], v[128:129]
	v_pk_fma_f32 v[128:129], v[102:103], v[102:103], v[128:129]
	v_pk_fma_f32 v[128:129], v[104:105], v[104:105], v[128:129]
	v_pk_fma_f32 v[128:129], v[106:107], v[106:107], v[128:129]
	v_pk_fma_f32 v[128:129], v[108:109], v[108:109], v[128:129]
	v_pk_fma_f32 v[128:129], v[110:111], v[110:111], v[128:129]
	s_nop 0
	v_add_f32_e32 v128, v128, v129
	s_waitcnt vmcnt(30)
	v_lshlrev_b32_e32 v112, 16, v64
	v_and_b32_e32 v113, 0xffff0000, v64
	v_lshlrev_b32_e32 v114, 16, v65
	v_and_b32_e32 v115, 0xffff0000, v65
	v_lshlrev_b32_e32 v116, 16, v66
	v_and_b32_e32 v117, 0xffff0000, v66
	v_lshlrev_b32_e32 v118, 16, v67
	v_and_b32_e32 v119, 0xffff0000, v67
	v_lshlrev_b32_e32 v120, 16, v68
	v_and_b32_e32 v121, 0xffff0000, v68
	v_lshlrev_b32_e32 v122, 16, v69
	v_and_b32_e32 v123, 0xffff0000, v69
	v_lshlrev_b32_e32 v124, 16, v70
	v_and_b32_e32 v125, 0xffff0000, v70
	v_lshlrev_b32_e32 v126, 16, v71
	v_and_b32_e32 v127, 0xffff0000, v71
	v_pk_mul_f32 v[130:131], v[112:113], v[112:113]
	v_pk_fma_f32 v[130:131], v[114:115], v[114:115], v[130:131]
	v_pk_fma_f32 v[130:131], v[116:117], v[116:117], v[130:131]
	v_pk_fma_f32 v[130:131], v[118:119], v[118:119], v[130:131]
	v_pk_fma_f32 v[130:131], v[120:121], v[120:121], v[130:131]
	v_pk_fma_f32 v[130:131], v[122:123], v[122:123], v[130:131]
	v_pk_fma_f32 v[130:131], v[124:125], v[124:125], v[130:131]
	v_pk_fma_f32 v[130:131], v[126:127], v[126:127], v[130:131]
	s_nop 0
	v_add_f32_e32 v130, v130, v131
	s_nop 1
	v_add_f32_dpp v128, v128, v128 quad_perm:[1,0,3,2] row_mask:0xf bank_mask:0xf
	v_add_f32_dpp v130, v130, v130 quad_perm:[1,0,3,2] row_mask:0xf bank_mask:0xf
	s_nop 0
	v_add_f32_dpp v128, v128, v128 quad_perm:[2,3,0,1] row_mask:0xf bank_mask:0xf
	v_add_f32_dpp v130, v130, v130 quad_perm:[2,3,0,1] row_mask:0xf bank_mask:0xf
	s_nop 0
	v_add_f32_dpp v128, v128, v128 row_half_mirror row_mask:0xf bank_mask:0xf
	v_add_f32_dpp v130, v130, v130 row_half_mirror row_mask:0xf bank_mask:0xf
	s_nop 0
	v_add_f32_dpp v128, v128, v128 row_mirror row_mask:0xf bank_mask:0xf
	v_add_f32_dpp v130, v130, v130 row_mirror row_mask:0xf bank_mask:0xf
	s_nop 0
	ds_bpermute_b32 v136, v187, v128
	ds_bpermute_b32 v137, v187, v130
	s_waitcnt lgkmcnt(0)
;     __device__ __forceinline__ float* out() const { return (float*)karg_in(33); }
; __device__ __forceinline__ const float* xrow_ptr(const Ctx& C, int row) { return row < MPROMPT ? C.in(0) + (size_t)row * DM : C.in(1) + (size_t)(row - MPROMPT) * DM; }
; __device__ __forceinline__ v4f ld4_bf16(const bf16* p) { const v2u w = *(const v2u*)p; return (v4f){bf_lo(w.x), bf_hi(w.x), bf_lo(w.y), bf_hi(w.y)}; }
; template <int R, bool BASE_F32, bool OUT_F32>
; __device__ __forceinline__ void rows_res(const Ctx& C, int m0, int stride, int mx, const float* gpost, float scale, int lane) {
;     ...
;     for (int r = 0; r < R; ++r) { mr[r] = (r == 4) ? mx : m0 + r * stride; ok[r] = (r == 4) ? (mx < M) : (mr[r] < MPROMPT); const int mm = ok[r] ? mr[r] : 0;
; #pragma unroll
;         for (int j = 0; j < 4; ++j) d[r][j] = ld4_bf16(D + (size_t)mm * DM + 4 * lane + 256 * j);
;         if (BASE_F32) { const float* x = xrow_ptr(C, mm);
; #pragma unroll
;             for (int j = 0; j < 4; ++j) b[r][j] = ld4_f32(x + 4 * lane + 256 * j);
;         } else { const float inv = C.RS()[mm];
; #pragma unroll
;             for (int j = 0; j < 4; ++j) b[r][j] = ld4_bf16(XN + (size_t)mm * DM + 4 * lane + 256 * j) * inv;
;         } }
;     ...
;     for (int r = 0; r < R; ++r) r1[r] = rsqrtf(wave_sum(r1[r]) * (1.f / DM) + EPS) * scale;
; #pragma unroll
;     for (int j = 0; j < 4; ++j) { const v4f gp = ld4_f32(gpost + 4 * lane + 256 * j);
; #pragma unroll
;         for (int r = 0; r < R; ++r) d[r][j] = b[r][j] + d[r][j] * r1[r] * gp; }
;     if (OUT_F32) { float* Y = C.out();
; #pragma unroll
;         for (int r = 0; r < R; ++r)
; #pragma unroll
;             for (int j = 0; j < 4; ++j) if (ok[r]) *(v4f*)(Y + (size_t)mr[r] * DM + 4 * lane + 256 * j) = d[r][j];
	v_add_f32_e32 v128, v128, v136
	v_add_f32_e32 v130, v130, v137
	ds_bpermute_b32 v136, v188, v128
	ds_bpermute_b32 v137, v188, v130
	s_waitcnt lgkmcnt(0)
	v_add_f32_e32 v128, v128, v136
	v_add_f32_e32 v130, v130, v137
	v_fmamk_f32 v128, v128, 0x3a800000, v138
	v_fmamk_f32 v130, v130, 0x3a800000, v138
	s_nop 0
	v_rsq_f32_e32 v128, v128
	v_rsq_f32_e32 v130, v130
	s_nop 1
	v_mul_f32_e32 v128, 0.5, v128
	v_mul_f32_e32 v130, 0.5, v130
	s_waitcnt vmcnt(26)
	v_pk_mul_f32 v[96:97], v[128:129], v[96:97] op_sel_hi:[0,1]
	v_pk_mul_f32 v[98:99], v[128:129], v[98:99] op_sel_hi:[0,1]
	v_pk_mul_f32 v[100:101], v[128:129], v[100:101] op_sel_hi:[0,1]
	v_pk_mul_f32 v[102:103], v[128:129], v[102:103] op_sel_hi:[0,1]
	v_pk_mul_f32 v[104:105], v[128:129], v[104:105] op_sel_hi:[0,1]
	v_pk_mul_f32 v[106:107], v[128:129], v[106:107] op_sel_hi:[0,1]
	v_pk_mul_f32 v[108:109], v[128:129], v[108:109] op_sel_hi:[0,1]
	v_pk_mul_f32 v[110:111], v[128:129], v[110:111] op_sel_hi:[0,1]
	v_pk_mul_f32 v[96:97], v[96:97], v[192:193]
	v_pk_mul_f32 v[98:99], v[98:99], v[194:195]
	v_pk_mul_f32 v[100:101], v[100:101], v[196:197]
	v_pk_mul_f32 v[102:103], v[102:103], v[198:199]
	v_pk_mul_f32 v[104:105], v[104:105], v[200:201]
	v_pk_mul_f32 v[106:107], v[106:107], v[202:203]
	v_pk_mul_f32 v[108:109], v[108:109], v[204:205]
	v_pk_mul_f32 v[110:111], v[110:111], v[206:207]
	v_lshlrev_b32_e32 v56, 16, v72
	v_and_b32_e32 v57, 0xffff0000, v72
	v_lshlrev_b32_e32 v58, 16, v73
	v_and_b32_e32 v59, 0xffff0000, v73
	v_lshlrev_b32_e32 v60, 16, v74
	v_and_b32_e32 v61, 0xffff0000, v74
	v_lshlrev_b32_e32 v62, 16, v75
	v_and_b32_e32 v63, 0xffff0000, v75
	v_pk_fma_f32 v[96:97], v[88:89], v[56:57], v[96:97] op_sel_hi:[0,1,1]
	v_pk_fma_f32 v[98:99], v[88:89], v[58:59], v[98:99] op_sel_hi:[0,1,1]
	v_pk_fma_f32 v[100:101], v[88:89], v[60:61], v[100:101] op_sel_hi:[0,1,1]
	v_pk_fma_f32 v[102:103], v[88:89], v[62:63], v[102:103] op_sel_hi:[0,1,1]
	v_lshlrev_b32_e32 v56, 16, v76
	v_and_b32_e32 v57, 0xffff0000, v76
	v_lshlrev_b32_e32 v58, 16, v77
	v_and_b32_e32 v59, 0xffff0000, v77
	v_lshlrev_b32_e32 v60, 16, v78
	v_and_b32_e32 v61, 0xffff0000, v78
	v_lshlrev_b32_e32 v62, 16, v79
	v_and_b32_e32 v63, 0xffff0000, v79
	v_pk_fma_f32 v[104:105], v[88:89], v[56:57], v[104:105] op_sel_hi:[0,1,1]
	v_pk_fma_f32 v[106:107], v[88:89], v[58:59], v[106:107] op_sel_hi:[0,1,1]
	v_pk_fma_f32 v[108:109], v[88:89], v[60:61], v[108:109] op_sel_hi:[0,1,1]
	v_pk_fma_f32 v[110:111], v[88:89], v[62:63], v[110:111] op_sel_hi:[0,1,1]
	global_store_dwordx4 v175, v[96:99], s[100:101]
	global_store_dwordx4 v175, v[100:103], s[100:101] offset:1024
	global_store_dwordx4 v175, v[104:107], s[100:101] offset:2048
	global_store_dwordx4 v175, v[108:111], s[100:101] offset:3072
	v_add_u32_e32 v175, 0xff800000, v175
	v_pk_mul_f32 v[112:113], v[130:131], v[112:113] op_sel_hi:[0,1]
	v_pk_mul_f32 v[114:115], v[130:131], v[114:115] op_sel_hi:[0,1]
	v_pk_mul_f32 v[116:117], v[130:131], v[116:117] op_sel_hi:[0,1]
	v_pk_mul_f32 v[118:119], v[130:131], v[118:119] op_sel_hi:[0,1]
	v_pk_mul_f32 v[120:121], v[130:131], v[120:121] op_sel_hi:[0,1]
	v_pk_mul_f32 v[122:123], v[130:131], v[122:123] op_sel_hi:[0,1]
	v_pk_mul_f32 v[124:125], v[130:131], v[124:125] op_sel_hi:[0,1]
	v_pk_mul_f32 v[126:127], v[130:131], v[126:127] op_sel_hi:[0,1]
	v_pk_mul_f32 v[112:113], v[112:113], v[192:193]
	v_pk_mul_f32 v[114:115], v[114:115], v[194:195]
	v_pk_mul_f32 v[116:117], v[116:117], v[196:197]
	v_pk_mul_f32 v[118:119], v[118:119], v[198:199]
	v_pk_mul_f32 v[120:121], v[120:121], v[200:201]
	v_pk_mul_f32 v[122:123], v[122:123], v[202:203]
	v_pk_mul_f32 v[124:125], v[124:125], v[204:205]
	v_pk_mul_f32 v[126:127], v[126:127], v[206:207]
	v_lshlrev_b32_e32 v64, 16, v80
	v_and_b32_e32 v65, 0xffff0000, v80
	v_lshlrev_b32_e32 v66, 16, v81
	v_and_b32_e32 v67, 0xffff0000, v81
	v_lshlrev_b32_e32 v68, 16, v82
	v_and_b32_e32 v69, 0xffff0000, v82
	v_lshlrev_b32_e32 v70, 16, v83
	v_and_b32_e32 v71, 0xffff0000, v83
	v_pk_fma_f32 v[112:113], v[90:91], v[64:65], v[112:113] op_sel_hi:[0,1,1]
	v_pk_fma_f32 v[114:115], v[90:91], v[66:67], v[114:115] op_sel_hi:[0,1,1]
	v_pk_fma_f32 v[116:117], v[90:91], v[68:69], v[116:117] op_sel_hi:[0,1,1]
	v_pk_fma_f32 v[118:119], v[90:91], v[70:71], v[118:119] op_sel_hi:[0,1,1]
	v_lshlrev_b32_e32 v64, 16, v84
	v_and_b32_e32 v65, 0xffff0000, v84
	v_lshlrev_b32_e32 v66, 16, v85
	v_and_b32_e32 v67, 0xffff0000, v85
	v_lshlrev_b32_e32 v68, 16, v86
	v_and_b32_e32 v69, 0xffff0000, v86
	v_lshlrev_b32_e32 v70, 16, v87
	v_and_b32_e32 v71, 0xffff0000, v87
	v_pk_fma_f32 v[120:121], v[90:91], v[64:65], v[120:121] op_sel_hi:[0,1,1]
	v_pk_fma_f32 v[122:123], v[90:91], v[66:67], v[122:123] op_sel_hi:[0,1,1]
	v_pk_fma_f32 v[124:125], v[90:91], v[68:69], v[124:125] op_sel_hi:[0,1,1]
	v_pk_fma_f32 v[126:127], v[90:91], v[70:71], v[126:127] op_sel_hi:[0,1,1]
	global_store_dwordx4 v175, v[112:115], s[100:101]
	global_store_dwordx4 v175, v[116:119], s[100:101] offset:1024
	global_store_dwordx4 v175, v[120:123], s[100:101] offset:2048
	global_store_dwordx4 v175, v[124:127], s[100:101] offset:3072
	v_add_u32_e32 v175, 0xff800000, v175
	global_load_dword v88, v172, s[98:99]
	global_load_dwordx2 v[56:57], v170, s[98:99]
	global_load_dwordx2 v[58:59], v170, s[98:99] offset:512
	global_load_dwordx2 v[60:61], v170, s[98:99] offset:1024
	global_load_dwordx2 v[62:63], v170, s[98:99] offset:1536
	global_load_dwordx2 v[72:73], v171, s[98:99]
	global_load_dwordx2 v[74:75], v171, s[98:99] offset:512
	global_load_dwordx2 v[76:77], v171, s[98:99] offset:1024
	global_load_dwordx2 v[78:79], v171, s[98:99] offset:1536
	v_add_u32_e32 v170, 0xffc00000, v170
	v_add_u32_e32 v171, 0xffc00000, v171
	v_add_u32_e32 v172, 0xffffe000, v172
	global_load_dword v90, v172, s[98:99]
	global_load_dwordx2 v[64:65], v170, s[98:99]
	global_load_dwordx2 v[66:67], v170, s[98:99] offset:512
	global_load_dwordx2 v[68:69], v170, s[98:99] offset:1024
	global_load_dwordx2 v[70:71], v170, s[98:99] offset:1536
	global_load_dwordx2 v[80:81], v171, s[98:99]
	global_load_dwordx2 v[82:83], v171, s[98:99] offset:512
	global_load_dwordx2 v[84:85], v171, s[98:99] offset:1024
	global_load_dwordx2 v[86:87], v171, s[98:99] offset:1536
	v_add_u32_e32 v170, 0xffc00000, v170
	v_add_u32_e32 v171, 0xffc00000, v171
	v_add_u32_e32 v172, 0xffffe000, v172
	s_waitcnt vmcnt(39)
;     __device__ __forceinline__ float* out() const { return (float*)karg_in(33); }
; __device__ __forceinline__ float ssq4(v4f v) { return (v.x * v.x + v.y * v.y) + (v.z * v.z + v.w * v.w); }
; template <int R, bool BASE_F32, bool OUT_F32>
; __device__ __forceinline__ void rows_res(const Ctx& C, int m0, int stride, int mx, const float* gpost, float scale, int lane) {
;     ...
;     for (int r = 0; r < R; ++r) { float s = 0.f;
; #pragma unroll
;         for (int j = 0; j < 4; ++j) s += ssq4(d[r][j]);
;         r1[r] = s; }
; #pragma unroll
;     for (int r = 0; r < R; ++r) r1[r] = rsqrtf(wave_sum(r1[r]) * (1.f / DM) + EPS) * scale;
; #pragma unroll
;     for (int j = 0; j < 4; ++j) { const v4f gp = ld4_f32(gpost + 4 * lane + 256 * j);
; #pragma unroll
;         for (int r = 0; r < R; ++r) d[r][j] = b[r][j] + d[r][j] * r1[r] * gp; }
;     if (OUT_F32) { float* Y = C.out();
; #pragma unroll
;         for (int r = 0; r < R; ++r)
; #pragma unroll
;             for (int j = 0; j < 4; ++j) if (ok[r]) *(v4f*)(Y + (size_t)mr[r] * DM + 4 * lane + 256 * j) = d[r][j];
	v_lshlrev_b32_e32 v96, 16, v20
	v_and_b32_e32 v97, 0xffff0000, v20
	v_lshlrev_b32_e32 v98, 16, v21
	v_and_b32_e32 v99, 0xffff0000, v21
	v_lshlrev_b32_e32 v100, 16, v22
	v_and_b32_e32 v101, 0xffff0000, v22
	v_lshlrev_b32_e32 v102, 16, v23
	v_and_b32_e32 v103, 0xffff0000, v23
	v_lshlrev_b32_e32 v104, 16, v24
	v_and_b32_e32 v105, 0xffff0000, v24
	v_lshlrev_b32_e32 v106, 16, v25
	v_and_b32_e32 v107, 0xffff0000, v25
	v_lshlrev_b32_e32 v108, 16, v26
	v_and_b32_e32 v109, 0xffff0000, v26
	v_lshlrev_b32_e32 v110, 16, v27
	v_and_b32_e32 v111, 0xffff0000, v27
	v_pk_mul_f32 v[128:129], v[96:97], v[96:97]
	v_pk_fma_f32 v[128:129], v[98:99], v[98:99], v[128:129]
	v_pk_fma_f32 v[128:129], v[100:101], v[100:101], v[128:129]
	v_pk_fma_f32 v[128:129], v[102:103], v[102:103], v[128:129]
	v_pk_fma_f32 v[128:129], v[104:105], v[104:105], v[128:129]
	v_pk_fma_f32 v[128:129], v[106:107], v[106:107], v[128:129]
	v_pk_fma_f32 v[128:129], v[108:109], v[108:109], v[128:129]
	v_pk_fma_f32 v[128:129], v[110:111], v[110:111], v[128:129]
	s_nop 0
	v_add_f32_e32 v128, v128, v129
	s_waitcnt vmcnt(30)
	v_lshlrev_b32_e32 v112, 16, v28
	v_and_b32_e32 v113, 0xffff0000, v28
	v_lshlrev_b32_e32 v114, 16, v29
	v_and_b32_e32 v115, 0xffff0000, v29
	v_lshlrev_b32_e32 v116, 16, v30
	v_and_b32_e32 v117, 0xffff0000, v30
	v_lshlrev_b32_e32 v118, 16, v31
	v_and_b32_e32 v119, 0xffff0000, v31
	v_lshlrev_b32_e32 v120, 16, v32
	v_and_b32_e32 v121, 0xffff0000, v32
	v_lshlrev_b32_e32 v122, 16, v33
	v_and_b32_e32 v123, 0xffff0000, v33
	v_lshlrev_b32_e32 v124, 16, v34
	v_and_b32_e32 v125, 0xffff0000, v34
	v_lshlrev_b32_e32 v126, 16, v35
	v_and_b32_e32 v127, 0xffff0000, v35
	v_pk_mul_f32 v[130:131], v[112:113], v[112:113]
	v_pk_fma_f32 v[130:131], v[114:115], v[114:115], v[130:131]
	v_pk_fma_f32 v[130:131], v[116:117], v[116:117], v[130:131]
	v_pk_fma_f32 v[130:131], v[118:119], v[118:119], v[130:131]
	v_pk_fma_f32 v[130:131], v[120:121], v[120:121], v[130:131]
	v_pk_fma_f32 v[130:131], v[122:123], v[122:123], v[130:131]
	v_pk_fma_f32 v[130:131], v[124:125], v[124:125], v[130:131]
	v_pk_fma_f32 v[130:131], v[126:127], v[126:127], v[130:131]
	s_nop 0
	v_add_f32_e32 v130, v130, v131
	s_nop 1
	v_add_f32_dpp v128, v128, v128 quad_perm:[1,0,3,2] row_mask:0xf bank_mask:0xf
	v_add_f32_dpp v130, v130, v130 quad_perm:[1,0,3,2] row_mask:0xf bank_mask:0xf
	s_nop 0
	v_add_f32_dpp v128, v128, v128 quad_perm:[2,3,0,1] row_mask:0xf bank_mask:0xf
	v_add_f32_dpp v130, v130, v130 quad_perm:[2,3,0,1] row_mask:0xf bank_mask:0xf
	s_nop 0
	v_add_f32_dpp v128, v128, v128 row_half_mirror row_mask:0xf bank_mask:0xf
	v_add_f32_dpp v130, v130, v130 row_half_mirror row_mask:0xf bank_mask:0xf
	s_nop 0
	v_add_f32_dpp v128, v128, v128 row_mirror row_mask:0xf bank_mask:0xf
	v_add_f32_dpp v130, v130, v130 row_mirror row_mask:0xf bank_mask:0xf
	s_nop 0
	ds_bpermute_b32 v136, v187, v128
	ds_bpermute_b32 v137, v187, v130
	s_waitcnt lgkmcnt(0)
	v_add_f32_e32 v128, v128, v136
	v_add_f32_e32 v130, v130, v137
	ds_bpermute_b32 v136, v188, v128
	ds_bpermute_b32 v137, v188, v130
	s_waitcnt lgkmcnt(0)
	v_add_f32_e32 v128, v128, v136
	v_add_f32_e32 v130, v130, v137
	v_fmamk_f32 v128, v128, 0x3a800000, v138
	v_fmamk_f32 v130, v130, 0x3a800000, v138
	s_nop 0
	v_rsq_f32_e32 v128, v128
	v_rsq_f32_e32 v130, v130
	s_nop 1
	v_mul_f32_e32 v128, 0.5, v128
	v_mul_f32_e32 v130, 0.5, v130
	s_waitcnt vmcnt(26)
	v_pk_mul_f32 v[96:97], v[128:129], v[96:97] op_sel_hi:[0,1]
	v_pk_mul_f32 v[98:99], v[128:129], v[98:99] op_sel_hi:[0,1]
	v_pk_mul_f32 v[100:101], v[128:129], v[100:101] op_sel_hi:[0,1]
	v_pk_mul_f32 v[102:103], v[128:129], v[102:103] op_sel_hi:[0,1]
	v_pk_mul_f32 v[104:105], v[128:129], v[104:105] op_sel_hi:[0,1]
	v_pk_mul_f32 v[106:107], v[128:129], v[106:107] op_sel_hi:[0,1]
	v_pk_mul_f32 v[108:109], v[128:129], v[108:109] op_sel_hi:[0,1]
	v_pk_mul_f32 v[110:111], v[128:129], v[110:111] op_sel_hi:[0,1]
	v_pk_mul_f32 v[96:97], v[96:97], v[192:193]
	v_pk_mul_f32 v[98:99], v[98:99], v[194:195]
	v_pk_mul_f32 v[100:101], v[100:101], v[196:197]
	v_pk_mul_f32 v[102:103], v[102:103], v[198:199]
	v_pk_mul_f32 v[104:105], v[104:105], v[200:201]
	v_pk_mul_f32 v[106:107], v[106:107], v[202:203]
	v_pk_mul_f32 v[108:109], v[108:109], v[204:205]
	v_pk_mul_f32 v[110:111], v[110:111], v[206:207]
	v_lshlrev_b32_e32 v20, 16, v36
	v_and_b32_e32 v21, 0xffff0000, v36
	v_lshlrev_b32_e32 v22, 16, v37
	v_and_b32_e32 v23, 0xffff0000, v37
	v_lshlrev_b32_e32 v24, 16, v38
	v_and_b32_e32 v25, 0xffff0000, v38
	v_lshlrev_b32_e32 v26, 16, v39
	v_and_b32_e32 v27, 0xffff0000, v39
	v_pk_fma_f32 v[96:97], v[52:53], v[20:21], v[96:97] op_sel_hi:[0,1,1]
	v_pk_fma_f32 v[98:99], v[52:53], v[22:23], v[98:99] op_sel_hi:[0,1,1]
	v_pk_fma_f32 v[100:101], v[52:53], v[24:25], v[100:101] op_sel_hi:[0,1,1]
	v_pk_fma_f32 v[102:103], v[52:53], v[26:27], v[102:103] op_sel_hi:[0,1,1]
	v_lshlrev_b32_e32 v20, 16, v40
	v_and_b32_e32 v21, 0xffff0000, v40
	v_lshlrev_b32_e32 v22, 16, v41
	v_and_b32_e32 v23, 0xffff0000, v41
	v_lshlrev_b32_e32 v24, 16, v42
	v_and_b32_e32 v25, 0xffff0000, v42
	v_lshlrev_b32_e32 v26, 16, v43
	v_and_b32_e32 v27, 0xffff0000, v43
	v_pk_fma_f32 v[104:105], v[52:53], v[20:21], v[104:105] op_sel_hi:[0,1,1]
	v_pk_fma_f32 v[106:107], v[52:53], v[22:23], v[106:107] op_sel_hi:[0,1,1]
	v_pk_fma_f32 v[108:109], v[52:53], v[24:25], v[108:109] op_sel_hi:[0,1,1]
	v_pk_fma_f32 v[110:111], v[52:53], v[26:27], v[110:111] op_sel_hi:[0,1,1]
	global_store_dwordx4 v175, v[96:99], s[100:101]
	global_store_dwordx4 v175, v[100:103], s[100:101] offset:1024
	global_store_dwordx4 v175, v[104:107], s[100:101] offset:2048
	global_store_dwordx4 v175, v[108:111], s[100:101] offset:3072
;     __device__ __forceinline__ float* out() const { return (float*)karg_in(33); }
; __device__ __forceinline__ float ssq4(v4f v) { return (v.x * v.x + v.y * v.y) + (v.z * v.z + v.w * v.w); }
; template <int R, bool BASE_F32, bool OUT_F32>
; __device__ __forceinline__ void rows_res(const Ctx& C, int m0, int stride, int mx, const float* gpost, float scale, int lane) {
;     ...
;     for (int r = 0; r < R; ++r) { float s = 0.f;
; #pragma unroll
;         for (int j = 0; j < 4; ++j) s += ssq4(d[r][j]);
;         r1[r] = s; }
; #pragma unroll
;     for (int r = 0; r < R; ++r) r1[r] = rsqrtf(wave_sum(r1[r]) * (1.f / DM) + EPS) * scale;
; #pragma unroll
;     for (int j = 0; j < 4; ++j) { const v4f gp = ld4_f32(gpost + 4 * lane + 256 * j);
; #pragma unroll
;         for (int r = 0; r < R; ++r) d[r][j] = b[r][j] + d[r][j] * r1[r] * gp; }
;     if (OUT_F32) { float* Y = C.out();
; #pragma unroll
;         for (int r = 0; r < R; ++r)
; #pragma unroll
;             for (int j = 0; j < 4; ++j) if (ok[r]) *(v4f*)(Y + (size_t)mr[r] * DM + 4 * lane + 256 * j) = d[r][j];
	v_add_u32_e32 v175, 0xff800000, v175
	v_pk_mul_f32 v[112:113], v[130:131], v[112:113] op_sel_hi:[0,1]
	v_pk_mul_f32 v[114:115], v[130:131], v[114:115] op_sel_hi:[0,1]
	v_pk_mul_f32 v[116:117], v[130:131], v[116:117] op_sel_hi:[0,1]
	v_pk_mul_f32 v[118:119], v[130:131], v[118:119] op_sel_hi:[0,1]
	v_pk_mul_f32 v[120:121], v[130:131], v[120:121] op_sel_hi:[0,1]
	v_pk_mul_f32 v[122:123], v[130:131], v[122:123] op_sel_hi:[0,1]
	v_pk_mul_f32 v[124:125], v[130:131], v[124:125] op_sel_hi:[0,1]
	v_pk_mul_f32 v[126:127], v[130:131], v[126:127] op_sel_hi:[0,1]
	v_pk_mul_f32 v[112:113], v[112:113], v[192:193]
	v_pk_mul_f32 v[114:115], v[114:115], v[194:195]
	v_pk_mul_f32 v[116:117], v[116:117], v[196:197]
	v_pk_mul_f32 v[118:119], v[118:119], v[198:199]
	v_pk_mul_f32 v[120:121], v[120:121], v[200:201]
	v_pk_mul_f32 v[122:123], v[122:123], v[202:203]
	v_pk_mul_f32 v[124:125], v[124:125], v[204:205]
	v_pk_mul_f32 v[126:127], v[126:127], v[206:207]
	v_lshlrev_b32_e32 v28, 16, v44
	v_and_b32_e32 v29, 0xffff0000, v44
	v_lshlrev_b32_e32 v30, 16, v45
	v_and_b32_e32 v31, 0xffff0000, v45
	v_lshlrev_b32_e32 v32, 16, v46
	v_and_b32_e32 v33, 0xffff0000, v46
	v_lshlrev_b32_e32 v34, 16, v47
	v_and_b32_e32 v35, 0xffff0000, v47
	v_pk_fma_f32 v[112:113], v[54:55], v[28:29], v[112:113] op_sel_hi:[0,1,1]
	v_pk_fma_f32 v[114:115], v[54:55], v[30:31], v[114:115] op_sel_hi:[0,1,1]
	v_pk_fma_f32 v[116:117], v[54:55], v[32:33], v[116:117] op_sel_hi:[0,1,1]
	v_pk_fma_f32 v[118:119], v[54:55], v[34:35], v[118:119] op_sel_hi:[0,1,1]
	v_lshlrev_b32_e32 v28, 16, v48
	v_and_b32_e32 v29, 0xffff0000, v48
	v_lshlrev_b32_e32 v30, 16, v49
	v_and_b32_e32 v31, 0xffff0000, v49
	v_lshlrev_b32_e32 v32, 16, v50
	v_and_b32_e32 v33, 0xffff0000, v50
	v_lshlrev_b32_e32 v34, 16, v51
	v_and_b32_e32 v35, 0xffff0000, v51
	v_pk_fma_f32 v[120:121], v[54:55], v[28:29], v[120:121] op_sel_hi:[0,1,1]
	v_pk_fma_f32 v[122:123], v[54:55], v[30:31], v[122:123] op_sel_hi:[0,1,1]
	v_pk_fma_f32 v[124:125], v[54:55], v[32:33], v[124:125] op_sel_hi:[0,1,1]
	v_pk_fma_f32 v[126:127], v[54:55], v[34:35], v[126:127] op_sel_hi:[0,1,1]
	global_store_dwordx4 v175, v[112:115], s[100:101]
	global_store_dwordx4 v175, v[116:119], s[100:101] offset:1024
	global_store_dwordx4 v175, v[120:123], s[100:101] offset:2048
	global_store_dwordx4 v175, v[124:127], s[100:101] offset:3072
	v_add_u32_e32 v175, 0xff800000, v175
	s_waitcnt vmcnt(21)
	v_lshlrev_b32_e32 v96, 16, v56
	v_and_b32_e32 v97, 0xffff0000, v56
	v_lshlrev_b32_e32 v98, 16, v57
	v_and_b32_e32 v99, 0xffff0000, v57
	v_lshlrev_b32_e32 v100, 16, v58
	v_and_b32_e32 v101, 0xffff0000, v58
	v_lshlrev_b32_e32 v102, 16, v59
	v_and_b32_e32 v103, 0xffff0000, v59
	v_lshlrev_b32_e32 v104, 16, v60
	v_and_b32_e32 v105, 0xffff0000, v60
	v_lshlrev_b32_e32 v106, 16, v61
	v_and_b32_e32 v107, 0xffff0000, v61
	v_lshlrev_b32_e32 v108, 16, v62
	v_and_b32_e32 v109, 0xffff0000, v62
	v_lshlrev_b32_e32 v110, 16, v63
	v_and_b32_e32 v111, 0xffff0000, v63
	v_pk_mul_f32 v[128:129], v[96:97], v[96:97]
	v_pk_fma_f32 v[128:129], v[98:99], v[98:99], v[128:129]
	v_pk_fma_f32 v[128:129], v[100:101], v[100:101], v[128:129]
	v_pk_fma_f32 v[128:129], v[102:103], v[102:103], v[128:129]
	v_pk_fma_f32 v[128:129], v[104:105], v[104:105], v[128:129]
	v_pk_fma_f32 v[128:129], v[106:107], v[106:107], v[128:129]
	v_pk_fma_f32 v[128:129], v[108:109], v[108:109], v[128:129]
	v_pk_fma_f32 v[128:129], v[110:111], v[110:111], v[128:129]
	s_nop 0
	v_add_f32_e32 v128, v128, v129
	s_waitcnt vmcnt(12)
	v_lshlrev_b32_e32 v112, 16, v64
	v_and_b32_e32 v113, 0xffff0000, v64
	v_lshlrev_b32_e32 v114, 16, v65
	v_and_b32_e32 v115, 0xffff0000, v65
	v_lshlrev_b32_e32 v116, 16, v66
	v_and_b32_e32 v117, 0xffff0000, v66
	v_lshlrev_b32_e32 v118, 16, v67
	v_and_b32_e32 v119, 0xffff0000, v67
	v_lshlrev_b32_e32 v120, 16, v68
	v_and_b32_e32 v121, 0xffff0000, v68
	v_lshlrev_b32_e32 v122, 16, v69
	v_and_b32_e32 v123, 0xffff0000, v69
	v_lshlrev_b32_e32 v124, 16, v70
	v_and_b32_e32 v125, 0xffff0000, v70
	v_lshlrev_b32_e32 v126, 16, v71
	v_and_b32_e32 v127, 0xffff0000, v71
	v_pk_mul_f32 v[130:131], v[112:113], v[112:113]
	v_pk_fma_f32 v[130:131], v[114:115], v[114:115], v[130:131]
	v_pk_fma_f32 v[130:131], v[116:117], v[116:117], v[130:131]
	v_pk_fma_f32 v[130:131], v[118:119], v[118:119], v[130:131]
	v_pk_fma_f32 v[130:131], v[120:121], v[120:121], v[130:131]
	v_pk_fma_f32 v[130:131], v[122:123], v[122:123], v[130:131]
	v_pk_fma_f32 v[130:131], v[124:125], v[124:125], v[130:131]
	v_pk_fma_f32 v[130:131], v[126:127], v[126:127], v[130:131]
	s_nop 0
	v_add_f32_e32 v130, v130, v131
	s_nop 1
	v_add_f32_dpp v128, v128, v128 quad_perm:[1,0,3,2] row_mask:0xf bank_mask:0xf
	v_add_f32_dpp v130, v130, v130 quad_perm:[1,0,3,2] row_mask:0xf bank_mask:0xf
	s_nop 0
	v_add_f32_dpp v128, v128, v128 quad_perm:[2,3,0,1] row_mask:0xf bank_mask:0xf
	v_add_f32_dpp v130, v130, v130 quad_perm:[2,3,0,1] row_mask:0xf bank_mask:0xf
	s_nop 0
	v_add_f32_dpp v128, v128, v128 row_half_mirror row_mask:0xf bank_mask:0xf
	v_add_f32_dpp v130, v130, v130 row_half_mirror row_mask:0xf bank_mask:0xf
	s_nop 0
	v_add_f32_dpp v128, v128, v128 row_mirror row_mask:0xf bank_mask:0xf
	v_add_f32_dpp v130, v130, v130 row_mirror row_mask:0xf bank_mask:0xf
	s_nop 0
	ds_bpermute_b32 v136, v187, v128
	ds_bpermute_b32 v137, v187, v130
	s_waitcnt lgkmcnt(0)
;     __device__ __forceinline__ float* out() const { return (float*)karg_in(33); }
; __device__ __forceinline__ float ssq4(v4f v) { return (v.x * v.x + v.y * v.y) + (v.z * v.z + v.w * v.w); }
; template <int R, bool BASE_F32, bool OUT_F32>
; __device__ __forceinline__ void rows_res(const Ctx& C, int m0, int stride, int mx, const float* gpost, float scale, int lane) {
;     ...
;     for (int r = 0; r < R; ++r) { float s = 0.f;
; #pragma unroll
;         for (int j = 0; j < 4; ++j) s += ssq4(d[r][j]);
;         r1[r] = s; }
; #pragma unroll
;     for (int r = 0; r < R; ++r) r1[r] = rsqrtf(wave_sum(r1[r]) * (1.f / DM) + EPS) * scale;
; #pragma unroll
;     for (int j = 0; j < 4; ++j) { const v4f gp = ld4_f32(gpost + 4 * lane + 256 * j);
; #pragma unroll
;         for (int r = 0; r < R; ++r) d[r][j] = b[r][j] + d[r][j] * r1[r] * gp; }
;     if (OUT_F32) { float* Y = C.out();
; #pragma unroll
;         for (int r = 0; r < R; ++r)
; #pragma unroll
;             for (int j = 0; j < 4; ++j) if (ok[r]) *(v4f*)(Y + (size_t)mr[r] * DM + 4 * lane + 256 * j) = d[r][j];
	v_add_f32_e32 v128, v128, v136
	v_add_f32_e32 v130, v130, v137
	ds_bpermute_b32 v136, v188, v128
	ds_bpermute_b32 v137, v188, v130
	s_waitcnt lgkmcnt(0)
	v_add_f32_e32 v128, v128, v136
	v_add_f32_e32 v130, v130, v137
	v_fmamk_f32 v128, v128, 0x3a800000, v138
	v_fmamk_f32 v130, v130, 0x3a800000, v138
	s_nop 0
	v_rsq_f32_e32 v128, v128
	v_rsq_f32_e32 v130, v130
	s_nop 1
	v_mul_f32_e32 v128, 0.5, v128
	v_mul_f32_e32 v130, 0.5, v130
	s_waitcnt vmcnt(8)
	v_pk_mul_f32 v[96:97], v[128:129], v[96:97] op_sel_hi:[0,1]
	v_pk_mul_f32 v[98:99], v[128:129], v[98:99] op_sel_hi:[0,1]
	v_pk_mul_f32 v[100:101], v[128:129], v[100:101] op_sel_hi:[0,1]
	v_pk_mul_f32 v[102:103], v[128:129], v[102:103] op_sel_hi:[0,1]
	v_pk_mul_f32 v[104:105], v[128:129], v[104:105] op_sel_hi:[0,1]
	v_pk_mul_f32 v[106:107], v[128:129], v[106:107] op_sel_hi:[0,1]
	v_pk_mul_f32 v[108:109], v[128:129], v[108:109] op_sel_hi:[0,1]
	v_pk_mul_f32 v[110:111], v[128:129], v[110:111] op_sel_hi:[0,1]
	v_pk_mul_f32 v[96:97], v[96:97], v[192:193]
	v_pk_mul_f32 v[98:99], v[98:99], v[194:195]
	v_pk_mul_f32 v[100:101], v[100:101], v[196:197]
	v_pk_mul_f32 v[102:103], v[102:103], v[198:199]
	v_pk_mul_f32 v[104:105], v[104:105], v[200:201]
	v_pk_mul_f32 v[106:107], v[106:107], v[202:203]
	v_pk_mul_f32 v[108:109], v[108:109], v[204:205]
	v_pk_mul_f32 v[110:111], v[110:111], v[206:207]
	v_lshlrev_b32_e32 v56, 16, v72
	v_and_b32_e32 v57, 0xffff0000, v72
	v_lshlrev_b32_e32 v58, 16, v73
	v_and_b32_e32 v59, 0xffff0000, v73
	v_lshlrev_b32_e32 v60, 16, v74
	v_and_b32_e32 v61, 0xffff0000, v74
	v_lshlrev_b32_e32 v62, 16, v75
	v_and_b32_e32 v63, 0xffff0000, v75
	v_pk_fma_f32 v[96:97], v[88:89], v[56:57], v[96:97] op_sel_hi:[0,1,1]
	v_pk_fma_f32 v[98:99], v[88:89], v[58:59], v[98:99] op_sel_hi:[0,1,1]
	v_pk_fma_f32 v[100:101], v[88:89], v[60:61], v[100:101] op_sel_hi:[0,1,1]
	v_pk_fma_f32 v[102:103], v[88:89], v[62:63], v[102:103] op_sel_hi:[0,1,1]
	v_lshlrev_b32_e32 v56, 16, v76
	v_and_b32_e32 v57, 0xffff0000, v76
	v_lshlrev_b32_e32 v58, 16, v77
	v_and_b32_e32 v59, 0xffff0000, v77
	v_lshlrev_b32_e32 v60, 16, v78
	v_and_b32_e32 v61, 0xffff0000, v78
	v_lshlrev_b32_e32 v62, 16, v79
	v_and_b32_e32 v63, 0xffff0000, v79
	v_pk_fma_f32 v[104:105], v[88:89], v[56:57], v[104:105] op_sel_hi:[0,1,1]
	v_pk_fma_f32 v[106:107], v[88:89], v[58:59], v[106:107] op_sel_hi:[0,1,1]
	v_pk_fma_f32 v[108:109], v[88:89], v[60:61], v[108:109] op_sel_hi:[0,1,1]
	v_pk_fma_f32 v[110:111], v[88:89], v[62:63], v[110:111] op_sel_hi:[0,1,1]
	global_store_dwordx4 v175, v[96:99], s[100:101]
	global_store_dwordx4 v175, v[100:103], s[100:101] offset:1024
	global_store_dwordx4 v175, v[104:107], s[100:101] offset:2048
	global_store_dwordx4 v175, v[108:111], s[100:101] offset:3072
	v_add_u32_e32 v175, 0xff800000, v175
	v_pk_mul_f32 v[112:113], v[130:131], v[112:113] op_sel_hi:[0,1]
	v_pk_mul_f32 v[114:115], v[130:131], v[114:115] op_sel_hi:[0,1]
	v_pk_mul_f32 v[116:117], v[130:131], v[116:117] op_sel_hi:[0,1]
	v_pk_mul_f32 v[118:119], v[130:131], v[118:119] op_sel_hi:[0,1]
	v_pk_mul_f32 v[120:121], v[130:131], v[120:121] op_sel_hi:[0,1]
	v_pk_mul_f32 v[122:123], v[130:131], v[122:123] op_sel_hi:[0,1]
	v_pk_mul_f32 v[124:125], v[130:131], v[124:125] op_sel_hi:[0,1]
	v_pk_mul_f32 v[126:127], v[130:131], v[126:127] op_sel_hi:[0,1]
	v_pk_mul_f32 v[112:113], v[112:113], v[192:193]
	v_pk_mul_f32 v[114:115], v[114:115], v[194:195]
	v_pk_mul_f32 v[116:117], v[116:117], v[196:197]
	v_pk_mul_f32 v[118:119], v[118:119], v[198:199]
	v_pk_mul_f32 v[120:121], v[120:121], v[200:201]
	v_pk_mul_f32 v[122:123], v[122:123], v[202:203]
	v_pk_mul_f32 v[124:125], v[124:125], v[204:205]
	v_pk_mul_f32 v[126:127], v[126:127], v[206:207]
	v_lshlrev_b32_e32 v64, 16, v80
	v_and_b32_e32 v65, 0xffff0000, v80
	v_lshlrev_b32_e32 v66, 16, v81
	v_and_b32_e32 v67, 0xffff0000, v81
	v_lshlrev_b32_e32 v68, 16, v82
	v_and_b32_e32 v69, 0xffff0000, v82
	v_lshlrev_b32_e32 v70, 16, v83
	v_and_b32_e32 v71, 0xffff0000, v83
	v_pk_fma_f32 v[112:113], v[90:91], v[64:65], v[112:113] op_sel_hi:[0,1,1]
	v_pk_fma_f32 v[114:115], v[90:91], v[66:67], v[114:115] op_sel_hi:[0,1,1]
	v_pk_fma_f32 v[116:117], v[90:91], v[68:69], v[116:117] op_sel_hi:[0,1,1]
	v_pk_fma_f32 v[118:119], v[90:91], v[70:71], v[118:119] op_sel_hi:[0,1,1]
	v_lshlrev_b32_e32 v64, 16, v84
	v_and_b32_e32 v65, 0xffff0000, v84
	v_lshlrev_b32_e32 v66, 16, v85
	v_and_b32_e32 v67, 0xffff0000, v85
	v_lshlrev_b32_e32 v68, 16, v86
	v_and_b32_e32 v69, 0xffff0000, v86
	v_lshlrev_b32_e32 v70, 16, v87
	v_and_b32_e32 v71, 0xffff0000, v87
	v_pk_fma_f32 v[120:121], v[90:91], v[64:65], v[120:121] op_sel_hi:[0,1,1]
	v_pk_fma_f32 v[122:123], v[90:91], v[66:67], v[122:123] op_sel_hi:[0,1,1]
	v_pk_fma_f32 v[124:125], v[90:91], v[68:69], v[124:125] op_sel_hi:[0,1,1]
	v_pk_fma_f32 v[126:127], v[90:91], v[70:71], v[126:127] op_sel_hi:[0,1,1]
	global_store_dwordx4 v175, v[112:115], s[100:101]
	global_store_dwordx4 v175, v[116:119], s[100:101] offset:1024
	global_store_dwordx4 v175, v[120:123], s[100:101] offset:2048
	global_store_dwordx4 v175, v[124:127], s[100:101] offset:3072
	v_add_u32_e32 v175, 0xff800000, v175
	s_branch .LBB0_1283
	s_waitcnt lgkmcnt(0)
	v_lshl_add_u64 v[20:21], s[8:9], 0, v[16:17]
	v_mov_b32_e32 v19, v17
	s_mov_b64 s[10:11], 0x7100000
	s_mov_b64 s[12:13], 0x3000000
	v_mov_b32_e32 v23, 0x2a80000
	v_mov_b32_e32 v22, 0x358637bd
	s_mov_b32 s14, 0x3a800000
	s_mov_b32 s27, 0x800000
	s_mov_b32 s16, s15
	s_branch .LBB0_1275
